# v11: v10 + kernarg pointers from registers (ws from s[72:73], +48/+56/+80/+104 stashed in v255 lanes) instead of per-phase flat loads
# speedup vs baseline: 1.0027x; 1.0027x over previous
;     __host__ __device__ bool next(int i, Unit& u) const { return StaticOrder::next(i >> 1, u); }
;     __device__ __forceinline__ bool next(int i, Unit& u) const { const int s = i * G + c; if (s >= 128) return false; const int t = s >> 2; u.pm = pm0 + (t & 3); u.pn = t >> 2; u.k0 = (s & 3) * ksub; return true; }
;     __host__ __device__ bool next(int i, Unit& u) const {
;         const long L = (long)i * G + c; if (!(PG8_ROUND_MAJOR && G % NXCD == 0) && L >= nwg) return false; if ((long)i * G >= nwg) return false;
;         int wgid = (int)L;
;         if (PG8_ROUND_MAJOR && G % NXCD == 0) { const int per = G / NXCD; wgid = ((i * NXCD) + (c % NXCD)) * per + (c / NXCD); if (wgid >= nwg) return false; }
;         else { const int q = nwg / NXCD, r = nwg % NXCD, xcd = wgid % NXCD, off = wgid / NXCD; wgid = (xcd < r ? xcd * (q + 1) : r * (q + 1) + (xcd - r) * q) + off; }
;         const int nig = wgm * nN, gid = wgid / nig, fm = gid * wgm, gsz = (nM - fm) < wgm ? (nM - fm) : wgm;
;         u.pm = fm + ((wgid % nig) % gsz); u.pn = (wgid % nig) / gsz; u.k0 = 0; return true;
; __global__ void __launch_bounds__(NWAVES * 64, 2) fwd_kernel(Args args_in) {
;     ...
;         const int pb = 2 + 8 * layer;
;         const bool last = (layer == DEPTH - 1), hg = (layer & 1) != 0;
;         const int j = layer >> 1;
;         const int Mr = last ? ML : M;
;     ...
;         const int tc_slot = ((int)blockIdx.x & 7) * 32 + ((int)blockIdx.x >> 3);
;         const int tc_rem1 = (hg ? (M / 256) * 40 : (M / 256) * 32) % 256, tc_idle1 = 256 - tc_rem1;
.LBB0_201:
	s_cmpk_eq_i32 s3, 0x100
	s_cselect_b64 s[0:1], -1, 0
	v_writelane_b32 v254, s0, 20
	s_cmpk_lg_i32 s3, 0x100
	s_mov_b32 s85, 0
	v_writelane_b32 v254, s1, 21
	s_cselect_b64 s[0:1], -1, 0
	v_writelane_b32 v254, s0, 22
	s_ashr_i32 s97, s2, 31
	s_lshl_b32 s42, s3, 3
	v_writelane_b32 v254, s1, 23
	s_lshl_b32 s0, s2, 5
	s_and_b32 s0, s0, 0xe0
	s_ashr_i32 s1, s2, 3
	s_add_i32 s8, s0, s1
	s_lshr_b32 s0, s97, 29
	s_add_i32 s0, s2, s0
	s_ashr_i32 s10, s0, 3
	s_and_b32 s0, s0, -8
	s_sub_i32 s11, s2, s0
	s_ashr_i32 s0, s3, 3
	v_readlane_b32 s1, v254, 4
	v_writelane_b32 v254, s0, 24
	s_mul_i32 s0, s0, s11
	s_lshl_b32 s91, s1, 3
	s_add_i32 s14, s0, s10
	s_ashr_i32 s65, s3, 31
	s_cmpk_lt_i32 s1, 0x100
	s_cselect_b64 s[0:1], -1, 0
	v_writelane_b32 v254, s0, 25
	s_cmpk_lt_i32 s2, 0x200
	s_mov_b32 s52, 0xf7800000
	v_writelane_b32 v254, s1, 26
	s_cselect_b64 s[0:1], -1, 0
	s_lshl_b32 s6, s11, 6
	s_cmpk_lt_i32 s14, 0x200
	s_cselect_b64 s[4:5], -1, 0
	s_cmpk_lt_i32 s2, 0x80
	s_cselect_b64 s[12:13], -1, 0
	v_writelane_b32 v254, s12, 27
	s_bfe_u32 s7, s2, 0x20002
	s_or_b32 s9, s7, 64
	v_writelane_b32 v254, s13, 28
	s_lshl_b32 s7, s2, 9
	v_writelane_b32 v254, s9, 29
	s_lshl_b32 s9, s9, 20
	s_and_b32 s7, s7, 0x600
	v_writelane_b32 v254, s9, 30
	s_ashr_i32 s16, s2, 4
	v_writelane_b32 v254, s7, 31
	s_lshl_b32 s7, s7, 1
	v_writelane_b32 v254, s7, 32
	s_mov_b32 s12, s16
	s_ashr_i32 s17, s16, 31
	v_writelane_b32 v254, s12, 33
	v_cndmask_b32_e64 v1, 0, 1, s[0:1]
	v_cndmask_b32_e64 v0, 0, 1, s[4:5]
	v_writelane_b32 v254, s13, 34
	s_lshl_b64 s[12:13], s[16:17], 20
	v_writelane_b32 v254, s12, 35
	s_cmpk_gt_i32 s2, 0x7f
	v_cndmask_b32_e64 v0, v1, v0, s[38:39]
	v_writelane_b32 v254, s13, 36
	s_cselect_b64 s[12:13], -1, 0
	s_lshl_b32 s7, s2, 3
	v_writelane_b32 v254, s12, 37
	s_add_i32 s9, s7, 0xfffffc00
	s_cmpk_gt_i32 s8, 0xaf
	v_writelane_b32 v254, s13, 38
	v_writelane_b32 v254, s9, 39
	s_cselect_b64 s[12:13], -1, 0
	v_writelane_b32 v254, s12, 40
	s_addk_i32 s7, 0x2a00
	v_and_b32_e32 v0, 1, v0
	v_writelane_b32 v254, s13, 41
	v_writelane_b32 v254, s8, 42
	s_lshl_b32 s8, s8, 3
	s_addk_i32 s8, 0xa80
	v_writelane_b32 v254, s8, 43
	s_and_b32 s8, s2, 3
	v_writelane_b32 v254, s7, 44
	s_mul_i32 s9, s8, 0x580
	v_writelane_b32 v254, s9, 45
	s_mulk_i32 s8, 0xb00
	s_cmp_lt_i32 s11, 0
	v_writelane_b32 v254, s8, 46
	s_movk_i32 s8, 0x155
	s_movk_i32 s9, 0x111
	s_mul_i32 s7, s11, 0x41
	s_cselect_b32 s8, s8, 0x154
	s_cselect_b32 s9, s9, 0x110
	s_mul_i32 s8, s11, s8
	s_mul_i32 s9, s11, s9
	s_cselect_b32 s6, s7, s6
	v_writelane_b32 v254, s10, 47
	s_add_i32 s8, s8, s10
	s_add_i32 s9, s9, s10
	s_add_i32 s10, s6, s10
	v_writelane_b32 v254, s11, 48
	s_lshr_b32 s6, s11, 31
	v_writelane_b32 v254, s6, 49
	s_and_b64 s[6:7], s[38:39], exec
	s_cselect_b32 s11, s14, s2
	s_cmpk_lt_i32 s11, 0xaa0
	s_cselect_b64 s[6:7], -1, 0
	v_writelane_b32 v254, s6, 50
	s_waitcnt lgkmcnt(0)
;     __host__ __device__ bool next(int i, Unit& u) const {
;         const long L = (long)i * G + c; if (!(PG8_ROUND_MAJOR && G % NXCD == 0) && L >= nwg) return false; if ((long)i * G >= nwg) return false;
;         int wgid = (int)L;
;         if (PG8_ROUND_MAJOR && G % NXCD == 0) { const int per = G / NXCD; wgid = ((i * NXCD) + (c % NXCD)) * per + (c / NXCD); if (wgid >= nwg) return false; }
;         else { const int q = nwg / NXCD, r = nwg % NXCD, xcd = wgid % NXCD, off = wgid / NXCD; wgid = (xcd < r ? xcd * (q + 1) : r * (q + 1) + (xcd - r) * q) + off; }
;         const int nig = wgm * nN, gid = wgid / nig, fm = gid * wgm, gsz = (nM - fm) < wgm ? (nM - fm) : wgm;
;         u.pm = fm + ((wgid % nig) % gsz); u.pn = (wgid % nig) / gsz; u.k0 = 0; return true;
; __global__ void __launch_bounds__(NWAVES * 64, 2) fwd_kernel(Args args_in) {
;     ...
;         const Args* kap = (const Args*)__builtin_amdgcn_kernarg_segment_ptr(); asm volatile("" : "+s"(kap));
;         const Args& args = *kap;
;         const float* MOD = (const float*)(ws + WS_MOD);
	s_mov_b32 s69, 0x3c000
	v_mov_b32_e32 v252, 0x358637bd
	v_writelane_b32 v254, s7, 51
	s_and_b64 s[6:7], s[38:39], exec
	s_cselect_b32 s6, s14, s8
	s_mul_hi_i32 s7, s6, 0x66666667
	s_lshr_b32 s8, s7, 31
	s_ashr_i32 s7, s7, 6
	s_add_i32 s7, s7, s8
	s_lshl_b32 s8, s7, 2
	s_sub_i32 s12, 0x44, s8
	s_mulk_i32 s7, 0xa0
	s_min_i32 s12, s12, 4
	s_sub_i32 s13, s6, s7
	s_cmpk_lt_i32 s11, 0x880
	s_cselect_b64 s[6:7], -1, 0
	v_writelane_b32 v254, s6, 52
	s_mov_b32 s55, 0xf800000
	v_mov_b32_e32 v253, 0x260
	v_writelane_b32 v254, s7, 53
	s_and_b64 s[6:7], s[38:39], exec
	s_cselect_b32 s6, s14, s9
	s_ashr_i32 s7, s6, 31
	s_lshr_b32 s7, s7, 25
	s_add_i32 s7, s6, s7
	s_ashr_i32 s9, s7, 7
	s_lshl_b32 s9, s9, 2
	s_sub_i32 s11, 0x44, s9
	s_and_b32 s7, s7, 0xffffff80
	s_min_i32 s11, s11, 4
	s_sub_i32 s6, s6, s7
	s_and_b64 s[0:1], s[38:39], exec
	s_cselect_b32 s0, s14, s10
	s_abs_i32 s5, s12
	v_cvt_f32_u32_e32 v1, s5
	v_writelane_b32 v254, s14, 54
	s_sub_i32 s14, 0, s5
	s_ashr_i32 s1, s0, 31
	v_rcp_iflag_f32_e32 v1, v1
	s_lshr_b32 s1, s1, 27
	s_add_i32 s1, s0, s1
	s_abs_i32 s10, s13
	v_mul_f32_e32 v1, 0x4f7ffffe, v1
	v_cvt_u32_f32_e32 v1, v1
	s_ashr_i32 s4, s1, 5
	s_lshl_b32 s4, s4, 2
	s_andn2_b32 s1, s1, 31
	v_readfirstlane_b32 s15, v1
	s_mul_i32 s14, s14, s15
	s_mul_hi_u32 s14, s15, s14
	s_add_i32 s15, s15, s14
	s_mul_hi_u32 s14, s10, s15
	s_mul_i32 s15, s14, s5
	s_sub_i32 s7, 64, s4
	s_sub_i32 s0, s0, s1
	s_xor_b32 s1, s13, s12
	s_sub_i32 s10, s10, s15
	s_min_i32 s7, s7, 4
	s_ashr_i32 s1, s1, 31
	s_add_i32 s15, s14, 1
	s_sub_i32 s16, s10, s5
	s_cmp_ge_u32 s10, s5
	s_cselect_b32 s14, s15, s14
	s_cselect_b32 s10, s16, s10
	s_add_i32 s15, s14, 1
	s_cmp_ge_u32 s10, s5
	s_cselect_b32 s5, s15, s14
	s_abs_i32 s10, s11
	v_cvt_f32_u32_e32 v1, s10
	s_xor_b32 s5, s5, s1
	s_sub_i32 s1, s5, s1
	v_writelane_b32 v254, s1, 55
	v_rcp_iflag_f32_e32 v1, v1
	s_mul_i32 s1, s1, s12
	s_sub_i32 s1, s13, s1
	s_add_i32 s1, s8, s1
	v_mul_f32_e32 v1, 0x4f7ffffe, v1
	v_cvt_u32_f32_e32 v1, v1
	s_sub_i32 s8, 0, s10
	s_abs_i32 s5, s6
	v_writelane_b32 v254, s1, 56
	v_readfirstlane_b32 s12, v1
	s_mul_i32 s8, s8, s12
	s_mul_hi_u32 s8, s12, s8
	s_add_i32 s12, s12, s8
	s_mul_hi_u32 s8, s5, s12
	s_mul_i32 s12, s8, s10
	s_xor_b32 s1, s6, s11
	s_sub_i32 s5, s5, s12
	s_ashr_i32 s1, s1, 31
	s_add_i32 s12, s8, 1
	s_sub_i32 s13, s5, s10
	s_cmp_ge_u32 s5, s10
	s_cselect_b32 s8, s12, s8
	s_cselect_b32 s5, s13, s5
	s_add_i32 s12, s8, 1
	s_cmp_ge_u32 s5, s10
	s_cselect_b32 s5, s12, s8
	s_abs_i32 s8, s7
	v_cvt_f32_u32_e32 v1, s8
	s_xor_b32 s5, s5, s1
	s_sub_i32 s1, s5, s1
	v_writelane_b32 v254, s1, 57
	v_rcp_iflag_f32_e32 v1, v1
	s_mul_i32 s1, s1, s11
	s_sub_i32 s1, s6, s1
	s_add_i32 s1, s9, s1
	v_mul_f32_e32 v1, 0x4f7ffffe, v1
	v_cvt_u32_f32_e32 v1, v1
	s_sub_i32 s6, 0, s8
	s_abs_i32 s5, s0
	v_writelane_b32 v254, s1, 58
	v_readfirstlane_b32 s9, v1
	s_mul_i32 s6, s6, s9
	s_mul_hi_u32 s6, s9, s6
	s_add_i32 s9, s9, s6
	s_mul_hi_u32 s6, s5, s9
	s_mul_i32 s9, s6, s8
	s_xor_b32 s1, s0, s7
	s_sub_i32 s5, s5, s9
	s_ashr_i32 s1, s1, 31
	s_add_i32 s9, s6, 1
	s_sub_i32 s10, s5, s8
	s_cmp_ge_u32 s5, s8
	s_cselect_b32 s6, s9, s6
	s_cselect_b32 s5, s10, s5
	s_add_i32 s9, s6, 1
	s_cmp_ge_u32 s5, s8
	s_cselect_b32 s5, s9, s6
	s_xor_b32 s5, s5, s1
	s_sub_i32 s6, s5, s1
	s_mul_i32 s1, s6, s7
	s_sub_i32 s0, s0, s1
	s_add_i32 s4, s4, s0
	s_ashr_i32 s0, s91, 31
	v_writelane_b32 v254, s0, 59
	s_add_i32 s0, 0, 0x20160
	v_writelane_b32 v254, s0, 60
	s_add_i32 s0, 0, 0x20164
	v_writelane_b32 v254, s0, 61
	s_add_i32 s0, 0, 0x12800
	v_writelane_b32 v254, s0, 62
	s_add_i32 s0, 0, 0x13800
	v_writelane_b32 v254, s0, 63
	s_add_i32 s0, 0, 0x16000
	v_writelane_b32 v255, s0, 0
	s_add_i32 s0, 0, 0x11000
	v_writelane_b32 v255, s0, 1
	v_cmp_eq_u32_e64 s[0:1], 1, v0
	s_ashr_i32 s5, s4, 31
	s_ashr_i32 s7, s6, 31
	v_writelane_b32 v255, s0, 2
	s_ashr_i32 s43, s42, 31
	v_mov_b32_e32 v1, 0
	v_writelane_b32 v255, s1, 3
	s_mov_b32 s0, s4
	v_writelane_b32 v255, s0, 4
	s_movk_i32 s94, 0x7ff
	v_mov_b32_e32 v182, 0x42a00000
	v_writelane_b32 v255, s1, 5
	s_lshl_b64 s[0:1], s[4:5], 20
	v_writelane_b32 v255, s0, 6
	v_mov_b32_e32 v183, 0x7f800000
	s_mov_b32 s95, 0xc2a00000
	v_writelane_b32 v255, s1, 7
	s_mov_b32 s0, s6
	v_writelane_b32 v255, s0, 8
	s_mov_b32 s50, 0x20000
	s_mov_b32 s90, 0x30000
	v_writelane_b32 v255, s1, 9
	s_lshl_b64 s[0:1], s[6:7], 20
	v_writelane_b32 v255, s0, 10
	s_mov_b32 s83, 0x80000
	s_mov_b32 s64, 0x50000
	v_writelane_b32 v255, s1, 11
	s_mov_b32 s67, 0xd5800000
	s_lshl_b64 s[74:75], s[42:43], 12
	s_mov_b32 s53, -1
	s_mov_b32 s96, 0xbfb8aa3b
	s_mov_b32 s68, 0x3f317218
	s_mov_b32 s56, 0x3fb8aa3b
	s_mov_b32 s54, 0x3d800000
	s_mov_b64 s[72:73], s[70:71]
	s_mov_b32 s76, s85
	v_writelane_b32 v255, s91, 12
	v_readlane_b32 s0, v254, 0
	v_readlane_b32 s1, v254, 1
	s_nop 4
	s_load_dwordx4 s[4:7], s[0:1], 0x30
	s_load_dwordx2 s[8:9], s[0:1], 0x50
	s_load_dwordx2 s[10:11], s[0:1], 0x68
	s_waitcnt lgkmcnt(0)
	v_writelane_b32 v255, s4, 32
	v_writelane_b32 v255, s5, 33
	v_writelane_b32 v255, s6, 34
	v_writelane_b32 v255, s7, 35
	v_writelane_b32 v255, s8, 36
	v_writelane_b32 v255, s9, 37
	v_writelane_b32 v255, s10, 38
	v_writelane_b32 v255, s11, 39
	s_branch .LBB0_205

; #define GAS __attribute__((address_space(1)))
; __device__ __forceinline__ void relaunder(Frame& F) { int t = mk_tid(); asm volatile("" : "+v"(t)); F.tid = t; F.lane = t & 63; F.wave = __builtin_amdgcn_readfirstlane(t >> 6); }
; #define NORM_FN(...) do { if (NORM_PIPE && F.G == 256) norm_mod_phase2(__VA_ARGS__); else norm_mod_phase(__VA_ARGS__); } while (0)
; __device__ __forceinline__ void norm_mod_phase(const Args& a, Frame& F, const float* gain, const float* modl, int sh_off, int sc_off, int nrows, const float* slab_gate) {
;     relaunder(F);
;     const int gw = F.vcu * NWAVES + F.wave, NGW = F.G * NWAVES;
;     bf16* X = (bf16*)(a.ws + WS_X); bf16* HN = (bf16*)(a.ws + WS_HN);
;     for (int r = gw; r < nrows; r += NGW) {
;         const int b = (r < ML) ? (r >> 12) : 4;
;         const GAS v2u* xr = (const GAS v2u*)(X + (size_t)r * D) + F.lane;
;         f32x4 v[8]; float ss = 0.f;
; #pragma unroll
; __global__ void __launch_bounds__(NWAVES * 64, 2) fwd_kernel(Args args_in) {
;     ...
;         if (IN(pb + 0)) NORM_FN(args, F, args.in[6] + (size_t)layer * D, modl, 0, D, M, layer > 0 ? (modl - 5 * MOD_LD) + 4 * MOD_LD + 5 * D : nullptr);
.LBB0_207:
	s_andn2_b64 vcc, exec, s[4:5]
	s_mov_b32 s77, s85
	s_cbranch_vccnz .LBB0_270
	v_mov_b64_e32 v[2:3], s[0:1]
	s_waitcnt vmcnt(0) lgkmcnt(0)
	v_readlane_b32 s100, v255, 32
	v_readlane_b32 s101, v255, 33
	v_mov_b32_e32 v74, s100
	v_mov_b32_e32 v75, s101
	v_readlane_b32 s6, v254, 22
	v_readlane_b32 s7, v254, 23
	s_mov_b64 s[4:5], -1
	s_and_b64 vcc, exec, s[6:7]
	s_cbranch_vccz .LBB0_215
	s_getreg_b32 s4, hwreg(HW_REG_HW_ID, 0, 6)
	s_lshl_b32 s4, s4, 2
	s_add_i32 s4, s4, 0
	s_add_i32 s4, s4, 0x20540
	v_mov_b32_e32 v0, s4
	ds_read_b32 v0, v0
	s_waitcnt lgkmcnt(0)
	v_readfirstlane_b32 s4, v0
	v_mbcnt_lo_u32_b32 v0, -1, 0
	v_mbcnt_hi_u32_b32 v0, -1, v0
	s_nop 1
	v_lshl_add_u32 v0, s4, 6, v0
	s_nop 0
	v_readfirstlane_b32 s4, v0
	s_ashr_i32 s8, s4, 6
	s_add_i32 s10, s8, s91
	s_cmpk_gt_i32 s10, 0x43ff
	s_cbranch_scc1 .LBB0_214
	v_mov_b64_e32 v[2:3], s[0:1]
	flat_load_dwordx2 v[36:37], v[2:3] offset:152
	s_cmp_lg_u32 s76, 0
	s_cselect_b64 s[4:5], -1, 0
	s_add_u32 s9, s86, 0xffffe000
	v_and_b32_e32 v14, 63, v0
	s_addc_u32 s11, s87, -1
	s_and_b64 s[6:7], s[4:5], exec
	v_lshlrev_b32_e32 v10, 2, v14
	s_cselect_b32 s7, s11, 0
	s_cselect_b32 s6, s9, 0
	s_lshl_b64 s[12:13], s[76:77], 13
	v_or_b32_e32 v2, 0x400, v10
	s_waitcnt vmcnt(0)
	v_lshl_add_u64 v[24:25], v[74:75], 0, s[12:13]
	v_lshlrev_b32_e32 v12, 2, v2
	v_mov_b32_e32 v13, v1
	v_or_b32_e32 v38, 0x500, v10
	v_lshl_add_u64 v[18:19], v[24:25], 0, v[12:13]
	v_lshlrev_b32_e32 v12, 2, v38
	v_or_b32_e32 v40, 0x600, v10
	v_lshl_add_u64 v[20:21], v[24:25], 0, v[12:13]
	v_lshlrev_b32_e32 v12, 2, v40
	v_lshl_add_u64 v[22:23], v[24:25], 0, v[12:13]
	v_or_b32_e32 v12, 0x700, v10
	v_lshlrev_b32_e32 v0, 4, v14
	v_lshlrev_b32_e32 v26, 2, v12
	v_mov_b32_e32 v27, v1
	v_lshl_add_u64 v[16:17], v[24:25], 0, v[0:1]
	v_lshl_add_u64 v[24:25], v[24:25], 0, v[26:27]
	v_lshl_add_u64 v[26:27], s[6:7], 0, v[0:1]
	s_mov_b64 s[6:7], 0x1000
	v_lshl_add_u64 v[28:29], v[26:27], 0, s[6:7]
	s_mov_b64 s[6:7], 0x1400
	v_lshl_add_u64 v[30:31], v[26:27], 0, s[6:7]
	s_mov_b64 s[6:7], 0x1800
	v_lshl_add_u64 v[32:33], v[26:27], 0, s[6:7]
	s_mov_b64 s[6:7], 0x1c00
	v_lshl_add_u64 v[34:35], v[26:27], 0, s[6:7]
	s_ashr_i32 s7, s8, 31
	s_add_u32 s6, s91, s8
	v_readlane_b32 s8, v254, 59
	s_addc_u32 s7, s8, s7
	s_lshl_b64 s[6:7], s[6:7], 12
	v_or_b32_e32 v8, 0x100, v10
	v_or_b32_e32 v6, 0x200, v10
	v_or_b32_e32 v4, 0x300, v10
	v_lshlrev_b32_e32 v0, 3, v14
	s_xor_b64 s[4:5], s[4:5], -1
	v_lshlrev_b32_e32 v15, 2, v10
	v_lshlrev_b32_e32 v78, 2, v8
	v_lshlrev_b32_e32 v79, 2, v6
	v_lshlrev_b32_e32 v80, 2, v4
	v_lshlrev_b32_e32 v81, 2, v2
	v_lshlrev_b32_e32 v82, 2, v38
	v_lshlrev_b32_e32 v83, 2, v40
	v_lshlrev_b32_e32 v84, 2, v12
	s_waitcnt lgkmcnt(0)
	v_lshl_add_u64 v[36:37], v[36:37], 0, s[6:7]
	s_mov_b64 s[6:7], 0x8c00000
	v_lshl_add_u64 v[36:37], v[36:37], 0, s[6:7]
	s_branch .LBB0_212

; #define GAS __attribute__((address_space(1)))
; #define LAS __attribute__((address_space(3)))
; __device__ __forceinline__ void relaunder(Frame& F) { int t = mk_tid(); asm volatile("" : "+v"(t)); F.tid = t; F.lane = t & 63; F.wave = __builtin_amdgcn_readfirstlane(t >> 6); }
; #define NR_LOAD(dst, k_) do { const GAS v2u* xr_ = (const GAS v2u*)(X + (size_t)(nw + 2048 * (k_)) * D) + F.lane; \
;         _Pragma("unroll") for (int j = 0; j < 8; ++j) dst[j] = __builtin_nontemporal_load(xr_ + 64 * j); } while (0)
; __device__ __forceinline__ void norm_mod_phase2(const Args& a, Frame& F, const float* gain, const float* modl, int sh_off, int sc_off, int nrows, const float* slab_gate) {
;     relaunder(F);
;     static_assert(ML == 8 * 2048 && MC <= 2048, "8 latent rows and at most one context row per wave of 2048");
;     const int nw = F.vcu * NWAVES + F.wave;
;     bf16* X = (bf16*)(a.ws + WS_X); bf16* HN = (bf16*)(a.ws + WS_HN);
;     LAS float* CA = (LAS float*)F.lds; LAS float* CB = CA + 5 * D;
;     v2u r0[8], r1[8], r2[8], r3[8], r4[8], r5[8], r6[8], r7[8];
;     ...
;     NR_LOAD(r0, 0); NR_LOAD(r1, 1); NR_LOAD(r2, 2); NR_LOAD(r3, 3); NR_LOAD(r4, 4); NR_LOAD(r5, 5); NR_LOAD(r6, 6); NR_LOAD(r7, 7);
;     { const GAS f32x4* g4 = (const GAS f32x4*)gain;
;       for (int q = F.tid; q < 5 * D / 4; q += NWAVES * 64) { const int bq = q >> 9, cq = q & 511; const GAS f32x4* mb4 = (const GAS f32x4*)(modl + (size_t)bq * MOD_LD);
;           ((LAS f32x4*)CA)[q] = g4[cq] * (mb4[sc_off / 4 + cq] + 1.0f); ((LAS f32x4*)CB)[q] = mb4[sh_off / 4 + cq]; } }
.LBB0_215:
	s_andn2_b64 vcc, exec, s[4:5]
	s_cbranch_vccnz .LBB0_224
	s_getreg_b32 s4, hwreg(HW_REG_HW_ID, 0, 6)
	s_lshl_b32 s4, s4, 2
	s_add_i32 s4, s4, 0
	s_add_i32 s4, s4, 0x20540
	v_mov_b32_e32 v0, s4
	ds_read_b32 v0, v0
	v_mov_b64_e32 v[2:3], s[0:1]
	v_mbcnt_lo_u32_b32 v4, -1, 0
	v_mbcnt_hi_u32_b32 v4, -1, v4
	s_mov_b64 s[20:21], 0x400000
	v_mov_b32_e32 v7, v1
	s_waitcnt lgkmcnt(0)
	v_readfirstlane_b32 s4, v0
	s_nop 1
	v_lshl_add_u32 v142, s4, 6, v4
	v_mov_b32_e32 v128, s72
	v_mov_b32_e32 v129, s73
	v_readfirstlane_b32 s4, v142
	s_ashr_i32 s4, s4, 6
	s_add_i32 s4, s4, s91
	s_ashr_i32 s5, s4, 31
	s_add_i32 s36, s4, 0x800
	s_add_i32 s30, s4, 0x1000
	s_add_i32 s26, s4, 0x1800
	s_add_i32 s22, s4, 0x2000
	s_add_i32 s18, s4, 0x2800
	v_and_b32_e32 v143, 63, v142
	s_lshl_b64 s[6:7], s[4:5], 12
	s_ashr_i32 s37, s36, 31
	s_ashr_i32 s31, s30, 31
	s_ashr_i32 s27, s26, 31
	s_ashr_i32 s23, s22, 31
	s_ashr_i32 s19, s18, 31
	v_lshlrev_b32_e32 v6, 3, v143
	s_lshl_b64 s[8:9], s[36:37], 12
	s_lshl_b64 s[10:11], s[30:31], 12
	s_lshl_b64 s[12:13], s[26:27], 12
	s_lshl_b64 s[14:15], s[22:23], 12
	s_lshl_b64 s[16:17], s[18:19], 12
	s_waitcnt vmcnt(0) lgkmcnt(0)
	v_lshl_add_u64 v[8:9], v[128:129], 0, s[20:21]
	v_lshl_add_u64 v[2:3], v[8:9], 0, s[6:7]
	v_lshl_add_u64 v[4:5], v[8:9], 0, s[8:9]
	v_lshl_add_u64 v[10:11], v[8:9], 0, s[10:11]
	v_lshl_add_u64 v[12:13], v[8:9], 0, s[12:13]
	v_lshl_add_u64 v[14:15], v[8:9], 0, s[14:15]
	v_lshl_add_u64 v[16:17], v[8:9], 0, s[16:17]
	v_lshl_add_u64 v[2:3], v[2:3], 0, v[6:7]
	v_lshl_add_u64 v[4:5], v[4:5], 0, v[6:7]
	v_lshl_add_u64 v[10:11], v[10:11], 0, v[6:7]
	v_lshl_add_u64 v[12:13], v[12:13], 0, v[6:7]
	v_lshl_add_u64 v[14:15], v[14:15], 0, v[6:7]
	v_lshl_add_u64 v[16:17], v[16:17], 0, v[6:7]
	global_load_dwordx2 v[140:141], v[2:3], off nt
	global_load_dwordx2 v[138:139], v[2:3], off offset:512 nt
	global_load_dwordx2 v[136:137], v[2:3], off offset:1024 nt
	global_load_dwordx2 v[132:133], v[2:3], off offset:1536 nt
	global_load_dwordx2 v[134:135], v[2:3], off offset:2048 nt
	global_load_dwordx2 v[124:125], v[2:3], off offset:2560 nt
	global_load_dwordx2 v[126:127], v[2:3], off offset:3072 nt
	global_load_dwordx2 v[130:131], v[2:3], off offset:3584 nt
	global_load_dwordx2 v[122:123], v[4:5], off nt
	global_load_dwordx2 v[120:121], v[4:5], off offset:512 nt
	global_load_dwordx2 v[118:119], v[4:5], off offset:1024 nt
	global_load_dwordx2 v[116:117], v[4:5], off offset:1536 nt
	global_load_dwordx2 v[114:115], v[4:5], off offset:2048 nt
	global_load_dwordx2 v[112:113], v[4:5], off offset:2560 nt
	global_load_dwordx2 v[110:111], v[4:5], off offset:3072 nt
	global_load_dwordx2 v[108:109], v[4:5], off offset:3584 nt
	global_load_dwordx2 v[106:107], v[10:11], off nt
	global_load_dwordx2 v[104:105], v[10:11], off offset:512 nt
	global_load_dwordx2 v[102:103], v[10:11], off offset:1024 nt
	global_load_dwordx2 v[100:101], v[10:11], off offset:1536 nt
	global_load_dwordx2 v[98:99], v[10:11], off offset:2048 nt
	global_load_dwordx2 v[96:97], v[10:11], off offset:2560 nt
	global_load_dwordx2 v[94:95], v[10:11], off offset:3072 nt
	global_load_dwordx2 v[92:93], v[10:11], off offset:3584 nt
	global_load_dwordx2 v[90:91], v[12:13], off nt
	global_load_dwordx2 v[88:89], v[12:13], off offset:512 nt
	global_load_dwordx2 v[86:87], v[12:13], off offset:1024 nt
	global_load_dwordx2 v[84:85], v[12:13], off offset:1536 nt
	global_load_dwordx2 v[82:83], v[12:13], off offset:2048 nt
	global_load_dwordx2 v[80:81], v[12:13], off offset:2560 nt
	global_load_dwordx2 v[78:79], v[12:13], off offset:3072 nt
	global_load_dwordx2 v[76:77], v[12:13], off offset:3584 nt
	global_load_dwordx2 v[72:73], v[14:15], off nt
	global_load_dwordx2 v[70:71], v[14:15], off offset:512 nt
	global_load_dwordx2 v[68:69], v[14:15], off offset:1024 nt
	global_load_dwordx2 v[66:67], v[14:15], off offset:1536 nt
	global_load_dwordx2 v[64:65], v[14:15], off offset:2048 nt
	global_load_dwordx2 v[62:63], v[14:15], off offset:2560 nt
	global_load_dwordx2 v[60:61], v[14:15], off offset:3072 nt
	global_load_dwordx2 v[58:59], v[14:15], off offset:3584 nt
	global_load_dwordx2 v[56:57], v[16:17], off nt
	global_load_dwordx2 v[54:55], v[16:17], off offset:512 nt
	global_load_dwordx2 v[52:53], v[16:17], off offset:1024 nt
	global_load_dwordx2 v[50:51], v[16:17], off offset:1536 nt
	global_load_dwordx2 v[48:49], v[16:17], off offset:2048 nt
	global_load_dwordx2 v[46:47], v[16:17], off offset:2560 nt
	global_load_dwordx2 v[44:45], v[16:17], off offset:3072 nt
	global_load_dwordx2 v[42:43], v[16:17], off offset:3584 nt
	s_add_i32 s14, s4, 0x3000
	s_ashr_i32 s15, s14, 31
	s_lshl_b64 s[6:7], s[14:15], 12
	s_add_i32 s10, s4, 0x3800
	v_lshl_add_u64 v[2:3], v[8:9], 0, s[6:7]
	s_ashr_i32 s11, s10, 31
	v_lshl_add_u64 v[2:3], v[2:3], 0, v[6:7]
	s_lshl_b64 s[6:7], s[10:11], 12
	global_load_dwordx2 v[40:41], v[2:3], off nt
	global_load_dwordx2 v[38:39], v[2:3], off offset:512 nt
	global_load_dwordx2 v[36:37], v[2:3], off offset:1024 nt
	global_load_dwordx2 v[34:35], v[2:3], off offset:1536 nt
	global_load_dwordx2 v[32:33], v[2:3], off offset:2048 nt
	global_load_dwordx2 v[30:31], v[2:3], off offset:2560 nt
	global_load_dwordx2 v[28:29], v[2:3], off offset:3072 nt
	global_load_dwordx2 v[26:27], v[2:3], off offset:3584 nt
	v_lshl_add_u64 v[2:3], v[8:9], 0, s[6:7]
	v_lshl_add_u64 v[2:3], v[2:3], 0, v[6:7]
	global_load_dwordx2 v[24:25], v[2:3], off nt
	global_load_dwordx2 v[22:23], v[2:3], off offset:512 nt
	global_load_dwordx2 v[20:21], v[2:3], off offset:1024 nt
	global_load_dwordx2 v[18:19], v[2:3], off offset:1536 nt
	global_load_dwordx2 v[16:17], v[2:3], off offset:2048 nt
	global_load_dwordx2 v[14:15], v[2:3], off offset:2560 nt
	global_load_dwordx2 v[12:13], v[2:3], off offset:3072 nt
	global_load_dwordx2 v[10:11], v[2:3], off offset:3584 nt
	s_movk_i32 s6, 0xa00
	v_cmp_gt_i32_e32 vcc, s6, v142
	s_and_saveexec_b64 s[6:7], vcc
	s_cbranch_execz .LBB0_219
	s_lshl_b64 s[8:9], s[76:77], 13
	v_lshl_add_u64 v[2:3], v[74:75], 0, s[8:9]
	v_and_b32_e32 v74, 0x1ff, v142
	v_lshlrev_b32_e32 v0, 4, v74
	v_lshl_add_u64 v[2:3], v[2:3], 0, v[0:1]
	global_load_dwordx4 v[2:5], v[2:3], off
	v_lshl_add_u32 v7, v142, 4, 0
	s_mov_b64 s[8:9], 0
	v_lshlrev_b32_e32 v0, 4, v74

; #define LAS __attribute__((address_space(3)))
; __device__ __forceinline__ void relaunder(Frame& F) { int t = mk_tid(); asm volatile("" : "+v"(t)); F.tid = t; F.lane = t & 63; F.wave = __builtin_amdgcn_readfirstlane(t >> 6); }
; __device__ __forceinline__ void mixer_hg2(const Args& a, Frame& F, bool ctx_out) {
;     relaunder(F);
;     float zf_ = 0.f; asm volatile("" : "+v"(zf_));
;     const f32x4 ZERO4 = {zf_, zf_, zf_, zf_};
;     constexpr int HD = 128, NH = 16, NEB = 2, C = 64, NCTX = CTXL / C, NCH = (CTXL + SEQ) / C, KS = HD / 32;
;     constexpr int QS = HD * 2 + 16, IMG = 64 * QS, PS = MX_PS;
;     constexpr int O_VT = 3 * IMG, O_P = O_VT + 64 * PS, O_ST = O_P + 64 * PS, O_END = O_ST + IMG;
;     static_assert(O_END <= RING_BYTES && MX_SWZ == 0, "mixer_hg2 LDS (padded images)");
;     const int lane = F.lane, w = F.wave, tid = F.tid, g = lane >> 4, i = lane & 15;
;     const int rg = w >> 1, cg = w & 1, nq0 = 16 * rg;
;     LAS unsigned char* const L = F.lds;
;     const bf16* act = (const bf16*)(a.ws + WS_ACT);
;     mx_bf16x8 bt0, bt1;
; #pragma unroll
;     for (int j = 0; j < 8; ++j) { bt0[j] = (8 * g + j <= i) ? (short)0x3F80 : (short)0; bt1[j] = (8 * g + j <= 16 + i) ? (short)0x3F80 : (short)0; }
;     for (int task = F.vcu; task < BATCH * NH * 2 * NEB; task += F.G) {
;         const int eb = task % NEB, dir = (task / NEB) & 1, h = (task / (2 * NEB)) % NH, b = task / (2 * NEB * NH);
;         bf16* O = (bf16*)(a.ws + (dir ? WS_OB : WS_OF));
;         const bf16* src0 = act;
;         const bf16* src1 = act + (size_t)(2 + 2 * dir) * ACT_STRIDE;
;         const bf16* src2 = act + (size_t)(1 + 2 * dir) * ACT_STRIDE;
;         const bf16* srcv = act + (size_t)5 * ACT_STRIDE;
;         const int vrow = tid & 63, vcc = tid >> 6, vs = dir ? 63 - vrow : vrow;
.LBB0_507:
	s_andn2_b64 vcc, exec, s[8:9]
	s_cbranch_vccnz .LBB0_570
	s_getreg_b32 s6, hwreg(HW_REG_HW_ID, 0, 6)
	s_lshl_b32 s6, s6, 2
	s_add_i32 s6, s6, 0
	s_add_i32 s6, s6, 0x20540
	v_mov_b32_e32 v0, s6
	ds_read_b32 v0, v0
	v_readlane_b32 s8, v254, 25
	v_mbcnt_lo_u32_b32 v3, -1, 0
	v_mbcnt_hi_u32_b32 v3, -1, v3
	v_readlane_b32 s9, v254, 26
	v_mov_b32_e32 v2, v1
	s_waitcnt lgkmcnt(0)
	v_readfirstlane_b32 s6, v0
	s_andn2_b64 vcc, exec, s[8:9]
	s_nop 0
	v_lshl_add_u32 v0, s6, 6, v3
	s_nop 0
	v_readfirstlane_b32 s6, v0
	s_cbranch_vccnz .LBB0_524
	s_waitcnt vmcnt(0)
	v_mov_b64_e32 v[4:5], s[0:1]
	v_mov_b32_e32 v14, s72
	v_mov_b32_e32 v15, s73
	v_and_b32_e32 v18, 15, v0
	v_bfe_u32 v19, v0, 4, 2
	v_or_b32_e32 v11, 16, v18
	v_lshlrev_b32_e32 v12, 3, v19
	v_lshlrev_b32_e32 v8, 4, v0
	v_cmp_gt_u32_e32 vcc, v12, v11
	v_mov_b32_e32 v31, 0x3f80
	v_lshlrev_b32_e32 v6, 3, v0
	v_bfe_u32 v9, v0, 2, 2
	v_lshrrev_b32_e32 v10, 1, v0
	v_and_b32_e32 v186, 0xf0, v8
	v_cndmask_b32_e64 v8, v31, 0, vcc
	v_cmp_lt_u32_e32 vcc, v12, v11
	v_and_b32_e32 v184, 0x78, v6
	v_and_or_b32 v6, v10, 24, v9
	v_cndmask_b32_e32 v9, 0, v31, vcc
	v_cmp_gt_u32_e32 vcc, v12, v18
	v_and_b32_e32 v185, 63, v0
	s_ashr_i32 s6, s6, 6
	v_ashrrev_i32_e32 v7, 3, v0
	v_cndmask_b32_e64 v10, v31, 0, vcc
	v_cmp_lt_u32_e32 vcc, v12, v18
	v_or_b32_e32 v21, 2, v12
	v_and_b32_e32 v16, -8, v7
	s_lshl_b32 s9, s6, 5
	v_lshlrev_b32_e32 v7, 3, v185
	v_cndmask_b32_e32 v13, 0, v31, vcc
	v_or_b32_e32 v20, 3, v12
	v_cmp_gt_u32_e32 vcc, v21, v11
	v_and_or_b32 v27, v7, 16, s9
	v_and_b32_e32 v28, 8, v7
	s_mov_b32 s10, 0x5040100
	v_cndmask_b32_e64 v7, v31, 0, vcc
	v_cmp_gt_u32_e32 vcc, v20, v11
	v_mul_u32_u24_e32 v26, 0x120, v6
	v_perm_b32 v6, v9, v8, s10
	v_cndmask_b32_e64 v8, v31, 0, vcc
	v_cmp_gt_u32_e32 vcc, v21, v18
	v_or_b32_e32 v23, 4, v12
	v_or_b32_e32 v22, 5, v12
	v_cndmask_b32_e64 v9, v31, 0, vcc
	v_cmp_gt_u32_e32 vcc, v20, v18
	v_perm_b32 v10, v13, v10, s10
	v_or_b32_e32 v25, 6, v12
	v_cndmask_b32_e64 v13, v31, 0, vcc
	v_cmp_gt_u32_e32 vcc, v23, v11
	v_or_b32_e32 v24, 7, v12
	v_readlane_b32 s24, v254, 62
	v_cndmask_b32_e64 v20, v31, 0, vcc
	v_cmp_gt_u32_e32 vcc, v22, v11
	s_lshl_b32 s8, s6, 3
	s_add_i32 s6, s9, s24
	v_cndmask_b32_e64 v21, v31, 0, vcc
	v_cmp_gt_u32_e32 vcc, v23, v18
	s_add_i32 s7, s9, 0
	v_add3_u32 v26, 0, v26, v27
	v_cndmask_b32_e64 v23, v31, 0, vcc
	v_cmp_gt_u32_e32 vcc, v22, v18
	v_add_u32_e32 v27, s6, v12
	v_bfi_b32 v229, -16, s8, v0
	v_cndmask_b32_e64 v22, v31, 0, vcc
	v_cmp_gt_u32_e32 vcc, v25, v11
	s_movk_i32 s25, 0x120
	v_perm_b32 v7, v8, v7, s10
	v_cndmask_b32_e64 v29, v31, 0, vcc
	v_cmp_gt_u32_e32 vcc, v24, v11
	v_perm_b32 v8, v21, v20, s10
	v_and_b32_e32 v232, 48, v0
	v_cndmask_b32_e64 v30, v31, 0, vcc
	v_cmp_gt_u32_e32 vcc, v25, v18
	v_ashrrev_i32_e32 v237, 4, v0
	v_add_u32_e32 v0, 0x200, v0
	v_cndmask_b32_e64 v25, v31, 0, vcc
	v_cmp_gt_u32_e32 vcc, v24, v18
	v_perm_b32 v11, v13, v9, s10
	v_perm_b32 v9, v30, v29, s10
	v_cndmask_b32_e64 v24, v31, 0, vcc
	v_add_u32_e32 v31, s7, v12
	s_mov_b64 s[6:7], 0xd000000
	s_waitcnt vmcnt(0) lgkmcnt(0)
	v_lshl_add_u64 v[188:189], v[14:15], 0, s[6:7]
	s_mov_b64 s[6:7], 0x22400000
	v_lshl_add_u64 v[190:191], v[14:15], 0, s[6:7]
	v_mul_lo_u32 v14, v229, s25
	v_add_u32_e32 v230, 0, v14
	s_and_b32 s6, s9, 32
	v_lshlrev_b32_e32 v14, 2, v19
	v_or_b32_e32 v19, s6, v14
	v_or_b32_e32 v21, 2, v19
	v_cmp_gt_i32_e64 s[12:13], v21, v229
	v_or_b32_e32 v21, 3, v19
	v_cmp_gt_i32_e64 s[14:15], v21, v229
	v_lshlrev_b32_e32 v21, 7, v229
	v_sub_u32_e32 v233, v230, v21
	v_add_u32_e32 v233, 0x10000, v233
	v_or_b32_e32 v21, 17, v19
	s_movk_i32 s7, 0xa0
	v_perm_b32 v12, v22, v23, s10
	v_perm_b32 v13, v24, v25, s10
	v_or_b32_e32 v20, 16, v19
	v_cmp_gt_i32_e64 s[8:9], v19, v229
	v_cmp_lt_i32_e64 s[10:11], v19, v229
	v_lshlrev_b32_e32 v234, 1, v19
	v_cmp_gt_i32_e64 s[18:19], v21, v229
	v_or_b32_e32 v21, 18, v19
	v_or_b32_e32 v19, 19, v19
	v_ashrrev_i32_e32 v238, 4, v0
	v_mul_lo_u32 v0, v16, s7
	v_lshlrev_b32_e32 v187, 1, v185
	v_ashrrev_i32_e32 v17, 31, v16
	v_or_b32_e32 v15, s6, v18
	v_cmp_gt_i32_e64 s[22:23], v19, v229
	v_add_u32_e32 v241, 0, v0
	v_mul_u32_u24_e32 v19, 0x120, v18
	v_mad_u32_u24 v18, v18, s7, 0
	v_mov_b32_e32 v0, s24
	v_mov_b32_e32 v3, v2
	v_mov_b32_e32 v4, v2
	v_mov_b32_e32 v5, v2
	v_xor_b32_e32 v228, 0x7e, v187
	v_mad_u32_u24 v231, v15, s25, 0
	v_cmp_gt_i32_e64 s[16:17], v20, v229
	v_cmp_gt_i32_e64 s[20:21], v21, v229
	v_lshlrev_b32_e32 v235, 1, v20
	v_sub_u32_e32 v236, 63, v229
	v_sub_u32_e32 v239, 63, v237
	v_sub_u32_e32 v240, 63, v238
	v_mad_u32_u24 v242, v15, s25, v0
	v_mad_u32_u24 v243, v15, s7, 0
	v_lshlrev_b64 v[192:193], 1, v[16:17]
	s_lshl_b32 s28, s6, 1
	v_lshlrev_b32_e32 v0, 1, v14
	v_add_u32_e32 v244, v18, v232
	v_add_u32_e32 v245, v26, v28
	v_add_u32_e32 v246, v27, v19
	v_add_u32_e32 v247, v31, v19
	v_readlane_b32 s6, v254, 4
	s_branch .LBB0_511

; __device__ __forceinline__ void mixer_hg2(const Args& a, Frame& F, bool ctx_out) {
;     ...
;     for (int task = F.vcu; task < BATCH * NH * 2 * NEB; task += F.G) {
;         const int eb = task % NEB, dir = (task / NEB) & 1, h = (task / (2 * NEB)) % NH, b = task / (2 * NEB * NH);
;         bf16* O = (bf16*)(a.ws + (dir ? WS_OB : WS_OF));
;         const bf16* src0 = act;
;         const bf16* src1 = act + (size_t)(2 + 2 * dir) * ACT_STRIDE;
;         const bf16* src2 = act + (size_t)(1 + 2 * dir) * ACT_STRIDE;
;         const bf16* srcv = act + (size_t)5 * ACT_STRIDE;
;         const int vrow = tid & 63, vcc = tid >> 6, vs = dir ? 63 - vrow : vrow;
;         f32x4 accS[4];
; #pragma unroll
;         for (int te = 0; te < 4; ++te) accS[te] = ZERO4;
;         constexpr int PF = MX_PF_HG;
;         static_assert(NCH % PF == 0, "prefetch depth must divide the chunk count");
;         v4u rq[PF][3][2]; v4u rv[PF];
;     ...
;         __syncthreads();
; #pragma unroll
;         for (int u = 0; u < PF; ++u) H2_LOAD(u, u);
.LBB0_511:
	s_lshr_b32 s7, s6, 31
	s_add_i32 s7, s6, s7
	s_ashr_i32 s24, s7, 1
	s_ashr_i32 s33, s6, 31
	s_bfe_i32 s29, s24, 0x10000
	s_and_b32 s31, s24, 1
	s_lshr_b32 s24, s33, 30
	s_add_i32 s24, s6, s24
	s_ashr_i32 s25, s24, 2
	s_ashr_i32 s24, s24, 31
	s_lshr_b32 s24, s24, 28
	s_add_i32 s24, s25, s24
	s_and_b32 s24, s24, 0x1fffff0
	s_sub_i32 s34, s25, s24
	s_cmp_eq_u32 s31, 0
	s_cselect_b64 s[24:25], -1, 0
	s_and_b64 s[26:27], s[24:25], exec
	v_mov_b64_e32 v[94:95], s[0:1]
	s_mov_b32 s26, 0x2ac00000
	s_mul_i32 s84, s31, 0x8800000
	v_mov_b32_e32 v122, s72
	v_mov_b32_e32 v123, s73
	s_cselect_b32 s30, s26, 0x33400000
	v_lshl_add_u64 v[94:95], v[188:189], 0, s[84:85]
	s_mov_b64 s[26:27], 0x8800000
	v_lshl_add_u64 v[196:197], v[94:95], 0, s[26:27]
	s_lshr_b32 s26, s33, 26
	s_add_i32 s26, s6, s26
	s_ashr_i32 s36, s26, 6
	s_mov_b64 s[26:27], 0x4400000
	s_lshl_b32 s33, s36, 8
	v_lshl_add_u64 v[198:199], v[94:95], 0, s[26:27]
	s_addk_i32 s33, 0x4000
	s_and_b32 s26, s29, 0xc0
	s_or_b32 s29, s26, s33
	s_lshl_b32 s26, s34, 7
	v_add_u32_e32 v94, s29, v237
	v_add_u32_e32 v104, s29, v238
	s_and_b32 s7, s7, 0x3fffffe
	v_or_b32_e32 v118, s29, v185
	s_ashr_i32 s27, s26, 31
	v_ashrrev_i32_e32 v95, 31, v94
	v_ashrrev_i32_e32 v105, 31, v104
	s_sub_i32 s7, s6, s7
	v_ashrrev_i32_e32 v119, 31, v118
	v_mov_b32_e32 v201, s27
	v_or_b32_e32 v200, s26, v184
	v_lshlrev_b64 v[94:95], 11, v[94:95]
	v_lshlrev_b64 v[104:105], 11, v[104:105]
	v_lshlrev_b64 v[118:119], 12, v[118:119]
	s_lshl_b32 s34, s7, 6
	v_lshl_add_u64 v[94:95], v[94:95], 0, v[200:201]
	v_lshl_add_u64 v[104:105], v[104:105], 0, v[200:201]
	v_lshl_add_u64 v[118:119], v[190:191], 0, v[118:119]
	s_lshl_b64 s[26:27], s[26:27], 1
	s_ashr_i32 s35, s34, 31
	v_lshlrev_b64 v[102:103], 1, v[94:95]
	v_lshlrev_b64 v[106:107], 1, v[104:105]
	v_lshl_add_u64 v[118:119], v[118:119], 0, s[26:27]
	s_lshl_b64 s[34:35], s[34:35], 1
	v_lshl_add_u64 v[94:95], v[188:189], 0, v[102:103]
	v_lshl_add_u64 v[98:99], v[196:197], 0, v[102:103]
	v_lshl_add_u64 v[102:103], v[198:199], 0, v[102:103]
	v_lshl_add_u64 v[108:109], v[188:189], 0, v[106:107]
	v_lshl_add_u64 v[118:119], v[118:119], 0, s[34:35]
	s_waitcnt lgkmcnt(0)
	s_barrier
	global_load_dwordx4 v[94:97], v[94:95], off
	s_nop 0
	global_load_dwordx4 v[98:101], v[98:99], off
	s_nop 0
	global_load_dwordx4 v[102:105], v[102:103], off
	s_nop 0
	global_load_dwordx4 v[110:113], v[108:109], off
	v_lshl_add_u64 v[108:109], v[196:197], 0, v[106:107]
	v_lshl_add_u64 v[114:115], v[198:199], 0, v[106:107]
	v_lshl_add_u64 v[118:119], v[118:119], 0, v[192:193]
	global_load_dwordx4 v[106:109], v[108:109], off
	s_nop 0
	global_load_dwordx4 v[114:117], v[114:115], off
	s_mov_b32 s31, 0
	global_load_dwordx4 v[118:121], v[118:119], off
	s_mov_b32 s29, s85
	v_lshl_add_u64 v[124:125], v[190:191], 0, s[26:27]
	v_lshl_add_u64 v[124:125], v[124:125], 0, s[34:35]
	v_cndmask_b32_e64 v126, v228, v187, s[24:25]
	v_lshl_add_u64 v[216:217], v[124:125], 0, v[192:193]
	v_cndmask_b32_e64 v248, v236, v229, s[24:25]
	s_lshl_b32 s7, s36, 12
	v_add_u32_e32 v249, v241, v126
	v_mov_b32_e32 v202, v2
	v_mov_b32_e32 v203, v2
	v_mov_b32_e32 v204, v2
	v_mov_b32_e32 v205, v2
	v_mov_b32_e32 v206, v2
	v_mov_b32_e32 v207, v2
	v_mov_b32_e32 v208, v2
	v_mov_b32_e32 v209, v2
	v_mov_b32_e32 v210, v2
	v_mov_b32_e32 v211, v2
	v_mov_b32_e32 v212, v2
	v_mov_b32_e32 v213, v2
	v_mov_b32_e32 v214, v2
	v_mov_b32_e32 v215, v2
	v_mov_b32_e32 v218, v2
	v_mov_b32_e32 v219, v2
	s_waitcnt vmcnt(0)
	v_lshl_add_u64 v[122:123], v[122:123], 0, s[30:31]
	v_lshl_add_u64 v[122:123], v[122:123], 0, s[26:27]
	v_lshl_add_u64 v[122:123], v[122:123], 0, s[34:35]
	v_lshl_add_u64 v[122:123], v[122:123], 0, s[28:29]
	v_lshl_add_u64 v[194:195], v[122:123], 0, v[0:1]
	v_cndmask_b32_e64 v122, v239, v237, s[24:25]
	s_movk_i32 s29, 0x120
	v_mad_u64_u32 v[122:123], s[26:27], v122, s29, v[186:187]
	v_cndmask_b32_e64 v123, v240, v238, s[24:25]
	v_mad_u64_u32 v[124:125], s[26:27], v123, s29, v[186:187]
	s_movk_i32 s30, 0x43
	v_add_u32_e32 v251, 0, v122
	v_add_u32_e32 v250, 0, v124

; #define GAS __attribute__((address_space(1)))
; __device__ __forceinline__ void relaunder(Frame& F) { int t = mk_tid(); asm volatile("" : "+v"(t)); F.tid = t; F.lane = t & 63; F.wave = __builtin_amdgcn_readfirstlane(t >> 6); }
; template <bool HG>
; __device__ __forceinline__ void readout_phase(const Args& a, Frame& F, const float* gain, int nrows) {
;     relaunder(F);
;     const int gw = F.vcu * NWAVES + F.wave, NGW = F.G * NWAVES;
;     const bf16* OF = (const bf16*)(a.ws + WS_OF); const bf16* OB = (const bf16*)(a.ws + WS_OB);
;     const bf16* G = (const bf16*)(a.ws + WS_ACT) + (size_t)(HG ? 6 : 3) * ACT_STRIDE; bf16* HN = (bf16*)(a.ws + WS_HN);
;     for (int r = gw; r < nrows; r += NGW) {
;         const GAS v2u* f = (const GAS v2u*)(OF + (size_t)r * D) + F.lane; const GAS v2u* bk = (const GAS v2u*)(OB + (size_t)r * D) + F.lane;
;         const GAS v2u* g8 = (const GAS v2u*)(G + (size_t)r * D) + F.lane;
; __global__ void __launch_bounds__(NWAVES * 64, 2) fwd_kernel(Args args_in) {
;     ...
;             if (IN(pb + 3)) for (int rep = 0; rep < REP_READ; ++rep) { if (NORM_PIPE && F.G == 256) readout_phase2<true>(args, F, args.in[13] + (size_t)j * D, Mr); else readout_phase<true>(args, F, args.in[13] + (size_t)j * D, Mr); }
.LBB0_570:
	s_cmp_le_i32 s60, s6
	s_cselect_b64 s[8:9], -1, 0
	s_cmp_lt_i32 s6, s61
	s_cselect_b64 s[6:7], -1, 0
	s_and_b64 s[6:7], s[8:9], s[6:7]
	s_mov_b64 s[78:79], 0
	s_andn2_b64 vcc, exec, s[6:7]
	s_mov_b64 s[80:81], 0
	s_cbranch_vccnz .LBB0_629
	v_mov_b64_e32 v[2:3], s[0:1]
	s_waitcnt vmcnt(0) lgkmcnt(0)
	v_readlane_b32 s100, v255, 38
	v_readlane_b32 s101, v255, 39
	v_mov_b32_e32 v6, s100
	v_mov_b32_e32 v7, s101
	v_readlane_b32 s6, v255, 14
	v_readlane_b32 s7, v255, 15
	s_lshl_b32 s84, s6, 11
	v_readlane_b32 s6, v254, 22
	v_readlane_b32 s7, v254, 23
	s_mov_b64 s[8:9], -1
	s_and_b64 vcc, exec, s[6:7]
	s_cbranch_vccz .LBB0_576
	s_getreg_b32 s6, hwreg(HW_REG_HW_ID, 0, 6)
	s_lshl_b32 s6, s6, 2
	s_add_i32 s6, s6, 0
	s_add_i32 s6, s6, 0x20540
	v_mov_b32_e32 v0, s6
	ds_read_b32 v0, v0
	s_mov_b32 s12, 0xd5800000
	s_mov_b32 s13, -1
	s_waitcnt lgkmcnt(0)
	v_readfirstlane_b32 s6, v0
	v_mbcnt_lo_u32_b32 v0, -1, 0
	v_mbcnt_hi_u32_b32 v0, -1, v0
	s_nop 1
	v_lshl_add_u32 v0, s6, 6, v0
	s_nop 0
	v_readfirstlane_b32 s6, v0
	s_ashr_i32 s7, s6, 6
	s_add_i32 s6, s7, s91
	s_cmp_ge_i32 s6, s47
	s_cbranch_scc1 .LBB0_575
	v_mov_b64_e32 v[2:3], s[0:1]
	flat_load_dwordx2 v[2:3], v[2:3] offset:152
	v_and_b32_e32 v4, 63, v0
	s_waitcnt vmcnt(0)
	v_lshl_add_u64 v[8:9], s[84:85], 2, v[6:7]
	s_ashr_i32 s9, s7, 31
	v_lshlrev_b32_e32 v0, 4, v4
	s_add_u32 s8, s91, s7
	v_lshl_add_u64 v[8:9], v[8:9], 0, v[0:1]
	v_readlane_b32 s7, v254, 59
	s_mov_b64 s[10:11], 0x1000
	s_addc_u32 s9, s7, s9
	v_lshl_add_u64 v[10:11], v[8:9], 0, s[10:11]
	s_mov_b64 s[10:11], 0x1400
	v_lshl_add_u64 v[12:13], v[8:9], 0, s[10:11]
	s_mov_b64 s[10:11], 0x1800
	s_lshl_b64 s[8:9], s[8:9], 12
	v_lshl_add_u64 v[14:15], v[8:9], 0, s[10:11]
	s_mov_b64 s[10:11], 0x1c00
	v_lshl_add_u64 v[16:17], v[8:9], 0, s[10:11]
	v_lshlrev_b32_e32 v0, 3, v4
	s_waitcnt lgkmcnt(0)
	v_lshl_add_u64 v[2:3], v[2:3], 0, s[8:9]
	s_mov_b64 s[8:9], 0x33400000
	v_lshl_add_u64 v[18:19], v[2:3], 0, s[8:9]

; #define GAS __attribute__((address_space(1)))
; #define LAS __attribute__((address_space(3)))
; __device__ __forceinline__ void relaunder(Frame& F) { int t = mk_tid(); asm volatile("" : "+v"(t)); F.tid = t; F.lane = t & 63; F.wave = __builtin_amdgcn_readfirstlane(t >> 6); }
; template <bool HG>
; __device__ __forceinline__ void readout_phase2(const Args& a, Frame& F, const float* gain, int nrows) {
;     relaunder(F);
;     const int nw = F.vcu * NWAVES + F.wave;
;     const bf16* OF = (const bf16*)(a.ws + WS_OF); const bf16* OB = (const bf16*)(a.ws + WS_OB);
;     const bf16* G = (const bf16*)(a.ws + WS_ACT) + (size_t)(HG ? 6 : 3) * ACT_STRIDE; bf16* HN = (bf16*)(a.ws + WS_HN);
;     LAS float* GL = (LAS float*)F.lds;
;     v2u f0[8], b0[8], g0[8], f1[8], b1[8], g1[8], f2[8], b2[8], g2[8];
;     ...
;     RO_LOAD(f0, b0, g0, nw); RO_LOAD(f1, b1, g1, nw + 2048); RO_LOAD(f2, b2, g2, nw + 2 * 2048);
;     if (HG) { for (int q = F.tid; q < D / 4; q += NWAVES * 64) ((LAS f32x4*)GL)[q] = ((const GAS f32x4*)gain)[q];
.LBB0_576:
	s_andn2_b64 vcc, exec, s[8:9]
	s_cbranch_vccnz .LBB0_583
	s_getreg_b32 s6, hwreg(HW_REG_HW_ID, 0, 6)
	s_lshl_b32 s6, s6, 2
	s_add_i32 s6, s6, 0
	s_add_i32 s6, s6, 0x20540
	v_mov_b32_e32 v0, s6
	ds_read_b32 v0, v0
	v_mov_b64_e32 v[2:3], s[0:1]
	s_waitcnt lgkmcnt(0)
	v_readfirstlane_b32 s6, v0
	v_mbcnt_lo_u32_b32 v0, -1, 0
	v_mbcnt_hi_u32_b32 v0, -1, v0
	s_nop 1
	v_lshl_add_u32 v100, s6, 6, v0
	v_mov_b32_e32 v2, s72
	v_mov_b32_e32 v3, s73
	v_readfirstlane_b32 s6, v100
	s_ashr_i32 s6, s6, 6
	s_add_i32 s10, s6, s91
	s_mov_b64 s[6:7], 0x2ac00000
	s_ashr_i32 s11, s10, 31
	v_and_b32_e32 v166, 63, v100
	v_lshlrev_b32_e32 v0, 3, v166
	s_add_i32 s8, s10, 0x800
	s_ashr_i32 s9, s8, 31
	s_add_i32 s12, s10, 0x1000
	s_ashr_i32 s13, s12, 31
	s_waitcnt vmcnt(0) lgkmcnt(0)
	v_lshl_add_u64 v[36:37], v[2:3], 0, s[6:7]
	s_mov_b64 s[6:7], 0x33400000
	v_lshl_add_u64 v[38:39], v[2:3], 0, s[6:7]
	s_mov_b64 s[6:7], 0x26800000
	v_lshl_add_u64 v[40:41], v[2:3], 0, s[6:7]
	s_lshl_b64 s[6:7], s[10:11], 12
	v_lshl_add_u64 v[8:9], v[38:39], 0, s[6:7]
	v_lshl_add_u64 v[4:5], v[36:37], 0, s[6:7]
	v_lshl_add_u64 v[42:43], v[8:9], 0, v[0:1]
	v_lshl_add_u64 v[8:9], v[40:41], 0, s[6:7]
	v_lshl_add_u64 v[4:5], v[4:5], 0, v[0:1]
	v_lshl_add_u64 v[44:45], v[8:9], 0, v[0:1]
	s_lshl_b64 s[6:7], s[8:9], 12
	global_load_dwordx2 v[156:157], v[4:5], off nt
	global_load_dwordx2 v[154:155], v[42:43], off nt
	global_load_dwordx2 v[8:9], v[44:45], off nt
	global_load_dwordx2 v[152:153], v[4:5], off offset:512 nt
	global_load_dwordx2 v[150:151], v[42:43], off offset:512 nt
	global_load_dwordx2 v[10:11], v[44:45], off offset:512 nt
	global_load_dwordx2 v[148:149], v[4:5], off offset:1024 nt
	global_load_dwordx2 v[140:141], v[42:43], off offset:1024 nt
	global_load_dwordx2 v[14:15], v[44:45], off offset:1024 nt
	global_load_dwordx2 v[90:91], v[4:5], off offset:1536 nt
	global_load_dwordx2 v[80:81], v[42:43], off offset:1536 nt
	global_load_dwordx2 v[18:19], v[44:45], off offset:1536 nt
	global_load_dwordx2 v[34:35], v[4:5], off offset:2048 nt
	global_load_dwordx2 v[32:33], v[42:43], off offset:2048 nt
	global_load_dwordx2 v[22:23], v[44:45], off offset:2048 nt
	global_load_dwordx2 v[28:29], v[4:5], off offset:2560 nt
	global_load_dwordx2 v[24:25], v[42:43], off offset:2560 nt
	global_load_dwordx2 v[26:27], v[44:45], off offset:2560 nt
	global_load_dwordx2 v[20:21], v[4:5], off offset:3072 nt
	global_load_dwordx2 v[16:17], v[42:43], off offset:3072 nt
	global_load_dwordx2 v[30:31], v[44:45], off offset:3072 nt
	global_load_dwordx2 v[12:13], v[4:5], off offset:3584 nt
	s_nop 0
	global_load_dwordx2 v[4:5], v[42:43], off offset:3584 nt
	global_load_dwordx2 v[76:77], v[44:45], off offset:3584 nt
	v_lshl_add_u64 v[42:43], v[36:37], 0, s[6:7]
	v_lshl_add_u64 v[44:45], v[38:39], 0, s[6:7]
	v_lshl_add_u64 v[42:43], v[42:43], 0, v[0:1]
	v_lshl_add_u64 v[48:49], v[44:45], 0, v[0:1]
	v_lshl_add_u64 v[44:45], v[40:41], 0, s[6:7]
	s_lshl_b64 s[6:7], s[12:13], 12
	v_lshl_add_u64 v[50:51], v[44:45], 0, v[0:1]
	global_load_dwordx2 v[146:147], v[42:43], off nt
	global_load_dwordx2 v[144:145], v[48:49], off nt
	global_load_dwordx2 v[72:73], v[50:51], off nt
	global_load_dwordx2 v[142:143], v[42:43], off offset:512 nt
	global_load_dwordx2 v[138:139], v[48:49], off offset:512 nt
	global_load_dwordx2 v[70:71], v[50:51], off offset:512 nt
	global_load_dwordx2 v[128:129], v[42:43], off offset:1024 nt
	global_load_dwordx2 v[126:127], v[48:49], off offset:1024 nt
	global_load_dwordx2 v[66:67], v[50:51], off offset:1024 nt
	global_load_dwordx2 v[120:121], v[42:43], off offset:1536 nt
	global_load_dwordx2 v[118:119], v[48:49], off offset:1536 nt
	global_load_dwordx2 v[60:61], v[50:51], off offset:1536 nt
	global_load_dwordx2 v[108:109], v[42:43], off offset:2048 nt
	global_load_dwordx2 v[106:107], v[48:49], off offset:2048 nt
	global_load_dwordx2 v[54:55], v[50:51], off offset:2048 nt
	global_load_dwordx2 v[98:99], v[42:43], off offset:2560 nt
	global_load_dwordx2 v[96:97], v[48:49], off offset:2560 nt
	global_load_dwordx2 v[46:47], v[50:51], off offset:2560 nt
	global_load_dwordx2 v[84:85], v[42:43], off offset:3072 nt
	global_load_dwordx2 v[82:83], v[48:49], off offset:3072 nt
	global_load_dwordx2 v[44:45], v[50:51], off offset:3072 nt
	global_load_dwordx2 v[78:79], v[42:43], off offset:3584 nt
	global_load_dwordx2 v[74:75], v[48:49], off offset:3584 nt
	s_nop 0
	global_load_dwordx2 v[42:43], v[50:51], off offset:3584 nt
	v_lshl_add_u64 v[48:49], v[36:37], 0, s[6:7]
	v_lshl_add_u64 v[86:87], v[48:49], 0, v[0:1]
	v_lshl_add_u64 v[48:49], v[38:39], 0, s[6:7]
	v_lshl_add_u64 v[50:51], v[48:49], 0, v[0:1]
	v_lshl_add_u64 v[48:49], v[40:41], 0, s[6:7]
	v_lshl_add_u64 v[158:159], v[48:49], 0, v[0:1]
	global_load_dwordx2 v[136:137], v[86:87], off nt
	global_load_dwordx2 v[134:135], v[50:51], off nt
	global_load_dwordx2 v[68:69], v[158:159], off nt
	global_load_dwordx2 v[132:133], v[86:87], off offset:512 nt
	global_load_dwordx2 v[130:131], v[50:51], off offset:512 nt
	global_load_dwordx2 v[64:65], v[158:159], off offset:512 nt
	global_load_dwordx2 v[124:125], v[86:87], off offset:1024 nt
	global_load_dwordx2 v[122:123], v[50:51], off offset:1024 nt
	global_load_dwordx2 v[58:59], v[158:159], off offset:1024 nt
	global_load_dwordx2 v[114:115], v[86:87], off offset:1536 nt
	global_load_dwordx2 v[116:117], v[50:51], off offset:1536 nt
	global_load_dwordx2 v[62:63], v[158:159], off offset:1536 nt
	global_load_dwordx2 v[112:113], v[86:87], off offset:2048 nt
	global_load_dwordx2 v[110:111], v[50:51], off offset:2048 nt
	global_load_dwordx2 v[56:57], v[158:159], off offset:2048 nt
	global_load_dwordx2 v[104:105], v[86:87], off offset:2560 nt
	global_load_dwordx2 v[102:103], v[50:51], off offset:2560 nt
	global_load_dwordx2 v[52:53], v[158:159], off offset:2560 nt
	global_load_dwordx2 v[94:95], v[86:87], off offset:3072 nt
	global_load_dwordx2 v[92:93], v[50:51], off offset:3072 nt
	global_load_dwordx2 v[48:49], v[158:159], off offset:3072 nt
	s_nop 0
	global_load_dwordx2 v[86:87], v[86:87], off offset:3584 nt
	s_nop 0
	global_load_dwordx2 v[88:89], v[50:51], off offset:3584 nt
	s_nop 0
	global_load_dwordx2 v[50:51], v[158:159], off offset:3584 nt
	s_movk_i32 s6, 0x200
	v_cmp_gt_i32_e32 vcc, s6, v100
	s_and_saveexec_b64 s[14:15], vcc
	s_cbranch_execz .LBB0_580
	v_lshl_add_u64 v[6:7], s[84:85], 2, v[6:7]
	v_ashrrev_i32_e32 v101, 31, v100
	v_add_u32_e32 v158, 0xfffffe00, v100
	v_lshl_add_u32 v159, v100, 4, 0
	v_lshl_add_u64 v[6:7], v[100:101], 4, v[6:7]
	s_mov_b64 s[16:17], 0

; #define LAS __attribute__((address_space(3)))
;     ...
;     const int lane = F.lane, w = F.wave, tid = F.tid, g = lane >> 4, i = lane & 15;
;     const int rg = w >> 1, cg = w & 1, nq0 = 16 * rg;
;     LAS unsigned char* const L = F.lds;
;     const bf16* act = (const bf16*)(a.ws + WS_ACT);
;     for (int task = F.vcu; task < BATCH * NH * 2 * NEB; task += F.G) {
;         const int eb = task % NEB, dir = (task / NEB) & 1, h = (task / (2 * NEB)) % NH, b = task / (2 * NEB * NH);
;         bf16* O = (bf16*)(a.ws + (dir ? WS_OB : WS_OF));
;         const bf16* src0 = act;
;         const bf16* src1 = act + (size_t)(HG ? (2 + 2 * dir) : 1) * ACT_STRIDE;
;         const bf16* src2 = act + (size_t)(1 + 2 * dir) * ACT_STRIDE;
;         const bf16* srcv = act + (size_t)(HG ? 5 : 2) * ACT_STRIDE;
;         float lg2 = 0.f;
;         if (!HG) { const float x = a.in[10][(j_layer * 2 + dir) * 8 + h]; lg2 = -log1pf(expf(-x)) * 1.4426950408889634f; }
;         const float r1 = HG ? 1.f : exp2f((float)(nq0 + i - 63) * lg2), r2 = HG ? 1.f : exp2f((float)(nq0 + i + 1) * lg2), cdec = HG ? 1.f : exp2f(64.f * lg2);
;         const int vrow = tid & 63, vcc = tid >> 6;
;         const int vs = dir ? 63 - vrow : vrow;
;         const float kdec = HG ? 1.f : exp2f((float)(63 - vs) * lg2);
.LBB0_795:
	s_andn2_b64 vcc, exec, s[6:7]
	s_cbranch_vccnz .LBB0_855
	s_getreg_b32 s6, hwreg(HW_REG_HW_ID, 0, 6)
	s_lshl_b32 s6, s6, 2
	s_add_i32 s6, s6, 0
	s_add_i32 s6, s6, 0x20540
	v_mov_b32_e32 v0, s6
	ds_read_b32 v0, v0
	v_mbcnt_lo_u32_b32 v3, -1, 0
	v_mbcnt_hi_u32_b32 v3, -1, v3
	v_mov_b32_e32 v2, v1
	s_waitcnt lgkmcnt(0)
	v_readfirstlane_b32 s6, v0
	s_nop 1
	v_lshl_add_u32 v0, s6, 6, v3
	v_readlane_b32 s6, v254, 25
	v_readlane_b32 s7, v254, 26
	s_andn2_b64 vcc, exec, s[6:7]
	v_readfirstlane_b32 s24, v0
	s_cbranch_vccnz .LBB0_809
	s_waitcnt vmcnt(0)
	v_mov_b64_e32 v[4:5], s[0:1]
	s_waitcnt vmcnt(0)
	v_mov_b32_e32 v6, s72
	v_mov_b32_e32 v7, s73
	s_ashr_i32 s8, s24, 6
	v_ashrrev_i32_e32 v16, 31, v0
	v_add_u32_e32 v17, 0x200, v0
	s_lshl_b32 s9, s8, 3
	s_lshl_b32 s8, s8, 5
	v_lshrrev_b32_e32 v16, 27, v16
	v_ashrrev_i32_e32 v19, 31, v17
	s_mov_b64 s[26:27], 0xd000000
	v_and_b32_e32 v11, 15, v0
	v_readlane_b32 s29, v255, 0
	s_and_b32 s25, s8, 32
	v_add_u32_e32 v16, v0, v16
	v_lshrrev_b32_e32 v19, 27, v19
	v_mov_b32_e32 v15, s29
	s_movk_i32 s12, 0x220
	v_or_b32_e32 v23, s25, v11
	v_ashrrev_i32_e32 v149, 5, v16
	v_and_b32_e32 v16, 0xffffffe0, v16
	v_add_u32_e32 v19, v17, v19
	v_mad_u32_u24 v155, v23, s12, v15
	v_sub_u32_e32 v15, v0, v16
	v_and_b32_e32 v16, 0xffffffe0, v19
	v_bfe_u32 v9, v0, 4, 2
	v_bfe_u32 v12, v0, 2, 2
	v_lshrrev_b32_e32 v13, 1, v0
	v_lshlrev_b32_e32 v10, 2, v9
	v_bfi_b32 v119, -16, s9, v0
	s_movk_i32 s28, 0xa0
	v_lshlrev_b32_e32 v14, 3, v0
	v_lshlrev_b32_e32 v18, 3, v9
	v_and_or_b32 v12, v13, 24, v12
	v_subrev_u32_e32 v20, 63, v119
	v_add_u32_e32 v21, 1, v119
	v_mul_lo_u32 v22, v119, s12
	v_or_b32_e32 v24, s25, v10
	v_mul_lo_u32 v25, v119, s28
	v_readlane_b32 s13, v254, 63
	v_ashrrev_i32_e32 v8, 3, v0
	v_and_b32_e32 v13, 8, v14
	v_and_b32_e32 v148, 8, v18
	v_mul_u32_u24_e32 v12, 0x220, v12
	v_cvt_f32_i32_e32 v150, v20
	v_cvt_f32_i32_e32 v151, v21
	v_add_u32_e32 v152, 0, v22
	v_or_b32_e32 v20, 2, v24
	v_add_u32_e32 v154, s13, v25
	v_lshlrev_b32_e32 v22, 1, v24
	v_or_b32_e32 v25, 16, v24
	v_readlane_b32 s6, v255, 14
	s_andn2_b32 s24, s24, 63
	v_and_b32_e32 v8, -8, v8
	v_add3_u32 v12, 0, v12, v13
	v_add_u32_e32 v13, s29, v148
	v_mad_u32_u24 v153, v23, s12, 0
	v_ashrrev_i32_e32 v156, 5, v19
	v_cmp_gt_i32_e64 s[12:13], v20, v119
	v_and_b32_e32 v19, 0x50, v22
	v_lshlrev_b32_e32 v20, 1, v25
	v_readlane_b32 s7, v255, 15
	s_lshl_b32 s33, s6, 4
	s_movk_i32 s6, 0x880
	v_and_b32_e32 v117, 48, v0
	v_ashrrev_i32_e32 v9, 31, v8
	v_cmp_gt_i32_e64 s[8:9], v24, v119
	v_cmp_lt_i32_e64 s[10:11], v24, v119
	v_or_b32_e32 v21, 3, v24
	v_or_b32_e32 v26, 17, v24
	v_or_b32_e32 v27, 18, v24
	v_or_b32_e32 v24, 19, v24
	v_lshlrev_b32_e32 v157, 3, v15
	v_add_u32_e32 v158, v154, v19
	v_and_b32_e32 v19, 0x70, v20
	v_lshlrev_b32_e32 v112, 4, v15
	v_mul_lo_u32 v165, v8, s28
	v_and_or_b32 v14, v14, 16, s24
	v_and_b32_e32 v113, 63, v0
	v_mov_b32_e32 v3, v2
	v_mov_b32_e32 v4, v2
	v_mov_b32_e32 v5, v2
	s_waitcnt vmcnt(0) lgkmcnt(0)
	v_lshl_add_u64 v[106:107], v[6:7], 0, s[26:27]
	s_mov_b64 s[26:27], 0x11400000
	v_lshl_add_u64 v[108:109], v[6:7], 0, s[26:27]
	s_mov_b64 s[26:27], 0x15800000
	v_lshl_add_u64 v[110:111], v[6:7], 0, s[26:27]
	v_add_u32_e32 v7, 0x400, v0
	v_sub_u32_e32 v6, v17, v16
	v_ashrrev_i32_e32 v16, 31, v7
	v_lshrrev_b32_e32 v16, 27, v16
	v_add_u32_e32 v16, v7, v16
	v_ashrrev_i32_e32 v161, 5, v16
	v_and_b32_e32 v16, 0xffffffe0, v16
	v_sub_u32_e32 v7, v7, v16
	v_add_u32_e32 v16, 0x600, v0
	v_ashrrev_i32_e32 v17, 31, v16
	v_lshrrev_b32_e32 v17, 27, v17
	v_add_u32_e32 v17, v16, v17
	v_readlane_b32 s26, v255, 1
	v_lshlrev_b32_e32 v160, 3, v6
	v_ashrrev_i32_e32 v163, 5, v17
	v_and_b32_e32 v17, 0xffffffe0, v17
	v_lshlrev_b32_e32 v114, 4, v6
	v_mov_b32_e32 v6, s26
	v_sub_u32_e32 v16, v16, v17
	v_mad_u32_u24 v167, v11, s28, v6
	v_mad_u32_u24 v168, v23, s28, v6
	v_and_b32_e32 v6, 16, v18
	v_lshlrev_b32_e32 v162, 3, v7
	v_lshlrev_b32_e32 v164, 3, v16
	v_lshlrev_b32_e32 v116, 4, v7
	v_lshlrev_b32_e32 v118, 4, v16
	v_add_u32_e32 v7, 0xa00, v167
	v_add_u32_e32 v15, 0x1400, v167
	v_add_u32_e32 v16, 0x1e00, v167
	v_add3_u32 v6, v13, v6, s24
	v_mul_u32_u24_e32 v11, 0x220, v11
	v_bitop3_b32 v115, v0, 63, v0 bitop3:0xc
	v_cmp_gt_i32_e64 s[6:7], s6, v0
	v_cmp_gt_i32_e64 s[14:15], v21, v119
	v_cmp_gt_i32_e64 s[16:17], v25, v119
	v_cmp_gt_i32_e64 s[18:19], v26, v119
	v_cmp_gt_i32_e64 s[20:21], v27, v119
	v_cmp_gt_i32_e64 s[22:23], v24, v119
	v_add_u32_e32 v159, v154, v19
	v_add_u32_e32 v166, s26, v165
	v_add_u32_e32 v169, 0xfffffe00, v0
	v_lshl_add_u32 v170, v0, 4, s29
	v_lshlrev_b64 v[120:121], 1, v[8:9]
	s_lshl_b32 s84, s25, 1
	v_lshlrev_b32_e32 v0, 1, v10
	v_add_u32_e32 v171, v7, v117
	v_add_u32_e32 v172, v15, v117
	v_add_u32_e32 v173, v16, v117
	v_add_u32_e32 v174, v12, v14
	v_add_u32_e32 v175, v6, v11
	v_readlane_b32 s44, v254, 4
	s_branch .LBB0_799

; #define LAS __attribute__((address_space(3)))
;     ...
;     for (int task = F.vcu; task < BATCH * NH * 2 * NEB; task += F.G) {
;         const int eb = task % NEB, dir = (task / NEB) & 1, h = (task / (2 * NEB)) % NH, b = task / (2 * NEB * NH);
;         bf16* O = (bf16*)(a.ws + (dir ? WS_OB : WS_OF));
;         const bf16* src0 = act;
;         const bf16* src1 = act + (size_t)(HG ? (2 + 2 * dir) : 1) * ACT_STRIDE;
;         const bf16* src2 = act + (size_t)(1 + 2 * dir) * ACT_STRIDE;
;         const bf16* srcv = act + (size_t)(HG ? 5 : 2) * ACT_STRIDE;
;         float lg2 = 0.f;
;         if (!HG) { const float x = a.in[10][(j_layer * 2 + dir) * 8 + h]; lg2 = -log1pf(expf(-x)) * 1.4426950408889634f; }
;         const float r1 = HG ? 1.f : exp2f((float)(nq0 + i - 63) * lg2), r2 = HG ? 1.f : exp2f((float)(nq0 + i + 1) * lg2), cdec = HG ? 1.f : exp2f(64.f * lg2);
;         const int vrow = tid & 63, vcc = tid >> 6;
;         const int vs = dir ? 63 - vrow : vrow;
;         const float kdec = HG ? 1.f : exp2f((float)(63 - vs) * lg2);
;     ...
;         __syncthreads();
;         for (int u = tid; u < IMG / 16; u += NWAVES * 64) { const unsigned zu_ = __builtin_bit_cast(unsigned, zf_); *(LAS v4u*)(L + O_ST + u * 16) = (v4u){zu_, zu_, zu_, zu_}; }
; #pragma unroll
;         for (int u = 0; u < PF; ++u) MX_LOAD(u, u);
.LBB0_799:
	v_mov_b64_e32 v[40:41], s[0:1]
	v_mov_b32_e32 v38, s72
	v_mov_b32_e32 v39, s73
	s_ashr_i32 s48, s44, 31
	v_readlane_b32 s100, v255, 36
	v_readlane_b32 s101, v255, 37
	v_mov_b32_e32 v40, s100
	v_mov_b32_e32 v41, s101
	s_lshr_b32 s24, s48, 30
	s_add_i32 s24, s44, s24
	s_ashr_i32 s51, s24, 2
	s_lshr_b32 s24, s48, 29
	s_add_i32 s24, s44, s24
	s_ashr_i32 s24, s24, 3
	s_lshr_b32 s25, s24, 29
	s_add_i32 s25, s24, s25
	s_and_b32 s25, s25, -8
	s_and_b32 s26, s51, 1
	s_sub_i32 s49, s24, s25
	s_cmp_eq_u32 s26, 0
	s_cselect_b64 s[24:25], -1, 0
	s_lshl_b32 s26, s26, 3
	s_add_i32 s27, s49, s33
	s_add_i32 s26, s27, s26
	s_ashr_i32 s27, s26, 31
	s_mov_b32 s34, 0xc2fc0000
	s_waitcnt vmcnt(0) lgkmcnt(0)
	v_lshl_add_u64 v[40:41], s[26:27], 2, v[40:41]
	flat_load_dword v40, v[40:41]
	s_mov_b32 s26, 0x42ce8ed0
	s_waitcnt lgkmcnt(0)
	s_barrier
	s_waitcnt vmcnt(0)
	v_mul_f32_e32 v41, 0xbfb8aa3b, v40
	v_fma_f32 v42, v40, s96, -v41
	v_rndne_f32_e32 v43, v41
	v_fmac_f32_e32 v42, 0xb2a5705f, v40
	v_sub_f32_e32 v41, v41, v43
	v_add_f32_e32 v41, v41, v42
	v_exp_f32_e32 v41, v41
	v_cvt_i32_f32_e32 v42, v43
	v_cmp_nlt_f32_e32 vcc, s26, v40
	s_mov_b32 s26, 0xc2b17218
	v_ldexp_f32 v41, v41, v42
	v_cndmask_b32_e32 v41, 0, v41, vcc
	v_cmp_ngt_f32_e32 vcc, s26, v40
	s_mov_b32 s26, 0x3f2aaaab
	s_nop 0
	v_cndmask_b32_e32 v42, v183, v41, vcc
	v_add_f32_e32 v43, 1.0, v42
	v_add_f32_e32 v40, -1.0, v43
	v_sub_f32_e32 v41, v40, v43
	v_add_f32_e32 v41, 1.0, v41
	v_sub_f32_e32 v40, v42, v40
	v_add_f32_e32 v44, v40, v41
	v_frexp_mant_f32_e32 v40, v43
	v_cmp_gt_f32_e32 vcc, s26, v40
	v_cvt_f64_f32_e32 v[40:41], v43
	v_frexp_exp_i32_f64_e32 v40, v[40:41]
	v_subbrev_co_u32_e32 v40, vcc, 0, v40, vcc
	v_sub_u32_e32 v41, 0, v40
	v_ldexp_f32 v43, v43, v41
	v_ldexp_f32 v41, v44, v41
	v_add_f32_e32 v44, -1.0, v43
	v_add_f32_e32 v45, 1.0, v44
	v_sub_f32_e32 v45, v43, v45
	v_add_f32_e32 v45, v41, v45
	v_add_f32_e32 v46, v44, v45
	v_sub_f32_e32 v44, v44, v46
	v_add_f32_e32 v44, v45, v44
	v_add_f32_e32 v45, 1.0, v43
	v_add_f32_e32 v47, -1.0, v45
	v_sub_f32_e32 v43, v43, v47
	v_add_f32_e32 v41, v41, v43
	v_add_f32_e32 v43, v45, v41
	v_sub_f32_e32 v45, v45, v43
	v_add_f32_e32 v41, v41, v45
	v_rcp_f32_e32 v45, v43
	v_cvt_f32_i32_e32 v40, v40
	s_mov_b32 s26, 0x7f800000
	v_cmp_neq_f32_e32 vcc, s26, v42
	v_mul_f32_e32 v47, v46, v45
	v_mul_f32_e32 v48, v43, v47
	v_fma_f32 v49, v47, v43, -v48
	v_fmac_f32_e32 v49, v47, v41
	v_add_f32_e32 v50, v48, v49
	v_sub_f32_e32 v51, v46, v50
	v_sub_f32_e32 v46, v46, v51
	v_sub_f32_e32 v48, v50, v48
	v_sub_f32_e32 v46, v46, v50
	v_add_f32_e32 v44, v44, v46
	v_sub_f32_e32 v46, v48, v49
	v_add_f32_e32 v44, v46, v44
	v_add_f32_e32 v46, v51, v44
	v_mul_f32_e32 v48, v45, v46
	v_mul_f32_e32 v49, v43, v48
	v_fma_f32 v43, v48, v43, -v49
	v_fmac_f32_e32 v43, v48, v41
	v_sub_f32_e32 v41, v51, v46
	v_add_f32_e32 v41, v44, v41
	v_add_f32_e32 v44, v49, v43
	v_sub_f32_e32 v50, v46, v44
	v_sub_f32_e32 v46, v46, v50
	v_sub_f32_e32 v49, v44, v49
	v_sub_f32_e32 v44, v46, v44
	v_add_f32_e32 v41, v41, v44
	v_sub_f32_e32 v43, v49, v43
	v_add_f32_e32 v41, v43, v41
	v_add_f32_e32 v43, v47, v48
	v_add_f32_e32 v41, v50, v41
	v_sub_f32_e32 v44, v43, v47
	v_mul_f32_e32 v41, v45, v41
	v_sub_f32_e32 v44, v48, v44
	v_add_f32_e32 v41, v44, v41
	v_mul_f32_e32 v47, 0x3f317218, v40
	v_add_f32_e32 v44, v43, v41
	v_fma_f32 v48, v40, s68, -v47
	v_mul_f32_e32 v45, v44, v44
	v_mov_b32_e32 v46, 0x3ecc95a3
	v_fmac_f32_e32 v48, 0xb102e308, v40
	v_sub_f32_e32 v40, v44, v43
	v_fmamk_f32 v46, v45, 0x3e9b6dac, v46
	v_sub_f32_e32 v40, v41, v40
	v_add_f32_e32 v41, v47, v48
	v_fmaak_f32 v46, v45, v46, 0x3f2aaada
	v_sub_f32_e32 v43, v41, v47
	v_ldexp_f32 v47, v44, 1
	v_mul_f32_e32 v44, v44, v45
	v_mul_f32_e32 v44, v44, v46
	v_add_f32_e32 v45, v47, v44
	v_sub_f32_e32 v46, v45, v47
	v_ldexp_f32 v40, v40, 1
	v_sub_f32_e32 v44, v44, v46
	v_add_f32_e32 v40, v40, v44
	v_add_f32_e32 v44, v45, v40
	v_sub_f32_e32 v45, v44, v45
	v_sub_f32_e32 v40, v40, v45
	v_add_f32_e32 v45, v41, v44
	v_sub_f32_e32 v46, v45, v41
	v_sub_f32_e32 v47, v45, v46
	v_sub_f32_e32 v43, v48, v43
	v_sub_f32_e32 v41, v41, v47
	v_sub_f32_e32 v44, v44, v46
	v_add_f32_e32 v41, v44, v41
	v_add_f32_e32 v44, v43, v40
	v_sub_f32_e32 v46, v44, v43
	v_sub_f32_e32 v47, v44, v46
	v_sub_f32_e32 v43, v43, v47
	v_sub_f32_e32 v40, v40, v46
	v_add_f32_e32 v41, v44, v41
	v_add_f32_e32 v40, v40, v43
	v_add_f32_e32 v43, v45, v41
	v_sub_f32_e32 v44, v43, v45
	v_sub_f32_e32 v41, v41, v44
	v_add_f32_e32 v40, v40, v41
	v_add_f32_e32 v40, v43, v40
	s_mov_b32 s26, 0x33800000
	v_cndmask_b32_e32 v40, v183, v40, vcc
	v_cmp_lt_f32_e64 vcc, |v42|, s26
	v_cndmask_b32_e64 v41, v115, v113, s[24:25]
	s_nop 0
	v_cndmask_b32_e32 v40, v40, v42, vcc
	v_xor_b32_e32 v42, 63, v41
	v_mul_f32_e32 v40, 0xbfb8aa3b, v40
	v_cvt_f32_ubyte0_e32 v42, v42
	v_mul_f32_e32 v43, v40, v150
	v_mul_f32_e32 v44, v40, v151
	v_mul_f32_e32 v45, 0x42800000, v40
	v_mul_f32_e32 v46, v40, v42
	v_cmp_gt_f32_e64 s[30:31], s34, v43
	v_cmp_gt_f32_e64 s[28:29], s34, v44
	v_cmp_gt_f32_e64 s[26:27], s34, v45
	v_cmp_gt_f32_e32 vcc, s34, v46
	s_and_saveexec_b64 s[36:37], s[6:7]
	s_cbranch_execz .LBB0_802
	s_mov_b64 s[40:41], 0
	v_mov_b32_e32 v43, v170
	v_mov_b32_e32 v44, v169

; #define LAS __attribute__((address_space(3)))
; __device__ __forceinline__ void relaunder(Frame& F) { int t = mk_tid(); asm volatile("" : "+v"(t)); F.tid = t; F.lane = t & 63; F.wave = __builtin_amdgcn_readfirstlane(t >> 6); }
; template <bool HG>
; __device__ __forceinline__ void readout_phase2(const Args& a, Frame& F, const float* gain, int nrows) {
;     relaunder(F);
;     const int nw = F.vcu * NWAVES + F.wave;
;     const bf16* OF = (const bf16*)(a.ws + WS_OF); const bf16* OB = (const bf16*)(a.ws + WS_OB);
;     const bf16* G = (const bf16*)(a.ws + WS_ACT) + (size_t)(HG ? 6 : 3) * ACT_STRIDE; bf16* HN = (bf16*)(a.ws + WS_HN);
;     LAS float* GL = (LAS float*)F.lds;
;     v2u f0[8], b0[8], g0[8], f1[8], b1[8], g1[8], f2[8], b2[8], g2[8];
;     ...
;     RO_LOAD(f0, b0, g0, nw); RO_LOAD(f1, b1, g1, nw + 2048); RO_LOAD(f2, b2, g2, nw + 2 * 2048);
.LBB0_861:
	s_andn2_b64 vcc, exec, s[6:7]
	s_cbranch_vccnz .LBB0_864
	s_getreg_b32 s6, hwreg(HW_REG_HW_ID, 0, 6)
	s_lshl_b32 s6, s6, 2
	s_add_i32 s6, s6, 0
	s_add_i32 s6, s6, 0x20540
	v_mov_b32_e32 v0, s6
	ds_read_b32 v0, v0
	v_mov_b64_e32 v[2:3], s[0:1]
	s_waitcnt lgkmcnt(0)
	v_readfirstlane_b32 s6, v0
	v_mbcnt_lo_u32_b32 v0, -1, 0
	v_mbcnt_hi_u32_b32 v0, -1, v0
	s_nop 1
	v_lshl_add_u32 v0, s6, 6, v0
	v_mov_b32_e32 v2, s72
	v_mov_b32_e32 v3, s73
	v_readfirstlane_b32 s6, v0
	s_ashr_i32 s6, s6, 6
	s_add_i32 s8, s6, s91
	s_mov_b64 s[6:7], 0x2ac00000
	s_ashr_i32 s9, s8, 31
	v_and_b32_e32 v12, 63, v0
	s_lshl_b64 s[10:11], s[8:9], 12
	v_lshlrev_b32_e32 v0, 3, v12
	s_add_u32 s16, s10, 0x800000
	s_addc_u32 s17, s11, 0
	s_add_u32 s12, s10, 0x1000000
	s_addc_u32 s13, s11, 0
	s_waitcnt vmcnt(0) lgkmcnt(0)
	v_lshl_add_u64 v[4:5], v[2:3], 0, s[6:7]
	s_mov_b64 s[6:7], 0x33400000
	v_lshl_add_u64 v[6:7], v[2:3], 0, s[6:7]
	s_mov_b64 s[6:7], 0x19c00000
	v_lshl_add_u64 v[8:9], v[2:3], 0, s[6:7]
	v_lshl_add_u64 v[10:11], v[4:5], 0, s[10:11]
	v_lshl_add_u64 v[10:11], v[10:11], 0, v[0:1]
	v_lshl_add_u64 v[12:13], v[6:7], 0, s[10:11]
	v_lshl_add_u64 v[14:15], v[8:9], 0, s[10:11]
	v_lshl_add_u64 v[12:13], v[12:13], 0, v[0:1]
	v_lshl_add_u64 v[14:15], v[14:15], 0, v[0:1]
	global_load_dwordx2 v[152:153], v[10:11], off nt
	global_load_dwordx2 v[150:151], v[12:13], off nt
	global_load_dwordx2 v[64:65], v[14:15], off nt
	global_load_dwordx2 v[148:149], v[10:11], off offset:512 nt
	global_load_dwordx2 v[142:143], v[12:13], off offset:512 nt
	global_load_dwordx2 v[58:59], v[14:15], off offset:512 nt
	global_load_dwordx2 v[136:137], v[10:11], off offset:1024 nt
	global_load_dwordx2 v[130:131], v[12:13], off offset:1024 nt
	global_load_dwordx2 v[52:53], v[14:15], off offset:1024 nt
	global_load_dwordx2 v[126:127], v[10:11], off offset:1536 nt
	global_load_dwordx2 v[122:123], v[12:13], off offset:1536 nt
	global_load_dwordx2 v[46:47], v[14:15], off offset:1536 nt
	global_load_dwordx2 v[118:119], v[10:11], off offset:2048 nt
	global_load_dwordx2 v[114:115], v[12:13], off offset:2048 nt
	global_load_dwordx2 v[40:41], v[14:15], off offset:2048 nt
	global_load_dwordx2 v[110:111], v[10:11], off offset:2560 nt
	global_load_dwordx2 v[106:107], v[12:13], off offset:2560 nt
	global_load_dwordx2 v[24:25], v[14:15], off offset:2560 nt
	global_load_dwordx2 v[102:103], v[10:11], off offset:3072 nt
	global_load_dwordx2 v[98:99], v[12:13], off offset:3072 nt
	global_load_dwordx2 v[20:21], v[14:15], off offset:3072 nt
	global_load_dwordx2 v[94:95], v[10:11], off offset:3584 nt
	global_load_dwordx2 v[90:91], v[12:13], off offset:3584 nt
	global_load_dwordx2 v[16:17], v[14:15], off offset:3584 nt
	v_lshl_add_u64 v[10:11], v[4:5], 0, s[16:17]
	v_lshl_add_u64 v[10:11], v[10:11], 0, v[0:1]
	v_lshl_add_u64 v[12:13], v[6:7], 0, s[16:17]
	v_lshl_add_u64 v[14:15], v[8:9], 0, s[16:17]
	v_lshl_add_u64 v[12:13], v[12:13], 0, v[0:1]
	v_lshl_add_u64 v[14:15], v[14:15], 0, v[0:1]
	global_load_dwordx2 v[146:147], v[10:11], off nt
	global_load_dwordx2 v[144:145], v[12:13], off nt
	global_load_dwordx2 v[66:67], v[14:15], off nt
	global_load_dwordx2 v[140:141], v[10:11], off offset:512 nt
	global_load_dwordx2 v[138:139], v[12:13], off offset:512 nt
	global_load_dwordx2 v[60:61], v[14:15], off offset:512 nt
	global_load_dwordx2 v[134:135], v[10:11], off offset:1024 nt
	global_load_dwordx2 v[132:133], v[12:13], off offset:1024 nt
	global_load_dwordx2 v[54:55], v[14:15], off offset:1024 nt
	global_load_dwordx2 v[128:129], v[10:11], off offset:1536 nt
	global_load_dwordx2 v[124:125], v[12:13], off offset:1536 nt
	global_load_dwordx2 v[48:49], v[14:15], off offset:1536 nt
	global_load_dwordx2 v[120:121], v[10:11], off offset:2048 nt
	global_load_dwordx2 v[116:117], v[12:13], off offset:2048 nt
	global_load_dwordx2 v[42:43], v[14:15], off offset:2048 nt
	global_load_dwordx2 v[112:113], v[10:11], off offset:2560 nt
	global_load_dwordx2 v[108:109], v[12:13], off offset:2560 nt
	global_load_dwordx2 v[36:37], v[14:15], off offset:2560 nt
	global_load_dwordx2 v[104:105], v[10:11], off offset:3072 nt
	global_load_dwordx2 v[100:101], v[12:13], off offset:3072 nt
	global_load_dwordx2 v[32:33], v[14:15], off offset:3072 nt
	global_load_dwordx2 v[96:97], v[10:11], off offset:3584 nt
	global_load_dwordx2 v[92:93], v[12:13], off offset:3584 nt
	global_load_dwordx2 v[28:29], v[14:15], off offset:3584 nt
	v_lshl_add_u64 v[10:11], v[4:5], 0, s[12:13]
	v_lshl_add_u64 v[38:39], v[10:11], 0, v[0:1]
	v_lshl_add_u64 v[10:11], v[6:7], 0, s[12:13]
	v_lshl_add_u64 v[12:13], v[8:9], 0, s[12:13]
	v_lshl_add_u64 v[10:11], v[10:11], 0, v[0:1]
	v_lshl_add_u64 v[154:155], v[12:13], 0, v[0:1]
	global_load_dwordx2 v[88:89], v[38:39], off nt
	global_load_dwordx2 v[86:87], v[10:11], off nt
	global_load_dwordx2 v[34:35], v[154:155], off nt
	global_load_dwordx2 v[84:85], v[38:39], off offset:512 nt
	global_load_dwordx2 v[82:83], v[10:11], off offset:512 nt
	global_load_dwordx2 v[30:31], v[154:155], off offset:512 nt
	global_load_dwordx2 v[80:81], v[38:39], off offset:1024 nt
	global_load_dwordx2 v[78:79], v[10:11], off offset:1024 nt
	global_load_dwordx2 v[26:27], v[154:155], off offset:1024 nt
	global_load_dwordx2 v[74:75], v[38:39], off offset:1536 nt
	global_load_dwordx2 v[76:77], v[10:11], off offset:1536 nt
	global_load_dwordx2 v[22:23], v[154:155], off offset:1536 nt
	global_load_dwordx2 v[72:73], v[38:39], off offset:2048 nt
	global_load_dwordx2 v[70:71], v[10:11], off offset:2048 nt
	global_load_dwordx2 v[18:19], v[154:155], off offset:2048 nt
	global_load_dwordx2 v[68:69], v[38:39], off offset:2560 nt
	global_load_dwordx2 v[62:63], v[10:11], off offset:2560 nt
	global_load_dwordx2 v[14:15], v[154:155], off offset:2560 nt
	global_load_dwordx2 v[56:57], v[38:39], off offset:3072 nt
	global_load_dwordx2 v[50:51], v[10:11], off offset:3072 nt
	global_load_dwordx2 v[12:13], v[154:155], off offset:3072 nt
	s_nop 0
	global_load_dwordx2 v[38:39], v[38:39], off offset:3584 nt
	s_nop 0
	global_load_dwordx2 v[44:45], v[10:11], off offset:3584 nt
	s_nop 0
	global_load_dwordx2 v[10:11], v[154:155], off offset:3584 nt
	s_mov_b64 s[6:7], 0x8c00000
	v_lshl_add_u64 v[2:3], v[2:3], 0, s[6:7]
	s_waitcnt vmcnt(62)
	v_lshlrev_b32_e32 v154, 16, v152
	v_and_b32_e32 v155, 0xffff0000, v152
	v_lshlrev_b32_e32 v156, 16, v150
	v_and_b32_e32 v157, 0xffff0000, v150
	v_lshlrev_b32_e32 v152, 16, v153
	v_and_b32_e32 v153, 0xffff0000, v153
	v_lshlrev_b32_e32 v150, 16, v151
	v_and_b32_e32 v151, 0xffff0000, v151
	v_pk_add_f32 v[154:155], v[154:155], v[156:157]
	v_pk_add_f32 v[152:153], v[152:153], v[150:151]
	v_mov_b32_e32 v156, v155
	v_mov_b32_e32 v157, v153
	v_mov_b32_e32 v150, v154
	v_mov_b32_e32 v151, v152
	v_pk_mul_f32 v[156:157], v[156:157], v[156:157]
	s_waitcnt vmcnt(49)
	v_lshlrev_b32_e32 v162, 16, v90
	v_pk_fma_f32 v[150:151], v[150:151], v[150:151], v[156:157]
	v_lshlrev_b32_e32 v156, 16, v142
	v_add_f32_e32 v161, v150, v151
	v_lshlrev_b32_e32 v150, 16, v148
	v_and_b32_e32 v151, 0xffff0000, v148
	v_and_b32_e32 v157, 0xffff0000, v142
	v_lshlrev_b32_e32 v148, 16, v149
	v_and_b32_e32 v149, 0xffff0000, v149
	v_lshlrev_b32_e32 v142, 16, v143
	v_and_b32_e32 v143, 0xffff0000, v143
	v_pk_add_f32 v[150:151], v[150:151], v[156:157]
	v_pk_add_f32 v[148:149], v[148:149], v[142:143]
	v_mov_b32_e32 v156, v151
	v_mov_b32_e32 v157, v149
	v_mov_b32_e32 v142, v150
	v_mov_b32_e32 v143, v148
	v_pk_mul_f32 v[156:157], v[156:157], v[156:157]
	v_add_f32_dpp v161, v161, v161 quad_perm:[1,0,3,2] row_mask:0xf bank_mask:0xf bound_ctrl:1
	v_pk_fma_f32 v[142:143], v[142:143], v[142:143], v[156:157]
	v_lshlrev_b32_e32 v156, 16, v130
	v_add_f32_e32 v166, v142, v143
	v_lshlrev_b32_e32 v142, 16, v136
	v_and_b32_e32 v143, 0xffff0000, v136
	v_and_b32_e32 v157, 0xffff0000, v130
	v_lshlrev_b32_e32 v136, 16, v137
	v_and_b32_e32 v137, 0xffff0000, v137
	v_lshlrev_b32_e32 v130, 16, v131
	v_and_b32_e32 v131, 0xffff0000, v131
	v_pk_add_f32 v[142:143], v[142:143], v[156:157]
	v_pk_add_f32 v[136:137], v[136:137], v[130:131]
	v_mov_b32_e32 v156, v143
	v_mov_b32_e32 v157, v137
	v_mov_b32_e32 v130, v142
	v_mov_b32_e32 v131, v136
	v_pk_mul_f32 v[156:157], v[156:157], v[156:157]
	v_and_b32_e32 v163, 0xffff0000, v90
	v_pk_fma_f32 v[130:131], v[130:131], v[130:131], v[156:157]
	v_lshlrev_b32_e32 v156, 16, v122
	v_add_f32_e32 v160, v130, v131
	v_lshlrev_b32_e32 v130, 16, v126
	v_and_b32_e32 v131, 0xffff0000, v126
	v_and_b32_e32 v157, 0xffff0000, v122
	v_lshlrev_b32_e32 v126, 16, v127
	v_and_b32_e32 v127, 0xffff0000, v127
	v_lshlrev_b32_e32 v122, 16, v123
	v_and_b32_e32 v123, 0xffff0000, v123
	v_pk_add_f32 v[130:131], v[130:131], v[156:157]
	v_pk_add_f32 v[126:127], v[126:127], v[122:123]
	v_mov_b32_e32 v156, v131
	v_mov_b32_e32 v157, v127
	v_mov_b32_e32 v122, v130
	v_mov_b32_e32 v123, v126
	v_pk_mul_f32 v[156:157], v[156:157], v[156:157]
	v_lshlrev_b32_e32 v90, 16, v91
	v_pk_fma_f32 v[122:123], v[122:123], v[122:123], v[156:157]
	v_lshlrev_b32_e32 v156, 16, v114
	v_add_f32_e32 v167, v122, v123
	v_lshlrev_b32_e32 v122, 16, v118
	v_and_b32_e32 v123, 0xffff0000, v118
	v_and_b32_e32 v157, 0xffff0000, v114
	v_lshlrev_b32_e32 v118, 16, v119
	v_and_b32_e32 v119, 0xffff0000, v119
	v_lshlrev_b32_e32 v114, 16, v115
	v_and_b32_e32 v115, 0xffff0000, v115
	v_pk_add_f32 v[122:123], v[122:123], v[156:157]
	v_pk_add_f32 v[118:119], v[118:119], v[114:115]
	v_mov_b32_e32 v156, v123
	v_mov_b32_e32 v157, v119
	v_mov_b32_e32 v114, v122
	v_mov_b32_e32 v115, v118
	v_pk_mul_f32 v[156:157], v[156:157], v[156:157]
	v_and_b32_e32 v91, 0xffff0000, v91
	v_pk_fma_f32 v[114:115], v[114:115], v[114:115], v[156:157]
	v_lshlrev_b32_e32 v156, 16, v106
	v_add_f32_e32 v159, v114, v115
	v_lshlrev_b32_e32 v114, 16, v110
	v_and_b32_e32 v115, 0xffff0000, v110
	v_and_b32_e32 v157, 0xffff0000, v106
	v_lshlrev_b32_e32 v110, 16, v111
	v_and_b32_e32 v111, 0xffff0000, v111
	v_lshlrev_b32_e32 v106, 16, v107
	v_and_b32_e32 v107, 0xffff0000, v107
	v_pk_add_f32 v[114:115], v[114:115], v[156:157]
	v_pk_add_f32 v[110:111], v[110:111], v[106:107]
	v_mov_b32_e32 v156, v115
	v_mov_b32_e32 v157, v111
	v_mov_b32_e32 v106, v114
	v_mov_b32_e32 v107, v110
	v_pk_mul_f32 v[156:157], v[156:157], v[156:157]
	v_add_f32_dpp v161, v161, v161 quad_perm:[2,3,0,1] row_mask:0xf bank_mask:0xf bound_ctrl:1
	v_pk_fma_f32 v[106:107], v[106:107], v[106:107], v[156:157]
	v_lshlrev_b32_e32 v156, 16, v98
	v_add_f32_e32 v158, v106, v107
	v_lshlrev_b32_e32 v106, 16, v102
	v_and_b32_e32 v107, 0xffff0000, v102
	v_and_b32_e32 v157, 0xffff0000, v98
	v_lshlrev_b32_e32 v102, 16, v103
	v_and_b32_e32 v103, 0xffff0000, v103
	v_lshlrev_b32_e32 v98, 16, v99
	v_and_b32_e32 v99, 0xffff0000, v99
	v_pk_add_f32 v[106:107], v[106:107], v[156:157]
	v_pk_add_f32 v[102:103], v[102:103], v[98:99]
	v_mov_b32_e32 v156, v107
	v_mov_b32_e32 v157, v103
	v_mov_b32_e32 v98, v106
	v_mov_b32_e32 v99, v102
	v_pk_mul_f32 v[156:157], v[156:157], v[156:157]
	v_add_f32_dpp v161, v161, v161 row_half_mirror row_mask:0xf bank_mask:0xf bound_ctrl:1
	v_pk_fma_f32 v[98:99], v[98:99], v[98:99], v[156:157]
	s_nop 0
	v_add_f32_e32 v157, v98, v99
	v_lshlrev_b32_e32 v98, 16, v94
	v_and_b32_e32 v99, 0xffff0000, v94
	v_lshlrev_b32_e32 v94, 16, v95
	v_and_b32_e32 v95, 0xffff0000, v95
	v_pk_add_f32 v[98:99], v[98:99], v[162:163]
	v_pk_add_f32 v[90:91], v[94:95], v[90:91]
	v_mov_b32_e32 v162, v99
	v_mov_b32_e32 v163, v91
	v_add_f32_dpp v161, v161, v161 row_mirror row_mask:0xf bank_mask:0xf bound_ctrl:1
	v_mov_b32_e32 v94, v98
	v_mov_b32_e32 v95, v90
	v_pk_mul_f32 v[162:163], v[162:163], v[162:163]
	v_readlane_b32 s9, v161, 16
	v_readlane_b32 s14, v161, 48
	v_pk_fma_f32 v[94:95], v[94:95], v[94:95], v[162:163]
	v_readlane_b32 s6, v161, 0
	v_readlane_b32 s7, v161, 32
	v_mov_b32_e32 v162, s9
	v_mov_b32_e32 v163, s14
	v_pk_add_f32 v[162:163], s[6:7], v[162:163]
	v_add_f32_e32 v156, v94, v95
	v_add_f32_e32 v161, v162, v163
	v_fmamk_f32 v161, v161, 0x3b800000, v252
	v_cmp_gt_f32_e32 vcc, s55, v161
	v_mul_f32_e32 v162, 0x4f800000, v161
	v_lshl_add_u64 v[94:95], v[2:3], 0, s[10:11]
	v_cndmask_b32_e32 v161, v161, v162, vcc
	v_sqrt_f32_e32 v162, v161
	v_lshl_add_u64 v[94:95], v[94:95], 0, v[0:1]
	v_add_u32_e32 v163, -1, v162
	v_fma_f32 v164, -v163, v162, v161
	v_cmp_ge_f32_e64 s[6:7], 0, v164
	v_add_u32_e32 v164, 1, v162
	s_nop 0
	v_cndmask_b32_e64 v163, v162, v163, s[6:7]
	v_fma_f32 v162, -v164, v162, v161
	v_cmp_lt_f32_e64 s[6:7], 0, v162
	s_nop 1
	v_cndmask_b32_e64 v162, v163, v164, s[6:7]
	v_mul_f32_e32 v163, 0x37800000, v162
	v_cndmask_b32_e32 v162, v162, v163, vcc
	v_cmp_class_f32_e32 vcc, v161, v253
	s_nop 1
	v_cndmask_b32_e32 v161, v162, v161, vcc
	v_div_scale_f32 v162, s[6:7], v161, v161, 1.0
	v_rcp_f32_e32 v163, v162
	s_nop 0
	v_fma_f32 v164, -v162, v163, 1.0
	v_fmac_f32_e32 v163, v164, v163
	v_div_scale_f32 v164, vcc, 1.0, v161, 1.0
	v_mul_f32_e32 v165, v164, v163
	v_fma_f32 v168, -v162, v165, v164
	v_fmac_f32_e32 v165, v168, v163
	v_fma_f32 v162, -v162, v165, v164
	v_div_fmas_f32 v162, v162, v163, v165
	v_div_fixup_f32 v162, v162, v161, 1.0
	v_lshlrev_b32_e32 v164, 16, v64
	v_and_b32_e32 v165, 0xffff0000, v64
	v_lshlrev_b32_e32 v64, 16, v65
	v_and_b32_e32 v65, 0xffff0000, v65
	v_pk_mul_f32 v[154:155], v[154:155], v[162:163] op_sel_hi:[1,0]
	v_pk_mul_f32 v[152:153], v[152:153], v[162:163] op_sel_hi:[1,0]
	s_nop 0
	v_pk_mul_f32 v[64:65], v[152:153], v[64:65]
	v_pk_mul_f32 v[152:153], v[154:155], v[164:165]
	s_nop 0
	v_cvt_pk_bf16_f32 v152, v152, v153
	v_cvt_pk_bf16_f32 v153, v64, v65
	v_add_f32_dpp v64, v166, v166 quad_perm:[1,0,3,2] row_mask:0xf bank_mask:0xf bound_ctrl:1
	global_store_dwordx2 v[94:95], v[152:153], off
	s_nop 0
	v_add_f32_dpp v64, v64, v64 quad_perm:[2,3,0,1] row_mask:0xf bank_mask:0xf bound_ctrl:1
	s_nop 1
	v_add_f32_dpp v64, v64, v64 row_half_mirror row_mask:0xf bank_mask:0xf bound_ctrl:1
	s_nop 1
	v_add_f32_dpp v64, v64, v64 row_mirror row_mask:0xf bank_mask:0xf bound_ctrl:1
	s_nop 0
	v_readlane_b32 s9, v64, 16
	v_readlane_b32 s14, v64, 48
	v_readlane_b32 s6, v64, 0
	v_readlane_b32 s7, v64, 32
	v_mov_b32_e32 v64, s9
	v_mov_b32_e32 v65, s14
	v_pk_add_f32 v[64:65], s[6:7], v[64:65]
	s_nop 0
	v_add_f32_e32 v64, v64, v65
	v_fmamk_f32 v64, v64, 0x3b800000, v252
	v_cmp_gt_f32_e32 vcc, s55, v64
	v_mul_f32_e32 v65, 0x4f800000, v64
	s_nop 0
	v_cndmask_b32_e32 v64, v64, v65, vcc
	v_sqrt_f32_e32 v65, v64
	s_nop 0
	v_add_u32_e32 v152, -1, v65
	v_fma_f32 v153, -v152, v65, v64
	v_cmp_ge_f32_e64 s[6:7], 0, v153
	v_add_u32_e32 v153, 1, v65
	s_nop 0
	v_cndmask_b32_e64 v152, v65, v152, s[6:7]
	v_fma_f32 v65, -v153, v65, v64
	v_cmp_lt_f32_e64 s[6:7], 0, v65
	s_nop 1
	v_cndmask_b32_e64 v65, v152, v153, s[6:7]
	v_mul_f32_e32 v152, 0x37800000, v65
	v_cndmask_b32_e32 v65, v65, v152, vcc
	v_cmp_class_f32_e32 vcc, v64, v253
	s_nop 1
	v_cndmask_b32_e32 v64, v65, v64, vcc
	v_div_scale_f32 v65, s[6:7], v64, v64, 1.0
	v_rcp_f32_e32 v152, v65
	s_nop 0
	v_fma_f32 v153, -v65, v152, 1.0
	v_fmac_f32_e32 v152, v153, v152
	v_div_scale_f32 v153, vcc, 1.0, v64, 1.0
	v_mul_f32_e32 v154, v153, v152
	v_fma_f32 v155, -v65, v154, v153
	v_fmac_f32_e32 v154, v155, v152
	v_fma_f32 v65, -v65, v154, v153
	v_div_fmas_f32 v65, v65, v152, v154
	v_div_fixup_f32 v64, v65, v64, 1.0
	v_lshlrev_b32_e32 v152, 16, v58
	v_and_b32_e32 v153, 0xffff0000, v58
	v_lshlrev_b32_e32 v58, 16, v59
	v_and_b32_e32 v59, 0xffff0000, v59
	v_pk_mul_f32 v[150:151], v[150:151], v[64:65] op_sel_hi:[1,0]
	v_pk_mul_f32 v[64:65], v[148:149], v[64:65] op_sel_hi:[1,0]
	s_nop 0
	v_pk_mul_f32 v[58:59], v[64:65], v[58:59]
	v_pk_mul_f32 v[64:65], v[150:151], v[152:153]
	s_waitcnt vmcnt(47)
	v_lshlrev_b32_e32 v152, 16, v144
	v_cvt_pk_bf16_f32 v64, v64, v65
	v_cvt_pk_bf16_f32 v65, v58, v59
	v_add_f32_dpp v58, v160, v160 quad_perm:[1,0,3,2] row_mask:0xf bank_mask:0xf bound_ctrl:1
	global_store_dwordx2 v[94:95], v[64:65], off offset:512
	v_and_b32_e32 v153, 0xffff0000, v144
	v_add_f32_dpp v58, v58, v58 quad_perm:[2,3,0,1] row_mask:0xf bank_mask:0xf bound_ctrl:1
	v_lshlrev_b32_e32 v144, 16, v145
	v_and_b32_e32 v145, 0xffff0000, v145
	v_add_f32_dpp v58, v58, v58 row_half_mirror row_mask:0xf bank_mask:0xf bound_ctrl:1
	s_nop 1
	v_add_f32_dpp v58, v58, v58 row_mirror row_mask:0xf bank_mask:0xf bound_ctrl:1
	s_nop 0
	v_readlane_b32 s9, v58, 16
	v_readlane_b32 s14, v58, 48
	v_readlane_b32 s6, v58, 0
	v_readlane_b32 s7, v58, 32
	v_mov_b32_e32 v58, s9
	v_mov_b32_e32 v59, s14
	v_pk_add_f32 v[58:59], s[6:7], v[58:59]
	s_nop 0
	v_add_f32_e32 v58, v58, v59
	v_fmamk_f32 v58, v58, 0x3b800000, v252
	v_cmp_gt_f32_e32 vcc, s55, v58
	v_mul_f32_e32 v59, 0x4f800000, v58
	s_nop 0
	v_cndmask_b32_e32 v58, v58, v59, vcc
	v_sqrt_f32_e32 v59, v58
	s_nop 0
	v_add_u32_e32 v64, -1, v59
	v_fma_f32 v65, -v64, v59, v58
	v_cmp_ge_f32_e64 s[6:7], 0, v65
	v_add_u32_e32 v65, 1, v59
	s_nop 0
	v_cndmask_b32_e64 v64, v59, v64, s[6:7]
	v_fma_f32 v59, -v65, v59, v58
	v_cmp_lt_f32_e64 s[6:7], 0, v59
	s_nop 1
	v_cndmask_b32_e64 v59, v64, v65, s[6:7]
	v_mul_f32_e32 v64, 0x37800000, v59
	v_cndmask_b32_e32 v59, v59, v64, vcc
	v_cmp_class_f32_e32 vcc, v58, v253
	s_nop 1
	v_cndmask_b32_e32 v58, v59, v58, vcc
	v_div_scale_f32 v59, s[6:7], v58, v58, 1.0
	v_rcp_f32_e32 v64, v59
	s_nop 0
	v_fma_f32 v65, -v59, v64, 1.0
	v_fmac_f32_e32 v64, v65, v64
	v_div_scale_f32 v65, vcc, 1.0, v58, 1.0
	v_mul_f32_e32 v148, v65, v64
	v_fma_f32 v149, -v59, v148, v65
	v_fmac_f32_e32 v148, v149, v64
	v_fma_f32 v59, -v59, v148, v65
	v_div_fmas_f32 v59, v59, v64, v148
	v_div_fixup_f32 v58, v59, v58, 1.0
	v_lshlrev_b32_e32 v64, 16, v52
	v_and_b32_e32 v65, 0xffff0000, v52
	v_lshlrev_b32_e32 v52, 16, v53
	v_and_b32_e32 v53, 0xffff0000, v53
	v_pk_mul_f32 v[142:143], v[142:143], v[58:59] op_sel_hi:[1,0]
	v_pk_mul_f32 v[58:59], v[136:137], v[58:59] op_sel_hi:[1,0]
	s_nop 0
	v_pk_mul_f32 v[52:53], v[58:59], v[52:53]
	v_pk_mul_f32 v[58:59], v[142:143], v[64:65]
	s_nop 0
	v_cvt_pk_bf16_f32 v58, v58, v59
	v_cvt_pk_bf16_f32 v59, v52, v53
	v_add_f32_dpp v52, v167, v167 quad_perm:[1,0,3,2] row_mask:0xf bank_mask:0xf bound_ctrl:1
	global_store_dwordx2 v[94:95], v[58:59], off offset:1024
	s_nop 0
	v_add_f32_dpp v52, v52, v52 quad_perm:[2,3,0,1] row_mask:0xf bank_mask:0xf bound_ctrl:1
	s_nop 1
	v_add_f32_dpp v52, v52, v52 row_half_mirror row_mask:0xf bank_mask:0xf bound_ctrl:1
	s_nop 1
	v_add_f32_dpp v52, v52, v52 row_mirror row_mask:0xf bank_mask:0xf bound_ctrl:1
	s_nop 0
	v_readlane_b32 s9, v52, 16
	v_readlane_b32 s14, v52, 48
	v_readlane_b32 s6, v52, 0
	v_readlane_b32 s7, v52, 32
	v_mov_b32_e32 v52, s9
	v_mov_b32_e32 v53, s14
	v_pk_add_f32 v[52:53], s[6:7], v[52:53]
	s_nop 0
	v_add_f32_e32 v52, v52, v53
	v_fmamk_f32 v52, v52, 0x3b800000, v252
	v_cmp_gt_f32_e32 vcc, s55, v52
	v_mul_f32_e32 v53, 0x4f800000, v52
	s_nop 0
	v_cndmask_b32_e32 v52, v52, v53, vcc
	v_sqrt_f32_e32 v53, v52
	s_nop 0
	v_add_u32_e32 v58, -1, v53
	v_fma_f32 v59, -v58, v53, v52
	v_cmp_ge_f32_e64 s[6:7], 0, v59
	v_add_u32_e32 v59, 1, v53
	s_nop 0
	v_cndmask_b32_e64 v58, v53, v58, s[6:7]
	v_fma_f32 v53, -v59, v53, v52
	v_cmp_lt_f32_e64 s[6:7], 0, v53
	s_nop 1
	v_cndmask_b32_e64 v53, v58, v59, s[6:7]
	v_mul_f32_e32 v58, 0x37800000, v53
	v_cndmask_b32_e32 v53, v53, v58, vcc
	v_cmp_class_f32_e32 vcc, v52, v253
	s_nop 1
	v_cndmask_b32_e32 v52, v53, v52, vcc
	v_div_scale_f32 v53, s[6:7], v52, v52, 1.0
	v_rcp_f32_e32 v58, v53
	s_nop 0
	v_fma_f32 v59, -v53, v58, 1.0
	v_fmac_f32_e32 v58, v59, v58
	v_div_scale_f32 v59, vcc, 1.0, v52, 1.0
	v_mul_f32_e32 v64, v59, v58
	v_fma_f32 v65, -v53, v64, v59
	v_fmac_f32_e32 v64, v65, v58
	v_fma_f32 v53, -v53, v64, v59
	v_div_fmas_f32 v53, v53, v58, v64
	v_div_fixup_f32 v52, v53, v52, 1.0
	v_lshlrev_b32_e32 v58, 16, v46
	v_and_b32_e32 v59, 0xffff0000, v46
	v_lshlrev_b32_e32 v46, 16, v47
	v_and_b32_e32 v47, 0xffff0000, v47
	v_pk_mul_f32 v[64:65], v[130:131], v[52:53] op_sel_hi:[1,0]
	v_pk_mul_f32 v[52:53], v[126:127], v[52:53] op_sel_hi:[1,0]
	s_nop 0
	v_pk_mul_f32 v[46:47], v[52:53], v[46:47]
	v_pk_mul_f32 v[52:53], v[64:65], v[58:59]
	s_nop 0
	v_cvt_pk_bf16_f32 v52, v52, v53
	v_cvt_pk_bf16_f32 v53, v46, v47
	v_add_f32_dpp v46, v159, v159 quad_perm:[1,0,3,2] row_mask:0xf bank_mask:0xf bound_ctrl:1
	global_store_dwordx2 v[94:95], v[52:53], off offset:1536
	s_waitcnt vmcnt(29)
	v_and_b32_e32 v159, 0xffff0000, v92
	v_add_f32_dpp v46, v46, v46 quad_perm:[2,3,0,1] row_mask:0xf bank_mask:0xf bound_ctrl:1
	s_nop 1
	v_add_f32_dpp v46, v46, v46 row_half_mirror row_mask:0xf bank_mask:0xf bound_ctrl:1
	s_nop 1
	v_add_f32_dpp v46, v46, v46 row_mirror row_mask:0xf bank_mask:0xf bound_ctrl:1
	s_nop 0
	v_readlane_b32 s9, v46, 16
	v_readlane_b32 s14, v46, 48
	v_readlane_b32 s6, v46, 0
	v_readlane_b32 s7, v46, 32
	v_mov_b32_e32 v46, s9
	v_mov_b32_e32 v47, s14
	v_pk_add_f32 v[46:47], s[6:7], v[46:47]
	s_nop 0
	v_add_f32_e32 v46, v46, v47
	v_fmamk_f32 v46, v46, 0x3b800000, v252
	v_cmp_gt_f32_e32 vcc, s55, v46
	v_mul_f32_e32 v47, 0x4f800000, v46
	s_nop 0
	v_cndmask_b32_e32 v46, v46, v47, vcc
	v_sqrt_f32_e32 v47, v46
	s_nop 0
	v_add_u32_e32 v52, -1, v47
	v_fma_f32 v53, -v52, v47, v46
	v_cmp_ge_f32_e64 s[6:7], 0, v53
	v_add_u32_e32 v53, 1, v47
	s_nop 0
	v_cndmask_b32_e64 v52, v47, v52, s[6:7]
	v_fma_f32 v47, -v53, v47, v46
	v_cmp_lt_f32_e64 s[6:7], 0, v47
	s_nop 1
	v_cndmask_b32_e64 v47, v52, v53, s[6:7]
	v_mul_f32_e32 v52, 0x37800000, v47
	v_cndmask_b32_e32 v47, v47, v52, vcc
	v_cmp_class_f32_e32 vcc, v46, v253
	s_nop 1
	v_cndmask_b32_e32 v46, v47, v46, vcc
	v_div_scale_f32 v47, s[6:7], v46, v46, 1.0
	v_rcp_f32_e32 v52, v47
	s_nop 0
	v_fma_f32 v53, -v47, v52, 1.0
	v_fmac_f32_e32 v52, v53, v52
	v_div_scale_f32 v53, vcc, 1.0, v46, 1.0
	v_mul_f32_e32 v58, v53, v52
	v_fma_f32 v59, -v47, v58, v53
	v_fmac_f32_e32 v58, v59, v52
	v_fma_f32 v47, -v47, v58, v53
	v_div_fmas_f32 v47, v47, v52, v58
	v_div_fixup_f32 v46, v47, v46, 1.0
	v_lshlrev_b32_e32 v52, 16, v40
	v_and_b32_e32 v53, 0xffff0000, v40
	v_lshlrev_b32_e32 v40, 16, v41
	v_and_b32_e32 v41, 0xffff0000, v41
	v_pk_mul_f32 v[58:59], v[122:123], v[46:47] op_sel_hi:[1,0]
	v_pk_mul_f32 v[46:47], v[118:119], v[46:47] op_sel_hi:[1,0]
	s_nop 0
	v_pk_mul_f32 v[40:41], v[46:47], v[40:41]
	v_pk_mul_f32 v[46:47], v[58:59], v[52:53]
	s_nop 0
	v_cvt_pk_bf16_f32 v46, v46, v47
	v_cvt_pk_bf16_f32 v47, v40, v41
	v_add_f32_dpp v40, v158, v158 quad_perm:[1,0,3,2] row_mask:0xf bank_mask:0xf bound_ctrl:1
	global_store_dwordx2 v[94:95], v[46:47], off offset:2048
	v_lshlrev_b32_e32 v158, 16, v92
	v_add_f32_dpp v40, v40, v40 quad_perm:[2,3,0,1] row_mask:0xf bank_mask:0xf bound_ctrl:1
	v_lshlrev_b32_e32 v92, 16, v93
	v_and_b32_e32 v93, 0xffff0000, v93
	v_add_f32_dpp v40, v40, v40 row_half_mirror row_mask:0xf bank_mask:0xf bound_ctrl:1
	s_nop 1
	v_add_f32_dpp v40, v40, v40 row_mirror row_mask:0xf bank_mask:0xf bound_ctrl:1
	s_nop 0
	v_readlane_b32 s9, v40, 16
	v_readlane_b32 s14, v40, 48
	v_readlane_b32 s6, v40, 0
	v_readlane_b32 s7, v40, 32
	v_mov_b32_e32 v40, s9
	v_mov_b32_e32 v41, s14
	v_pk_add_f32 v[40:41], s[6:7], v[40:41]
	s_nop 0
	v_add_f32_e32 v40, v40, v41
	v_fmamk_f32 v40, v40, 0x3b800000, v252
	v_cmp_gt_f32_e32 vcc, s55, v40
	v_mul_f32_e32 v41, 0x4f800000, v40
	s_nop 0
	v_cndmask_b32_e32 v40, v40, v41, vcc
	v_sqrt_f32_e32 v41, v40
	s_nop 0
	v_add_u32_e32 v46, -1, v41
	v_fma_f32 v47, -v46, v41, v40
	v_cmp_ge_f32_e64 s[6:7], 0, v47
; template <bool HG>
; __device__ __forceinline__ void readout_phase2(const Args& a, Frame& F, const float* gain, int nrows) {
;     ...
;     RO_FINISH(f0, b0, g0, nw);            RO_LOAD(f0, b0, g0, nw + 3 * 2048);
	v_add_u32_e32 v47, 1, v41
	s_nop 0
	v_cndmask_b32_e64 v46, v41, v46, s[6:7]
	v_fma_f32 v41, -v47, v41, v40
	v_cmp_lt_f32_e64 s[6:7], 0, v41
	s_nop 1
	v_cndmask_b32_e64 v41, v46, v47, s[6:7]
	v_mul_f32_e32 v46, 0x37800000, v41
	v_cndmask_b32_e32 v41, v41, v46, vcc
	v_cmp_class_f32_e32 vcc, v40, v253
	s_nop 1
	v_cndmask_b32_e32 v40, v41, v40, vcc
	v_div_scale_f32 v41, s[6:7], v40, v40, 1.0
	v_rcp_f32_e32 v46, v41
	s_nop 0
	v_fma_f32 v47, -v41, v46, 1.0
	v_fmac_f32_e32 v46, v47, v46
	v_div_scale_f32 v47, vcc, 1.0, v40, 1.0
	v_mul_f32_e32 v52, v47, v46
	v_fma_f32 v53, -v41, v52, v47
	v_fmac_f32_e32 v52, v53, v46
	v_fma_f32 v41, -v41, v52, v47
	v_div_fmas_f32 v41, v41, v46, v52
	v_div_fixup_f32 v40, v41, v40, 1.0
	v_lshlrev_b32_e32 v46, 16, v24
	v_and_b32_e32 v47, 0xffff0000, v24
	v_lshlrev_b32_e32 v24, 16, v25
	v_and_b32_e32 v25, 0xffff0000, v25
	v_pk_mul_f32 v[52:53], v[114:115], v[40:41] op_sel_hi:[1,0]
	v_pk_mul_f32 v[40:41], v[110:111], v[40:41] op_sel_hi:[1,0]
	s_nop 0
	v_pk_mul_f32 v[24:25], v[40:41], v[24:25]
	v_pk_mul_f32 v[40:41], v[52:53], v[46:47]
	s_nop 0
	v_cvt_pk_bf16_f32 v40, v40, v41
	v_cvt_pk_bf16_f32 v41, v24, v25
	v_add_f32_dpp v24, v157, v157 quad_perm:[1,0,3,2] row_mask:0xf bank_mask:0xf bound_ctrl:1
	global_store_dwordx2 v[94:95], v[40:41], off offset:2560
	s_nop 0
	v_add_f32_dpp v24, v24, v24 quad_perm:[2,3,0,1] row_mask:0xf bank_mask:0xf bound_ctrl:1
	s_nop 1
	v_add_f32_dpp v24, v24, v24 row_half_mirror row_mask:0xf bank_mask:0xf bound_ctrl:1
	s_nop 1
	v_add_f32_dpp v24, v24, v24 row_mirror row_mask:0xf bank_mask:0xf bound_ctrl:1
	s_nop 0
	v_readlane_b32 s9, v24, 16
	v_readlane_b32 s14, v24, 48
	v_readlane_b32 s6, v24, 0
	v_readlane_b32 s7, v24, 32
	v_mov_b32_e32 v24, s9
	v_mov_b32_e32 v25, s14
	v_pk_add_f32 v[24:25], s[6:7], v[24:25]
	s_nop 0
	v_add_f32_e32 v24, v24, v25
	v_fmamk_f32 v24, v24, 0x3b800000, v252
	v_cmp_gt_f32_e32 vcc, s55, v24
	v_mul_f32_e32 v25, 0x4f800000, v24
	s_nop 0
	v_cndmask_b32_e32 v24, v24, v25, vcc
	v_sqrt_f32_e32 v25, v24
	s_nop 0
	v_add_u32_e32 v40, -1, v25
	v_fma_f32 v41, -v40, v25, v24
	v_cmp_ge_f32_e64 s[6:7], 0, v41
	v_add_u32_e32 v41, 1, v25
	s_nop 0
	v_cndmask_b32_e64 v40, v25, v40, s[6:7]
	v_fma_f32 v25, -v41, v25, v24
	v_cmp_lt_f32_e64 s[6:7], 0, v25
	s_nop 1
	v_cndmask_b32_e64 v25, v40, v41, s[6:7]
	v_mul_f32_e32 v40, 0x37800000, v25
	v_cndmask_b32_e32 v25, v25, v40, vcc
	v_cmp_class_f32_e32 vcc, v24, v253
	s_nop 1
	v_cndmask_b32_e32 v24, v25, v24, vcc
	v_div_scale_f32 v25, s[6:7], v24, v24, 1.0
	v_rcp_f32_e32 v40, v25
	s_nop 0
	v_fma_f32 v41, -v25, v40, 1.0
	v_fmac_f32_e32 v40, v41, v40
	v_div_scale_f32 v41, vcc, 1.0, v24, 1.0
	v_mul_f32_e32 v46, v41, v40
	v_fma_f32 v47, -v25, v46, v41
	v_fmac_f32_e32 v46, v47, v40
	v_fma_f32 v25, -v25, v46, v41
	v_div_fmas_f32 v25, v25, v40, v46
	v_div_fixup_f32 v24, v25, v24, 1.0
	v_lshlrev_b32_e32 v40, 16, v20
	v_and_b32_e32 v41, 0xffff0000, v20
	v_lshlrev_b32_e32 v20, 16, v21
	v_and_b32_e32 v21, 0xffff0000, v21
	v_pk_mul_f32 v[46:47], v[106:107], v[24:25] op_sel_hi:[1,0]
	v_pk_mul_f32 v[24:25], v[102:103], v[24:25] op_sel_hi:[1,0]
	s_nop 0
	v_pk_mul_f32 v[20:21], v[24:25], v[20:21]
	v_pk_mul_f32 v[24:25], v[46:47], v[40:41]
	s_nop 0
	v_cvt_pk_bf16_f32 v24, v24, v25
	v_cvt_pk_bf16_f32 v25, v20, v21
	v_add_f32_dpp v20, v156, v156 quad_perm:[1,0,3,2] row_mask:0xf bank_mask:0xf bound_ctrl:1
	global_store_dwordx2 v[94:95], v[24:25], off offset:3072
	s_nop 0
	v_add_f32_dpp v20, v20, v20 quad_perm:[2,3,0,1] row_mask:0xf bank_mask:0xf bound_ctrl:1
	s_nop 1
	v_add_f32_dpp v20, v20, v20 row_half_mirror row_mask:0xf bank_mask:0xf bound_ctrl:1
	s_nop 1
	v_add_f32_dpp v20, v20, v20 row_mirror row_mask:0xf bank_mask:0xf bound_ctrl:1
	s_nop 0
	v_readlane_b32 s9, v20, 16
	v_readlane_b32 s14, v20, 48
	v_readlane_b32 s6, v20, 0
	v_readlane_b32 s7, v20, 32
	v_mov_b32_e32 v20, s9
	v_mov_b32_e32 v21, s14
	v_pk_add_f32 v[20:21], s[6:7], v[20:21]
	s_add_u32 s14, s10, 0x1800000
	v_add_f32_e32 v20, v20, v21
	v_fmamk_f32 v20, v20, 0x3b800000, v252
	v_cmp_gt_f32_e32 vcc, s55, v20
	v_mul_f32_e32 v21, 0x4f800000, v20
	s_addc_u32 s15, s11, 0
	v_cndmask_b32_e32 v20, v20, v21, vcc
	v_sqrt_f32_e32 v21, v20
	s_nop 0
	v_add_u32_e32 v24, -1, v21
	v_fma_f32 v25, -v24, v21, v20
	v_cmp_ge_f32_e64 s[6:7], 0, v25
	v_add_u32_e32 v25, 1, v21
	s_nop 0
	v_cndmask_b32_e64 v24, v21, v24, s[6:7]
	v_fma_f32 v21, -v25, v21, v20
	v_cmp_lt_f32_e64 s[6:7], 0, v21
	s_nop 1
	v_cndmask_b32_e64 v21, v24, v25, s[6:7]
	v_mul_f32_e32 v24, 0x37800000, v21
	v_cndmask_b32_e32 v21, v21, v24, vcc
	v_cmp_class_f32_e32 vcc, v20, v253
	s_nop 1
	v_cndmask_b32_e32 v20, v21, v20, vcc
	v_div_scale_f32 v21, s[6:7], v20, v20, 1.0
	v_rcp_f32_e32 v24, v21
	s_nop 0
	v_fma_f32 v25, -v21, v24, 1.0
	v_fmac_f32_e32 v24, v25, v24
	v_div_scale_f32 v25, vcc, 1.0, v20, 1.0
	v_mul_f32_e32 v40, v25, v24
	v_fma_f32 v41, -v21, v40, v25
	v_fmac_f32_e32 v40, v41, v24
	v_fma_f32 v21, -v21, v40, v25
	v_div_fmas_f32 v21, v21, v24, v40
	v_div_fixup_f32 v20, v21, v20, 1.0
	v_lshlrev_b32_e32 v24, 16, v16
	v_and_b32_e32 v25, 0xffff0000, v16
	v_lshlrev_b32_e32 v16, 16, v17
	v_and_b32_e32 v17, 0xffff0000, v17
	v_pk_mul_f32 v[40:41], v[98:99], v[20:21] op_sel_hi:[1,0]
	v_pk_mul_f32 v[20:21], v[90:91], v[20:21] op_sel_hi:[1,0]
	s_nop 0
	v_pk_mul_f32 v[16:17], v[20:21], v[16:17]
	v_pk_mul_f32 v[20:21], v[40:41], v[24:25]
	s_nop 0
	v_cvt_pk_bf16_f32 v20, v20, v21
	v_cvt_pk_bf16_f32 v21, v16, v17
	global_store_dwordx2 v[94:95], v[20:21], off offset:3584
	v_lshl_add_u64 v[20:21], v[6:7], 0, s[14:15]
	v_lshl_add_u64 v[16:17], v[4:5], 0, s[14:15]
	v_lshl_add_u64 v[94:95], v[20:21], 0, v[0:1]
	v_lshl_add_u64 v[20:21], v[8:9], 0, s[14:15]
; template <bool HG>
; __device__ __forceinline__ void readout_phase2(const Args& a, Frame& F, const float* gain, int nrows) {
;     ...
;     RO_FINISH(f0, b0, g0, nw);            RO_LOAD(f0, b0, g0, nw + 3 * 2048);
;     RO_FINISH(f1, b1, g1, nw + 2048);     RO_LOAD(f1, b1, g1, nw + 4 * 2048);
	v_lshl_add_u64 v[16:17], v[16:17], 0, v[0:1]
	v_lshl_add_u64 v[150:151], v[20:21], 0, v[0:1]
	global_load_dwordx2 v[160:161], v[16:17], off nt
	global_load_dwordx2 v[154:155], v[94:95], off nt
	global_load_dwordx2 v[64:65], v[150:151], off nt
	global_load_dwordx2 v[148:149], v[16:17], off offset:512 nt
	global_load_dwordx2 v[142:143], v[94:95], off offset:512 nt
	global_load_dwordx2 v[58:59], v[150:151], off offset:512 nt
	global_load_dwordx2 v[136:137], v[16:17], off offset:1024 nt
	global_load_dwordx2 v[130:131], v[94:95], off offset:1024 nt
	global_load_dwordx2 v[52:53], v[150:151], off offset:1024 nt
	global_load_dwordx2 v[122:123], v[16:17], off offset:1536 nt
	global_load_dwordx2 v[126:127], v[94:95], off offset:1536 nt
	global_load_dwordx2 v[46:47], v[150:151], off offset:1536 nt
	global_load_dwordx2 v[118:119], v[16:17], off offset:2048 nt
	global_load_dwordx2 v[114:115], v[94:95], off offset:2048 nt
	global_load_dwordx2 v[40:41], v[150:151], off offset:2048 nt
	global_load_dwordx2 v[110:111], v[16:17], off offset:2560 nt
	global_load_dwordx2 v[106:107], v[94:95], off offset:2560 nt
	global_load_dwordx2 v[24:25], v[150:151], off offset:2560 nt
	global_load_dwordx2 v[102:103], v[16:17], off offset:3072 nt
	global_load_dwordx2 v[98:99], v[94:95], off offset:3072 nt
	global_load_dwordx2 v[20:21], v[150:151], off offset:3072 nt
	global_load_dwordx2 v[90:91], v[16:17], off offset:3584 nt
	s_nop 0
	global_load_dwordx2 v[94:95], v[94:95], off offset:3584 nt
	s_nop 0
	global_load_dwordx2 v[16:17], v[150:151], off offset:3584 nt
	v_lshlrev_b32_e32 v150, 16, v146
	v_and_b32_e32 v151, 0xffff0000, v146
	v_lshlrev_b32_e32 v146, 16, v147
	v_and_b32_e32 v147, 0xffff0000, v147
	v_pk_add_f32 v[150:151], v[150:151], v[152:153]
	v_pk_add_f32 v[146:147], v[146:147], v[144:145]
	v_mov_b32_e32 v152, v151
	v_mov_b32_e32 v153, v147
	v_mov_b32_e32 v144, v150
	v_mov_b32_e32 v145, v146
	v_pk_mul_f32 v[152:153], v[152:153], v[152:153]
	s_nop 0
	v_pk_fma_f32 v[144:145], v[144:145], v[144:145], v[152:153]
	v_lshlrev_b32_e32 v152, 16, v138
	v_add_f32_e32 v162, v144, v145
	v_lshlrev_b32_e32 v144, 16, v140
	v_and_b32_e32 v145, 0xffff0000, v140
	v_and_b32_e32 v153, 0xffff0000, v138
	v_lshlrev_b32_e32 v140, 16, v141
	v_and_b32_e32 v141, 0xffff0000, v141
	v_lshlrev_b32_e32 v138, 16, v139
	v_and_b32_e32 v139, 0xffff0000, v139
	v_pk_add_f32 v[144:145], v[144:145], v[152:153]
	v_pk_add_f32 v[140:141], v[140:141], v[138:139]
	v_mov_b32_e32 v152, v145
	v_mov_b32_e32 v153, v141
	v_mov_b32_e32 v138, v144
	v_mov_b32_e32 v139, v140
	v_pk_mul_f32 v[152:153], v[152:153], v[152:153]
	s_nop 0
	v_pk_fma_f32 v[138:139], v[138:139], v[138:139], v[152:153]
	v_lshlrev_b32_e32 v152, 16, v132
	v_add_f32_e32 v164, v138, v139
	v_lshlrev_b32_e32 v138, 16, v134
	v_and_b32_e32 v139, 0xffff0000, v134
	v_and_b32_e32 v153, 0xffff0000, v132
	v_lshlrev_b32_e32 v134, 16, v135
	v_and_b32_e32 v135, 0xffff0000, v135
	v_lshlrev_b32_e32 v132, 16, v133
	v_and_b32_e32 v133, 0xffff0000, v133
	v_pk_add_f32 v[138:139], v[138:139], v[152:153]
	v_pk_add_f32 v[134:135], v[134:135], v[132:133]
	v_mov_b32_e32 v152, v139
	v_mov_b32_e32 v153, v135
	v_mov_b32_e32 v132, v138
	v_mov_b32_e32 v133, v134
	v_pk_mul_f32 v[152:153], v[152:153], v[152:153]
	s_nop 0
	v_pk_fma_f32 v[132:133], v[132:133], v[132:133], v[152:153]
	v_lshlrev_b32_e32 v152, 16, v124
	v_add_f32_e32 v165, v132, v133
	v_lshlrev_b32_e32 v132, 16, v128
	v_and_b32_e32 v133, 0xffff0000, v128
	v_and_b32_e32 v153, 0xffff0000, v124
	v_lshlrev_b32_e32 v128, 16, v129
	v_and_b32_e32 v129, 0xffff0000, v129
	v_lshlrev_b32_e32 v124, 16, v125
	v_and_b32_e32 v125, 0xffff0000, v125
	v_pk_add_f32 v[132:133], v[132:133], v[152:153]
	v_pk_add_f32 v[128:129], v[128:129], v[124:125]
	v_mov_b32_e32 v152, v133
	v_mov_b32_e32 v153, v129
	v_mov_b32_e32 v124, v132
	v_mov_b32_e32 v125, v128
	v_pk_mul_f32 v[152:153], v[152:153], v[152:153]
	s_nop 0
	v_pk_fma_f32 v[124:125], v[124:125], v[124:125], v[152:153]
	v_lshlrev_b32_e32 v152, 16, v116
	v_add_f32_e32 v166, v124, v125
	v_lshlrev_b32_e32 v124, 16, v120
	v_and_b32_e32 v125, 0xffff0000, v120
	v_and_b32_e32 v153, 0xffff0000, v116
	v_lshlrev_b32_e32 v120, 16, v121
	v_and_b32_e32 v121, 0xffff0000, v121
	v_lshlrev_b32_e32 v116, 16, v117
	v_and_b32_e32 v117, 0xffff0000, v117
	v_pk_add_f32 v[124:125], v[124:125], v[152:153]
	v_pk_add_f32 v[120:121], v[120:121], v[116:117]
	v_mov_b32_e32 v152, v125
	v_mov_b32_e32 v153, v121
	v_mov_b32_e32 v116, v124
	v_mov_b32_e32 v117, v120
	v_pk_mul_f32 v[152:153], v[152:153], v[152:153]
	s_nop 0
	v_pk_fma_f32 v[116:117], v[116:117], v[116:117], v[152:153]
	v_lshlrev_b32_e32 v152, 16, v108
	v_add_f32_e32 v157, v116, v117
	v_lshlrev_b32_e32 v116, 16, v112
	v_and_b32_e32 v117, 0xffff0000, v112
	v_and_b32_e32 v153, 0xffff0000, v108
	v_lshlrev_b32_e32 v112, 16, v113
	v_and_b32_e32 v113, 0xffff0000, v113
	v_lshlrev_b32_e32 v108, 16, v109
	v_and_b32_e32 v109, 0xffff0000, v109
	v_pk_add_f32 v[116:117], v[116:117], v[152:153]
	v_pk_add_f32 v[112:113], v[112:113], v[108:109]
	v_mov_b32_e32 v152, v117
	v_mov_b32_e32 v153, v113
	v_mov_b32_e32 v108, v116
	v_mov_b32_e32 v109, v112
	v_pk_mul_f32 v[152:153], v[152:153], v[152:153]
	s_nop 0
	v_pk_fma_f32 v[108:109], v[108:109], v[108:109], v[152:153]
	v_lshlrev_b32_e32 v152, 16, v100
	v_add_f32_e32 v156, v108, v109
	v_lshlrev_b32_e32 v108, 16, v104
	v_and_b32_e32 v109, 0xffff0000, v104
	v_and_b32_e32 v153, 0xffff0000, v100
	v_lshlrev_b32_e32 v104, 16, v105
	v_and_b32_e32 v105, 0xffff0000, v105
	v_lshlrev_b32_e32 v100, 16, v101
	v_and_b32_e32 v101, 0xffff0000, v101
	v_pk_add_f32 v[108:109], v[108:109], v[152:153]
	v_pk_add_f32 v[104:105], v[104:105], v[100:101]
	v_mov_b32_e32 v152, v109
	v_mov_b32_e32 v153, v105
	v_mov_b32_e32 v100, v108
	v_mov_b32_e32 v101, v104
	v_pk_mul_f32 v[152:153], v[152:153], v[152:153]
	s_nop 0
	v_pk_fma_f32 v[100:101], v[100:101], v[100:101], v[152:153]
	s_nop 0
	v_add_f32_e32 v153, v100, v101
	v_lshlrev_b32_e32 v100, 16, v96
	v_and_b32_e32 v101, 0xffff0000, v96
	v_lshlrev_b32_e32 v96, 16, v97
	v_and_b32_e32 v97, 0xffff0000, v97
	v_pk_add_f32 v[100:101], v[100:101], v[158:159]
	v_pk_add_f32 v[92:93], v[96:97], v[92:93]
	v_mov_b32_e32 v158, v101
	v_mov_b32_e32 v159, v93
	v_mov_b32_e32 v96, v100
	v_mov_b32_e32 v97, v92
	v_pk_mul_f32 v[158:159], v[158:159], v[158:159]
	s_nop 0
	v_pk_fma_f32 v[96:97], v[96:97], v[96:97], v[158:159]
	v_add_f32_dpp v158, v162, v162 quad_perm:[1,0,3,2] row_mask:0xf bank_mask:0xf bound_ctrl:1
	v_add_f32_e32 v152, v96, v97
	v_lshl_add_u64 v[96:97], v[2:3], 0, s[16:17]
	v_add_f32_dpp v158, v158, v158 quad_perm:[2,3,0,1] row_mask:0xf bank_mask:0xf bound_ctrl:1
	v_lshl_add_u64 v[96:97], v[96:97], 0, v[0:1]
	s_nop 0
	v_add_f32_dpp v158, v158, v158 row_half_mirror row_mask:0xf bank_mask:0xf bound_ctrl:1
	s_nop 1
	v_add_f32_dpp v158, v158, v158 row_mirror row_mask:0xf bank_mask:0xf bound_ctrl:1
	s_nop 0
	v_readlane_b32 s9, v158, 16
	v_readlane_b32 s16, v158, 48
	v_readlane_b32 s6, v158, 0
	v_readlane_b32 s7, v158, 32
	v_mov_b32_e32 v158, s9
	v_mov_b32_e32 v159, s16
	v_pk_add_f32 v[158:159], s[6:7], v[158:159]
	s_nop 0
	v_add_f32_e32 v158, v158, v159
	v_fmamk_f32 v158, v158, 0x3b800000, v252
	v_cmp_gt_f32_e32 vcc, s55, v158
	v_mul_f32_e32 v159, 0x4f800000, v158
	s_nop 0
	v_cndmask_b32_e32 v158, v158, v159, vcc
	v_sqrt_f32_e32 v159, v158
	s_nop 0
	v_add_u32_e32 v162, -1, v159
	v_fma_f32 v163, -v162, v159, v158
	v_cmp_ge_f32_e64 s[6:7], 0, v163
	v_add_u32_e32 v163, 1, v159
	s_nop 0
	v_cndmask_b32_e64 v162, v159, v162, s[6:7]
	v_fma_f32 v159, -v163, v159, v158
	v_cmp_lt_f32_e64 s[6:7], 0, v159
	s_nop 1
	v_cndmask_b32_e64 v159, v162, v163, s[6:7]
	v_mul_f32_e32 v162, 0x37800000, v159
	v_cndmask_b32_e32 v159, v159, v162, vcc
	v_cmp_class_f32_e32 vcc, v158, v253
	s_nop 1
	v_cndmask_b32_e32 v158, v159, v158, vcc
	v_div_scale_f32 v159, s[6:7], v158, v158, 1.0
	v_rcp_f32_e32 v162, v159
	s_nop 0
	v_fma_f32 v163, -v159, v162, 1.0
	v_fmac_f32_e32 v162, v163, v162
	v_div_scale_f32 v163, vcc, 1.0, v158, 1.0
	v_mul_f32_e32 v167, v163, v162
	v_fma_f32 v168, -v159, v167, v163
	v_fmac_f32_e32 v167, v168, v162
	v_fma_f32 v159, -v159, v167, v163
	v_div_fmas_f32 v159, v159, v162, v167
	v_div_fixup_f32 v158, v159, v158, 1.0
	v_lshlrev_b32_e32 v162, 16, v66
	v_and_b32_e32 v163, 0xffff0000, v66
	v_lshlrev_b32_e32 v66, 16, v67
	v_and_b32_e32 v67, 0xffff0000, v67
	v_pk_mul_f32 v[150:151], v[150:151], v[158:159] op_sel_hi:[1,0]
	v_pk_mul_f32 v[146:147], v[146:147], v[158:159] op_sel_hi:[1,0]
	s_nop 0
	v_pk_mul_f32 v[66:67], v[146:147], v[66:67]
	v_pk_mul_f32 v[146:147], v[150:151], v[162:163]
	s_nop 0
	v_cvt_pk_bf16_f32 v146, v146, v147
	v_cvt_pk_bf16_f32 v147, v66, v67
	v_add_f32_dpp v66, v164, v164 quad_perm:[1,0,3,2] row_mask:0xf bank_mask:0xf bound_ctrl:1
	global_store_dwordx2 v[96:97], v[146:147], off
	s_nop 0
	v_add_f32_dpp v66, v66, v66 quad_perm:[2,3,0,1] row_mask:0xf bank_mask:0xf bound_ctrl:1
	s_nop 1
	v_add_f32_dpp v66, v66, v66 row_half_mirror row_mask:0xf bank_mask:0xf bound_ctrl:1
	s_nop 1
	v_add_f32_dpp v66, v66, v66 row_mirror row_mask:0xf bank_mask:0xf bound_ctrl:1
	s_nop 0
	v_readlane_b32 s9, v66, 16
	v_readlane_b32 s16, v66, 48
	v_readlane_b32 s6, v66, 0
	v_readlane_b32 s7, v66, 32
	v_mov_b32_e32 v66, s9
	v_mov_b32_e32 v67, s16
	v_pk_add_f32 v[66:67], s[6:7], v[66:67]
	s_nop 0
	v_add_f32_e32 v66, v66, v67
	v_fmamk_f32 v66, v66, 0x3b800000, v252
	v_cmp_gt_f32_e32 vcc, s55, v66
	v_mul_f32_e32 v67, 0x4f800000, v66
	s_nop 0
	v_cndmask_b32_e32 v66, v66, v67, vcc
	v_sqrt_f32_e32 v67, v66
	s_nop 0
	v_add_u32_e32 v146, -1, v67
	v_fma_f32 v147, -v146, v67, v66
	v_cmp_ge_f32_e64 s[6:7], 0, v147
	v_add_u32_e32 v147, 1, v67
	s_nop 0
	v_cndmask_b32_e64 v146, v67, v146, s[6:7]
	v_fma_f32 v67, -v147, v67, v66
	v_cmp_lt_f32_e64 s[6:7], 0, v67
	s_nop 1
	v_cndmask_b32_e64 v67, v146, v147, s[6:7]
	v_mul_f32_e32 v146, 0x37800000, v67
	v_cndmask_b32_e32 v67, v67, v146, vcc
	v_cmp_class_f32_e32 vcc, v66, v253
	s_nop 1
	v_cndmask_b32_e32 v66, v67, v66, vcc
	v_div_scale_f32 v67, s[6:7], v66, v66, 1.0
	v_rcp_f32_e32 v146, v67
	s_nop 0
	v_fma_f32 v147, -v67, v146, 1.0
	v_fmac_f32_e32 v146, v147, v146
	v_div_scale_f32 v147, vcc, 1.0, v66, 1.0
	v_mul_f32_e32 v150, v147, v146
	v_fma_f32 v151, -v67, v150, v147
	v_fmac_f32_e32 v150, v151, v146
	v_fma_f32 v67, -v67, v150, v147
	v_div_fmas_f32 v67, v67, v146, v150
	v_div_fixup_f32 v66, v67, v66, 1.0
	v_lshlrev_b32_e32 v146, 16, v60
	v_and_b32_e32 v147, 0xffff0000, v60
	v_lshlrev_b32_e32 v60, 16, v61
	v_and_b32_e32 v61, 0xffff0000, v61
	v_pk_mul_f32 v[144:145], v[144:145], v[66:67] op_sel_hi:[1,0]
	v_pk_mul_f32 v[66:67], v[140:141], v[66:67] op_sel_hi:[1,0]
	s_nop 0
	v_pk_mul_f32 v[60:61], v[66:67], v[60:61]
	v_pk_mul_f32 v[66:67], v[144:145], v[146:147]
	s_nop 0
	v_cvt_pk_bf16_f32 v66, v66, v67
	v_cvt_pk_bf16_f32 v67, v60, v61
	v_add_f32_dpp v60, v165, v165 quad_perm:[1,0,3,2] row_mask:0xf bank_mask:0xf bound_ctrl:1
	global_store_dwordx2 v[96:97], v[66:67], off offset:512
	s_nop 0
	v_add_f32_dpp v60, v60, v60 quad_perm:[2,3,0,1] row_mask:0xf bank_mask:0xf bound_ctrl:1
	s_nop 1
	v_add_f32_dpp v60, v60, v60 row_half_mirror row_mask:0xf bank_mask:0xf bound_ctrl:1
	s_nop 1
	v_add_f32_dpp v60, v60, v60 row_mirror row_mask:0xf bank_mask:0xf bound_ctrl:1
	s_nop 0
	v_readlane_b32 s9, v60, 16
	v_readlane_b32 s16, v60, 48
	v_readlane_b32 s6, v60, 0
	v_readlane_b32 s7, v60, 32
	v_mov_b32_e32 v60, s9
	v_mov_b32_e32 v61, s16
	v_pk_add_f32 v[60:61], s[6:7], v[60:61]
	s_nop 0
	v_add_f32_e32 v60, v60, v61
	v_fmamk_f32 v60, v60, 0x3b800000, v252
	v_cmp_gt_f32_e32 vcc, s55, v60
	v_mul_f32_e32 v61, 0x4f800000, v60
	s_nop 0
	v_cndmask_b32_e32 v60, v60, v61, vcc
	v_sqrt_f32_e32 v61, v60
	s_nop 0
	v_add_u32_e32 v66, -1, v61
	v_fma_f32 v67, -v66, v61, v60
	v_cmp_ge_f32_e64 s[6:7], 0, v67
	v_add_u32_e32 v67, 1, v61
	s_nop 0
	v_cndmask_b32_e64 v66, v61, v66, s[6:7]
	v_fma_f32 v61, -v67, v61, v60
	v_cmp_lt_f32_e64 s[6:7], 0, v61
	s_nop 1
	v_cndmask_b32_e64 v61, v66, v67, s[6:7]
	v_mul_f32_e32 v66, 0x37800000, v61
	v_cndmask_b32_e32 v61, v61, v66, vcc
	v_cmp_class_f32_e32 vcc, v60, v253
	s_nop 1
	v_cndmask_b32_e32 v60, v61, v60, vcc
	v_div_scale_f32 v61, s[6:7], v60, v60, 1.0
	v_rcp_f32_e32 v66, v61
	s_nop 0
	v_fma_f32 v67, -v61, v66, 1.0
	v_fmac_f32_e32 v66, v67, v66
	v_div_scale_f32 v67, vcc, 1.0, v60, 1.0
	v_mul_f32_e32 v140, v67, v66
	v_fma_f32 v141, -v61, v140, v67
	v_fmac_f32_e32 v140, v141, v66
	v_fma_f32 v61, -v61, v140, v67
	v_div_fmas_f32 v61, v61, v66, v140
	v_div_fixup_f32 v60, v61, v60, 1.0
	v_lshlrev_b32_e32 v66, 16, v54
	v_and_b32_e32 v67, 0xffff0000, v54
	v_lshlrev_b32_e32 v54, 16, v55
	v_and_b32_e32 v55, 0xffff0000, v55
	v_pk_mul_f32 v[138:139], v[138:139], v[60:61] op_sel_hi:[1,0]
	v_pk_mul_f32 v[60:61], v[134:135], v[60:61] op_sel_hi:[1,0]
	s_waitcnt vmcnt(56)
	v_lshlrev_b32_e32 v140, 16, v86
	v_pk_mul_f32 v[54:55], v[60:61], v[54:55]
	v_pk_mul_f32 v[60:61], v[138:139], v[66:67]
	v_and_b32_e32 v141, 0xffff0000, v86
	v_cvt_pk_bf16_f32 v60, v60, v61
	v_cvt_pk_bf16_f32 v61, v54, v55
	v_add_f32_dpp v54, v166, v166 quad_perm:[1,0,3,2] row_mask:0xf bank_mask:0xf bound_ctrl:1
	global_store_dwordx2 v[96:97], v[60:61], off offset:1024
	v_lshlrev_b32_e32 v86, 16, v87
	v_add_f32_dpp v54, v54, v54 quad_perm:[2,3,0,1] row_mask:0xf bank_mask:0xf bound_ctrl:1
	v_and_b32_e32 v87, 0xffff0000, v87
	s_nop 0
	v_add_f32_dpp v54, v54, v54 row_half_mirror row_mask:0xf bank_mask:0xf bound_ctrl:1
	s_nop 1
	v_add_f32_dpp v54, v54, v54 row_mirror row_mask:0xf bank_mask:0xf bound_ctrl:1
	s_nop 0
	v_readlane_b32 s9, v54, 16
	v_readlane_b32 s16, v54, 48
	v_readlane_b32 s6, v54, 0
	v_readlane_b32 s7, v54, 32
	v_mov_b32_e32 v54, s9
	v_mov_b32_e32 v55, s16
	v_pk_add_f32 v[54:55], s[6:7], v[54:55]
	s_nop 0
	v_add_f32_e32 v54, v54, v55
	v_fmamk_f32 v54, v54, 0x3b800000, v252
	v_cmp_gt_f32_e32 vcc, s55, v54
	v_mul_f32_e32 v55, 0x4f800000, v54
	s_nop 0
	v_cndmask_b32_e32 v54, v54, v55, vcc
	v_sqrt_f32_e32 v55, v54
	s_nop 0
	v_add_u32_e32 v60, -1, v55
	v_fma_f32 v61, -v60, v55, v54
	v_cmp_ge_f32_e64 s[6:7], 0, v61
	v_add_u32_e32 v61, 1, v55
	s_nop 0
	v_cndmask_b32_e64 v60, v55, v60, s[6:7]
	v_fma_f32 v55, -v61, v55, v54
	v_cmp_lt_f32_e64 s[6:7], 0, v55
	s_nop 1
	v_cndmask_b32_e64 v55, v60, v61, s[6:7]
	v_mul_f32_e32 v60, 0x37800000, v55
	v_cndmask_b32_e32 v55, v55, v60, vcc
	v_cmp_class_f32_e32 vcc, v54, v253
	s_nop 1
	v_cndmask_b32_e32 v54, v55, v54, vcc
	v_div_scale_f32 v55, s[6:7], v54, v54, 1.0
	v_rcp_f32_e32 v60, v55
	s_nop 0
	v_fma_f32 v61, -v55, v60, 1.0
	v_fmac_f32_e32 v60, v61, v60
	v_div_scale_f32 v61, vcc, 1.0, v54, 1.0
	v_mul_f32_e32 v66, v61, v60
	v_fma_f32 v67, -v55, v66, v61
	v_fmac_f32_e32 v66, v67, v60
	v_fma_f32 v55, -v55, v66, v61
	v_div_fmas_f32 v55, v55, v60, v66
	v_div_fixup_f32 v54, v55, v54, 1.0
	v_lshlrev_b32_e32 v60, 16, v48
	v_and_b32_e32 v61, 0xffff0000, v48
	v_lshlrev_b32_e32 v48, 16, v49
	v_and_b32_e32 v49, 0xffff0000, v49
	v_pk_mul_f32 v[66:67], v[132:133], v[54:55] op_sel_hi:[1,0]
	v_pk_mul_f32 v[54:55], v[128:129], v[54:55] op_sel_hi:[1,0]
	s_nop 0
	v_pk_mul_f32 v[48:49], v[54:55], v[48:49]
	v_pk_mul_f32 v[54:55], v[66:67], v[60:61]
	s_nop 0
	v_cvt_pk_bf16_f32 v54, v54, v55
	v_cvt_pk_bf16_f32 v55, v48, v49
	v_add_f32_dpp v48, v157, v157 quad_perm:[1,0,3,2] row_mask:0xf bank_mask:0xf bound_ctrl:1
	global_store_dwordx2 v[96:97], v[54:55], off offset:1536
	s_nop 0
	v_add_f32_dpp v48, v48, v48 quad_perm:[2,3,0,1] row_mask:0xf bank_mask:0xf bound_ctrl:1
	s_nop 1
	v_add_f32_dpp v48, v48, v48 row_half_mirror row_mask:0xf bank_mask:0xf bound_ctrl:1
	s_nop 1
	v_add_f32_dpp v48, v48, v48 row_mirror row_mask:0xf bank_mask:0xf bound_ctrl:1
	s_nop 0
	v_readlane_b32 s9, v48, 16
	v_readlane_b32 s16, v48, 48
	v_readlane_b32 s6, v48, 0
	v_readlane_b32 s7, v48, 32
	v_mov_b32_e32 v48, s9
	v_mov_b32_e32 v49, s16
	v_pk_add_f32 v[48:49], s[6:7], v[48:49]
	s_nop 0
	v_add_f32_e32 v48, v48, v49
	v_fmamk_f32 v48, v48, 0x3b800000, v252
	v_cmp_gt_f32_e32 vcc, s55, v48
	v_mul_f32_e32 v49, 0x4f800000, v48
	s_nop 0
	v_cndmask_b32_e32 v48, v48, v49, vcc
	v_sqrt_f32_e32 v49, v48
	s_nop 0
	v_add_u32_e32 v54, -1, v49
	v_fma_f32 v55, -v54, v49, v48
	v_cmp_ge_f32_e64 s[6:7], 0, v55
	v_add_u32_e32 v55, 1, v49
	s_nop 0
	v_cndmask_b32_e64 v54, v49, v54, s[6:7]
	v_fma_f32 v49, -v55, v49, v48
	v_cmp_lt_f32_e64 s[6:7], 0, v49
	s_nop 1
	v_cndmask_b32_e64 v49, v54, v55, s[6:7]
	v_mul_f32_e32 v54, 0x37800000, v49
	v_cndmask_b32_e32 v49, v49, v54, vcc
	v_cmp_class_f32_e32 vcc, v48, v253
	s_nop 1
	v_cndmask_b32_e32 v48, v49, v48, vcc
	v_div_scale_f32 v49, s[6:7], v48, v48, 1.0
	v_rcp_f32_e32 v54, v49
	s_nop 0
	v_fma_f32 v55, -v49, v54, 1.0
	v_fmac_f32_e32 v54, v55, v54
	v_div_scale_f32 v55, vcc, 1.0, v48, 1.0
	v_mul_f32_e32 v60, v55, v54
	v_fma_f32 v61, -v49, v60, v55
	v_fmac_f32_e32 v60, v61, v54
	v_fma_f32 v49, -v49, v60, v55
	v_div_fmas_f32 v49, v49, v54, v60
	v_div_fixup_f32 v48, v49, v48, 1.0
	v_lshlrev_b32_e32 v54, 16, v42
	v_and_b32_e32 v55, 0xffff0000, v42
	v_lshlrev_b32_e32 v42, 16, v43
	v_and_b32_e32 v43, 0xffff0000, v43
; template <bool HG>
; __device__ __forceinline__ void readout_phase2(const Args& a, Frame& F, const float* gain, int nrows) {
;     ...
;     RO_FINISH(f1, b1, g1, nw + 2048);     RO_LOAD(f1, b1, g1, nw + 4 * 2048);
	v_pk_mul_f32 v[60:61], v[124:125], v[48:49] op_sel_hi:[1,0]
	v_pk_mul_f32 v[48:49], v[120:121], v[48:49] op_sel_hi:[1,0]
	s_nop 0
	v_pk_mul_f32 v[42:43], v[48:49], v[42:43]
	v_pk_mul_f32 v[48:49], v[60:61], v[54:55]
	s_nop 0
	v_cvt_pk_bf16_f32 v48, v48, v49
	v_cvt_pk_bf16_f32 v49, v42, v43
	v_add_f32_dpp v42, v156, v156 quad_perm:[1,0,3,2] row_mask:0xf bank_mask:0xf bound_ctrl:1
	global_store_dwordx2 v[96:97], v[48:49], off offset:2048
	s_nop 0
	v_add_f32_dpp v42, v42, v42 quad_perm:[2,3,0,1] row_mask:0xf bank_mask:0xf bound_ctrl:1
	s_nop 1
	v_add_f32_dpp v42, v42, v42 row_half_mirror row_mask:0xf bank_mask:0xf bound_ctrl:1
	s_nop 1
	v_add_f32_dpp v42, v42, v42 row_mirror row_mask:0xf bank_mask:0xf bound_ctrl:1
	s_nop 0
	v_readlane_b32 s9, v42, 16
	v_readlane_b32 s16, v42, 48
	v_readlane_b32 s6, v42, 0
	v_readlane_b32 s7, v42, 32
	v_mov_b32_e32 v42, s9
	v_mov_b32_e32 v43, s16
	v_pk_add_f32 v[42:43], s[6:7], v[42:43]
	s_nop 0
	v_add_f32_e32 v42, v42, v43
	v_fmamk_f32 v42, v42, 0x3b800000, v252
	v_cmp_gt_f32_e32 vcc, s55, v42
	v_mul_f32_e32 v43, 0x4f800000, v42
	s_nop 0
	v_cndmask_b32_e32 v42, v42, v43, vcc
	v_sqrt_f32_e32 v43, v42
	s_nop 0
	v_add_u32_e32 v48, -1, v43
	v_fma_f32 v49, -v48, v43, v42
	v_cmp_ge_f32_e64 s[6:7], 0, v49
	v_add_u32_e32 v49, 1, v43
	s_nop 0
	v_cndmask_b32_e64 v48, v43, v48, s[6:7]
	v_fma_f32 v43, -v49, v43, v42
	v_cmp_lt_f32_e64 s[6:7], 0, v43
	s_nop 1
	v_cndmask_b32_e64 v43, v48, v49, s[6:7]
	v_mul_f32_e32 v48, 0x37800000, v43
	v_cndmask_b32_e32 v43, v43, v48, vcc
	v_cmp_class_f32_e32 vcc, v42, v253
	s_nop 1
	v_cndmask_b32_e32 v42, v43, v42, vcc
	v_div_scale_f32 v43, s[6:7], v42, v42, 1.0
	v_rcp_f32_e32 v48, v43
	s_nop 0
	v_fma_f32 v49, -v43, v48, 1.0
	v_fmac_f32_e32 v48, v49, v48
	v_div_scale_f32 v49, vcc, 1.0, v42, 1.0
	v_mul_f32_e32 v54, v49, v48
	v_fma_f32 v55, -v43, v54, v49
	v_fmac_f32_e32 v54, v55, v48
	v_fma_f32 v43, -v43, v54, v49
	v_div_fmas_f32 v43, v43, v48, v54
	v_div_fixup_f32 v42, v43, v42, 1.0
	v_lshlrev_b32_e32 v48, 16, v36
	v_and_b32_e32 v49, 0xffff0000, v36
	v_lshlrev_b32_e32 v36, 16, v37
	v_and_b32_e32 v37, 0xffff0000, v37
	v_pk_mul_f32 v[54:55], v[116:117], v[42:43] op_sel_hi:[1,0]
	v_pk_mul_f32 v[42:43], v[112:113], v[42:43] op_sel_hi:[1,0]
	s_nop 0
	v_pk_mul_f32 v[36:37], v[42:43], v[36:37]
	v_pk_mul_f32 v[42:43], v[54:55], v[48:49]
	s_nop 0
	v_cvt_pk_bf16_f32 v42, v42, v43
	v_cvt_pk_bf16_f32 v43, v36, v37
	v_add_f32_dpp v36, v153, v153 quad_perm:[1,0,3,2] row_mask:0xf bank_mask:0xf bound_ctrl:1
	global_store_dwordx2 v[96:97], v[42:43], off offset:2560
	s_waitcnt vmcnt(39)
	v_and_b32_e32 v153, 0xffff0000, v44
	v_add_f32_dpp v36, v36, v36 quad_perm:[2,3,0,1] row_mask:0xf bank_mask:0xf bound_ctrl:1
	s_nop 1
	v_add_f32_dpp v36, v36, v36 row_half_mirror row_mask:0xf bank_mask:0xf bound_ctrl:1
	s_nop 1
	v_add_f32_dpp v36, v36, v36 row_mirror row_mask:0xf bank_mask:0xf bound_ctrl:1
	s_nop 0
	v_readlane_b32 s9, v36, 16
	v_readlane_b32 s16, v36, 48
	v_readlane_b32 s6, v36, 0
	v_readlane_b32 s7, v36, 32
	v_mov_b32_e32 v36, s9
	v_mov_b32_e32 v37, s16
	v_pk_add_f32 v[36:37], s[6:7], v[36:37]
	s_nop 0
	v_add_f32_e32 v36, v36, v37
	v_fmamk_f32 v36, v36, 0x3b800000, v252
	v_cmp_gt_f32_e32 vcc, s55, v36
	v_mul_f32_e32 v37, 0x4f800000, v36
	s_nop 0
	v_cndmask_b32_e32 v36, v36, v37, vcc
	v_sqrt_f32_e32 v37, v36
	s_nop 0
	v_add_u32_e32 v42, -1, v37
	v_fma_f32 v43, -v42, v37, v36
	v_cmp_ge_f32_e64 s[6:7], 0, v43
	v_add_u32_e32 v43, 1, v37
	s_nop 0
	v_cndmask_b32_e64 v42, v37, v42, s[6:7]
	v_fma_f32 v37, -v43, v37, v36
	v_cmp_lt_f32_e64 s[6:7], 0, v37
	s_nop 1
	v_cndmask_b32_e64 v37, v42, v43, s[6:7]
	v_mul_f32_e32 v42, 0x37800000, v37
	v_cndmask_b32_e32 v37, v37, v42, vcc
	v_cmp_class_f32_e32 vcc, v36, v253
	s_nop 1
	v_cndmask_b32_e32 v36, v37, v36, vcc
	v_div_scale_f32 v37, s[6:7], v36, v36, 1.0
	v_rcp_f32_e32 v42, v37
	s_nop 0
	v_fma_f32 v43, -v37, v42, 1.0
	v_fmac_f32_e32 v42, v43, v42
	v_div_scale_f32 v43, vcc, 1.0, v36, 1.0
	v_mul_f32_e32 v48, v43, v42
	v_fma_f32 v49, -v37, v48, v43
	v_fmac_f32_e32 v48, v49, v42
	v_fma_f32 v37, -v37, v48, v43
	v_div_fmas_f32 v37, v37, v42, v48
	v_div_fixup_f32 v36, v37, v36, 1.0
	v_lshlrev_b32_e32 v42, 16, v32
	v_and_b32_e32 v43, 0xffff0000, v32
	v_lshlrev_b32_e32 v32, 16, v33
	v_and_b32_e32 v33, 0xffff0000, v33
	v_pk_mul_f32 v[48:49], v[108:109], v[36:37] op_sel_hi:[1,0]
	v_pk_mul_f32 v[36:37], v[104:105], v[36:37] op_sel_hi:[1,0]
	s_nop 0
	v_pk_mul_f32 v[32:33], v[36:37], v[32:33]
	v_pk_mul_f32 v[36:37], v[48:49], v[42:43]
	s_nop 0
	v_cvt_pk_bf16_f32 v36, v36, v37
	v_cvt_pk_bf16_f32 v37, v32, v33
	v_add_f32_dpp v32, v152, v152 quad_perm:[1,0,3,2] row_mask:0xf bank_mask:0xf bound_ctrl:1
	global_store_dwordx2 v[96:97], v[36:37], off offset:3072
	v_lshlrev_b32_e32 v152, 16, v44
	v_add_f32_dpp v32, v32, v32 quad_perm:[2,3,0,1] row_mask:0xf bank_mask:0xf bound_ctrl:1
	v_lshlrev_b32_e32 v44, 16, v45
	v_and_b32_e32 v45, 0xffff0000, v45
	v_add_f32_dpp v32, v32, v32 row_half_mirror row_mask:0xf bank_mask:0xf bound_ctrl:1
	s_nop 1
	v_add_f32_dpp v32, v32, v32 row_mirror row_mask:0xf bank_mask:0xf bound_ctrl:1
	s_nop 0
	v_readlane_b32 s9, v32, 16
	v_readlane_b32 s16, v32, 48
	v_readlane_b32 s6, v32, 0
	v_readlane_b32 s7, v32, 32
	v_mov_b32_e32 v32, s9
	v_mov_b32_e32 v33, s16
	v_pk_add_f32 v[32:33], s[6:7], v[32:33]
	s_add_u32 s16, s10, 0x2000000
	v_add_f32_e32 v32, v32, v33
	v_fmamk_f32 v32, v32, 0x3b800000, v252
	v_cmp_gt_f32_e32 vcc, s55, v32
	v_mul_f32_e32 v33, 0x4f800000, v32
	s_addc_u32 s17, s11, 0
	v_cndmask_b32_e32 v32, v32, v33, vcc
	v_sqrt_f32_e32 v33, v32
	s_nop 0
	v_add_u32_e32 v36, -1, v33
	v_fma_f32 v37, -v36, v33, v32
	v_cmp_ge_f32_e64 s[6:7], 0, v37
; template <bool HG>
; __device__ __forceinline__ void readout_phase2(const Args& a, Frame& F, const float* gain, int nrows) {
;     ...
;     RO_FINISH(f1, b1, g1, nw + 2048);     RO_LOAD(f1, b1, g1, nw + 4 * 2048);
;     RO_FINISH(f2, b2, g2, nw + 2 * 2048); RO_LOAD(f2, b2, g2, nw + 5 * 2048);
	v_add_u32_e32 v37, 1, v33
	s_nop 0
	v_cndmask_b32_e64 v36, v33, v36, s[6:7]
	v_fma_f32 v33, -v37, v33, v32
	v_cmp_lt_f32_e64 s[6:7], 0, v33
	s_nop 1
	v_cndmask_b32_e64 v33, v36, v37, s[6:7]
	v_mul_f32_e32 v36, 0x37800000, v33
	v_cndmask_b32_e32 v33, v33, v36, vcc
	v_cmp_class_f32_e32 vcc, v32, v253
	s_nop 1
	v_cndmask_b32_e32 v32, v33, v32, vcc
	v_div_scale_f32 v33, s[6:7], v32, v32, 1.0
	v_rcp_f32_e32 v36, v33
	s_nop 0
	v_fma_f32 v37, -v33, v36, 1.0
	v_fmac_f32_e32 v36, v37, v36
	v_div_scale_f32 v37, vcc, 1.0, v32, 1.0
	v_mul_f32_e32 v42, v37, v36
	v_fma_f32 v43, -v33, v42, v37
	v_fmac_f32_e32 v42, v43, v36
	v_fma_f32 v33, -v33, v42, v37
	v_div_fmas_f32 v33, v33, v36, v42
	v_div_fixup_f32 v32, v33, v32, 1.0
	v_lshlrev_b32_e32 v36, 16, v28
	v_and_b32_e32 v37, 0xffff0000, v28
	v_lshlrev_b32_e32 v28, 16, v29
	v_and_b32_e32 v29, 0xffff0000, v29
	v_pk_mul_f32 v[42:43], v[100:101], v[32:33] op_sel_hi:[1,0]
	v_pk_mul_f32 v[32:33], v[92:93], v[32:33] op_sel_hi:[1,0]
	s_nop 0
	v_pk_mul_f32 v[28:29], v[32:33], v[28:29]
	v_pk_mul_f32 v[32:33], v[42:43], v[36:37]
	s_nop 0
	v_cvt_pk_bf16_f32 v32, v32, v33
	v_cvt_pk_bf16_f32 v33, v28, v29
	global_store_dwordx2 v[96:97], v[32:33], off offset:3584
	v_lshl_add_u64 v[32:33], v[6:7], 0, s[16:17]
	v_lshl_add_u64 v[28:29], v[4:5], 0, s[16:17]
	v_lshl_add_u64 v[96:97], v[32:33], 0, v[0:1]
	v_lshl_add_u64 v[32:33], v[8:9], 0, s[16:17]
	v_lshl_add_u64 v[28:29], v[28:29], 0, v[0:1]
	v_lshl_add_u64 v[134:135], v[32:33], 0, v[0:1]
	global_load_dwordx2 v[162:163], v[28:29], off nt
	global_load_dwordx2 v[156:157], v[96:97], off nt
	global_load_dwordx2 v[66:67], v[134:135], off nt
	global_load_dwordx2 v[150:151], v[28:29], off offset:512 nt
	global_load_dwordx2 v[144:145], v[96:97], off offset:512 nt
	global_load_dwordx2 v[60:61], v[134:135], off offset:512 nt
	global_load_dwordx2 v[138:139], v[28:29], off offset:1024 nt
	global_load_dwordx2 v[132:133], v[96:97], off offset:1024 nt
	global_load_dwordx2 v[54:55], v[134:135], off offset:1024 nt
	global_load_dwordx2 v[124:125], v[28:29], off offset:1536 nt
	global_load_dwordx2 v[128:129], v[96:97], off offset:1536 nt
	global_load_dwordx2 v[48:49], v[134:135], off offset:1536 nt
	global_load_dwordx2 v[120:121], v[28:29], off offset:2048 nt
	global_load_dwordx2 v[116:117], v[96:97], off offset:2048 nt
	global_load_dwordx2 v[42:43], v[134:135], off offset:2048 nt
	global_load_dwordx2 v[112:113], v[28:29], off offset:2560 nt
	global_load_dwordx2 v[108:109], v[96:97], off offset:2560 nt
	global_load_dwordx2 v[36:37], v[134:135], off offset:2560 nt
	global_load_dwordx2 v[104:105], v[28:29], off offset:3072 nt
	global_load_dwordx2 v[100:101], v[96:97], off offset:3072 nt
	global_load_dwordx2 v[32:33], v[134:135], off offset:3072 nt
	global_load_dwordx2 v[92:93], v[28:29], off offset:3584 nt
	s_nop 0
	global_load_dwordx2 v[96:97], v[96:97], off offset:3584 nt
	s_nop 0
	global_load_dwordx2 v[28:29], v[134:135], off offset:3584 nt
	v_lshlrev_b32_e32 v134, 16, v88
	v_and_b32_e32 v135, 0xffff0000, v88
	v_lshlrev_b32_e32 v88, 16, v89
	v_and_b32_e32 v89, 0xffff0000, v89
	v_pk_add_f32 v[134:135], v[134:135], v[140:141]
	v_pk_add_f32 v[88:89], v[88:89], v[86:87]
	v_mov_b32_e32 v140, v135
	v_mov_b32_e32 v141, v89
	v_mov_b32_e32 v86, v134
	v_mov_b32_e32 v87, v88
	v_pk_mul_f32 v[140:141], v[140:141], v[140:141]
	s_nop 0
	v_pk_fma_f32 v[86:87], v[86:87], v[86:87], v[140:141]
	v_lshlrev_b32_e32 v140, 16, v82
	v_add_f32_e32 v158, v86, v87
	v_lshlrev_b32_e32 v86, 16, v84
	v_and_b32_e32 v87, 0xffff0000, v84
	v_and_b32_e32 v141, 0xffff0000, v82
	v_lshlrev_b32_e32 v84, 16, v85
	v_and_b32_e32 v85, 0xffff0000, v85
	v_lshlrev_b32_e32 v82, 16, v83
	v_and_b32_e32 v83, 0xffff0000, v83
	v_pk_add_f32 v[86:87], v[86:87], v[140:141]
	v_pk_add_f32 v[84:85], v[84:85], v[82:83]
	v_mov_b32_e32 v140, v87
	v_mov_b32_e32 v141, v85
	v_mov_b32_e32 v82, v86
	v_mov_b32_e32 v83, v84
	v_pk_mul_f32 v[140:141], v[140:141], v[140:141]
	s_nop 0
	v_pk_fma_f32 v[82:83], v[82:83], v[82:83], v[140:141]
	v_lshlrev_b32_e32 v140, 16, v78
	v_add_f32_e32 v164, v82, v83
	v_lshlrev_b32_e32 v82, 16, v80
	v_and_b32_e32 v83, 0xffff0000, v80
	v_and_b32_e32 v141, 0xffff0000, v78
	v_lshlrev_b32_e32 v80, 16, v81
	v_and_b32_e32 v81, 0xffff0000, v81
	v_lshlrev_b32_e32 v78, 16, v79
	v_and_b32_e32 v79, 0xffff0000, v79
	v_pk_add_f32 v[82:83], v[82:83], v[140:141]
	v_pk_add_f32 v[80:81], v[80:81], v[78:79]
	v_mov_b32_e32 v140, v83
	v_mov_b32_e32 v141, v81
	v_mov_b32_e32 v78, v82
	v_mov_b32_e32 v79, v80
	v_pk_mul_f32 v[140:141], v[140:141], v[140:141]
	s_nop 0
	v_pk_fma_f32 v[78:79], v[78:79], v[78:79], v[140:141]
	v_lshlrev_b32_e32 v140, 16, v76
	v_add_f32_e32 v165, v78, v79
	v_lshlrev_b32_e32 v78, 16, v74
	v_and_b32_e32 v79, 0xffff0000, v74
	v_and_b32_e32 v141, 0xffff0000, v76
	v_lshlrev_b32_e32 v74, 16, v75
	v_and_b32_e32 v75, 0xffff0000, v75
	v_lshlrev_b32_e32 v76, 16, v77
	v_and_b32_e32 v77, 0xffff0000, v77
	v_pk_add_f32 v[78:79], v[78:79], v[140:141]
	v_pk_add_f32 v[76:77], v[74:75], v[76:77]
	v_mov_b32_e32 v140, v79
	v_mov_b32_e32 v141, v77
	v_mov_b32_e32 v74, v78
	v_mov_b32_e32 v75, v76
	v_pk_mul_f32 v[140:141], v[140:141], v[140:141]
	s_nop 0
	v_pk_fma_f32 v[74:75], v[74:75], v[74:75], v[140:141]
	v_lshlrev_b32_e32 v140, 16, v70
	v_add_f32_e32 v166, v74, v75
	v_lshlrev_b32_e32 v74, 16, v72
	v_and_b32_e32 v75, 0xffff0000, v72
	v_and_b32_e32 v141, 0xffff0000, v70
	v_lshlrev_b32_e32 v72, 16, v73
	v_and_b32_e32 v73, 0xffff0000, v73
	v_lshlrev_b32_e32 v70, 16, v71
	v_and_b32_e32 v71, 0xffff0000, v71
	v_pk_add_f32 v[74:75], v[74:75], v[140:141]
	v_pk_add_f32 v[72:73], v[72:73], v[70:71]
	v_mov_b32_e32 v140, v75
	v_mov_b32_e32 v141, v73
	v_mov_b32_e32 v70, v74
	v_mov_b32_e32 v71, v72
	v_pk_mul_f32 v[140:141], v[140:141], v[140:141]
	s_nop 0
	v_pk_fma_f32 v[70:71], v[70:71], v[70:71], v[140:141]
	v_lshlrev_b32_e32 v140, 16, v62
	v_add_f32_e32 v147, v70, v71
	v_lshlrev_b32_e32 v70, 16, v68
	v_and_b32_e32 v71, 0xffff0000, v68
	v_and_b32_e32 v141, 0xffff0000, v62
	v_lshlrev_b32_e32 v68, 16, v69
	v_and_b32_e32 v69, 0xffff0000, v69
	v_lshlrev_b32_e32 v62, 16, v63
	v_and_b32_e32 v63, 0xffff0000, v63
	v_pk_add_f32 v[70:71], v[70:71], v[140:141]
	v_pk_add_f32 v[68:69], v[68:69], v[62:63]
	v_mov_b32_e32 v140, v71
	v_mov_b32_e32 v141, v69
	v_mov_b32_e32 v62, v70
	v_mov_b32_e32 v63, v68
	v_pk_mul_f32 v[140:141], v[140:141], v[140:141]
	s_nop 0
	v_pk_fma_f32 v[62:63], v[62:63], v[62:63], v[140:141]
	v_lshlrev_b32_e32 v140, 16, v50
	v_add_f32_e32 v146, v62, v63
	v_lshlrev_b32_e32 v62, 16, v56
	v_and_b32_e32 v63, 0xffff0000, v56
	v_and_b32_e32 v141, 0xffff0000, v50
	v_lshlrev_b32_e32 v56, 16, v57
	v_and_b32_e32 v57, 0xffff0000, v57
	v_lshlrev_b32_e32 v50, 16, v51
	v_and_b32_e32 v51, 0xffff0000, v51
	v_pk_add_f32 v[62:63], v[62:63], v[140:141]
	v_pk_add_f32 v[56:57], v[56:57], v[50:51]
	v_mov_b32_e32 v140, v63
	v_mov_b32_e32 v141, v57
	v_mov_b32_e32 v50, v62
	v_mov_b32_e32 v51, v56
	v_pk_mul_f32 v[140:141], v[140:141], v[140:141]
	s_nop 0
	v_pk_fma_f32 v[50:51], v[50:51], v[50:51], v[140:141]
	s_nop 0
	v_add_f32_e32 v141, v50, v51
	v_lshlrev_b32_e32 v50, 16, v38
	v_and_b32_e32 v51, 0xffff0000, v38
	v_lshlrev_b32_e32 v38, 16, v39
	v_and_b32_e32 v39, 0xffff0000, v39
	v_pk_add_f32 v[50:51], v[50:51], v[152:153]
	v_pk_add_f32 v[38:39], v[38:39], v[44:45]
	v_mov_b32_e32 v152, v51
	v_mov_b32_e32 v153, v39
	v_mov_b32_e32 v44, v50
	v_mov_b32_e32 v45, v38
	v_pk_mul_f32 v[152:153], v[152:153], v[152:153]
	s_nop 0
	v_pk_fma_f32 v[44:45], v[44:45], v[44:45], v[152:153]
	v_add_f32_dpp v152, v158, v158 quad_perm:[1,0,3,2] row_mask:0xf bank_mask:0xf bound_ctrl:1
	v_add_f32_e32 v140, v44, v45
	v_lshl_add_u64 v[44:45], v[2:3], 0, s[12:13]
	v_add_f32_dpp v152, v152, v152 quad_perm:[2,3,0,1] row_mask:0xf bank_mask:0xf bound_ctrl:1
	v_lshl_add_u64 v[44:45], v[44:45], 0, v[0:1]
	s_nop 0
	v_add_f32_dpp v152, v152, v152 row_half_mirror row_mask:0xf bank_mask:0xf bound_ctrl:1
	s_nop 1
	v_add_f32_dpp v152, v152, v152 row_mirror row_mask:0xf bank_mask:0xf bound_ctrl:1
	s_nop 0
	v_readlane_b32 s9, v152, 16
	v_readlane_b32 s12, v152, 48
	v_readlane_b32 s6, v152, 0
	v_readlane_b32 s7, v152, 32
	v_mov_b32_e32 v152, s9
	v_mov_b32_e32 v153, s12
	v_pk_add_f32 v[152:153], s[6:7], v[152:153]
	s_nop 0
	v_add_f32_e32 v152, v152, v153
	v_fmamk_f32 v152, v152, 0x3b800000, v252
	v_cmp_gt_f32_e32 vcc, s55, v152
	v_mul_f32_e32 v153, 0x4f800000, v152
	s_nop 0
	v_cndmask_b32_e32 v152, v152, v153, vcc
	v_sqrt_f32_e32 v153, v152
	s_nop 0
	v_add_u32_e32 v158, -1, v153
	v_fma_f32 v159, -v158, v153, v152
	v_cmp_ge_f32_e64 s[6:7], 0, v159
	v_add_u32_e32 v159, 1, v153
	s_nop 0
	v_cndmask_b32_e64 v158, v153, v158, s[6:7]
	v_fma_f32 v153, -v159, v153, v152
	v_cmp_lt_f32_e64 s[6:7], 0, v153
	s_nop 1
	v_cndmask_b32_e64 v153, v158, v159, s[6:7]
	v_mul_f32_e32 v158, 0x37800000, v153
	v_cndmask_b32_e32 v153, v153, v158, vcc
	v_cmp_class_f32_e32 vcc, v152, v253
	s_nop 1
	v_cndmask_b32_e32 v152, v153, v152, vcc
	v_div_scale_f32 v153, s[6:7], v152, v152, 1.0
	v_rcp_f32_e32 v158, v153
	s_nop 0
	v_fma_f32 v159, -v153, v158, 1.0
	v_fmac_f32_e32 v158, v159, v158
	v_div_scale_f32 v159, vcc, 1.0, v152, 1.0
	v_mul_f32_e32 v167, v159, v158
	v_fma_f32 v168, -v153, v167, v159
	v_fmac_f32_e32 v167, v168, v158
	v_fma_f32 v153, -v153, v167, v159
	v_div_fmas_f32 v153, v153, v158, v167
	v_div_fixup_f32 v152, v153, v152, 1.0
	v_lshlrev_b32_e32 v158, 16, v34
	v_and_b32_e32 v159, 0xffff0000, v34
	v_lshlrev_b32_e32 v34, 16, v35
	v_and_b32_e32 v35, 0xffff0000, v35
	v_pk_mul_f32 v[134:135], v[134:135], v[152:153] op_sel_hi:[1,0]
	v_pk_mul_f32 v[88:89], v[88:89], v[152:153] op_sel_hi:[1,0]
	s_nop 0
	v_pk_mul_f32 v[34:35], v[88:89], v[34:35]
	v_pk_mul_f32 v[88:89], v[134:135], v[158:159]
	s_nop 0
	v_cvt_pk_bf16_f32 v88, v88, v89
	v_cvt_pk_bf16_f32 v89, v34, v35
	v_add_f32_dpp v34, v164, v164 quad_perm:[1,0,3,2] row_mask:0xf bank_mask:0xf bound_ctrl:1
	global_store_dwordx2 v[44:45], v[88:89], off
	s_nop 0
	v_add_f32_dpp v34, v34, v34 quad_perm:[2,3,0,1] row_mask:0xf bank_mask:0xf bound_ctrl:1
	s_nop 1
	v_add_f32_dpp v34, v34, v34 row_half_mirror row_mask:0xf bank_mask:0xf bound_ctrl:1
	s_nop 1
	v_add_f32_dpp v34, v34, v34 row_mirror row_mask:0xf bank_mask:0xf bound_ctrl:1
	s_nop 0
	v_readlane_b32 s9, v34, 16
	v_readlane_b32 s12, v34, 48
	v_readlane_b32 s6, v34, 0
	v_readlane_b32 s7, v34, 32
	v_mov_b32_e32 v34, s9
	v_mov_b32_e32 v35, s12
	v_pk_add_f32 v[34:35], s[6:7], v[34:35]
	s_nop 0
	v_add_f32_e32 v34, v34, v35
	v_fmamk_f32 v34, v34, 0x3b800000, v252
	v_cmp_gt_f32_e32 vcc, s55, v34
	v_mul_f32_e32 v35, 0x4f800000, v34
	s_nop 0
	v_cndmask_b32_e32 v34, v34, v35, vcc
	v_sqrt_f32_e32 v35, v34
	s_nop 0
	v_add_u32_e32 v88, -1, v35
	v_fma_f32 v89, -v88, v35, v34
	v_cmp_ge_f32_e64 s[6:7], 0, v89
	v_add_u32_e32 v89, 1, v35
	s_nop 0
	v_cndmask_b32_e64 v88, v35, v88, s[6:7]
	v_fma_f32 v35, -v89, v35, v34
	v_cmp_lt_f32_e64 s[6:7], 0, v35
	s_nop 1
	v_cndmask_b32_e64 v35, v88, v89, s[6:7]
	v_mul_f32_e32 v88, 0x37800000, v35
	v_cndmask_b32_e32 v35, v35, v88, vcc
	v_cmp_class_f32_e32 vcc, v34, v253
	s_nop 1
	v_cndmask_b32_e32 v34, v35, v34, vcc
	v_div_scale_f32 v35, s[6:7], v34, v34, 1.0
	v_rcp_f32_e32 v88, v35
	s_nop 0
	v_fma_f32 v89, -v35, v88, 1.0
	v_fmac_f32_e32 v88, v89, v88
	v_div_scale_f32 v89, vcc, 1.0, v34, 1.0
	v_mul_f32_e32 v134, v89, v88
	v_fma_f32 v135, -v35, v134, v89
	v_fmac_f32_e32 v134, v135, v88
	v_fma_f32 v35, -v35, v134, v89
	v_div_fmas_f32 v35, v35, v88, v134
	v_div_fixup_f32 v34, v35, v34, 1.0
	v_lshlrev_b32_e32 v88, 16, v30
	v_and_b32_e32 v89, 0xffff0000, v30
	v_lshlrev_b32_e32 v30, 16, v31
	v_and_b32_e32 v31, 0xffff0000, v31
	v_pk_mul_f32 v[86:87], v[86:87], v[34:35] op_sel_hi:[1,0]
	v_pk_mul_f32 v[34:35], v[84:85], v[34:35] op_sel_hi:[1,0]
	s_nop 0
	v_pk_mul_f32 v[30:31], v[34:35], v[30:31]
	v_pk_mul_f32 v[34:35], v[86:87], v[88:89]
	s_nop 0
	v_cvt_pk_bf16_f32 v34, v34, v35
	v_cvt_pk_bf16_f32 v35, v30, v31
	v_add_f32_dpp v30, v165, v165 quad_perm:[1,0,3,2] row_mask:0xf bank_mask:0xf bound_ctrl:1
	global_store_dwordx2 v[44:45], v[34:35], off offset:512
	s_nop 0
	v_add_f32_dpp v30, v30, v30 quad_perm:[2,3,0,1] row_mask:0xf bank_mask:0xf bound_ctrl:1
	s_nop 1
	v_add_f32_dpp v30, v30, v30 row_half_mirror row_mask:0xf bank_mask:0xf bound_ctrl:1
	s_nop 1
	v_add_f32_dpp v30, v30, v30 row_mirror row_mask:0xf bank_mask:0xf bound_ctrl:1
	s_nop 0
	v_readlane_b32 s9, v30, 16
	v_readlane_b32 s12, v30, 48
	v_readlane_b32 s6, v30, 0
	v_readlane_b32 s7, v30, 32
	v_mov_b32_e32 v30, s9
	v_mov_b32_e32 v31, s12
	v_pk_add_f32 v[30:31], s[6:7], v[30:31]
	s_nop 0
	v_add_f32_e32 v30, v30, v31
	v_fmamk_f32 v30, v30, 0x3b800000, v252
	v_cmp_gt_f32_e32 vcc, s55, v30
	v_mul_f32_e32 v31, 0x4f800000, v30
	s_nop 0
	v_cndmask_b32_e32 v30, v30, v31, vcc
	v_sqrt_f32_e32 v31, v30
	s_nop 0
	v_add_u32_e32 v34, -1, v31
	v_fma_f32 v35, -v34, v31, v30
	v_cmp_ge_f32_e64 s[6:7], 0, v35
	v_add_u32_e32 v35, 1, v31
	s_nop 0
	v_cndmask_b32_e64 v34, v31, v34, s[6:7]
	v_fma_f32 v31, -v35, v31, v30
	v_cmp_lt_f32_e64 s[6:7], 0, v31
	s_nop 1
	v_cndmask_b32_e64 v31, v34, v35, s[6:7]
	v_mul_f32_e32 v34, 0x37800000, v31
	v_cndmask_b32_e32 v31, v31, v34, vcc
	v_cmp_class_f32_e32 vcc, v30, v253
	s_nop 1
	v_cndmask_b32_e32 v30, v31, v30, vcc
	v_div_scale_f32 v31, s[6:7], v30, v30, 1.0
	v_rcp_f32_e32 v34, v31
	s_nop 0
	v_fma_f32 v35, -v31, v34, 1.0
	v_fmac_f32_e32 v34, v35, v34
	v_div_scale_f32 v35, vcc, 1.0, v30, 1.0
	v_mul_f32_e32 v84, v35, v34
	v_fma_f32 v85, -v31, v84, v35
	v_fmac_f32_e32 v84, v85, v34
	v_fma_f32 v31, -v31, v84, v35
	v_div_fmas_f32 v31, v31, v34, v84
	v_div_fixup_f32 v30, v31, v30, 1.0
	v_lshlrev_b32_e32 v34, 16, v26
	v_and_b32_e32 v35, 0xffff0000, v26
	v_lshlrev_b32_e32 v26, 16, v27
	v_and_b32_e32 v27, 0xffff0000, v27
	v_pk_mul_f32 v[82:83], v[82:83], v[30:31] op_sel_hi:[1,0]
	v_pk_mul_f32 v[30:31], v[80:81], v[30:31] op_sel_hi:[1,0]
	s_nop 0
	v_pk_mul_f32 v[26:27], v[30:31], v[26:27]
	v_pk_mul_f32 v[30:31], v[82:83], v[34:35]
	s_nop 0
	v_cvt_pk_bf16_f32 v30, v30, v31
	v_cvt_pk_bf16_f32 v31, v26, v27
	v_add_f32_dpp v26, v166, v166 quad_perm:[1,0,3,2] row_mask:0xf bank_mask:0xf bound_ctrl:1
	global_store_dwordx2 v[44:45], v[30:31], off offset:1024
	s_nop 0
	v_add_f32_dpp v26, v26, v26 quad_perm:[2,3,0,1] row_mask:0xf bank_mask:0xf bound_ctrl:1
	s_nop 1
	v_add_f32_dpp v26, v26, v26 row_half_mirror row_mask:0xf bank_mask:0xf bound_ctrl:1
	s_nop 1
	v_add_f32_dpp v26, v26, v26 row_mirror row_mask:0xf bank_mask:0xf bound_ctrl:1
	s_nop 0
	v_readlane_b32 s9, v26, 16
	v_readlane_b32 s12, v26, 48
	v_readlane_b32 s6, v26, 0
	v_readlane_b32 s7, v26, 32
	v_mov_b32_e32 v26, s9
	v_mov_b32_e32 v27, s12
	v_pk_add_f32 v[26:27], s[6:7], v[26:27]
	s_nop 0
	v_add_f32_e32 v26, v26, v27
	v_fmamk_f32 v26, v26, 0x3b800000, v252
	v_cmp_gt_f32_e32 vcc, s55, v26
	v_mul_f32_e32 v27, 0x4f800000, v26
	s_nop 0
	v_cndmask_b32_e32 v26, v26, v27, vcc
	v_sqrt_f32_e32 v27, v26
	s_nop 0
	v_add_u32_e32 v30, -1, v27
	v_fma_f32 v31, -v30, v27, v26
	v_cmp_ge_f32_e64 s[6:7], 0, v31
	v_add_u32_e32 v31, 1, v27
	s_nop 0
	v_cndmask_b32_e64 v30, v27, v30, s[6:7]
	v_fma_f32 v27, -v31, v27, v26
	v_cmp_lt_f32_e64 s[6:7], 0, v27
	s_nop 1
	v_cndmask_b32_e64 v27, v30, v31, s[6:7]
	v_mul_f32_e32 v30, 0x37800000, v27
	v_cndmask_b32_e32 v27, v27, v30, vcc
	v_cmp_class_f32_e32 vcc, v26, v253
	s_nop 1
	v_cndmask_b32_e32 v26, v27, v26, vcc
	v_div_scale_f32 v27, s[6:7], v26, v26, 1.0
	v_rcp_f32_e32 v30, v27
	s_nop 0
	v_fma_f32 v31, -v27, v30, 1.0
	v_fmac_f32_e32 v30, v31, v30
	v_div_scale_f32 v31, vcc, 1.0, v26, 1.0
	v_mul_f32_e32 v34, v31, v30
	v_fma_f32 v35, -v27, v34, v31
	v_fmac_f32_e32 v34, v35, v30
	v_fma_f32 v27, -v27, v34, v31
	v_div_fmas_f32 v27, v27, v30, v34
	v_div_fixup_f32 v26, v27, v26, 1.0
	v_lshlrev_b32_e32 v30, 16, v22
	v_and_b32_e32 v31, 0xffff0000, v22
	v_lshlrev_b32_e32 v22, 16, v23
	v_and_b32_e32 v23, 0xffff0000, v23
	v_pk_mul_f32 v[34:35], v[78:79], v[26:27] op_sel_hi:[1,0]
	v_pk_mul_f32 v[26:27], v[76:77], v[26:27] op_sel_hi:[1,0]
	s_nop 0
	v_pk_mul_f32 v[22:23], v[26:27], v[22:23]
	v_pk_mul_f32 v[26:27], v[34:35], v[30:31]
	s_nop 0
	v_cvt_pk_bf16_f32 v26, v26, v27
	v_cvt_pk_bf16_f32 v27, v22, v23
	v_add_f32_dpp v22, v147, v147 quad_perm:[1,0,3,2] row_mask:0xf bank_mask:0xf bound_ctrl:1
	global_store_dwordx2 v[44:45], v[26:27], off offset:1536
	s_nop 0
	v_add_f32_dpp v22, v22, v22 quad_perm:[2,3,0,1] row_mask:0xf bank_mask:0xf bound_ctrl:1
	s_nop 1
	v_add_f32_dpp v22, v22, v22 row_half_mirror row_mask:0xf bank_mask:0xf bound_ctrl:1
	s_nop 1
	v_add_f32_dpp v22, v22, v22 row_mirror row_mask:0xf bank_mask:0xf bound_ctrl:1
	s_nop 0
	v_readlane_b32 s9, v22, 16
	v_readlane_b32 s12, v22, 48
	v_readlane_b32 s6, v22, 0
	v_readlane_b32 s7, v22, 32
	v_mov_b32_e32 v22, s9
	v_mov_b32_e32 v23, s12
	v_pk_add_f32 v[22:23], s[6:7], v[22:23]
	s_nop 0
	v_add_f32_e32 v22, v22, v23
	v_fmamk_f32 v22, v22, 0x3b800000, v252
	v_cmp_gt_f32_e32 vcc, s55, v22
	v_mul_f32_e32 v23, 0x4f800000, v22
	s_nop 0
	v_cndmask_b32_e32 v22, v22, v23, vcc
	v_sqrt_f32_e32 v23, v22
	s_nop 0
	v_add_u32_e32 v26, -1, v23
	v_fma_f32 v27, -v26, v23, v22
	v_cmp_ge_f32_e64 s[6:7], 0, v27
	v_add_u32_e32 v27, 1, v23
	s_nop 0
	v_cndmask_b32_e64 v26, v23, v26, s[6:7]
	v_fma_f32 v23, -v27, v23, v22
	v_cmp_lt_f32_e64 s[6:7], 0, v23
	s_nop 1
	v_cndmask_b32_e64 v23, v26, v27, s[6:7]
	v_mul_f32_e32 v26, 0x37800000, v23
	v_cndmask_b32_e32 v23, v23, v26, vcc
	v_cmp_class_f32_e32 vcc, v22, v253
	s_nop 1
	v_cndmask_b32_e32 v22, v23, v22, vcc
	v_div_scale_f32 v23, s[6:7], v22, v22, 1.0
	v_rcp_f32_e32 v26, v23
	s_nop 0
	v_fma_f32 v27, -v23, v26, 1.0
	v_fmac_f32_e32 v26, v27, v26
	v_div_scale_f32 v27, vcc, 1.0, v22, 1.0
	v_mul_f32_e32 v30, v27, v26
	v_fma_f32 v31, -v23, v30, v27
	v_fmac_f32_e32 v30, v31, v26
	v_fma_f32 v23, -v23, v30, v27
	v_div_fmas_f32 v23, v23, v26, v30
	v_div_fixup_f32 v22, v23, v22, 1.0
	v_lshlrev_b32_e32 v26, 16, v18
	v_and_b32_e32 v27, 0xffff0000, v18
	v_lshlrev_b32_e32 v18, 16, v19
	v_and_b32_e32 v19, 0xffff0000, v19
	v_pk_mul_f32 v[30:31], v[74:75], v[22:23] op_sel_hi:[1,0]
	v_pk_mul_f32 v[22:23], v[72:73], v[22:23] op_sel_hi:[1,0]
	s_nop 0
	v_pk_mul_f32 v[18:19], v[22:23], v[18:19]
	v_pk_mul_f32 v[22:23], v[30:31], v[26:27]
	s_nop 0
	v_cvt_pk_bf16_f32 v22, v22, v23
	v_cvt_pk_bf16_f32 v23, v18, v19
	v_add_f32_dpp v18, v146, v146 quad_perm:[1,0,3,2] row_mask:0xf bank_mask:0xf bound_ctrl:1
	global_store_dwordx2 v[44:45], v[22:23], off offset:2048
	s_nop 0
	v_add_f32_dpp v18, v18, v18 quad_perm:[2,3,0,1] row_mask:0xf bank_mask:0xf bound_ctrl:1
	s_nop 1
	v_add_f32_dpp v18, v18, v18 row_half_mirror row_mask:0xf bank_mask:0xf bound_ctrl:1
	s_nop 1
	v_add_f32_dpp v18, v18, v18 row_mirror row_mask:0xf bank_mask:0xf bound_ctrl:1
	s_nop 0
	v_readlane_b32 s9, v18, 16
	v_readlane_b32 s12, v18, 48
	v_readlane_b32 s6, v18, 0
	v_readlane_b32 s7, v18, 32
	v_mov_b32_e32 v18, s9
	v_mov_b32_e32 v19, s12
	v_pk_add_f32 v[18:19], s[6:7], v[18:19]
	s_nop 0
	v_add_f32_e32 v18, v18, v19
	v_fmamk_f32 v18, v18, 0x3b800000, v252
	v_cmp_gt_f32_e32 vcc, s55, v18
	v_mul_f32_e32 v19, 0x4f800000, v18
	s_nop 0
	v_cndmask_b32_e32 v18, v18, v19, vcc
	v_sqrt_f32_e32 v19, v18
	s_nop 0
	v_add_u32_e32 v22, -1, v19
	v_fma_f32 v23, -v22, v19, v18
	v_cmp_ge_f32_e64 s[6:7], 0, v23
	v_add_u32_e32 v23, 1, v19
	s_nop 0
	v_cndmask_b32_e64 v22, v19, v22, s[6:7]
	v_fma_f32 v19, -v23, v19, v18
	v_cmp_lt_f32_e64 s[6:7], 0, v19
	s_nop 1
	v_cndmask_b32_e64 v19, v22, v23, s[6:7]
	v_mul_f32_e32 v22, 0x37800000, v19
	v_cndmask_b32_e32 v19, v19, v22, vcc
	v_cmp_class_f32_e32 vcc, v18, v253
	s_nop 1
	v_cndmask_b32_e32 v18, v19, v18, vcc
	v_div_scale_f32 v19, s[6:7], v18, v18, 1.0
	v_rcp_f32_e32 v22, v19
	s_nop 0
	v_fma_f32 v23, -v19, v22, 1.0
	v_fmac_f32_e32 v22, v23, v22
	v_div_scale_f32 v23, vcc, 1.0, v18, 1.0
	v_mul_f32_e32 v26, v23, v22
	v_fma_f32 v27, -v19, v26, v23
	v_fmac_f32_e32 v26, v27, v22
	v_fma_f32 v19, -v19, v26, v23
	v_div_fmas_f32 v19, v19, v22, v26
	v_div_fixup_f32 v18, v19, v18, 1.0
	v_lshlrev_b32_e32 v22, 16, v14
	v_and_b32_e32 v23, 0xffff0000, v14
	v_lshlrev_b32_e32 v14, 16, v15
	v_and_b32_e32 v15, 0xffff0000, v15
	v_pk_mul_f32 v[26:27], v[70:71], v[18:19] op_sel_hi:[1,0]
	v_pk_mul_f32 v[18:19], v[68:69], v[18:19] op_sel_hi:[1,0]
	s_nop 0
	v_pk_mul_f32 v[14:15], v[18:19], v[14:15]
	v_pk_mul_f32 v[18:19], v[26:27], v[22:23]
	s_nop 0
	v_cvt_pk_bf16_f32 v18, v18, v19
	v_cvt_pk_bf16_f32 v19, v14, v15
	v_add_f32_dpp v14, v141, v141 quad_perm:[1,0,3,2] row_mask:0xf bank_mask:0xf bound_ctrl:1
	global_store_dwordx2 v[44:45], v[18:19], off offset:2560
	s_nop 0
	v_add_f32_dpp v14, v14, v14 quad_perm:[2,3,0,1] row_mask:0xf bank_mask:0xf bound_ctrl:1
	s_nop 1
	v_add_f32_dpp v14, v14, v14 row_half_mirror row_mask:0xf bank_mask:0xf bound_ctrl:1
	s_nop 1
	v_add_f32_dpp v14, v14, v14 row_mirror row_mask:0xf bank_mask:0xf bound_ctrl:1
	s_nop 0
	v_readlane_b32 s9, v14, 16
	v_readlane_b32 s12, v14, 48
	v_readlane_b32 s6, v14, 0
	v_readlane_b32 s7, v14, 32
	v_mov_b32_e32 v14, s9
	v_mov_b32_e32 v15, s12
	v_pk_add_f32 v[14:15], s[6:7], v[14:15]
	s_nop 0
	v_add_f32_e32 v14, v14, v15
	v_fmamk_f32 v14, v14, 0x3b800000, v252
	v_cmp_gt_f32_e32 vcc, s55, v14
	v_mul_f32_e32 v15, 0x4f800000, v14
	s_nop 0
	v_cndmask_b32_e32 v14, v14, v15, vcc
	v_sqrt_f32_e32 v15, v14
	s_nop 0
	v_add_u32_e32 v18, -1, v15
	v_fma_f32 v19, -v18, v15, v14
	v_cmp_ge_f32_e64 s[6:7], 0, v19
	v_add_u32_e32 v19, 1, v15
	s_nop 0
	v_cndmask_b32_e64 v18, v15, v18, s[6:7]
	v_fma_f32 v15, -v19, v15, v14
	v_cmp_lt_f32_e64 s[6:7], 0, v15
	s_nop 1
	v_cndmask_b32_e64 v15, v18, v19, s[6:7]
	v_mul_f32_e32 v18, 0x37800000, v15
	v_cndmask_b32_e32 v15, v15, v18, vcc
	v_cmp_class_f32_e32 vcc, v14, v253
	s_nop 1
	v_cndmask_b32_e32 v14, v15, v14, vcc
	v_div_scale_f32 v15, s[6:7], v14, v14, 1.0
	v_rcp_f32_e32 v18, v15
	s_nop 0
	v_fma_f32 v19, -v15, v18, 1.0
	v_fmac_f32_e32 v18, v19, v18
	v_div_scale_f32 v19, vcc, 1.0, v14, 1.0
	v_mul_f32_e32 v22, v19, v18
	v_fma_f32 v23, -v15, v22, v19
	v_fmac_f32_e32 v22, v23, v18
	v_fma_f32 v15, -v15, v22, v19
	v_div_fmas_f32 v15, v15, v18, v22
	v_div_fixup_f32 v14, v15, v14, 1.0
	v_lshlrev_b32_e32 v18, 16, v12
	v_and_b32_e32 v19, 0xffff0000, v12
	v_lshlrev_b32_e32 v12, 16, v13
	v_and_b32_e32 v13, 0xffff0000, v13
	v_pk_mul_f32 v[22:23], v[62:63], v[14:15] op_sel_hi:[1,0]
	v_pk_mul_f32 v[14:15], v[56:57], v[14:15] op_sel_hi:[1,0]
	s_nop 0
	v_pk_mul_f32 v[12:13], v[14:15], v[12:13]
	v_pk_mul_f32 v[14:15], v[22:23], v[18:19]
	s_nop 0
	v_cvt_pk_bf16_f32 v14, v14, v15
	v_cvt_pk_bf16_f32 v15, v12, v13
	v_add_f32_dpp v12, v140, v140 quad_perm:[1,0,3,2] row_mask:0xf bank_mask:0xf bound_ctrl:1
	global_store_dwordx2 v[44:45], v[14:15], off offset:3072
	s_nop 0
	v_add_f32_dpp v12, v12, v12 quad_perm:[2,3,0,1] row_mask:0xf bank_mask:0xf bound_ctrl:1
; template <bool HG>
; __device__ __forceinline__ void readout_phase2(const Args& a, Frame& F, const float* gain, int nrows) {
;     ...
;     RO_FINISH(f2, b2, g2, nw + 2 * 2048); RO_LOAD(f2, b2, g2, nw + 5 * 2048);
;     RO_FINISH(f0, b0, g0, nw + 3 * 2048); RO_LOAD(f0, b0, g0, nw + 6 * 2048);
;     RO_FINISH(f1, b1, g1, nw + 4 * 2048); RO_LOAD(f1, b1, g1, nw + 7 * 2048);
;     RO_FINISH(f2, b2, g2, nw + 5 * 2048);
;     const bool cx = ML + nw < nrows;
	s_nop 1
	v_add_f32_dpp v12, v12, v12 row_half_mirror row_mask:0xf bank_mask:0xf bound_ctrl:1
	s_nop 1
	v_add_f32_dpp v12, v12, v12 row_mirror row_mask:0xf bank_mask:0xf bound_ctrl:1
	s_nop 0
	v_readlane_b32 s9, v12, 16
	v_readlane_b32 s12, v12, 48
	v_readlane_b32 s6, v12, 0
	v_readlane_b32 s7, v12, 32
	v_mov_b32_e32 v12, s9
	v_mov_b32_e32 v13, s12
	v_pk_add_f32 v[12:13], s[6:7], v[12:13]
	s_add_u32 s12, s10, 0x2800000
	v_add_f32_e32 v12, v12, v13
	v_fmamk_f32 v12, v12, 0x3b800000, v252
	v_cmp_gt_f32_e32 vcc, s55, v12
	v_mul_f32_e32 v13, 0x4f800000, v12
	s_addc_u32 s13, s11, 0
	v_cndmask_b32_e32 v12, v12, v13, vcc
	v_sqrt_f32_e32 v13, v12
	s_add_u32 s40, s10, 0x3000000
	s_addc_u32 s41, s11, 0
	s_add_i32 s82, s8, 0x4000
	v_add_u32_e32 v14, -1, v13
	v_fma_f32 v15, -v14, v13, v12
	v_cmp_ge_f32_e64 s[6:7], 0, v15
	v_add_u32_e32 v15, 1, v13
	s_nop 0
	v_cndmask_b32_e64 v14, v13, v14, s[6:7]
	v_fma_f32 v13, -v15, v13, v12
	v_cmp_lt_f32_e64 s[6:7], 0, v13
	s_nop 1
	v_cndmask_b32_e64 v13, v14, v15, s[6:7]
	v_mul_f32_e32 v14, 0x37800000, v13
	v_cndmask_b32_e32 v13, v13, v14, vcc
	v_cmp_class_f32_e32 vcc, v12, v253
	s_nop 1
	v_cndmask_b32_e32 v12, v13, v12, vcc
	v_div_scale_f32 v13, s[6:7], v12, v12, 1.0
	v_rcp_f32_e32 v14, v13
	s_nop 0
	v_fma_f32 v15, -v13, v14, 1.0
	v_fmac_f32_e32 v14, v15, v14
	v_div_scale_f32 v15, vcc, 1.0, v12, 1.0
	v_mul_f32_e32 v18, v15, v14
	v_fma_f32 v19, -v13, v18, v15
	v_fmac_f32_e32 v18, v19, v14
	v_fma_f32 v13, -v13, v18, v15
	v_div_fmas_f32 v13, v13, v14, v18
	v_div_fixup_f32 v12, v13, v12, 1.0
	s_waitcnt vmcnt(62)
	v_lshlrev_b32_e32 v14, 16, v10
	v_and_b32_e32 v15, 0xffff0000, v10
	v_lshlrev_b32_e32 v10, 16, v11
	v_and_b32_e32 v11, 0xffff0000, v11
	v_pk_mul_f32 v[18:19], v[50:51], v[12:13] op_sel_hi:[1,0]
	v_pk_mul_f32 v[12:13], v[38:39], v[12:13] op_sel_hi:[1,0]
	s_nop 0
	v_pk_mul_f32 v[10:11], v[12:13], v[10:11]
	v_pk_mul_f32 v[12:13], v[18:19], v[14:15]
	v_lshl_add_u64 v[14:15], v[8:9], 0, s[12:13]
	v_cvt_pk_bf16_f32 v12, v12, v13
	v_cvt_pk_bf16_f32 v13, v10, v11
	global_store_dwordx2 v[44:45], v[12:13], off offset:3584
	v_lshl_add_u64 v[10:11], v[4:5], 0, s[12:13]
	v_lshl_add_u64 v[12:13], v[6:7], 0, s[12:13]
	v_lshl_add_u64 v[10:11], v[10:11], 0, v[0:1]
	v_lshl_add_u64 v[12:13], v[12:13], 0, v[0:1]
	v_lshl_add_u64 v[14:15], v[14:15], 0, v[0:1]
	global_load_dwordx2 v[158:159], v[10:11], off nt
	global_load_dwordx2 v[152:153], v[12:13], off nt
	global_load_dwordx2 v[62:63], v[14:15], off nt
	global_load_dwordx2 v[146:147], v[10:11], off offset:512 nt
	global_load_dwordx2 v[140:141], v[12:13], off offset:512 nt
	global_load_dwordx2 v[56:57], v[14:15], off offset:512 nt
	global_load_dwordx2 v[134:135], v[10:11], off offset:1024 nt
	global_load_dwordx2 v[88:89], v[12:13], off offset:1024 nt
	global_load_dwordx2 v[50:51], v[14:15], off offset:1024 nt
	global_load_dwordx2 v[84:85], v[10:11], off offset:1536 nt
	global_load_dwordx2 v[86:87], v[12:13], off offset:1536 nt
	global_load_dwordx2 v[44:45], v[14:15], off offset:1536 nt
	global_load_dwordx2 v[82:83], v[10:11], off offset:2048 nt
	global_load_dwordx2 v[80:81], v[12:13], off offset:2048 nt
	global_load_dwordx2 v[38:39], v[14:15], off offset:2048 nt
	global_load_dwordx2 v[78:79], v[10:11], off offset:2560 nt
	global_load_dwordx2 v[76:77], v[12:13], off offset:2560 nt
	global_load_dwordx2 v[34:35], v[14:15], off offset:2560 nt
	global_load_dwordx2 v[74:75], v[10:11], off offset:3072 nt
	global_load_dwordx2 v[72:73], v[12:13], off offset:3072 nt
	global_load_dwordx2 v[30:31], v[14:15], off offset:3072 nt
	global_load_dwordx2 v[68:69], v[10:11], off offset:3584 nt
	global_load_dwordx2 v[70:71], v[12:13], off offset:3584 nt
	global_load_dwordx2 v[26:27], v[14:15], off offset:3584 nt
	v_lshlrev_b32_e32 v10, 16, v160
	v_and_b32_e32 v11, 0xffff0000, v160
	s_waitcnt vmcnt(62)
	v_lshlrev_b32_e32 v12, 16, v154
	v_and_b32_e32 v13, 0xffff0000, v154
	v_pk_add_f32 v[164:165], v[10:11], v[12:13]
	v_lshlrev_b32_e32 v10, 16, v161
	v_and_b32_e32 v11, 0xffff0000, v161
	v_lshlrev_b32_e32 v12, 16, v155
	v_and_b32_e32 v13, 0xffff0000, v155
	v_pk_add_f32 v[160:161], v[10:11], v[12:13]
	v_mov_b32_e32 v12, v165
	v_mov_b32_e32 v13, v161
	v_mov_b32_e32 v10, v164
	v_mov_b32_e32 v11, v160
	v_pk_mul_f32 v[12:13], v[12:13], v[12:13]
	v_lshlrev_b32_e32 v14, 16, v95
	v_pk_fma_f32 v[10:11], v[10:11], v[10:11], v[12:13]
	v_lshlrev_b32_e32 v12, 16, v142
	v_add_f32_e32 v167, v10, v11
	v_lshlrev_b32_e32 v10, 16, v148
	v_and_b32_e32 v11, 0xffff0000, v148
	v_and_b32_e32 v13, 0xffff0000, v142
	v_pk_add_f32 v[154:155], v[10:11], v[12:13]
	v_lshlrev_b32_e32 v10, 16, v149
	v_and_b32_e32 v11, 0xffff0000, v149
	v_lshlrev_b32_e32 v12, 16, v143
	v_and_b32_e32 v13, 0xffff0000, v143
	v_pk_add_f32 v[148:149], v[10:11], v[12:13]
	v_mov_b32_e32 v12, v155
	v_mov_b32_e32 v13, v149
	v_mov_b32_e32 v10, v154
	v_mov_b32_e32 v11, v148
	v_pk_mul_f32 v[12:13], v[12:13], v[12:13]
	v_and_b32_e32 v15, 0xffff0000, v95
	v_pk_fma_f32 v[10:11], v[10:11], v[10:11], v[12:13]
	v_lshlrev_b32_e32 v12, 16, v130
	v_add_f32_e32 v168, v10, v11
	v_lshlrev_b32_e32 v10, 16, v136
	v_and_b32_e32 v11, 0xffff0000, v136
	v_and_b32_e32 v13, 0xffff0000, v130
	v_pk_add_f32 v[142:143], v[10:11], v[12:13]
	v_lshlrev_b32_e32 v10, 16, v137
	v_and_b32_e32 v11, 0xffff0000, v137
	v_lshlrev_b32_e32 v12, 16, v131
	v_and_b32_e32 v13, 0xffff0000, v131
	v_pk_add_f32 v[136:137], v[10:11], v[12:13]
	v_mov_b32_e32 v12, v143
	v_mov_b32_e32 v13, v137
	v_mov_b32_e32 v10, v142
	v_mov_b32_e32 v11, v136
	v_pk_mul_f32 v[12:13], v[12:13], v[12:13]
	s_nop 0
	v_pk_fma_f32 v[10:11], v[10:11], v[10:11], v[12:13]
	v_lshlrev_b32_e32 v12, 16, v126
	v_add_f32_e32 v169, v10, v11
	v_lshlrev_b32_e32 v10, 16, v122
	v_and_b32_e32 v11, 0xffff0000, v122
	v_and_b32_e32 v13, 0xffff0000, v126
	v_pk_add_f32 v[130:131], v[10:11], v[12:13]
	v_lshlrev_b32_e32 v10, 16, v123
	v_and_b32_e32 v11, 0xffff0000, v123
	v_lshlrev_b32_e32 v12, 16, v127
	v_and_b32_e32 v13, 0xffff0000, v127
	v_pk_add_f32 v[126:127], v[10:11], v[12:13]
	v_mov_b32_e32 v12, v131
	v_mov_b32_e32 v13, v127
	v_mov_b32_e32 v10, v130
	v_mov_b32_e32 v11, v126
	v_pk_mul_f32 v[12:13], v[12:13], v[12:13]
	s_nop 0
	v_pk_fma_f32 v[10:11], v[10:11], v[10:11], v[12:13]
	v_lshlrev_b32_e32 v12, 16, v114
	v_add_f32_e32 v170, v10, v11
	v_lshlrev_b32_e32 v10, 16, v118
	v_and_b32_e32 v11, 0xffff0000, v118
	v_and_b32_e32 v13, 0xffff0000, v114
	v_pk_add_f32 v[122:123], v[10:11], v[12:13]
	v_lshlrev_b32_e32 v10, 16, v119
	v_and_b32_e32 v11, 0xffff0000, v119
	v_lshlrev_b32_e32 v12, 16, v115
	v_and_b32_e32 v13, 0xffff0000, v115
	v_pk_add_f32 v[118:119], v[10:11], v[12:13]
	v_mov_b32_e32 v12, v123
	v_mov_b32_e32 v13, v119
	v_mov_b32_e32 v10, v122
	v_mov_b32_e32 v11, v118
	v_pk_mul_f32 v[12:13], v[12:13], v[12:13]
	s_nop 0
	v_pk_fma_f32 v[10:11], v[10:11], v[10:11], v[12:13]
	v_lshlrev_b32_e32 v12, 16, v106
	v_add_f32_e32 v166, v10, v11
	v_lshlrev_b32_e32 v10, 16, v110
	v_and_b32_e32 v11, 0xffff0000, v110
	v_and_b32_e32 v13, 0xffff0000, v106
	v_pk_add_f32 v[114:115], v[10:11], v[12:13]
	v_lshlrev_b32_e32 v10, 16, v111
	v_and_b32_e32 v11, 0xffff0000, v111
	v_lshlrev_b32_e32 v12, 16, v107
	v_and_b32_e32 v13, 0xffff0000, v107
	v_pk_add_f32 v[106:107], v[10:11], v[12:13]
	v_mov_b32_e32 v12, v115
	v_mov_b32_e32 v13, v107
	v_mov_b32_e32 v10, v114
	v_mov_b32_e32 v11, v106
	v_pk_mul_f32 v[12:13], v[12:13], v[12:13]
	s_nop 0
	v_pk_fma_f32 v[10:11], v[10:11], v[10:11], v[12:13]
	v_lshlrev_b32_e32 v12, 16, v98
	v_add_f32_e32 v110, v10, v11
	v_lshlrev_b32_e32 v10, 16, v102
	v_and_b32_e32 v11, 0xffff0000, v102
	v_and_b32_e32 v13, 0xffff0000, v98
	v_pk_add_f32 v[18:19], v[10:11], v[12:13]
	v_lshlrev_b32_e32 v10, 16, v103
	v_and_b32_e32 v11, 0xffff0000, v103
	v_lshlrev_b32_e32 v12, 16, v99
	v_and_b32_e32 v13, 0xffff0000, v99
	v_pk_add_f32 v[22:23], v[10:11], v[12:13]
	v_mov_b32_e32 v12, v19
	v_mov_b32_e32 v13, v23
	v_mov_b32_e32 v10, v18
	v_mov_b32_e32 v11, v22
	v_pk_mul_f32 v[12:13], v[12:13], v[12:13]
	s_nop 0
	v_pk_fma_f32 v[10:11], v[10:11], v[10:11], v[12:13]
	v_lshlrev_b32_e32 v12, 16, v94
	v_add_f32_e32 v98, v10, v11
	v_lshlrev_b32_e32 v10, 16, v90
	v_and_b32_e32 v11, 0xffff0000, v90
	v_and_b32_e32 v13, 0xffff0000, v94
	v_pk_add_f32 v[10:11], v[10:11], v[12:13]
	v_lshlrev_b32_e32 v12, 16, v91
	v_and_b32_e32 v13, 0xffff0000, v91
	v_pk_add_f32 v[12:13], v[12:13], v[14:15]
	v_mov_b32_e32 v90, v11
	v_mov_b32_e32 v91, v13
	v_mov_b32_e32 v14, v10
	v_mov_b32_e32 v15, v12
	v_pk_mul_f32 v[90:91], v[90:91], v[90:91]
	s_nop 0
	v_pk_fma_f32 v[14:15], v[14:15], v[14:15], v[90:91]
	v_add_f32_dpp v91, v167, v167 quad_perm:[1,0,3,2] row_mask:0xf bank_mask:0xf bound_ctrl:1
	v_add_f32_e32 v90, v14, v15
	v_lshl_add_u64 v[14:15], v[2:3], 0, s[14:15]
	v_add_f32_dpp v91, v91, v91 quad_perm:[2,3,0,1] row_mask:0xf bank_mask:0xf bound_ctrl:1
	v_lshl_add_u64 v[14:15], v[14:15], 0, v[0:1]
	s_nop 0
	v_add_f32_dpp v91, v91, v91 row_half_mirror row_mask:0xf bank_mask:0xf bound_ctrl:1
	s_nop 1
	v_add_f32_dpp v91, v91, v91 row_mirror row_mask:0xf bank_mask:0xf bound_ctrl:1
	s_nop 0
	v_readlane_b32 s9, v91, 16
	v_readlane_b32 s14, v91, 48
	v_readlane_b32 s6, v91, 0
	v_readlane_b32 s7, v91, 32
	v_mov_b32_e32 v94, s9
	v_mov_b32_e32 v95, s14
	v_pk_add_f32 v[94:95], s[6:7], v[94:95]
	s_nop 0
	v_add_f32_e32 v91, v94, v95
	v_fmamk_f32 v91, v91, 0x3b800000, v252
	v_cmp_gt_f32_e32 vcc, s55, v91
	v_mul_f32_e32 v94, 0x4f800000, v91
	s_nop 0
	v_cndmask_b32_e32 v91, v91, v94, vcc
	v_sqrt_f32_e32 v94, v91
	s_nop 0
	v_add_u32_e32 v95, -1, v94
	v_fma_f32 v99, -v95, v94, v91
	v_cmp_ge_f32_e64 s[6:7], 0, v99
	v_add_u32_e32 v99, 1, v94
	s_nop 0
	v_cndmask_b32_e64 v95, v94, v95, s[6:7]
	v_fma_f32 v94, -v99, v94, v91
	v_cmp_lt_f32_e64 s[6:7], 0, v94
	s_nop 1
	v_cndmask_b32_e64 v94, v95, v99, s[6:7]
	v_mul_f32_e32 v95, 0x37800000, v94
	v_cndmask_b32_e32 v94, v94, v95, vcc
	v_cmp_class_f32_e32 vcc, v91, v253
	s_nop 1
	v_cndmask_b32_e32 v91, v94, v91, vcc
	v_div_scale_f32 v94, s[6:7], v91, v91, 1.0
	v_rcp_f32_e32 v95, v94
	s_nop 0
	v_fma_f32 v99, -v94, v95, 1.0
	v_fmac_f32_e32 v95, v99, v95
	v_div_scale_f32 v99, vcc, 1.0, v91, 1.0
	v_mul_f32_e32 v102, v99, v95
	v_fma_f32 v103, -v94, v102, v99
	v_fmac_f32_e32 v102, v103, v95
	v_fma_f32 v94, -v94, v102, v99
	v_div_fmas_f32 v94, v94, v95, v102
	v_div_fixup_f32 v94, v94, v91, 1.0
	v_lshlrev_b32_e32 v102, 16, v64
	v_and_b32_e32 v103, 0xffff0000, v64
	v_lshlrev_b32_e32 v64, 16, v65
	v_and_b32_e32 v65, 0xffff0000, v65
	v_pk_mul_f32 v[164:165], v[164:165], v[94:95] op_sel_hi:[1,0]
	v_pk_mul_f32 v[94:95], v[160:161], v[94:95] op_sel_hi:[1,0]
	s_nop 0
	v_pk_mul_f32 v[64:65], v[94:95], v[64:65]
	v_pk_mul_f32 v[94:95], v[164:165], v[102:103]
	s_nop 0
	v_cvt_pk_bf16_f32 v94, v94, v95
	v_cvt_pk_bf16_f32 v95, v64, v65
	v_add_f32_dpp v64, v168, v168 quad_perm:[1,0,3,2] row_mask:0xf bank_mask:0xf bound_ctrl:1
	global_store_dwordx2 v[14:15], v[94:95], off
	s_nop 0
	v_add_f32_dpp v64, v64, v64 quad_perm:[2,3,0,1] row_mask:0xf bank_mask:0xf bound_ctrl:1
	s_nop 1
	v_add_f32_dpp v64, v64, v64 row_half_mirror row_mask:0xf bank_mask:0xf bound_ctrl:1
	s_nop 1
	v_add_f32_dpp v64, v64, v64 row_mirror row_mask:0xf bank_mask:0xf bound_ctrl:1
	s_nop 0
	v_readlane_b32 s9, v64, 16
	v_readlane_b32 s14, v64, 48
	v_readlane_b32 s6, v64, 0
	v_readlane_b32 s7, v64, 32
	v_mov_b32_e32 v64, s9
	v_mov_b32_e32 v65, s14
	v_pk_add_f32 v[64:65], s[6:7], v[64:65]
	s_nop 0
	v_add_f32_e32 v64, v64, v65
	v_fmamk_f32 v64, v64, 0x3b800000, v252
	v_cmp_gt_f32_e32 vcc, s55, v64
	v_mul_f32_e32 v65, 0x4f800000, v64
	s_nop 0
	v_cndmask_b32_e32 v64, v64, v65, vcc
	v_sqrt_f32_e32 v65, v64
	s_nop 0
	v_add_u32_e32 v91, -1, v65
	v_fma_f32 v94, -v91, v65, v64
	v_cmp_ge_f32_e64 s[6:7], 0, v94
	v_add_u32_e32 v94, 1, v65
	s_nop 0
	v_cndmask_b32_e64 v91, v65, v91, s[6:7]
	v_fma_f32 v65, -v94, v65, v64
	v_cmp_lt_f32_e64 s[6:7], 0, v65
	s_nop 1
	v_cndmask_b32_e64 v65, v91, v94, s[6:7]
	v_mul_f32_e32 v91, 0x37800000, v65
	v_cndmask_b32_e32 v65, v65, v91, vcc
	v_cmp_class_f32_e32 vcc, v64, v253
	s_nop 1
	v_cndmask_b32_e32 v64, v65, v64, vcc
	v_div_scale_f32 v65, s[6:7], v64, v64, 1.0
	v_rcp_f32_e32 v91, v65
	s_nop 0
	v_fma_f32 v94, -v65, v91, 1.0
	v_fmac_f32_e32 v91, v94, v91
	v_div_scale_f32 v94, vcc, 1.0, v64, 1.0
	v_mul_f32_e32 v95, v94, v91
	v_fma_f32 v99, -v65, v95, v94
	v_fmac_f32_e32 v95, v99, v91
	v_fma_f32 v65, -v65, v95, v94
	v_div_fmas_f32 v65, v65, v91, v95
	v_div_fixup_f32 v64, v65, v64, 1.0
	v_lshlrev_b32_e32 v94, 16, v58
	v_and_b32_e32 v95, 0xffff0000, v58
	v_lshlrev_b32_e32 v58, 16, v59
	v_and_b32_e32 v59, 0xffff0000, v59
	v_pk_mul_f32 v[102:103], v[154:155], v[64:65] op_sel_hi:[1,0]
	v_pk_mul_f32 v[64:65], v[148:149], v[64:65] op_sel_hi:[1,0]
	s_nop 0
	v_pk_mul_f32 v[58:59], v[64:65], v[58:59]
	v_pk_mul_f32 v[64:65], v[102:103], v[94:95]
	s_nop 0
	v_cvt_pk_bf16_f32 v64, v64, v65
	v_cvt_pk_bf16_f32 v65, v58, v59
	v_add_f32_dpp v58, v169, v169 quad_perm:[1,0,3,2] row_mask:0xf bank_mask:0xf bound_ctrl:1
	global_store_dwordx2 v[14:15], v[64:65], off offset:512
	s_nop 0
	v_add_f32_dpp v58, v58, v58 quad_perm:[2,3,0,1] row_mask:0xf bank_mask:0xf bound_ctrl:1
	s_nop 1
	v_add_f32_dpp v58, v58, v58 row_half_mirror row_mask:0xf bank_mask:0xf bound_ctrl:1
	s_nop 1
	v_add_f32_dpp v58, v58, v58 row_mirror row_mask:0xf bank_mask:0xf bound_ctrl:1
	s_nop 0
	v_readlane_b32 s9, v58, 16
	v_readlane_b32 s14, v58, 48
	v_readlane_b32 s6, v58, 0
	v_readlane_b32 s7, v58, 32
	v_mov_b32_e32 v58, s9
	v_mov_b32_e32 v59, s14
	v_pk_add_f32 v[58:59], s[6:7], v[58:59]
	s_nop 0
	v_add_f32_e32 v58, v58, v59
	v_fmamk_f32 v58, v58, 0x3b800000, v252
	v_cmp_gt_f32_e32 vcc, s55, v58
	v_mul_f32_e32 v59, 0x4f800000, v58
	s_nop 0
	v_cndmask_b32_e32 v58, v58, v59, vcc
	v_sqrt_f32_e32 v59, v58
	s_nop 0
	v_add_u32_e32 v64, -1, v59
	v_fma_f32 v65, -v64, v59, v58
	v_cmp_ge_f32_e64 s[6:7], 0, v65
	v_add_u32_e32 v65, 1, v59
	s_nop 0
	v_cndmask_b32_e64 v64, v59, v64, s[6:7]
	v_fma_f32 v59, -v65, v59, v58
	v_cmp_lt_f32_e64 s[6:7], 0, v59
	s_nop 1
	v_cndmask_b32_e64 v59, v64, v65, s[6:7]
	v_mul_f32_e32 v64, 0x37800000, v59
	v_cndmask_b32_e32 v59, v59, v64, vcc
	v_cmp_class_f32_e32 vcc, v58, v253
	s_nop 1
	v_cndmask_b32_e32 v58, v59, v58, vcc
	v_div_scale_f32 v59, s[6:7], v58, v58, 1.0
	v_rcp_f32_e32 v64, v59
	s_nop 0
	v_fma_f32 v65, -v59, v64, 1.0
	v_fmac_f32_e32 v64, v65, v64
	v_div_scale_f32 v65, vcc, 1.0, v58, 1.0
	v_mul_f32_e32 v91, v65, v64
	v_fma_f32 v94, -v59, v91, v65
	v_fmac_f32_e32 v91, v94, v64
	v_fma_f32 v59, -v59, v91, v65
	v_div_fmas_f32 v59, v59, v64, v91
	v_div_fixup_f32 v58, v59, v58, 1.0
	v_lshlrev_b32_e32 v64, 16, v52
	v_and_b32_e32 v65, 0xffff0000, v52
	v_lshlrev_b32_e32 v52, 16, v53
	v_and_b32_e32 v53, 0xffff0000, v53
	v_pk_mul_f32 v[94:95], v[142:143], v[58:59] op_sel_hi:[1,0]
	v_pk_mul_f32 v[58:59], v[136:137], v[58:59] op_sel_hi:[1,0]
	s_nop 0
	v_pk_mul_f32 v[52:53], v[58:59], v[52:53]
	v_pk_mul_f32 v[58:59], v[94:95], v[64:65]
	s_nop 0
	v_cvt_pk_bf16_f32 v58, v58, v59
	v_cvt_pk_bf16_f32 v59, v52, v53
	v_add_f32_dpp v52, v170, v170 quad_perm:[1,0,3,2] row_mask:0xf bank_mask:0xf bound_ctrl:1
	global_store_dwordx2 v[14:15], v[58:59], off offset:1024
	s_nop 0
	v_add_f32_dpp v52, v52, v52 quad_perm:[2,3,0,1] row_mask:0xf bank_mask:0xf bound_ctrl:1
	s_nop 1
	v_add_f32_dpp v52, v52, v52 row_half_mirror row_mask:0xf bank_mask:0xf bound_ctrl:1
	s_nop 1
	v_add_f32_dpp v52, v52, v52 row_mirror row_mask:0xf bank_mask:0xf bound_ctrl:1
	s_nop 0
	v_readlane_b32 s9, v52, 16
	v_readlane_b32 s14, v52, 48
	v_readlane_b32 s6, v52, 0
	v_readlane_b32 s7, v52, 32
	v_mov_b32_e32 v52, s9
	v_mov_b32_e32 v53, s14
	v_pk_add_f32 v[52:53], s[6:7], v[52:53]
	s_nop 0
	v_add_f32_e32 v52, v52, v53
	v_fmamk_f32 v52, v52, 0x3b800000, v252
	v_cmp_gt_f32_e32 vcc, s55, v52
	v_mul_f32_e32 v53, 0x4f800000, v52
	s_nop 0
	v_cndmask_b32_e32 v52, v52, v53, vcc
	v_sqrt_f32_e32 v53, v52
	s_nop 0
	v_add_u32_e32 v58, -1, v53
	v_fma_f32 v59, -v58, v53, v52
	v_cmp_ge_f32_e64 s[6:7], 0, v59
	v_add_u32_e32 v59, 1, v53
	s_nop 0
	v_cndmask_b32_e64 v58, v53, v58, s[6:7]
	v_fma_f32 v53, -v59, v53, v52
	v_cmp_lt_f32_e64 s[6:7], 0, v53
	s_nop 1
	v_cndmask_b32_e64 v53, v58, v59, s[6:7]
	v_mul_f32_e32 v58, 0x37800000, v53
	v_cndmask_b32_e32 v53, v53, v58, vcc
	v_cmp_class_f32_e32 vcc, v52, v253
	s_nop 1
	v_cndmask_b32_e32 v52, v53, v52, vcc
	v_div_scale_f32 v53, s[6:7], v52, v52, 1.0
	v_rcp_f32_e32 v58, v53
	s_nop 0
	v_fma_f32 v59, -v53, v58, 1.0
	v_fmac_f32_e32 v58, v59, v58
	v_div_scale_f32 v59, vcc, 1.0, v52, 1.0
	v_mul_f32_e32 v64, v59, v58
	v_fma_f32 v65, -v53, v64, v59
	v_fmac_f32_e32 v64, v65, v58
	v_fma_f32 v53, -v53, v64, v59
	v_div_fmas_f32 v53, v53, v58, v64
	v_div_fixup_f32 v52, v53, v52, 1.0
	v_lshlrev_b32_e32 v58, 16, v46
	v_and_b32_e32 v59, 0xffff0000, v46
	v_lshlrev_b32_e32 v46, 16, v47
	v_and_b32_e32 v47, 0xffff0000, v47
	v_pk_mul_f32 v[64:65], v[130:131], v[52:53] op_sel_hi:[1,0]
	v_pk_mul_f32 v[52:53], v[126:127], v[52:53] op_sel_hi:[1,0]
	s_nop 0
	v_pk_mul_f32 v[46:47], v[52:53], v[46:47]
	v_pk_mul_f32 v[52:53], v[64:65], v[58:59]
	s_nop 0
	v_cvt_pk_bf16_f32 v52, v52, v53
	v_cvt_pk_bf16_f32 v53, v46, v47
	v_add_f32_dpp v46, v166, v166 quad_perm:[1,0,3,2] row_mask:0xf bank_mask:0xf bound_ctrl:1
	global_store_dwordx2 v[14:15], v[52:53], off offset:1536
	s_nop 0
	v_add_f32_dpp v46, v46, v46 quad_perm:[2,3,0,1] row_mask:0xf bank_mask:0xf bound_ctrl:1
	s_nop 1
	v_add_f32_dpp v46, v46, v46 row_half_mirror row_mask:0xf bank_mask:0xf bound_ctrl:1
	s_nop 1
	v_add_f32_dpp v46, v46, v46 row_mirror row_mask:0xf bank_mask:0xf bound_ctrl:1
	s_nop 0
	v_readlane_b32 s9, v46, 16
	v_readlane_b32 s14, v46, 48
	v_readlane_b32 s6, v46, 0
	v_readlane_b32 s7, v46, 32
	v_mov_b32_e32 v46, s9
	v_mov_b32_e32 v47, s14
	v_pk_add_f32 v[46:47], s[6:7], v[46:47]
	s_nop 0
	v_add_f32_e32 v46, v46, v47
	v_fmamk_f32 v46, v46, 0x3b800000, v252
	v_cmp_gt_f32_e32 vcc, s55, v46
	v_mul_f32_e32 v47, 0x4f800000, v46
	s_nop 0
	v_cndmask_b32_e32 v46, v46, v47, vcc
	v_sqrt_f32_e32 v47, v46
	s_nop 0
	v_add_u32_e32 v52, -1, v47
	v_fma_f32 v53, -v52, v47, v46
	v_cmp_ge_f32_e64 s[6:7], 0, v53
	v_add_u32_e32 v53, 1, v47
	s_nop 0
	v_cndmask_b32_e64 v52, v47, v52, s[6:7]
	v_fma_f32 v47, -v53, v47, v46
	v_cmp_lt_f32_e64 s[6:7], 0, v47
	s_nop 1
	v_cndmask_b32_e64 v47, v52, v53, s[6:7]
	v_mul_f32_e32 v52, 0x37800000, v47
	v_cndmask_b32_e32 v47, v47, v52, vcc
	v_cmp_class_f32_e32 vcc, v46, v253
	s_nop 1
	v_cndmask_b32_e32 v46, v47, v46, vcc
	v_div_scale_f32 v47, s[6:7], v46, v46, 1.0
	v_rcp_f32_e32 v52, v47
	s_nop 0
	v_fma_f32 v53, -v47, v52, 1.0
	v_fmac_f32_e32 v52, v53, v52
	v_div_scale_f32 v53, vcc, 1.0, v46, 1.0
	v_mul_f32_e32 v58, v53, v52
	v_fma_f32 v59, -v47, v58, v53
	v_fmac_f32_e32 v58, v59, v52
	v_fma_f32 v47, -v47, v58, v53
	v_div_fmas_f32 v47, v47, v52, v58
	v_div_fixup_f32 v46, v47, v46, 1.0
	v_lshlrev_b32_e32 v52, 16, v40
	v_and_b32_e32 v53, 0xffff0000, v40
	v_lshlrev_b32_e32 v40, 16, v41
	v_and_b32_e32 v41, 0xffff0000, v41
	v_pk_mul_f32 v[58:59], v[122:123], v[46:47] op_sel_hi:[1,0]
	v_pk_mul_f32 v[46:47], v[118:119], v[46:47] op_sel_hi:[1,0]
	s_nop 0
	v_pk_mul_f32 v[40:41], v[46:47], v[40:41]
	v_pk_mul_f32 v[46:47], v[58:59], v[52:53]
	s_nop 0
	v_cvt_pk_bf16_f32 v46, v46, v47
	v_cvt_pk_bf16_f32 v47, v40, v41
	v_add_f32_dpp v40, v110, v110 quad_perm:[1,0,3,2] row_mask:0xf bank_mask:0xf bound_ctrl:1
	global_store_dwordx2 v[14:15], v[46:47], off offset:2048
	s_nop 0
	v_add_f32_dpp v40, v40, v40 quad_perm:[2,3,0,1] row_mask:0xf bank_mask:0xf bound_ctrl:1
	s_nop 1
	v_add_f32_dpp v40, v40, v40 row_half_mirror row_mask:0xf bank_mask:0xf bound_ctrl:1
	s_nop 1
	v_add_f32_dpp v40, v40, v40 row_mirror row_mask:0xf bank_mask:0xf bound_ctrl:1
	s_nop 0
	v_readlane_b32 s9, v40, 16
	v_readlane_b32 s14, v40, 48
	v_readlane_b32 s6, v40, 0
	v_readlane_b32 s7, v40, 32
	v_mov_b32_e32 v40, s9
	v_mov_b32_e32 v41, s14
	v_pk_add_f32 v[40:41], s[6:7], v[40:41]
	s_nop 0
	v_add_f32_e32 v40, v40, v41
	v_fmamk_f32 v40, v40, 0x3b800000, v252
	v_cmp_gt_f32_e32 vcc, s55, v40
	v_mul_f32_e32 v41, 0x4f800000, v40
	s_nop 0
	v_cndmask_b32_e32 v40, v40, v41, vcc
	v_sqrt_f32_e32 v41, v40
	s_nop 0
	v_add_u32_e32 v46, -1, v41
	v_fma_f32 v47, -v46, v41, v40
	v_cmp_ge_f32_e64 s[6:7], 0, v47
	v_add_u32_e32 v47, 1, v41
	s_nop 0
	v_cndmask_b32_e64 v46, v41, v46, s[6:7]
	v_fma_f32 v41, -v47, v41, v40
	v_cmp_lt_f32_e64 s[6:7], 0, v41
	s_nop 1
	v_cndmask_b32_e64 v41, v46, v47, s[6:7]
	v_mul_f32_e32 v46, 0x37800000, v41
	v_cndmask_b32_e32 v41, v41, v46, vcc
	v_cmp_class_f32_e32 vcc, v40, v253
	s_nop 1
	v_cndmask_b32_e32 v40, v41, v40, vcc
	v_div_scale_f32 v41, s[6:7], v40, v40, 1.0
	v_rcp_f32_e32 v46, v41
	s_nop 0
	v_fma_f32 v47, -v41, v46, 1.0
	v_fmac_f32_e32 v46, v47, v46
	v_div_scale_f32 v47, vcc, 1.0, v40, 1.0
	v_mul_f32_e32 v52, v47, v46
	v_fma_f32 v53, -v41, v52, v47
	v_fmac_f32_e32 v52, v53, v46
	v_fma_f32 v41, -v41, v52, v47
	v_div_fmas_f32 v41, v41, v46, v52
	v_div_fixup_f32 v40, v41, v40, 1.0
	v_lshlrev_b32_e32 v46, 16, v24
	v_and_b32_e32 v47, 0xffff0000, v24
	v_lshlrev_b32_e32 v24, 16, v25
	v_and_b32_e32 v25, 0xffff0000, v25
	v_pk_mul_f32 v[52:53], v[114:115], v[40:41] op_sel_hi:[1,0]
	v_pk_mul_f32 v[40:41], v[106:107], v[40:41] op_sel_hi:[1,0]
	s_nop 0
	v_pk_mul_f32 v[24:25], v[40:41], v[24:25]
	v_pk_mul_f32 v[40:41], v[52:53], v[46:47]
	s_waitcnt vmcnt(38)
; template <bool HG>
; __device__ __forceinline__ void readout_phase2(const Args& a, Frame& F, const float* gain, int nrows) {
;     ...
;     RO_FINISH(f0, b0, g0, nw + 3 * 2048); RO_LOAD(f0, b0, g0, nw + 6 * 2048);
	v_lshlrev_b32_e32 v52, 16, v97
	v_cvt_pk_bf16_f32 v40, v40, v41
	v_cvt_pk_bf16_f32 v41, v24, v25
	v_add_f32_dpp v24, v98, v98 quad_perm:[1,0,3,2] row_mask:0xf bank_mask:0xf bound_ctrl:1
	global_store_dwordx2 v[14:15], v[40:41], off offset:2560
	v_and_b32_e32 v53, 0xffff0000, v97
	v_add_f32_dpp v24, v24, v24 quad_perm:[2,3,0,1] row_mask:0xf bank_mask:0xf bound_ctrl:1
	s_nop 1
	v_add_f32_dpp v24, v24, v24 row_half_mirror row_mask:0xf bank_mask:0xf bound_ctrl:1
	s_nop 1
	v_add_f32_dpp v24, v24, v24 row_mirror row_mask:0xf bank_mask:0xf bound_ctrl:1
	s_nop 0
	v_readlane_b32 s9, v24, 16
	v_readlane_b32 s14, v24, 48
	v_readlane_b32 s6, v24, 0
	v_readlane_b32 s7, v24, 32
	v_mov_b32_e32 v24, s9
	v_mov_b32_e32 v25, s14
	v_pk_add_f32 v[24:25], s[6:7], v[24:25]
	s_nop 0
	v_add_f32_e32 v24, v24, v25
	v_fmamk_f32 v24, v24, 0x3b800000, v252
	v_cmp_gt_f32_e32 vcc, s55, v24
	v_mul_f32_e32 v25, 0x4f800000, v24
	s_nop 0
	v_cndmask_b32_e32 v24, v24, v25, vcc
	v_sqrt_f32_e32 v25, v24
	s_nop 0
	v_add_u32_e32 v40, -1, v25
	v_fma_f32 v41, -v40, v25, v24
	v_cmp_ge_f32_e64 s[6:7], 0, v41
	v_add_u32_e32 v41, 1, v25
	s_nop 0
	v_cndmask_b32_e64 v40, v25, v40, s[6:7]
	v_fma_f32 v25, -v41, v25, v24
	v_cmp_lt_f32_e64 s[6:7], 0, v25
	s_nop 1
	v_cndmask_b32_e64 v25, v40, v41, s[6:7]
	v_mul_f32_e32 v40, 0x37800000, v25
	v_cndmask_b32_e32 v25, v25, v40, vcc
	v_cmp_class_f32_e32 vcc, v24, v253
	s_nop 1
	v_cndmask_b32_e32 v24, v25, v24, vcc
	v_div_scale_f32 v25, s[6:7], v24, v24, 1.0
	v_rcp_f32_e32 v40, v25
	s_nop 0
	v_fma_f32 v41, -v25, v40, 1.0
	v_fmac_f32_e32 v40, v41, v40
	v_div_scale_f32 v41, vcc, 1.0, v24, 1.0
	v_mul_f32_e32 v46, v41, v40
	v_fma_f32 v47, -v25, v46, v41
	v_fmac_f32_e32 v46, v47, v40
	v_fma_f32 v25, -v25, v46, v41
	v_div_fmas_f32 v25, v25, v40, v46
	v_div_fixup_f32 v24, v25, v24, 1.0
	v_lshlrev_b32_e32 v40, 16, v20
	v_and_b32_e32 v41, 0xffff0000, v20
	v_lshlrev_b32_e32 v20, 16, v21
	v_and_b32_e32 v21, 0xffff0000, v21
	v_pk_mul_f32 v[18:19], v[18:19], v[24:25] op_sel_hi:[1,0]
	v_pk_mul_f32 v[22:23], v[22:23], v[24:25] op_sel_hi:[1,0]
	v_pk_mul_f32 v[18:19], v[18:19], v[40:41]
	v_pk_mul_f32 v[20:21], v[22:23], v[20:21]
	v_cvt_pk_bf16_f32 v18, v18, v19
	v_cvt_pk_bf16_f32 v19, v20, v21
	global_store_dwordx2 v[14:15], v[18:19], off offset:3072
	v_add_f32_dpp v18, v90, v90 quad_perm:[1,0,3,2] row_mask:0xf bank_mask:0xf bound_ctrl:1
	s_nop 1
	v_add_f32_dpp v18, v18, v18 quad_perm:[2,3,0,1] row_mask:0xf bank_mask:0xf bound_ctrl:1
	s_nop 1
	v_add_f32_dpp v18, v18, v18 row_half_mirror row_mask:0xf bank_mask:0xf bound_ctrl:1
	s_nop 1
	v_add_f32_dpp v18, v18, v18 row_mirror row_mask:0xf bank_mask:0xf bound_ctrl:1
	s_nop 0
	v_readlane_b32 s9, v18, 16
	v_readlane_b32 s14, v18, 48
	v_readlane_b32 s6, v18, 0
	v_readlane_b32 s7, v18, 32
	v_mov_b32_e32 v18, s9
	v_mov_b32_e32 v19, s14
	v_pk_add_f32 v[18:19], s[6:7], v[18:19]
	s_nop 0
	v_add_f32_e32 v18, v18, v19
	v_fmamk_f32 v18, v18, 0x3b800000, v252
	v_cmp_gt_f32_e32 vcc, s55, v18
	v_mul_f32_e32 v19, 0x4f800000, v18
	s_nop 0
	v_cndmask_b32_e32 v18, v18, v19, vcc
	v_sqrt_f32_e32 v19, v18
	s_nop 0
	v_add_u32_e32 v20, -1, v19
	v_fma_f32 v21, -v20, v19, v18
	v_cmp_ge_f32_e64 s[6:7], 0, v21
	v_add_u32_e32 v21, 1, v19
	s_nop 0
	v_cndmask_b32_e64 v20, v19, v20, s[6:7]
	v_fma_f32 v19, -v21, v19, v18
	v_cmp_lt_f32_e64 s[6:7], 0, v19
	s_nop 1
	v_cndmask_b32_e64 v19, v20, v21, s[6:7]
	v_mul_f32_e32 v20, 0x37800000, v19
	v_cndmask_b32_e32 v19, v19, v20, vcc
	v_cmp_class_f32_e32 vcc, v18, v253
	s_nop 1
	v_cndmask_b32_e32 v18, v19, v18, vcc
	v_div_scale_f32 v19, s[6:7], v18, v18, 1.0
	v_rcp_f32_e32 v20, v19
	s_nop 0
	v_fma_f32 v21, -v19, v20, 1.0
	v_fmac_f32_e32 v20, v21, v20
	v_div_scale_f32 v21, vcc, 1.0, v18, 1.0
	v_mul_f32_e32 v22, v21, v20
	v_fma_f32 v23, -v19, v22, v21
	v_fmac_f32_e32 v22, v23, v20
	v_fma_f32 v19, -v19, v22, v21
	v_div_fmas_f32 v19, v19, v20, v22
	v_div_fixup_f32 v18, v19, v18, 1.0
	v_lshlrev_b32_e32 v20, 16, v16
	v_and_b32_e32 v21, 0xffff0000, v16
	v_lshlrev_b32_e32 v16, 16, v17
	v_and_b32_e32 v17, 0xffff0000, v17
	v_pk_mul_f32 v[10:11], v[10:11], v[18:19] op_sel_hi:[1,0]
	v_pk_mul_f32 v[12:13], v[12:13], v[18:19] op_sel_hi:[1,0]
	v_pk_mul_f32 v[10:11], v[10:11], v[20:21]
	v_pk_mul_f32 v[12:13], v[12:13], v[16:17]
	v_cvt_pk_bf16_f32 v10, v10, v11
	v_cvt_pk_bf16_f32 v11, v12, v13
	v_lshl_add_u64 v[12:13], v[6:7], 0, s[40:41]
	global_store_dwordx2 v[14:15], v[10:11], off offset:3584
	v_lshl_add_u64 v[10:11], v[4:5], 0, s[40:41]
	v_lshl_add_u64 v[40:41], v[12:13], 0, v[0:1]
	v_lshl_add_u64 v[12:13], v[8:9], 0, s[40:41]
	v_lshl_add_u64 v[10:11], v[10:11], 0, v[0:1]
	v_lshl_add_u64 v[46:47], v[12:13], 0, v[0:1]
	global_load_dwordx2 v[148:149], v[10:11], off nt
	global_load_dwordx2 v[142:143], v[40:41], off nt
	global_load_dwordx2 v[24:25], v[46:47], off nt
	global_load_dwordx2 v[136:137], v[10:11], off offset:512 nt
	global_load_dwordx2 v[130:131], v[40:41], off offset:512 nt
	global_load_dwordx2 v[22:23], v[46:47], off offset:512 nt
	global_load_dwordx2 v[126:127], v[10:11], off offset:1024 nt
	global_load_dwordx2 v[122:123], v[40:41], off offset:1024 nt
	global_load_dwordx2 v[20:21], v[46:47], off offset:1024 nt
	global_load_dwordx2 v[114:115], v[10:11], off offset:1536 nt
	global_load_dwordx2 v[118:119], v[40:41], off offset:1536 nt
	global_load_dwordx2 v[18:19], v[46:47], off offset:1536 nt
	global_load_dwordx2 v[110:111], v[10:11], off offset:2048 nt
	global_load_dwordx2 v[106:107], v[40:41], off offset:2048 nt
	global_load_dwordx2 v[16:17], v[46:47], off offset:2048 nt
	global_load_dwordx2 v[102:103], v[10:11], off offset:2560 nt
	global_load_dwordx2 v[98:99], v[40:41], off offset:2560 nt
; template <bool HG>
; __device__ __forceinline__ void readout_phase2(const Args& a, Frame& F, const float* gain, int nrows) {
;     ...
;     RO_FINISH(f0, b0, g0, nw + 3 * 2048); RO_LOAD(f0, b0, g0, nw + 6 * 2048);
;     RO_FINISH(f1, b1, g1, nw + 4 * 2048); RO_LOAD(f1, b1, g1, nw + 7 * 2048);
	global_load_dwordx2 v[14:15], v[46:47], off offset:2560 nt
	global_load_dwordx2 v[94:95], v[10:11], off offset:3072 nt
	global_load_dwordx2 v[90:91], v[40:41], off offset:3072 nt
	global_load_dwordx2 v[12:13], v[46:47], off offset:3072 nt
	global_load_dwordx2 v[58:59], v[10:11], off offset:3584 nt
	global_load_dwordx2 v[64:65], v[40:41], off offset:3584 nt
	s_nop 0
	global_load_dwordx2 v[10:11], v[46:47], off offset:3584 nt
	v_lshlrev_b32_e32 v40, 16, v162
	v_and_b32_e32 v41, 0xffff0000, v162
	v_lshlrev_b32_e32 v46, 16, v156
	v_and_b32_e32 v47, 0xffff0000, v156
	v_pk_add_f32 v[160:161], v[40:41], v[46:47]
	v_lshlrev_b32_e32 v40, 16, v163
	v_and_b32_e32 v41, 0xffff0000, v163
	v_lshlrev_b32_e32 v46, 16, v157
	v_and_b32_e32 v47, 0xffff0000, v157
	v_pk_add_f32 v[156:157], v[40:41], v[46:47]
	v_mov_b32_e32 v46, v161
	v_mov_b32_e32 v47, v157
	v_mov_b32_e32 v40, v160
	v_mov_b32_e32 v41, v156
	v_pk_mul_f32 v[46:47], v[46:47], v[46:47]
	s_nop 0
	v_pk_fma_f32 v[40:41], v[40:41], v[40:41], v[46:47]
	v_lshlrev_b32_e32 v46, 16, v144
	v_add_f32_e32 v164, v40, v41
	v_lshlrev_b32_e32 v40, 16, v150
	v_and_b32_e32 v41, 0xffff0000, v150
	v_and_b32_e32 v47, 0xffff0000, v144
	v_pk_add_f32 v[154:155], v[40:41], v[46:47]
	v_lshlrev_b32_e32 v40, 16, v151
	v_and_b32_e32 v41, 0xffff0000, v151
	v_lshlrev_b32_e32 v46, 16, v145
	v_and_b32_e32 v47, 0xffff0000, v145
	v_pk_add_f32 v[150:151], v[40:41], v[46:47]
	v_mov_b32_e32 v46, v155
	v_mov_b32_e32 v47, v151
	v_mov_b32_e32 v40, v154
	v_mov_b32_e32 v41, v150
	v_pk_mul_f32 v[46:47], v[46:47], v[46:47]
	s_nop 0
	v_pk_fma_f32 v[40:41], v[40:41], v[40:41], v[46:47]
	v_lshlrev_b32_e32 v46, 16, v132
	v_add_f32_e32 v166, v40, v41
	v_lshlrev_b32_e32 v40, 16, v138
	v_and_b32_e32 v41, 0xffff0000, v138
	v_and_b32_e32 v47, 0xffff0000, v132
	v_pk_add_f32 v[144:145], v[40:41], v[46:47]
	v_lshlrev_b32_e32 v40, 16, v139
	v_and_b32_e32 v41, 0xffff0000, v139
	v_lshlrev_b32_e32 v46, 16, v133
	v_and_b32_e32 v47, 0xffff0000, v133
	v_pk_add_f32 v[138:139], v[40:41], v[46:47]
	v_mov_b32_e32 v46, v145
	v_mov_b32_e32 v47, v139
	v_mov_b32_e32 v40, v144
	v_mov_b32_e32 v41, v138
	v_pk_mul_f32 v[46:47], v[46:47], v[46:47]
	s_nop 0
	v_pk_fma_f32 v[40:41], v[40:41], v[40:41], v[46:47]
	v_lshlrev_b32_e32 v46, 16, v128
	v_add_f32_e32 v167, v40, v41
	v_lshlrev_b32_e32 v40, 16, v124
	v_and_b32_e32 v41, 0xffff0000, v124
	v_and_b32_e32 v47, 0xffff0000, v128
	v_pk_add_f32 v[132:133], v[40:41], v[46:47]
	v_lshlrev_b32_e32 v40, 16, v125
	v_and_b32_e32 v41, 0xffff0000, v125
	v_lshlrev_b32_e32 v46, 16, v129
	v_and_b32_e32 v47, 0xffff0000, v129
	v_pk_add_f32 v[128:129], v[40:41], v[46:47]
	v_mov_b32_e32 v46, v133
	v_mov_b32_e32 v47, v129
	v_mov_b32_e32 v40, v132
	v_mov_b32_e32 v41, v128
	v_pk_mul_f32 v[46:47], v[46:47], v[46:47]
	s_nop 0
	v_pk_fma_f32 v[40:41], v[40:41], v[40:41], v[46:47]
	v_lshlrev_b32_e32 v46, 16, v116
	v_add_f32_e32 v168, v40, v41
	v_lshlrev_b32_e32 v40, 16, v120
	v_and_b32_e32 v41, 0xffff0000, v120
	v_and_b32_e32 v47, 0xffff0000, v116
	v_pk_add_f32 v[124:125], v[40:41], v[46:47]
	v_lshlrev_b32_e32 v40, 16, v121
	v_and_b32_e32 v41, 0xffff0000, v121
	v_lshlrev_b32_e32 v46, 16, v117
	v_and_b32_e32 v47, 0xffff0000, v117
	v_pk_add_f32 v[120:121], v[40:41], v[46:47]
	v_mov_b32_e32 v46, v125
	v_mov_b32_e32 v47, v121
	v_mov_b32_e32 v40, v124
	v_mov_b32_e32 v41, v120
	v_pk_mul_f32 v[46:47], v[46:47], v[46:47]
	s_nop 0
	v_pk_fma_f32 v[40:41], v[40:41], v[40:41], v[46:47]
	v_lshlrev_b32_e32 v46, 16, v108
	v_add_f32_e32 v163, v40, v41
	v_lshlrev_b32_e32 v40, 16, v112
	v_and_b32_e32 v41, 0xffff0000, v112
	v_and_b32_e32 v47, 0xffff0000, v108
	v_pk_add_f32 v[116:117], v[40:41], v[46:47]
	v_lshlrev_b32_e32 v40, 16, v113
	v_and_b32_e32 v41, 0xffff0000, v113
	v_lshlrev_b32_e32 v46, 16, v109
	v_and_b32_e32 v47, 0xffff0000, v109
	v_pk_add_f32 v[112:113], v[40:41], v[46:47]
	v_mov_b32_e32 v46, v117
	v_mov_b32_e32 v47, v113
	v_mov_b32_e32 v40, v116
	v_mov_b32_e32 v41, v112
	v_pk_mul_f32 v[46:47], v[46:47], v[46:47]
	s_nop 0
	v_pk_fma_f32 v[40:41], v[40:41], v[40:41], v[46:47]
	v_lshlrev_b32_e32 v46, 16, v100
	v_add_f32_e32 v162, v40, v41
	v_lshlrev_b32_e32 v40, 16, v104
	v_and_b32_e32 v41, 0xffff0000, v104
	v_and_b32_e32 v47, 0xffff0000, v100
	v_pk_add_f32 v[108:109], v[40:41], v[46:47]
	v_lshlrev_b32_e32 v40, 16, v105
	v_and_b32_e32 v41, 0xffff0000, v105
	v_lshlrev_b32_e32 v46, 16, v101
	v_and_b32_e32 v47, 0xffff0000, v101
	v_pk_add_f32 v[100:101], v[40:41], v[46:47]
	v_mov_b32_e32 v46, v109
	v_mov_b32_e32 v47, v101
	v_mov_b32_e32 v40, v108
	v_mov_b32_e32 v41, v100
	v_pk_mul_f32 v[46:47], v[46:47], v[46:47]
	s_nop 0
	v_pk_fma_f32 v[40:41], v[40:41], v[40:41], v[46:47]
	v_lshlrev_b32_e32 v46, 16, v96
	v_add_f32_e32 v104, v40, v41
	v_lshlrev_b32_e32 v40, 16, v92
	v_and_b32_e32 v41, 0xffff0000, v92
	v_and_b32_e32 v47, 0xffff0000, v96
	v_pk_add_f32 v[40:41], v[40:41], v[46:47]
	v_lshlrev_b32_e32 v46, 16, v93
	v_and_b32_e32 v47, 0xffff0000, v93
	v_pk_add_f32 v[46:47], v[46:47], v[52:53]
	v_mov_b32_e32 v92, v41
	v_mov_b32_e32 v93, v47
	v_mov_b32_e32 v52, v40
	v_mov_b32_e32 v53, v46
	v_pk_mul_f32 v[92:93], v[92:93], v[92:93]
	s_nop 0
	v_pk_fma_f32 v[52:53], v[52:53], v[52:53], v[92:93]
	v_add_f32_dpp v93, v164, v164 quad_perm:[1,0,3,2] row_mask:0xf bank_mask:0xf bound_ctrl:1
	v_add_f32_e32 v92, v52, v53
	v_lshl_add_u64 v[52:53], v[2:3], 0, s[16:17]
	v_add_f32_dpp v93, v93, v93 quad_perm:[2,3,0,1] row_mask:0xf bank_mask:0xf bound_ctrl:1
	v_lshl_add_u64 v[52:53], v[52:53], 0, v[0:1]
	s_nop 0
	v_add_f32_dpp v93, v93, v93 row_half_mirror row_mask:0xf bank_mask:0xf bound_ctrl:1
	s_nop 1
	v_add_f32_dpp v93, v93, v93 row_mirror row_mask:0xf bank_mask:0xf bound_ctrl:1
	s_nop 0
	v_readlane_b32 s9, v93, 16
	v_readlane_b32 s10, v93, 48
	v_readlane_b32 s6, v93, 0
	v_readlane_b32 s7, v93, 32
	v_mov_b32_e32 v96, s9
	v_mov_b32_e32 v97, s10
	v_pk_add_f32 v[96:97], s[6:7], v[96:97]
	s_nop 0
	v_add_f32_e32 v93, v96, v97
	v_fmamk_f32 v93, v93, 0x3b800000, v252
	v_cmp_gt_f32_e32 vcc, s55, v93
	v_mul_f32_e32 v96, 0x4f800000, v93
	s_nop 0
	v_cndmask_b32_e32 v93, v93, v96, vcc
	v_sqrt_f32_e32 v96, v93
	s_nop 0
	v_add_u32_e32 v97, -1, v96
	v_fma_f32 v105, -v97, v96, v93
	v_cmp_ge_f32_e64 s[6:7], 0, v105
	v_add_u32_e32 v105, 1, v96
	s_nop 0
	v_cndmask_b32_e64 v97, v96, v97, s[6:7]
	v_fma_f32 v96, -v105, v96, v93
	v_cmp_lt_f32_e64 s[6:7], 0, v96
	s_nop 1
	v_cndmask_b32_e64 v96, v97, v105, s[6:7]
	v_mul_f32_e32 v97, 0x37800000, v96
	v_cndmask_b32_e32 v96, v96, v97, vcc
	v_cmp_class_f32_e32 vcc, v93, v253
	s_nop 1
	v_cndmask_b32_e32 v93, v96, v93, vcc
	v_div_scale_f32 v96, s[6:7], v93, v93, 1.0
	v_rcp_f32_e32 v97, v96
	s_nop 0
	v_fma_f32 v105, -v96, v97, 1.0
	v_fmac_f32_e32 v97, v105, v97
	v_div_scale_f32 v105, vcc, 1.0, v93, 1.0
	v_mul_f32_e32 v164, v105, v97
	v_fma_f32 v165, -v96, v164, v105
	v_fmac_f32_e32 v164, v165, v97
	v_fma_f32 v96, -v96, v164, v105
	v_div_fmas_f32 v96, v96, v97, v164
	v_div_fixup_f32 v96, v96, v93, 1.0
	v_lshlrev_b32_e32 v164, 16, v66
	v_and_b32_e32 v165, 0xffff0000, v66
	v_lshlrev_b32_e32 v66, 16, v67
	v_and_b32_e32 v67, 0xffff0000, v67
	v_pk_mul_f32 v[160:161], v[160:161], v[96:97] op_sel_hi:[1,0]
	v_pk_mul_f32 v[96:97], v[156:157], v[96:97] op_sel_hi:[1,0]
	s_nop 0
	v_pk_mul_f32 v[66:67], v[96:97], v[66:67]
	v_pk_mul_f32 v[96:97], v[160:161], v[164:165]
	s_waitcnt vmcnt(33)
	v_lshlrev_b32_e32 v160, 16, v70
	v_cvt_pk_bf16_f32 v96, v96, v97
	v_cvt_pk_bf16_f32 v97, v66, v67
	v_add_f32_dpp v66, v166, v166 quad_perm:[1,0,3,2] row_mask:0xf bank_mask:0xf bound_ctrl:1
	global_store_dwordx2 v[52:53], v[96:97], off
	v_and_b32_e32 v161, 0xffff0000, v70
	v_add_f32_dpp v66, v66, v66 quad_perm:[2,3,0,1] row_mask:0xf bank_mask:0xf bound_ctrl:1
	v_lshlrev_b32_e32 v70, 16, v71
	v_and_b32_e32 v71, 0xffff0000, v71
	v_add_f32_dpp v66, v66, v66 row_half_mirror row_mask:0xf bank_mask:0xf bound_ctrl:1
	s_nop 1
	v_add_f32_dpp v66, v66, v66 row_mirror row_mask:0xf bank_mask:0xf bound_ctrl:1
	s_nop 0
	v_readlane_b32 s9, v66, 16
	v_readlane_b32 s10, v66, 48
	v_readlane_b32 s6, v66, 0
	v_readlane_b32 s7, v66, 32
	v_mov_b32_e32 v66, s9
	v_mov_b32_e32 v67, s10
	v_pk_add_f32 v[66:67], s[6:7], v[66:67]
	s_nop 0
	v_add_f32_e32 v66, v66, v67
	v_fmamk_f32 v66, v66, 0x3b800000, v252
	v_cmp_gt_f32_e32 vcc, s55, v66
	v_mul_f32_e32 v67, 0x4f800000, v66
	s_nop 0
	v_cndmask_b32_e32 v66, v66, v67, vcc
	v_sqrt_f32_e32 v67, v66
	s_nop 0
	v_add_u32_e32 v93, -1, v67
	v_fma_f32 v96, -v93, v67, v66
	v_cmp_ge_f32_e64 s[6:7], 0, v96
	v_add_u32_e32 v96, 1, v67
	s_nop 0
	v_cndmask_b32_e64 v93, v67, v93, s[6:7]
	v_fma_f32 v67, -v96, v67, v66
	v_cmp_lt_f32_e64 s[6:7], 0, v67
	s_nop 1
	v_cndmask_b32_e64 v67, v93, v96, s[6:7]
	v_mul_f32_e32 v93, 0x37800000, v67
	v_cndmask_b32_e32 v67, v67, v93, vcc
	v_cmp_class_f32_e32 vcc, v66, v253
	s_nop 1
	v_cndmask_b32_e32 v66, v67, v66, vcc
	v_div_scale_f32 v67, s[6:7], v66, v66, 1.0
	v_rcp_f32_e32 v93, v67
	s_nop 0
	v_fma_f32 v96, -v67, v93, 1.0
	v_fmac_f32_e32 v93, v96, v93
	v_div_scale_f32 v96, vcc, 1.0, v66, 1.0
	v_mul_f32_e32 v97, v96, v93
	v_fma_f32 v105, -v67, v97, v96
	v_fmac_f32_e32 v97, v105, v93
	v_fma_f32 v67, -v67, v97, v96
	v_div_fmas_f32 v67, v67, v93, v97
	v_div_fixup_f32 v66, v67, v66, 1.0
	v_lshlrev_b32_e32 v96, 16, v60
	v_and_b32_e32 v97, 0xffff0000, v60
	v_lshlrev_b32_e32 v60, 16, v61
	v_and_b32_e32 v61, 0xffff0000, v61
	v_pk_mul_f32 v[154:155], v[154:155], v[66:67] op_sel_hi:[1,0]
	v_pk_mul_f32 v[66:67], v[150:151], v[66:67] op_sel_hi:[1,0]
	s_nop 0
	v_pk_mul_f32 v[60:61], v[66:67], v[60:61]
	v_pk_mul_f32 v[66:67], v[154:155], v[96:97]
	v_lshlrev_b32_e32 v154, 16, v152
	v_cvt_pk_bf16_f32 v66, v66, v67
	v_cvt_pk_bf16_f32 v67, v60, v61
	v_add_f32_dpp v60, v167, v167 quad_perm:[1,0,3,2] row_mask:0xf bank_mask:0xf bound_ctrl:1
	global_store_dwordx2 v[52:53], v[66:67], off offset:512
	v_and_b32_e32 v155, 0xffff0000, v152
	v_add_f32_dpp v60, v60, v60 quad_perm:[2,3,0,1] row_mask:0xf bank_mask:0xf bound_ctrl:1
	v_lshlrev_b32_e32 v152, 16, v153
	v_and_b32_e32 v153, 0xffff0000, v153
	v_add_f32_dpp v60, v60, v60 row_half_mirror row_mask:0xf bank_mask:0xf bound_ctrl:1
	s_nop 1
	v_add_f32_dpp v60, v60, v60 row_mirror row_mask:0xf bank_mask:0xf bound_ctrl:1
	s_nop 0
	v_readlane_b32 s9, v60, 16
	v_readlane_b32 s10, v60, 48
	v_readlane_b32 s6, v60, 0
	v_readlane_b32 s7, v60, 32
	v_mov_b32_e32 v60, s9
	v_mov_b32_e32 v61, s10
	v_pk_add_f32 v[60:61], s[6:7], v[60:61]
	s_nop 0
	v_add_f32_e32 v60, v60, v61
	v_fmamk_f32 v60, v60, 0x3b800000, v252
	v_cmp_gt_f32_e32 vcc, s55, v60
	v_mul_f32_e32 v61, 0x4f800000, v60
	s_nop 0
	v_cndmask_b32_e32 v60, v60, v61, vcc
	v_sqrt_f32_e32 v61, v60
	s_nop 0
	v_add_u32_e32 v66, -1, v61
	v_fma_f32 v67, -v66, v61, v60
	v_cmp_ge_f32_e64 s[6:7], 0, v67
	v_add_u32_e32 v67, 1, v61
	s_nop 0
	v_cndmask_b32_e64 v66, v61, v66, s[6:7]
	v_fma_f32 v61, -v67, v61, v60
	v_cmp_lt_f32_e64 s[6:7], 0, v61
	s_nop 1
	v_cndmask_b32_e64 v61, v66, v67, s[6:7]
	v_mul_f32_e32 v66, 0x37800000, v61
	v_cndmask_b32_e32 v61, v61, v66, vcc
	v_cmp_class_f32_e32 vcc, v60, v253
	s_nop 1
	v_cndmask_b32_e32 v60, v61, v60, vcc
	v_div_scale_f32 v61, s[6:7], v60, v60, 1.0
	v_rcp_f32_e32 v66, v61
	s_nop 0
	v_fma_f32 v67, -v61, v66, 1.0
	v_fmac_f32_e32 v66, v67, v66
	v_div_scale_f32 v67, vcc, 1.0, v60, 1.0
	v_mul_f32_e32 v93, v67, v66
	v_fma_f32 v96, -v61, v93, v67
	v_fmac_f32_e32 v93, v96, v66
	v_fma_f32 v61, -v61, v93, v67
; template <int CTRL> __device__ __forceinline__ float dpp_mov(float v) { return __builtin_bit_cast(float, __builtin_amdgcn_update_dpp(0, __builtin_bit_cast(int, v), CTRL, 0xF, 0xF, true)); }
; __device__ __forceinline__ float wave_sum(float v) {
;     v += dpp_mov<0xB1>(v);
;     v += dpp_mov<0x4E>(v);
;     v += dpp_mov<0x141>(v);
;     v += dpp_mov<0x140>(v);
;     const int iv = __builtin_bit_cast(int, v);
;     const float a = __builtin_bit_cast(float, __builtin_amdgcn_readlane(iv, 0)), b = __builtin_bit_cast(float, __builtin_amdgcn_readlane(iv, 16));
;     const float c = __builtin_bit_cast(float, __builtin_amdgcn_readlane(iv, 32)), d = __builtin_bit_cast(float, __builtin_amdgcn_readlane(iv, 48));
;     return (a + b) + (c + d);
; }
	v_div_fmas_f32 v61, v61, v66, v93
	v_div_fixup_f32 v60, v61, v60, 1.0
	v_lshlrev_b32_e32 v66, 16, v54
	v_and_b32_e32 v67, 0xffff0000, v54
	v_lshlrev_b32_e32 v54, 16, v55
	v_and_b32_e32 v55, 0xffff0000, v55
	v_pk_mul_f32 v[96:97], v[144:145], v[60:61] op_sel_hi:[1,0]
	v_pk_mul_f32 v[60:61], v[138:139], v[60:61] op_sel_hi:[1,0]
	s_nop 0
	v_pk_mul_f32 v[54:55], v[60:61], v[54:55]
	v_pk_mul_f32 v[60:61], v[96:97], v[66:67]
	s_nop 0
	v_cvt_pk_bf16_f32 v60, v60, v61
	v_cvt_pk_bf16_f32 v61, v54, v55
	v_add_f32_dpp v54, v168, v168 quad_perm:[1,0,3,2] row_mask:0xf bank_mask:0xf bound_ctrl:1
	global_store_dwordx2 v[52:53], v[60:61], off offset:1024
	s_nop 0
	v_add_f32_dpp v54, v54, v54 quad_perm:[2,3,0,1] row_mask:0xf bank_mask:0xf bound_ctrl:1
	s_nop 1
	v_add_f32_dpp v54, v54, v54 row_half_mirror row_mask:0xf bank_mask:0xf bound_ctrl:1
	s_nop 1
	v_add_f32_dpp v54, v54, v54 row_mirror row_mask:0xf bank_mask:0xf bound_ctrl:1
	s_nop 0
	v_readlane_b32 s9, v54, 16
	v_readlane_b32 s10, v54, 48
	v_readlane_b32 s6, v54, 0
	v_readlane_b32 s7, v54, 32
	v_mov_b32_e32 v54, s9
	v_mov_b32_e32 v55, s10
	v_pk_add_f32 v[54:55], s[6:7], v[54:55]
	s_nop 0
	v_add_f32_e32 v54, v54, v55
	v_fmamk_f32 v54, v54, 0x3b800000, v252
	v_cmp_gt_f32_e32 vcc, s55, v54
	v_mul_f32_e32 v55, 0x4f800000, v54
	s_nop 0
	v_cndmask_b32_e32 v54, v54, v55, vcc
	v_sqrt_f32_e32 v55, v54
	s_nop 0
	v_add_u32_e32 v60, -1, v55
	v_fma_f32 v61, -v60, v55, v54
	v_cmp_ge_f32_e64 s[6:7], 0, v61
	v_add_u32_e32 v61, 1, v55
	s_nop 0
	v_cndmask_b32_e64 v60, v55, v60, s[6:7]
	v_fma_f32 v55, -v61, v55, v54
	v_cmp_lt_f32_e64 s[6:7], 0, v55
	s_nop 1
	v_cndmask_b32_e64 v55, v60, v61, s[6:7]
	v_mul_f32_e32 v60, 0x37800000, v55
	v_cndmask_b32_e32 v55, v55, v60, vcc
	v_cmp_class_f32_e32 vcc, v54, v253
	s_nop 1
	v_cndmask_b32_e32 v54, v55, v54, vcc
	v_div_scale_f32 v55, s[6:7], v54, v54, 1.0
	v_rcp_f32_e32 v60, v55
	s_nop 0
	v_fma_f32 v61, -v55, v60, 1.0
	v_fmac_f32_e32 v60, v61, v60
	v_div_scale_f32 v61, vcc, 1.0, v54, 1.0
	v_mul_f32_e32 v66, v61, v60
	v_fma_f32 v67, -v55, v66, v61
	v_fmac_f32_e32 v66, v67, v60
	v_fma_f32 v55, -v55, v66, v61
	v_div_fmas_f32 v55, v55, v60, v66
	v_div_fixup_f32 v54, v55, v54, 1.0
	v_lshlrev_b32_e32 v60, 16, v48
	v_and_b32_e32 v61, 0xffff0000, v48
	v_lshlrev_b32_e32 v48, 16, v49
	v_and_b32_e32 v49, 0xffff0000, v49
	v_pk_mul_f32 v[66:67], v[132:133], v[54:55] op_sel_hi:[1,0]
	v_pk_mul_f32 v[54:55], v[128:129], v[54:55] op_sel_hi:[1,0]
	s_nop 0
	v_pk_mul_f32 v[48:49], v[54:55], v[48:49]
	v_pk_mul_f32 v[54:55], v[66:67], v[60:61]
	s_nop 0
	v_cvt_pk_bf16_f32 v54, v54, v55
	v_cvt_pk_bf16_f32 v55, v48, v49
	v_add_f32_dpp v48, v163, v163 quad_perm:[1,0,3,2] row_mask:0xf bank_mask:0xf bound_ctrl:1
	global_store_dwordx2 v[52:53], v[54:55], off offset:1536
	s_nop 0
	v_add_f32_dpp v48, v48, v48 quad_perm:[2,3,0,1] row_mask:0xf bank_mask:0xf bound_ctrl:1
	s_nop 1
	v_add_f32_dpp v48, v48, v48 row_half_mirror row_mask:0xf bank_mask:0xf bound_ctrl:1
	s_nop 1
	v_add_f32_dpp v48, v48, v48 row_mirror row_mask:0xf bank_mask:0xf bound_ctrl:1
	s_nop 0
	v_readlane_b32 s9, v48, 16
	v_readlane_b32 s10, v48, 48
	v_readlane_b32 s6, v48, 0
	v_readlane_b32 s7, v48, 32
	v_mov_b32_e32 v48, s9
	v_mov_b32_e32 v49, s10
	v_pk_add_f32 v[48:49], s[6:7], v[48:49]
	s_nop 0
	v_add_f32_e32 v48, v48, v49
	v_fmamk_f32 v48, v48, 0x3b800000, v252
	v_cmp_gt_f32_e32 vcc, s55, v48
	v_mul_f32_e32 v49, 0x4f800000, v48
	s_nop 0
	v_cndmask_b32_e32 v48, v48, v49, vcc
	v_sqrt_f32_e32 v49, v48
	s_nop 0
	v_add_u32_e32 v54, -1, v49
	v_fma_f32 v55, -v54, v49, v48
	v_cmp_ge_f32_e64 s[6:7], 0, v55
	v_add_u32_e32 v55, 1, v49
	s_nop 0
	v_cndmask_b32_e64 v54, v49, v54, s[6:7]
	v_fma_f32 v49, -v55, v49, v48
	v_cmp_lt_f32_e64 s[6:7], 0, v49
	s_nop 1
	v_cndmask_b32_e64 v49, v54, v55, s[6:7]
	v_mul_f32_e32 v54, 0x37800000, v49
	v_cndmask_b32_e32 v49, v49, v54, vcc
	v_cmp_class_f32_e32 vcc, v48, v253
	s_nop 1
	v_cndmask_b32_e32 v48, v49, v48, vcc
	v_div_scale_f32 v49, s[6:7], v48, v48, 1.0
	v_rcp_f32_e32 v54, v49
	s_nop 0
	v_fma_f32 v55, -v49, v54, 1.0
	v_fmac_f32_e32 v54, v55, v54
	v_div_scale_f32 v55, vcc, 1.0, v48, 1.0
	v_mul_f32_e32 v60, v55, v54
	v_fma_f32 v61, -v49, v60, v55
	v_fmac_f32_e32 v60, v61, v54
	v_fma_f32 v49, -v49, v60, v55
	v_div_fmas_f32 v49, v49, v54, v60
	v_div_fixup_f32 v48, v49, v48, 1.0
	v_lshlrev_b32_e32 v54, 16, v42
	v_and_b32_e32 v55, 0xffff0000, v42
	v_lshlrev_b32_e32 v42, 16, v43
	v_and_b32_e32 v43, 0xffff0000, v43
	v_pk_mul_f32 v[60:61], v[124:125], v[48:49] op_sel_hi:[1,0]
	v_pk_mul_f32 v[48:49], v[120:121], v[48:49] op_sel_hi:[1,0]
	s_nop 0
	v_pk_mul_f32 v[42:43], v[48:49], v[42:43]
	v_pk_mul_f32 v[48:49], v[60:61], v[54:55]
	s_nop 0
	v_cvt_pk_bf16_f32 v48, v48, v49
	v_cvt_pk_bf16_f32 v49, v42, v43
	v_add_f32_dpp v42, v162, v162 quad_perm:[1,0,3,2] row_mask:0xf bank_mask:0xf bound_ctrl:1
	global_store_dwordx2 v[52:53], v[48:49], off offset:2048
	s_nop 0
	v_add_f32_dpp v42, v42, v42 quad_perm:[2,3,0,1] row_mask:0xf bank_mask:0xf bound_ctrl:1
	s_nop 1
	v_add_f32_dpp v42, v42, v42 row_half_mirror row_mask:0xf bank_mask:0xf bound_ctrl:1
	s_nop 1
	v_add_f32_dpp v42, v42, v42 row_mirror row_mask:0xf bank_mask:0xf bound_ctrl:1
	s_nop 0
	v_readlane_b32 s9, v42, 16
	v_readlane_b32 s10, v42, 48
	v_readlane_b32 s6, v42, 0
	v_readlane_b32 s7, v42, 32
	v_mov_b32_e32 v42, s9
	v_mov_b32_e32 v43, s10
	v_pk_add_f32 v[42:43], s[6:7], v[42:43]
	s_nop 0
	v_add_f32_e32 v42, v42, v43
	v_fmamk_f32 v42, v42, 0x3b800000, v252
	v_cmp_gt_f32_e32 vcc, s55, v42
	v_mul_f32_e32 v43, 0x4f800000, v42
	s_nop 0
	v_cndmask_b32_e32 v42, v42, v43, vcc
	v_sqrt_f32_e32 v43, v42
	s_nop 0
	v_add_u32_e32 v48, -1, v43
	v_fma_f32 v49, -v48, v43, v42
; template <bool HG>
; __device__ __forceinline__ void readout_phase2(const Args& a, Frame& F, const float* gain, int nrows) {
;     ...
;     RO_FINISH(f1, b1, g1, nw + 4 * 2048); RO_LOAD(f1, b1, g1, nw + 7 * 2048);
	v_cmp_ge_f32_e64 s[6:7], 0, v49
	v_add_u32_e32 v49, 1, v43
	s_nop 0
	v_cndmask_b32_e64 v48, v43, v48, s[6:7]
	v_fma_f32 v43, -v49, v43, v42
	v_cmp_lt_f32_e64 s[6:7], 0, v43
	s_nop 1
	v_cndmask_b32_e64 v43, v48, v49, s[6:7]
	v_mul_f32_e32 v48, 0x37800000, v43
	v_cndmask_b32_e32 v43, v43, v48, vcc
	v_cmp_class_f32_e32 vcc, v42, v253
	s_nop 1
	v_cndmask_b32_e32 v42, v43, v42, vcc
	v_div_scale_f32 v43, s[6:7], v42, v42, 1.0
	v_rcp_f32_e32 v48, v43
	s_nop 0
	v_fma_f32 v49, -v43, v48, 1.0
	v_fmac_f32_e32 v48, v49, v48
	v_div_scale_f32 v49, vcc, 1.0, v42, 1.0
	v_mul_f32_e32 v54, v49, v48
	v_fma_f32 v55, -v43, v54, v49
	v_fmac_f32_e32 v54, v55, v48
	v_fma_f32 v43, -v43, v54, v49
	v_div_fmas_f32 v43, v43, v48, v54
	v_div_fixup_f32 v42, v43, v42, 1.0
	v_lshlrev_b32_e32 v48, 16, v36
	v_and_b32_e32 v49, 0xffff0000, v36
	v_lshlrev_b32_e32 v36, 16, v37
	v_and_b32_e32 v37, 0xffff0000, v37
	v_pk_mul_f32 v[54:55], v[116:117], v[42:43] op_sel_hi:[1,0]
	v_pk_mul_f32 v[42:43], v[112:113], v[42:43] op_sel_hi:[1,0]
	s_nop 0
	v_pk_mul_f32 v[36:37], v[42:43], v[36:37]
	v_pk_mul_f32 v[42:43], v[54:55], v[48:49]
	s_nop 0
	v_cvt_pk_bf16_f32 v42, v42, v43
	v_cvt_pk_bf16_f32 v43, v36, v37
	v_add_f32_dpp v36, v104, v104 quad_perm:[1,0,3,2] row_mask:0xf bank_mask:0xf bound_ctrl:1
	global_store_dwordx2 v[52:53], v[42:43], off offset:2560
	s_nop 0
	v_add_f32_dpp v36, v36, v36 quad_perm:[2,3,0,1] row_mask:0xf bank_mask:0xf bound_ctrl:1
	s_nop 1
	v_add_f32_dpp v36, v36, v36 row_half_mirror row_mask:0xf bank_mask:0xf bound_ctrl:1
	s_nop 1
	v_add_f32_dpp v36, v36, v36 row_mirror row_mask:0xf bank_mask:0xf bound_ctrl:1
	s_nop 0
	v_readlane_b32 s9, v36, 16
	v_readlane_b32 s10, v36, 48
	v_readlane_b32 s6, v36, 0
	v_readlane_b32 s7, v36, 32
	v_mov_b32_e32 v36, s9
	v_mov_b32_e32 v37, s10
	v_pk_add_f32 v[36:37], s[6:7], v[36:37]
	s_nop 0
	v_add_f32_e32 v36, v36, v37
	v_fmamk_f32 v36, v36, 0x3b800000, v252
	v_cmp_gt_f32_e32 vcc, s55, v36
	v_mul_f32_e32 v37, 0x4f800000, v36
	s_nop 0
	v_cndmask_b32_e32 v36, v36, v37, vcc
	v_sqrt_f32_e32 v37, v36
	s_nop 0
	v_add_u32_e32 v42, -1, v37
	v_fma_f32 v43, -v42, v37, v36
	v_cmp_ge_f32_e64 s[6:7], 0, v43
	v_add_u32_e32 v43, 1, v37
	s_nop 0
	v_cndmask_b32_e64 v42, v37, v42, s[6:7]
	v_fma_f32 v37, -v43, v37, v36
	v_cmp_lt_f32_e64 s[6:7], 0, v37
	s_nop 1
	v_cndmask_b32_e64 v37, v42, v43, s[6:7]
	v_mul_f32_e32 v42, 0x37800000, v37
	v_cndmask_b32_e32 v37, v37, v42, vcc
	v_cmp_class_f32_e32 vcc, v36, v253
	s_nop 1
	v_cndmask_b32_e32 v36, v37, v36, vcc
	v_div_scale_f32 v37, s[6:7], v36, v36, 1.0
	v_rcp_f32_e32 v42, v37
	s_nop 0
	v_fma_f32 v43, -v37, v42, 1.0
	v_fmac_f32_e32 v42, v43, v42
	v_div_scale_f32 v43, vcc, 1.0, v36, 1.0
	v_mul_f32_e32 v48, v43, v42
	v_fma_f32 v49, -v37, v48, v43
	v_fmac_f32_e32 v48, v49, v42
	v_fma_f32 v37, -v37, v48, v43
	v_div_fmas_f32 v37, v37, v42, v48
	v_div_fixup_f32 v36, v37, v36, 1.0
	v_lshlrev_b32_e32 v42, 16, v32
	v_and_b32_e32 v43, 0xffff0000, v32
	v_lshlrev_b32_e32 v32, 16, v33
	v_and_b32_e32 v33, 0xffff0000, v33
	v_pk_mul_f32 v[48:49], v[108:109], v[36:37] op_sel_hi:[1,0]
	v_pk_mul_f32 v[36:37], v[100:101], v[36:37] op_sel_hi:[1,0]
	s_nop 0
	v_pk_mul_f32 v[32:33], v[36:37], v[32:33]
	v_pk_mul_f32 v[36:37], v[48:49], v[42:43]
	s_nop 0
	v_cvt_pk_bf16_f32 v36, v36, v37
	v_cvt_pk_bf16_f32 v37, v32, v33
	v_add_f32_dpp v32, v92, v92 quad_perm:[1,0,3,2] row_mask:0xf bank_mask:0xf bound_ctrl:1
	global_store_dwordx2 v[52:53], v[36:37], off offset:3072
	s_nop 0
	v_add_f32_dpp v32, v32, v32 quad_perm:[2,3,0,1] row_mask:0xf bank_mask:0xf bound_ctrl:1
	s_nop 1
	v_add_f32_dpp v32, v32, v32 row_half_mirror row_mask:0xf bank_mask:0xf bound_ctrl:1
	s_nop 1
	v_add_f32_dpp v32, v32, v32 row_mirror row_mask:0xf bank_mask:0xf bound_ctrl:1
	s_nop 0
	v_readlane_b32 s9, v32, 16
	v_readlane_b32 s10, v32, 48
	v_readlane_b32 s6, v32, 0
	v_readlane_b32 s7, v32, 32
	v_mov_b32_e32 v32, s9
	v_mov_b32_e32 v33, s10
	v_pk_add_f32 v[32:33], s[6:7], v[32:33]
	s_add_i32 s10, s8, 0x3800
	v_add_f32_e32 v32, v32, v33
	v_fmamk_f32 v32, v32, 0x3b800000, v252
	v_cmp_gt_f32_e32 vcc, s55, v32
	v_mul_f32_e32 v33, 0x4f800000, v32
	s_ashr_i32 s11, s10, 31
	v_cndmask_b32_e32 v32, v32, v33, vcc
	v_sqrt_f32_e32 v33, v32
	s_lshl_b64 s[78:79], s[10:11], 12
	s_cmp_lt_i32 s82, s47
	v_add_u32_e32 v36, -1, v33
	v_fma_f32 v37, -v36, v33, v32
	v_cmp_ge_f32_e64 s[6:7], 0, v37
	v_add_u32_e32 v37, 1, v33
	s_nop 0
	v_cndmask_b32_e64 v36, v33, v36, s[6:7]
	v_fma_f32 v33, -v37, v33, v32
	v_cmp_lt_f32_e64 s[6:7], 0, v33
	s_nop 1
	v_cndmask_b32_e64 v33, v36, v37, s[6:7]
	v_mul_f32_e32 v36, 0x37800000, v33
	v_cndmask_b32_e32 v33, v33, v36, vcc
	v_cmp_class_f32_e32 vcc, v32, v253
	s_nop 1
	v_cndmask_b32_e32 v32, v33, v32, vcc
	v_div_scale_f32 v33, s[6:7], v32, v32, 1.0
	v_rcp_f32_e32 v36, v33
	s_nop 0
	v_fma_f32 v37, -v33, v36, 1.0
	v_fmac_f32_e32 v36, v37, v36
	v_div_scale_f32 v37, vcc, 1.0, v32, 1.0
	v_mul_f32_e32 v42, v37, v36
	v_fma_f32 v43, -v33, v42, v37
	v_fmac_f32_e32 v42, v43, v36
	v_fma_f32 v33, -v33, v42, v37
	v_div_fmas_f32 v33, v33, v36, v42
	v_div_fixup_f32 v32, v33, v32, 1.0
	v_lshlrev_b32_e32 v36, 16, v28
	v_and_b32_e32 v37, 0xffff0000, v28
	v_lshlrev_b32_e32 v28, 16, v29
	v_and_b32_e32 v29, 0xffff0000, v29
	v_pk_mul_f32 v[40:41], v[40:41], v[32:33] op_sel_hi:[1,0]
	v_pk_mul_f32 v[32:33], v[46:47], v[32:33] op_sel_hi:[1,0]
	s_nop 0
	v_pk_mul_f32 v[28:29], v[32:33], v[28:29]
	v_pk_mul_f32 v[32:33], v[40:41], v[36:37]
	s_nop 0
	v_cvt_pk_bf16_f32 v32, v32, v33
	v_cvt_pk_bf16_f32 v33, v28, v29
	global_store_dwordx2 v[52:53], v[32:33], off offset:3584
	v_lshl_add_u64 v[32:33], v[6:7], 0, s[78:79]
	v_lshl_add_u64 v[28:29], v[4:5], 0, s[78:79]
	v_lshl_add_u64 v[60:61], v[32:33], 0, v[0:1]
	v_lshl_add_u64 v[32:33], v[8:9], 0, s[78:79]
	v_lshl_add_u64 v[28:29], v[28:29], 0, v[0:1]
	v_lshl_add_u64 v[150:151], v[32:33], 0, v[0:1]
	global_load_dwordx2 v[144:145], v[28:29], off nt
	global_load_dwordx2 v[138:139], v[60:61], off nt
	global_load_dwordx2 v[52:53], v[150:151], off nt
	global_load_dwordx2 v[132:133], v[28:29], off offset:512 nt
	global_load_dwordx2 v[128:129], v[60:61], off offset:512 nt
	global_load_dwordx2 v[48:49], v[150:151], off offset:512 nt
	global_load_dwordx2 v[124:125], v[28:29], off offset:1024 nt
	global_load_dwordx2 v[120:121], v[60:61], off offset:1024 nt
	global_load_dwordx2 v[46:47], v[150:151], off offset:1024 nt
	global_load_dwordx2 v[112:113], v[28:29], off offset:1536 nt
	global_load_dwordx2 v[116:117], v[60:61], off offset:1536 nt
	global_load_dwordx2 v[42:43], v[150:151], off offset:1536 nt
	global_load_dwordx2 v[108:109], v[28:29], off offset:2048 nt
	global_load_dwordx2 v[104:105], v[60:61], off offset:2048 nt
	global_load_dwordx2 v[40:41], v[150:151], off offset:2048 nt
	global_load_dwordx2 v[100:101], v[28:29], off offset:2560 nt
	global_load_dwordx2 v[96:97], v[60:61], off offset:2560 nt
	global_load_dwordx2 v[36:37], v[150:151], off offset:2560 nt
	global_load_dwordx2 v[92:93], v[28:29], off offset:3072 nt
	global_load_dwordx2 v[66:67], v[60:61], off offset:3072 nt
	global_load_dwordx2 v[32:33], v[150:151], off offset:3072 nt
	global_load_dwordx2 v[54:55], v[28:29], off offset:3584 nt
	s_nop 0
	global_load_dwordx2 v[60:61], v[60:61], off offset:3584 nt
	s_nop 0
	global_load_dwordx2 v[28:29], v[150:151], off offset:3584 nt
	v_lshlrev_b32_e32 v150, 16, v158
	v_and_b32_e32 v151, 0xffff0000, v158
	v_pk_add_f32 v[154:155], v[150:151], v[154:155]
	v_lshlrev_b32_e32 v150, 16, v159
	v_and_b32_e32 v151, 0xffff0000, v159
	v_pk_add_f32 v[152:153], v[150:151], v[152:153]
	v_mov_b32_e32 v156, v155
	v_mov_b32_e32 v157, v153
	v_mov_b32_e32 v150, v154
	v_mov_b32_e32 v151, v152
	v_pk_mul_f32 v[156:157], v[156:157], v[156:157]
	s_nop 0
	v_pk_fma_f32 v[150:151], v[150:151], v[150:151], v[156:157]
	v_lshlrev_b32_e32 v156, 16, v140
	v_add_f32_e32 v162, v150, v151
	v_lshlrev_b32_e32 v150, 16, v146
	v_and_b32_e32 v151, 0xffff0000, v146
	v_and_b32_e32 v157, 0xffff0000, v140
	v_lshlrev_b32_e32 v146, 16, v147
	v_and_b32_e32 v147, 0xffff0000, v147
	v_lshlrev_b32_e32 v140, 16, v141
	v_and_b32_e32 v141, 0xffff0000, v141
	v_pk_add_f32 v[150:151], v[150:151], v[156:157]
	v_pk_add_f32 v[146:147], v[146:147], v[140:141]
	v_mov_b32_e32 v156, v151
	v_mov_b32_e32 v157, v147
	v_mov_b32_e32 v140, v150
	v_mov_b32_e32 v141, v146
	v_pk_mul_f32 v[156:157], v[156:157], v[156:157]
	s_nop 0
	v_pk_fma_f32 v[140:141], v[140:141], v[140:141], v[156:157]
	v_lshlrev_b32_e32 v156, 16, v88
	v_add_f32_e32 v164, v140, v141
	v_lshlrev_b32_e32 v140, 16, v134
	v_and_b32_e32 v141, 0xffff0000, v134
	v_and_b32_e32 v157, 0xffff0000, v88
	v_lshlrev_b32_e32 v134, 16, v135
	v_and_b32_e32 v135, 0xffff0000, v135
	v_lshlrev_b32_e32 v88, 16, v89
	v_and_b32_e32 v89, 0xffff0000, v89
	v_pk_add_f32 v[140:141], v[140:141], v[156:157]
	v_pk_add_f32 v[134:135], v[134:135], v[88:89]
	v_mov_b32_e32 v156, v141
	v_mov_b32_e32 v157, v135
	v_mov_b32_e32 v88, v140
	v_mov_b32_e32 v89, v134
	v_pk_mul_f32 v[156:157], v[156:157], v[156:157]
	s_nop 0
	v_pk_fma_f32 v[88:89], v[88:89], v[88:89], v[156:157]
	v_lshlrev_b32_e32 v156, 16, v86
	v_add_f32_e32 v165, v88, v89
	v_lshlrev_b32_e32 v88, 16, v84
	v_and_b32_e32 v89, 0xffff0000, v84
	v_and_b32_e32 v157, 0xffff0000, v86
	v_lshlrev_b32_e32 v84, 16, v85
	v_and_b32_e32 v85, 0xffff0000, v85
	v_lshlrev_b32_e32 v86, 16, v87
	v_and_b32_e32 v87, 0xffff0000, v87
	v_pk_add_f32 v[88:89], v[88:89], v[156:157]
	v_pk_add_f32 v[86:87], v[84:85], v[86:87]
	v_mov_b32_e32 v156, v89
	v_mov_b32_e32 v157, v87
	v_mov_b32_e32 v84, v88
	v_mov_b32_e32 v85, v86
	v_pk_mul_f32 v[156:157], v[156:157], v[156:157]
	s_nop 0
	v_pk_fma_f32 v[84:85], v[84:85], v[84:85], v[156:157]
	v_lshlrev_b32_e32 v156, 16, v80
	v_add_f32_e32 v166, v84, v85
	v_lshlrev_b32_e32 v84, 16, v82
	v_and_b32_e32 v85, 0xffff0000, v82
	v_and_b32_e32 v157, 0xffff0000, v80
	v_lshlrev_b32_e32 v82, 16, v83
	v_and_b32_e32 v83, 0xffff0000, v83
	v_lshlrev_b32_e32 v80, 16, v81
	v_and_b32_e32 v81, 0xffff0000, v81
	v_pk_add_f32 v[84:85], v[84:85], v[156:157]
	v_pk_add_f32 v[82:83], v[82:83], v[80:81]
	v_mov_b32_e32 v156, v85
	v_mov_b32_e32 v157, v83
	v_mov_b32_e32 v80, v84
	v_mov_b32_e32 v81, v82
	v_pk_mul_f32 v[156:157], v[156:157], v[156:157]
	s_nop 0
	v_pk_fma_f32 v[80:81], v[80:81], v[80:81], v[156:157]
	v_lshlrev_b32_e32 v156, 16, v76
	v_add_f32_e32 v159, v80, v81
	v_lshlrev_b32_e32 v80, 16, v78
	v_and_b32_e32 v81, 0xffff0000, v78
	v_and_b32_e32 v157, 0xffff0000, v76
	v_lshlrev_b32_e32 v78, 16, v79
	v_and_b32_e32 v79, 0xffff0000, v79
	v_lshlrev_b32_e32 v76, 16, v77
	v_and_b32_e32 v77, 0xffff0000, v77
	v_pk_add_f32 v[80:81], v[80:81], v[156:157]
	v_pk_add_f32 v[78:79], v[78:79], v[76:77]
	v_mov_b32_e32 v156, v81
	v_mov_b32_e32 v157, v79
	v_mov_b32_e32 v76, v80
	v_mov_b32_e32 v77, v78
	v_pk_mul_f32 v[156:157], v[156:157], v[156:157]
	s_nop 0
	v_pk_fma_f32 v[76:77], v[76:77], v[76:77], v[156:157]
	v_lshlrev_b32_e32 v156, 16, v72
	v_add_f32_e32 v158, v76, v77
	v_lshlrev_b32_e32 v76, 16, v74
	v_and_b32_e32 v77, 0xffff0000, v74
	v_and_b32_e32 v157, 0xffff0000, v72
	v_lshlrev_b32_e32 v74, 16, v75
	v_and_b32_e32 v75, 0xffff0000, v75
	v_lshlrev_b32_e32 v72, 16, v73
	v_and_b32_e32 v73, 0xffff0000, v73
	v_pk_add_f32 v[76:77], v[76:77], v[156:157]
	v_pk_add_f32 v[74:75], v[74:75], v[72:73]
	v_mov_b32_e32 v156, v77
	v_mov_b32_e32 v157, v75
	v_mov_b32_e32 v72, v76
	v_mov_b32_e32 v73, v74
	v_pk_mul_f32 v[156:157], v[156:157], v[156:157]
	s_nop 0
	v_pk_fma_f32 v[72:73], v[72:73], v[72:73], v[156:157]
	s_nop 0
	v_add_f32_e32 v157, v72, v73
	v_lshlrev_b32_e32 v72, 16, v68
	v_and_b32_e32 v73, 0xffff0000, v68
	v_lshlrev_b32_e32 v68, 16, v69
	v_and_b32_e32 v69, 0xffff0000, v69
	v_pk_add_f32 v[72:73], v[72:73], v[160:161]
	v_pk_add_f32 v[68:69], v[68:69], v[70:71]
	v_mov_b32_e32 v160, v73
	v_mov_b32_e32 v161, v69
	v_mov_b32_e32 v70, v72
	v_mov_b32_e32 v71, v68
	v_pk_mul_f32 v[160:161], v[160:161], v[160:161]
	s_nop 0
	v_pk_fma_f32 v[70:71], v[70:71], v[70:71], v[160:161]
	v_add_f32_dpp v160, v162, v162 quad_perm:[1,0,3,2] row_mask:0xf bank_mask:0xf bound_ctrl:1
	v_add_f32_e32 v156, v70, v71
	v_lshl_add_u64 v[70:71], v[2:3], 0, s[12:13]
	v_add_f32_dpp v160, v160, v160 quad_perm:[2,3,0,1] row_mask:0xf bank_mask:0xf bound_ctrl:1
	v_lshl_add_u64 v[70:71], v[70:71], 0, v[0:1]
	s_nop 0
	v_add_f32_dpp v160, v160, v160 row_half_mirror row_mask:0xf bank_mask:0xf bound_ctrl:1
	s_nop 1
	v_add_f32_dpp v160, v160, v160 row_mirror row_mask:0xf bank_mask:0xf bound_ctrl:1
	s_nop 0
	v_readlane_b32 s9, v160, 16
	v_readlane_b32 s11, v160, 48
	v_readlane_b32 s6, v160, 0
	v_readlane_b32 s7, v160, 32
	v_mov_b32_e32 v160, s9
	v_mov_b32_e32 v161, s11
	v_pk_add_f32 v[160:161], s[6:7], v[160:161]
	s_nop 0
	v_add_f32_e32 v160, v160, v161
	v_fmamk_f32 v160, v160, 0x3b800000, v252
	v_cmp_gt_f32_e32 vcc, s55, v160
	v_mul_f32_e32 v161, 0x4f800000, v160
	s_nop 0
	v_cndmask_b32_e32 v160, v160, v161, vcc
	v_sqrt_f32_e32 v161, v160
	s_nop 0
	v_add_u32_e32 v162, -1, v161
	v_fma_f32 v163, -v162, v161, v160
	v_cmp_ge_f32_e64 s[6:7], 0, v163
	v_add_u32_e32 v163, 1, v161
	s_nop 0
	v_cndmask_b32_e64 v162, v161, v162, s[6:7]
	v_fma_f32 v161, -v163, v161, v160
	v_cmp_lt_f32_e64 s[6:7], 0, v161
	s_nop 1
	v_cndmask_b32_e64 v161, v162, v163, s[6:7]
	v_mul_f32_e32 v162, 0x37800000, v161
	v_cndmask_b32_e32 v161, v161, v162, vcc
	v_cmp_class_f32_e32 vcc, v160, v253
	s_nop 1
	v_cndmask_b32_e32 v160, v161, v160, vcc
	v_div_scale_f32 v161, s[6:7], v160, v160, 1.0
	v_rcp_f32_e32 v162, v161
	s_nop 0
	v_fma_f32 v163, -v161, v162, 1.0
	v_fmac_f32_e32 v162, v163, v162
	v_div_scale_f32 v163, vcc, 1.0, v160, 1.0
	v_mul_f32_e32 v167, v163, v162
	v_fma_f32 v168, -v161, v167, v163
	v_fmac_f32_e32 v167, v168, v162
	v_fma_f32 v161, -v161, v167, v163
	v_div_fmas_f32 v161, v161, v162, v167
	v_div_fixup_f32 v160, v161, v160, 1.0
	v_lshlrev_b32_e32 v162, 16, v62
	v_and_b32_e32 v163, 0xffff0000, v62
	v_lshlrev_b32_e32 v62, 16, v63
	v_and_b32_e32 v63, 0xffff0000, v63
	v_pk_mul_f32 v[154:155], v[154:155], v[160:161] op_sel_hi:[1,0]
	v_pk_mul_f32 v[152:153], v[152:153], v[160:161] op_sel_hi:[1,0]
	s_nop 0
	v_pk_mul_f32 v[62:63], v[152:153], v[62:63]
	v_pk_mul_f32 v[152:153], v[154:155], v[162:163]
	s_nop 0
	v_cvt_pk_bf16_f32 v152, v152, v153
	v_cvt_pk_bf16_f32 v153, v62, v63
	v_add_f32_dpp v62, v164, v164 quad_perm:[1,0,3,2] row_mask:0xf bank_mask:0xf bound_ctrl:1
	global_store_dwordx2 v[70:71], v[152:153], off
	s_nop 0
	v_add_f32_dpp v62, v62, v62 quad_perm:[2,3,0,1] row_mask:0xf bank_mask:0xf bound_ctrl:1
	s_nop 1
	v_add_f32_dpp v62, v62, v62 row_half_mirror row_mask:0xf bank_mask:0xf bound_ctrl:1
	s_nop 1
	v_add_f32_dpp v62, v62, v62 row_mirror row_mask:0xf bank_mask:0xf bound_ctrl:1
	s_nop 0
	v_readlane_b32 s9, v62, 16
	v_readlane_b32 s11, v62, 48
	v_readlane_b32 s6, v62, 0
	v_readlane_b32 s7, v62, 32
	v_mov_b32_e32 v62, s9
	v_mov_b32_e32 v63, s11
	v_pk_add_f32 v[62:63], s[6:7], v[62:63]
	s_nop 0
	v_add_f32_e32 v62, v62, v63
	v_fmamk_f32 v62, v62, 0x3b800000, v252
	v_cmp_gt_f32_e32 vcc, s55, v62
	v_mul_f32_e32 v63, 0x4f800000, v62
	s_nop 0
	v_cndmask_b32_e32 v62, v62, v63, vcc
	v_sqrt_f32_e32 v63, v62
	s_nop 0
	v_add_u32_e32 v152, -1, v63
	v_fma_f32 v153, -v152, v63, v62
	v_cmp_ge_f32_e64 s[6:7], 0, v153
	v_add_u32_e32 v153, 1, v63
	s_nop 0
	v_cndmask_b32_e64 v152, v63, v152, s[6:7]
	v_fma_f32 v63, -v153, v63, v62
	v_cmp_lt_f32_e64 s[6:7], 0, v63
	s_nop 1
	v_cndmask_b32_e64 v63, v152, v153, s[6:7]
	v_mul_f32_e32 v152, 0x37800000, v63
	v_cndmask_b32_e32 v63, v63, v152, vcc
	v_cmp_class_f32_e32 vcc, v62, v253
	s_nop 1
	v_cndmask_b32_e32 v62, v63, v62, vcc
	v_div_scale_f32 v63, s[6:7], v62, v62, 1.0
	v_rcp_f32_e32 v152, v63
	s_nop 0
	v_fma_f32 v153, -v63, v152, 1.0
	v_fmac_f32_e32 v152, v153, v152
	v_div_scale_f32 v153, vcc, 1.0, v62, 1.0
	v_mul_f32_e32 v154, v153, v152
	v_fma_f32 v155, -v63, v154, v153
	v_fmac_f32_e32 v154, v155, v152
	v_fma_f32 v63, -v63, v154, v153
	v_div_fmas_f32 v63, v63, v152, v154
	v_div_fixup_f32 v62, v63, v62, 1.0
	v_lshlrev_b32_e32 v152, 16, v56
	v_and_b32_e32 v153, 0xffff0000, v56
	v_lshlrev_b32_e32 v56, 16, v57
	v_and_b32_e32 v57, 0xffff0000, v57
	v_pk_mul_f32 v[150:151], v[150:151], v[62:63] op_sel_hi:[1,0]
	v_pk_mul_f32 v[62:63], v[146:147], v[62:63] op_sel_hi:[1,0]
	s_nop 0
	v_pk_mul_f32 v[56:57], v[62:63], v[56:57]
	v_pk_mul_f32 v[62:63], v[150:151], v[152:153]
	s_nop 0
	v_cvt_pk_bf16_f32 v62, v62, v63
	v_cvt_pk_bf16_f32 v63, v56, v57
	v_add_f32_dpp v56, v165, v165 quad_perm:[1,0,3,2] row_mask:0xf bank_mask:0xf bound_ctrl:1
	global_store_dwordx2 v[70:71], v[62:63], off offset:512
	s_nop 0
	v_add_f32_dpp v56, v56, v56 quad_perm:[2,3,0,1] row_mask:0xf bank_mask:0xf bound_ctrl:1
	s_nop 1
	v_add_f32_dpp v56, v56, v56 row_half_mirror row_mask:0xf bank_mask:0xf bound_ctrl:1
	s_nop 1
	v_add_f32_dpp v56, v56, v56 row_mirror row_mask:0xf bank_mask:0xf bound_ctrl:1
	s_nop 0
	v_readlane_b32 s9, v56, 16
	v_readlane_b32 s11, v56, 48
	v_readlane_b32 s6, v56, 0
	v_readlane_b32 s7, v56, 32
	v_mov_b32_e32 v56, s9
	v_mov_b32_e32 v57, s11
	v_pk_add_f32 v[56:57], s[6:7], v[56:57]
	s_nop 0
	v_add_f32_e32 v56, v56, v57
	v_fmamk_f32 v56, v56, 0x3b800000, v252
	v_cmp_gt_f32_e32 vcc, s55, v56
	v_mul_f32_e32 v57, 0x4f800000, v56
	s_nop 0
	v_cndmask_b32_e32 v56, v56, v57, vcc
	v_sqrt_f32_e32 v57, v56
	s_nop 0
	v_add_u32_e32 v62, -1, v57
	v_fma_f32 v63, -v62, v57, v56
	v_cmp_ge_f32_e64 s[6:7], 0, v63
	v_add_u32_e32 v63, 1, v57
	s_nop 0
	v_cndmask_b32_e64 v62, v57, v62, s[6:7]
	v_fma_f32 v57, -v63, v57, v56
	v_cmp_lt_f32_e64 s[6:7], 0, v57
	s_nop 1
	v_cndmask_b32_e64 v57, v62, v63, s[6:7]
	v_mul_f32_e32 v62, 0x37800000, v57
	v_cndmask_b32_e32 v57, v57, v62, vcc
	v_cmp_class_f32_e32 vcc, v56, v253
	s_nop 1
	v_cndmask_b32_e32 v56, v57, v56, vcc
	v_div_scale_f32 v57, s[6:7], v56, v56, 1.0
	v_rcp_f32_e32 v62, v57
	s_nop 0
	v_fma_f32 v63, -v57, v62, 1.0
	v_fmac_f32_e32 v62, v63, v62
	v_div_scale_f32 v63, vcc, 1.0, v56, 1.0
	v_mul_f32_e32 v146, v63, v62
	v_fma_f32 v147, -v57, v146, v63
	v_fmac_f32_e32 v146, v147, v62
	v_fma_f32 v57, -v57, v146, v63
	v_div_fmas_f32 v57, v57, v62, v146
	v_div_fixup_f32 v56, v57, v56, 1.0
	v_lshlrev_b32_e32 v62, 16, v50
	v_and_b32_e32 v63, 0xffff0000, v50
	v_lshlrev_b32_e32 v50, 16, v51
	v_and_b32_e32 v51, 0xffff0000, v51
	v_pk_mul_f32 v[140:141], v[140:141], v[56:57] op_sel_hi:[1,0]
	v_pk_mul_f32 v[56:57], v[134:135], v[56:57] op_sel_hi:[1,0]
	s_nop 0
	v_pk_mul_f32 v[50:51], v[56:57], v[50:51]
	v_pk_mul_f32 v[56:57], v[140:141], v[62:63]
	s_nop 0
	v_cvt_pk_bf16_f32 v56, v56, v57
	v_cvt_pk_bf16_f32 v57, v50, v51
	v_add_f32_dpp v50, v166, v166 quad_perm:[1,0,3,2] row_mask:0xf bank_mask:0xf bound_ctrl:1
	global_store_dwordx2 v[70:71], v[56:57], off offset:1024
	s_nop 0
	v_add_f32_dpp v50, v50, v50 quad_perm:[2,3,0,1] row_mask:0xf bank_mask:0xf bound_ctrl:1
	s_nop 1
	v_add_f32_dpp v50, v50, v50 row_half_mirror row_mask:0xf bank_mask:0xf bound_ctrl:1
	s_nop 1
	v_add_f32_dpp v50, v50, v50 row_mirror row_mask:0xf bank_mask:0xf bound_ctrl:1
	s_nop 0
	v_readlane_b32 s9, v50, 16
	v_readlane_b32 s11, v50, 48
	v_readlane_b32 s6, v50, 0
	v_readlane_b32 s7, v50, 32
	v_mov_b32_e32 v50, s9
	v_mov_b32_e32 v51, s11
	v_pk_add_f32 v[50:51], s[6:7], v[50:51]
	s_nop 0
	v_add_f32_e32 v50, v50, v51
	v_fmamk_f32 v50, v50, 0x3b800000, v252
	v_cmp_gt_f32_e32 vcc, s55, v50
	v_mul_f32_e32 v51, 0x4f800000, v50
	s_nop 0
	v_cndmask_b32_e32 v50, v50, v51, vcc
	v_sqrt_f32_e32 v51, v50
	s_nop 0
	v_add_u32_e32 v56, -1, v51
	v_fma_f32 v57, -v56, v51, v50
	v_cmp_ge_f32_e64 s[6:7], 0, v57
	v_add_u32_e32 v57, 1, v51
	s_nop 0
	v_cndmask_b32_e64 v56, v51, v56, s[6:7]
	v_fma_f32 v51, -v57, v51, v50
	v_cmp_lt_f32_e64 s[6:7], 0, v51
	s_nop 1
	v_cndmask_b32_e64 v51, v56, v57, s[6:7]
	v_mul_f32_e32 v56, 0x37800000, v51
	v_cndmask_b32_e32 v51, v51, v56, vcc
	v_cmp_class_f32_e32 vcc, v50, v253
	s_nop 1
	v_cndmask_b32_e32 v50, v51, v50, vcc
	v_div_scale_f32 v51, s[6:7], v50, v50, 1.0
	v_rcp_f32_e32 v56, v51
	s_nop 0
	v_fma_f32 v57, -v51, v56, 1.0
	v_fmac_f32_e32 v56, v57, v56
	v_div_scale_f32 v57, vcc, 1.0, v50, 1.0
	v_mul_f32_e32 v62, v57, v56
	v_fma_f32 v63, -v51, v62, v57
	v_fmac_f32_e32 v62, v63, v56
	v_fma_f32 v51, -v51, v62, v57
	v_div_fmas_f32 v51, v51, v56, v62
	v_div_fixup_f32 v50, v51, v50, 1.0
	v_lshlrev_b32_e32 v56, 16, v44
	v_and_b32_e32 v57, 0xffff0000, v44
	v_lshlrev_b32_e32 v44, 16, v45
	v_and_b32_e32 v45, 0xffff0000, v45
	v_pk_mul_f32 v[62:63], v[88:89], v[50:51] op_sel_hi:[1,0]
	v_pk_mul_f32 v[50:51], v[86:87], v[50:51] op_sel_hi:[1,0]
	s_nop 0
	v_pk_mul_f32 v[44:45], v[50:51], v[44:45]
	v_pk_mul_f32 v[50:51], v[62:63], v[56:57]
	s_nop 0
	v_cvt_pk_bf16_f32 v50, v50, v51
	v_cvt_pk_bf16_f32 v51, v44, v45
	v_add_f32_dpp v44, v159, v159 quad_perm:[1,0,3,2] row_mask:0xf bank_mask:0xf bound_ctrl:1
	global_store_dwordx2 v[70:71], v[50:51], off offset:1536
	s_nop 0
	v_add_f32_dpp v44, v44, v44 quad_perm:[2,3,0,1] row_mask:0xf bank_mask:0xf bound_ctrl:1
	s_nop 1
	v_add_f32_dpp v44, v44, v44 row_half_mirror row_mask:0xf bank_mask:0xf bound_ctrl:1
	s_nop 1
	v_add_f32_dpp v44, v44, v44 row_mirror row_mask:0xf bank_mask:0xf bound_ctrl:1
	s_nop 0
	v_readlane_b32 s9, v44, 16
	v_readlane_b32 s11, v44, 48
	v_readlane_b32 s6, v44, 0
	v_readlane_b32 s7, v44, 32
	v_mov_b32_e32 v44, s9
	v_mov_b32_e32 v45, s11
	v_pk_add_f32 v[44:45], s[6:7], v[44:45]
	s_nop 0
	v_add_f32_e32 v44, v44, v45
	v_fmamk_f32 v44, v44, 0x3b800000, v252
	v_cmp_gt_f32_e32 vcc, s55, v44
	v_mul_f32_e32 v45, 0x4f800000, v44
	s_nop 0
	v_cndmask_b32_e32 v44, v44, v45, vcc
	v_sqrt_f32_e32 v45, v44
	s_nop 0
	v_add_u32_e32 v50, -1, v45
	v_fma_f32 v51, -v50, v45, v44
	v_cmp_ge_f32_e64 s[6:7], 0, v51
	v_add_u32_e32 v51, 1, v45
	s_nop 0
	v_cndmask_b32_e64 v50, v45, v50, s[6:7]
	v_fma_f32 v45, -v51, v45, v44
	v_cmp_lt_f32_e64 s[6:7], 0, v45
	s_nop 1
	v_cndmask_b32_e64 v45, v50, v51, s[6:7]
	v_mul_f32_e32 v50, 0x37800000, v45
	v_cndmask_b32_e32 v45, v45, v50, vcc
	v_cmp_class_f32_e32 vcc, v44, v253
	s_nop 1
	v_cndmask_b32_e32 v44, v45, v44, vcc
	v_div_scale_f32 v45, s[6:7], v44, v44, 1.0
	v_rcp_f32_e32 v50, v45
	s_nop 0
	v_fma_f32 v51, -v45, v50, 1.0
	v_fmac_f32_e32 v50, v51, v50
	v_div_scale_f32 v51, vcc, 1.0, v44, 1.0
	v_mul_f32_e32 v56, v51, v50
	v_fma_f32 v57, -v45, v56, v51
	v_fmac_f32_e32 v56, v57, v50
	v_fma_f32 v45, -v45, v56, v51
	v_div_fmas_f32 v45, v45, v50, v56
	v_div_fixup_f32 v44, v45, v44, 1.0
	v_lshlrev_b32_e32 v50, 16, v38
	v_and_b32_e32 v51, 0xffff0000, v38
	v_lshlrev_b32_e32 v38, 16, v39
	v_and_b32_e32 v39, 0xffff0000, v39
	v_pk_mul_f32 v[56:57], v[84:85], v[44:45] op_sel_hi:[1,0]
	v_pk_mul_f32 v[44:45], v[82:83], v[44:45] op_sel_hi:[1,0]
	s_nop 0
	v_pk_mul_f32 v[38:39], v[44:45], v[38:39]
	v_pk_mul_f32 v[44:45], v[56:57], v[50:51]
; template <bool HG>
; __device__ __forceinline__ void readout_phase2(const Args& a, Frame& F, const float* gain, int nrows) {
;     ...
;     const bool cx = ML + nw < nrows;
;     RO_LOAD(f2, b2, g2, cx ? ML + nw : nw + 7 * 2048);
	s_nop 0
	v_cvt_pk_bf16_f32 v44, v44, v45
	v_cvt_pk_bf16_f32 v45, v38, v39
	v_add_f32_dpp v38, v158, v158 quad_perm:[1,0,3,2] row_mask:0xf bank_mask:0xf bound_ctrl:1
	global_store_dwordx2 v[70:71], v[44:45], off offset:2048
	s_nop 0
	v_add_f32_dpp v38, v38, v38 quad_perm:[2,3,0,1] row_mask:0xf bank_mask:0xf bound_ctrl:1
	s_nop 1
	v_add_f32_dpp v38, v38, v38 row_half_mirror row_mask:0xf bank_mask:0xf bound_ctrl:1
	s_nop 1
	v_add_f32_dpp v38, v38, v38 row_mirror row_mask:0xf bank_mask:0xf bound_ctrl:1
	s_nop 0
	v_readlane_b32 s9, v38, 16
	v_readlane_b32 s11, v38, 48
	v_readlane_b32 s6, v38, 0
	v_readlane_b32 s7, v38, 32
	v_mov_b32_e32 v38, s9
	v_mov_b32_e32 v39, s11
	v_pk_add_f32 v[38:39], s[6:7], v[38:39]
	s_nop 0
	v_add_f32_e32 v38, v38, v39
	v_fmamk_f32 v38, v38, 0x3b800000, v252
	v_cmp_gt_f32_e32 vcc, s55, v38
	v_mul_f32_e32 v39, 0x4f800000, v38
	s_nop 0
	v_cndmask_b32_e32 v38, v38, v39, vcc
	v_sqrt_f32_e32 v39, v38
	s_nop 0
	v_add_u32_e32 v44, -1, v39
	v_fma_f32 v45, -v44, v39, v38
	v_cmp_ge_f32_e64 s[6:7], 0, v45
	v_add_u32_e32 v45, 1, v39
	s_nop 0
	v_cndmask_b32_e64 v44, v39, v44, s[6:7]
	v_fma_f32 v39, -v45, v39, v38
	v_cmp_lt_f32_e64 s[6:7], 0, v39
	s_nop 1
	v_cndmask_b32_e64 v39, v44, v45, s[6:7]
	v_mul_f32_e32 v44, 0x37800000, v39
	v_cndmask_b32_e32 v39, v39, v44, vcc
	v_cmp_class_f32_e32 vcc, v38, v253
	s_nop 1
	v_cndmask_b32_e32 v38, v39, v38, vcc
	v_div_scale_f32 v39, s[6:7], v38, v38, 1.0
	v_rcp_f32_e32 v44, v39
	s_nop 0
	v_fma_f32 v45, -v39, v44, 1.0
	v_fmac_f32_e32 v44, v45, v44
	v_div_scale_f32 v45, vcc, 1.0, v38, 1.0
	v_mul_f32_e32 v50, v45, v44
	v_fma_f32 v51, -v39, v50, v45
	v_fmac_f32_e32 v50, v51, v44
	v_fma_f32 v39, -v39, v50, v45
	v_div_fmas_f32 v39, v39, v44, v50
	v_div_fixup_f32 v38, v39, v38, 1.0
	v_lshlrev_b32_e32 v44, 16, v34
	v_and_b32_e32 v45, 0xffff0000, v34
	v_lshlrev_b32_e32 v34, 16, v35
	v_and_b32_e32 v35, 0xffff0000, v35
	v_pk_mul_f32 v[50:51], v[80:81], v[38:39] op_sel_hi:[1,0]
	v_pk_mul_f32 v[38:39], v[78:79], v[38:39] op_sel_hi:[1,0]
	s_nop 0
	v_pk_mul_f32 v[34:35], v[38:39], v[34:35]
	v_pk_mul_f32 v[38:39], v[50:51], v[44:45]
	s_nop 0
	v_cvt_pk_bf16_f32 v38, v38, v39
	v_cvt_pk_bf16_f32 v39, v34, v35
	v_add_f32_dpp v34, v157, v157 quad_perm:[1,0,3,2] row_mask:0xf bank_mask:0xf bound_ctrl:1
	global_store_dwordx2 v[70:71], v[38:39], off offset:2560
	s_nop 0
	v_add_f32_dpp v34, v34, v34 quad_perm:[2,3,0,1] row_mask:0xf bank_mask:0xf bound_ctrl:1
	s_nop 1
	v_add_f32_dpp v34, v34, v34 row_half_mirror row_mask:0xf bank_mask:0xf bound_ctrl:1
	s_nop 1
	v_add_f32_dpp v34, v34, v34 row_mirror row_mask:0xf bank_mask:0xf bound_ctrl:1
	s_nop 0
	v_readlane_b32 s9, v34, 16
	v_readlane_b32 s11, v34, 48
	v_readlane_b32 s6, v34, 0
	v_readlane_b32 s7, v34, 32
	v_mov_b32_e32 v34, s9
	v_mov_b32_e32 v35, s11
	v_pk_add_f32 v[34:35], s[6:7], v[34:35]
	s_nop 0
	v_add_f32_e32 v34, v34, v35
	v_fmamk_f32 v34, v34, 0x3b800000, v252
	v_cmp_gt_f32_e32 vcc, s55, v34
	v_mul_f32_e32 v35, 0x4f800000, v34
	s_nop 0
	v_cndmask_b32_e32 v34, v34, v35, vcc
	v_sqrt_f32_e32 v35, v34
	s_nop 0
	v_add_u32_e32 v38, -1, v35
	v_fma_f32 v39, -v38, v35, v34
	v_cmp_ge_f32_e64 s[6:7], 0, v39
	v_add_u32_e32 v39, 1, v35
	s_nop 0
	v_cndmask_b32_e64 v38, v35, v38, s[6:7]
	v_fma_f32 v35, -v39, v35, v34
	v_cmp_lt_f32_e64 s[6:7], 0, v35
	s_nop 1
	v_cndmask_b32_e64 v35, v38, v39, s[6:7]
	v_mul_f32_e32 v38, 0x37800000, v35
	v_cndmask_b32_e32 v35, v35, v38, vcc
	v_cmp_class_f32_e32 vcc, v34, v253
	s_nop 1
	v_cndmask_b32_e32 v34, v35, v34, vcc
	v_div_scale_f32 v35, s[6:7], v34, v34, 1.0
	v_rcp_f32_e32 v38, v35
	s_nop 0
	v_fma_f32 v39, -v35, v38, 1.0
	v_fmac_f32_e32 v38, v39, v38
	v_div_scale_f32 v39, vcc, 1.0, v34, 1.0
	v_mul_f32_e32 v44, v39, v38
	v_fma_f32 v45, -v35, v44, v39
	v_fmac_f32_e32 v44, v45, v38
	v_fma_f32 v35, -v35, v44, v39
	v_div_fmas_f32 v35, v35, v38, v44
	v_div_fixup_f32 v34, v35, v34, 1.0
	v_lshlrev_b32_e32 v38, 16, v30
	v_and_b32_e32 v39, 0xffff0000, v30
	v_lshlrev_b32_e32 v30, 16, v31
	v_and_b32_e32 v31, 0xffff0000, v31
	v_pk_mul_f32 v[44:45], v[76:77], v[34:35] op_sel_hi:[1,0]
	v_pk_mul_f32 v[34:35], v[74:75], v[34:35] op_sel_hi:[1,0]
	s_nop 0
	v_pk_mul_f32 v[30:31], v[34:35], v[30:31]
	v_pk_mul_f32 v[34:35], v[44:45], v[38:39]
	s_nop 0
	v_cvt_pk_bf16_f32 v34, v34, v35
	v_cvt_pk_bf16_f32 v35, v30, v31
	v_add_f32_dpp v30, v156, v156 quad_perm:[1,0,3,2] row_mask:0xf bank_mask:0xf bound_ctrl:1
	global_store_dwordx2 v[70:71], v[34:35], off offset:3072
	s_nop 0
	v_add_f32_dpp v30, v30, v30 quad_perm:[2,3,0,1] row_mask:0xf bank_mask:0xf bound_ctrl:1
	s_nop 1
	v_add_f32_dpp v30, v30, v30 row_half_mirror row_mask:0xf bank_mask:0xf bound_ctrl:1
	s_nop 1
	v_add_f32_dpp v30, v30, v30 row_mirror row_mask:0xf bank_mask:0xf bound_ctrl:1
	s_nop 0
	v_readlane_b32 s9, v30, 16
	v_readlane_b32 s11, v30, 48
	v_readlane_b32 s6, v30, 0
	v_readlane_b32 s7, v30, 32
	v_mov_b32_e32 v30, s9
	v_mov_b32_e32 v31, s11
	v_pk_add_f32 v[30:31], s[6:7], v[30:31]
	s_nop 0
	v_add_f32_e32 v30, v30, v31
	v_fmamk_f32 v30, v30, 0x3b800000, v252
	v_cmp_gt_f32_e32 vcc, s55, v30
	v_mul_f32_e32 v31, 0x4f800000, v30
	s_nop 0
	v_cndmask_b32_e32 v30, v30, v31, vcc
	v_sqrt_f32_e32 v31, v30
	s_nop 0
	v_add_u32_e32 v34, -1, v31
	v_fma_f32 v35, -v34, v31, v30
	v_cmp_ge_f32_e64 s[6:7], 0, v35
	v_add_u32_e32 v35, 1, v31
	s_nop 0
	v_cndmask_b32_e64 v34, v31, v34, s[6:7]
	v_fma_f32 v31, -v35, v31, v30
	v_cmp_lt_f32_e64 s[6:7], 0, v31
	s_nop 1
	v_cndmask_b32_e64 v31, v34, v35, s[6:7]
	v_mul_f32_e32 v34, 0x37800000, v31
	v_cndmask_b32_e32 v31, v31, v34, vcc
	v_cmp_class_f32_e32 vcc, v30, v253
	s_nop 1
	v_cndmask_b32_e32 v30, v31, v30, vcc
	v_div_scale_f32 v31, s[6:7], v30, v30, 1.0
	v_rcp_f32_e32 v34, v31
	s_cselect_b32 s6, s82, s10
	s_ashr_i32 s7, s6, 31
	s_lshl_b64 s[48:49], s[6:7], 12
	v_fma_f32 v35, -v31, v34, 1.0
	v_fmac_f32_e32 v34, v35, v34
	v_div_scale_f32 v35, vcc, 1.0, v30, 1.0
	v_mul_f32_e32 v38, v35, v34
	v_fma_f32 v39, -v31, v38, v35
	v_fmac_f32_e32 v38, v39, v34
	v_fma_f32 v31, -v31, v38, v35
	v_div_fmas_f32 v31, v31, v34, v38
	v_div_fixup_f32 v30, v31, v30, 1.0
	s_waitcnt vmcnt(62)
; template <bool HG>
; __device__ __forceinline__ void readout_phase2(const Args& a, Frame& F, const float* gain, int nrows) {
;     ...
;     RO_FINISH(f2, b2, g2, nw + 2 * 2048); RO_LOAD(f2, b2, g2, nw + 5 * 2048);
;     RO_FINISH(f0, b0, g0, nw + 3 * 2048); RO_LOAD(f0, b0, g0, nw + 6 * 2048);
;     RO_FINISH(f1, b1, g1, nw + 4 * 2048); RO_LOAD(f1, b1, g1, nw + 7 * 2048);
;     RO_FINISH(f2, b2, g2, nw + 5 * 2048);
	v_lshlrev_b32_e32 v34, 16, v26
	v_and_b32_e32 v35, 0xffff0000, v26
	v_lshlrev_b32_e32 v26, 16, v27
	v_and_b32_e32 v27, 0xffff0000, v27
	v_pk_mul_f32 v[38:39], v[72:73], v[30:31] op_sel_hi:[1,0]
	v_pk_mul_f32 v[30:31], v[68:69], v[30:31] op_sel_hi:[1,0]
	v_lshl_add_u64 v[6:7], v[6:7], 0, s[48:49]
	v_pk_mul_f32 v[26:27], v[30:31], v[26:27]
	v_pk_mul_f32 v[30:31], v[38:39], v[34:35]
	v_lshl_add_u64 v[4:5], v[4:5], 0, s[48:49]
	v_cvt_pk_bf16_f32 v30, v30, v31
	v_cvt_pk_bf16_f32 v31, v26, v27
	global_store_dwordx2 v[70:71], v[30:31], off offset:3584
	v_lshlrev_b32_e32 v26, 16, v148
	v_and_b32_e32 v27, 0xffff0000, v148
	s_waitcnt vmcnt(62)
	v_lshlrev_b32_e32 v30, 16, v142
	v_and_b32_e32 v31, 0xffff0000, v142
	v_pk_add_f32 v[140:141], v[26:27], v[30:31]
	v_lshlrev_b32_e32 v26, 16, v149
	v_and_b32_e32 v27, 0xffff0000, v149
	v_lshlrev_b32_e32 v30, 16, v143
	v_and_b32_e32 v31, 0xffff0000, v143
	v_pk_add_f32 v[142:143], v[26:27], v[30:31]
	v_mov_b32_e32 v30, v141
	v_mov_b32_e32 v31, v143
	v_mov_b32_e32 v26, v140
	v_mov_b32_e32 v27, v142
	v_pk_mul_f32 v[30:31], v[30:31], v[30:31]
	v_lshl_add_u64 v[4:5], v[4:5], 0, v[0:1]
	v_pk_fma_f32 v[26:27], v[26:27], v[26:27], v[30:31]
	s_waitcnt vmcnt(59)
	v_lshlrev_b32_e32 v30, 16, v130
	v_add_f32_e32 v34, v26, v27
	v_lshlrev_b32_e32 v26, 16, v136
	v_and_b32_e32 v27, 0xffff0000, v136
	v_and_b32_e32 v31, 0xffff0000, v130
	v_pk_add_f32 v[134:135], v[26:27], v[30:31]
	v_lshlrev_b32_e32 v26, 16, v137
	v_and_b32_e32 v27, 0xffff0000, v137
	v_lshlrev_b32_e32 v30, 16, v131
	v_and_b32_e32 v31, 0xffff0000, v131
	v_pk_add_f32 v[136:137], v[26:27], v[30:31]
	v_mov_b32_e32 v30, v135
	v_mov_b32_e32 v31, v137
	v_mov_b32_e32 v26, v134
	v_mov_b32_e32 v27, v136
	v_pk_mul_f32 v[30:31], v[30:31], v[30:31]
	s_cmp_ge_i32 s82, s47
	v_pk_fma_f32 v[26:27], v[26:27], v[26:27], v[30:31]
	s_waitcnt vmcnt(56)
	v_lshlrev_b32_e32 v30, 16, v122
	v_add_f32_e32 v35, v26, v27
	v_lshlrev_b32_e32 v26, 16, v126
	v_and_b32_e32 v27, 0xffff0000, v126
	v_and_b32_e32 v31, 0xffff0000, v122
	v_pk_add_f32 v[130:131], v[26:27], v[30:31]
	v_lshlrev_b32_e32 v26, 16, v127
	v_and_b32_e32 v27, 0xffff0000, v127
	v_lshlrev_b32_e32 v30, 16, v123
	v_and_b32_e32 v31, 0xffff0000, v123
	v_pk_add_f32 v[122:123], v[26:27], v[30:31]
	v_mov_b32_e32 v30, v131
	v_mov_b32_e32 v31, v123
	v_mov_b32_e32 v26, v130
	v_mov_b32_e32 v27, v122
	v_pk_mul_f32 v[30:31], v[30:31], v[30:31]
	s_nop 0
	v_pk_fma_f32 v[26:27], v[26:27], v[26:27], v[30:31]
	s_waitcnt vmcnt(53)
	v_lshlrev_b32_e32 v30, 16, v118
	v_add_f32_e32 v38, v26, v27
	v_lshlrev_b32_e32 v26, 16, v114
	v_and_b32_e32 v27, 0xffff0000, v114
	v_and_b32_e32 v31, 0xffff0000, v118
	v_pk_add_f32 v[86:87], v[26:27], v[30:31]
	v_lshlrev_b32_e32 v26, 16, v115
	v_and_b32_e32 v27, 0xffff0000, v115
	v_lshlrev_b32_e32 v30, 16, v119
	v_and_b32_e32 v31, 0xffff0000, v119
	v_pk_add_f32 v[88:89], v[26:27], v[30:31]
	v_mov_b32_e32 v30, v87
	v_mov_b32_e32 v31, v89
	v_mov_b32_e32 v26, v86
	v_mov_b32_e32 v27, v88
	v_pk_mul_f32 v[30:31], v[30:31], v[30:31]
	s_nop 0
	v_pk_fma_f32 v[26:27], v[26:27], v[26:27], v[30:31]
	s_waitcnt vmcnt(50)
	v_lshlrev_b32_e32 v30, 16, v106
	v_add_f32_e32 v39, v26, v27
	v_lshlrev_b32_e32 v26, 16, v110
	v_and_b32_e32 v27, 0xffff0000, v110
	v_and_b32_e32 v31, 0xffff0000, v106
	v_pk_add_f32 v[78:79], v[26:27], v[30:31]
	v_lshlrev_b32_e32 v26, 16, v111
	v_and_b32_e32 v27, 0xffff0000, v111
	v_lshlrev_b32_e32 v30, 16, v107
	v_and_b32_e32 v31, 0xffff0000, v107
	v_pk_add_f32 v[80:81], v[26:27], v[30:31]
	v_mov_b32_e32 v30, v79
	v_mov_b32_e32 v31, v81
	v_mov_b32_e32 v26, v78
	v_mov_b32_e32 v27, v80
	v_pk_mul_f32 v[30:31], v[30:31], v[30:31]
	s_nop 0
	v_pk_fma_f32 v[26:27], v[26:27], v[26:27], v[30:31]
	s_waitcnt vmcnt(47)
	v_lshlrev_b32_e32 v30, 16, v98
	v_add_f32_e32 v56, v26, v27
	v_lshlrev_b32_e32 v26, 16, v102
	v_and_b32_e32 v27, 0xffff0000, v102
	v_and_b32_e32 v31, 0xffff0000, v98
	v_pk_add_f32 v[70:71], v[26:27], v[30:31]
	v_lshlrev_b32_e32 v26, 16, v103
	v_and_b32_e32 v27, 0xffff0000, v103
	v_lshlrev_b32_e32 v30, 16, v99
	v_and_b32_e32 v31, 0xffff0000, v99
	v_pk_add_f32 v[72:73], v[26:27], v[30:31]
	v_mov_b32_e32 v30, v71
	v_mov_b32_e32 v31, v73
	v_mov_b32_e32 v26, v70
	v_mov_b32_e32 v27, v72
	v_pk_mul_f32 v[30:31], v[30:31], v[30:31]
	s_nop 0
	v_pk_fma_f32 v[26:27], v[26:27], v[26:27], v[30:31]
	s_waitcnt vmcnt(44)
	v_lshlrev_b32_e32 v30, 16, v90
	v_add_f32_e32 v57, v26, v27
	v_lshlrev_b32_e32 v26, 16, v94
	v_and_b32_e32 v27, 0xffff0000, v94
	v_and_b32_e32 v31, 0xffff0000, v90
	v_pk_add_f32 v[62:63], v[26:27], v[30:31]
	v_lshlrev_b32_e32 v26, 16, v95
	v_and_b32_e32 v27, 0xffff0000, v95
	v_lshlrev_b32_e32 v30, 16, v91
	v_and_b32_e32 v31, 0xffff0000, v91
	v_pk_add_f32 v[68:69], v[26:27], v[30:31]
	v_mov_b32_e32 v30, v63
	v_mov_b32_e32 v31, v69
	v_mov_b32_e32 v26, v62
	v_mov_b32_e32 v27, v68
	v_pk_mul_f32 v[30:31], v[30:31], v[30:31]
	s_nop 0
	v_pk_fma_f32 v[26:27], v[26:27], v[26:27], v[30:31]
	s_waitcnt vmcnt(41)
	v_lshlrev_b32_e32 v30, 16, v64
	v_add_f32_e32 v74, v26, v27
	v_lshlrev_b32_e32 v26, 16, v58
	v_and_b32_e32 v27, 0xffff0000, v58
	v_and_b32_e32 v31, 0xffff0000, v64
	v_pk_add_f32 v[44:45], v[26:27], v[30:31]
	v_lshlrev_b32_e32 v26, 16, v59
	v_and_b32_e32 v27, 0xffff0000, v59
	v_lshlrev_b32_e32 v30, 16, v65
	v_and_b32_e32 v31, 0xffff0000, v65
	v_pk_add_f32 v[50:51], v[26:27], v[30:31]
	v_mov_b32_e32 v30, v45
	v_mov_b32_e32 v31, v51
	v_mov_b32_e32 v26, v44
	v_mov_b32_e32 v27, v50
	v_pk_mul_f32 v[30:31], v[30:31], v[30:31]
	s_nop 0
	v_pk_fma_f32 v[26:27], v[26:27], v[26:27], v[30:31]
	s_waitcnt vmcnt(30)
; template <int CTRL> __device__ __forceinline__ float dpp_mov(float v) { return __builtin_bit_cast(float, __builtin_amdgcn_update_dpp(0, __builtin_bit_cast(int, v), CTRL, 0xF, 0xF, true)); }
; __device__ __forceinline__ float wave_sum(float v) {
;     v += dpp_mov<0xB1>(v);
;     v += dpp_mov<0x4E>(v);
;     v += dpp_mov<0x141>(v);
;     v += dpp_mov<0x140>(v);
;     const int iv = __builtin_bit_cast(int, v);
;     const float a = __builtin_bit_cast(float, __builtin_amdgcn_readlane(iv, 0)), b = __builtin_bit_cast(float, __builtin_amdgcn_readlane(iv, 16));
;     const float c = __builtin_bit_cast(float, __builtin_amdgcn_readlane(iv, 32)), d = __builtin_bit_cast(float, __builtin_amdgcn_readlane(iv, 48));
;     return (a + b) + (c + d);
; }
	v_and_b32_e32 v31, 0xffff0000, v138
	v_add_f32_e32 v30, v26, v27
	v_add_f32_dpp v26, v34, v34 quad_perm:[1,0,3,2] row_mask:0xf bank_mask:0xf bound_ctrl:1
	s_nop 1
	v_add_f32_dpp v26, v26, v26 quad_perm:[2,3,0,1] row_mask:0xf bank_mask:0xf bound_ctrl:1
	s_nop 1
	v_add_f32_dpp v26, v26, v26 row_half_mirror row_mask:0xf bank_mask:0xf bound_ctrl:1
	s_nop 1
	v_add_f32_dpp v26, v26, v26 row_mirror row_mask:0xf bank_mask:0xf bound_ctrl:1
	s_nop 0
	v_readlane_b32 s8, v26, 16
	v_readlane_b32 s9, v26, 48
	v_readlane_b32 s6, v26, 0
	v_readlane_b32 s7, v26, 32
	v_mov_b32_e32 v26, s8
	v_mov_b32_e32 v27, s9
	v_pk_add_f32 v[26:27], s[6:7], v[26:27]
	s_nop 0
	v_add_f32_e32 v26, v26, v27
	v_fmamk_f32 v26, v26, 0x3b800000, v252
	v_cmp_gt_f32_e32 vcc, s55, v26
	v_mul_f32_e32 v27, 0x4f800000, v26
	s_nop 0
	v_cndmask_b32_e32 v211, v26, v27, vcc
	v_add_f32_dpp v26, v35, v35 quad_perm:[1,0,3,2] row_mask:0xf bank_mask:0xf bound_ctrl:1
	v_sqrt_f32_e32 v214, v211
	s_nop 0
	v_add_f32_dpp v26, v26, v26 quad_perm:[2,3,0,1] row_mask:0xf bank_mask:0xf bound_ctrl:1
	v_add_u32_e32 v216, -1, v214
	s_nop 0
	v_add_f32_dpp v26, v26, v26 row_half_mirror row_mask:0xf bank_mask:0xf bound_ctrl:1
	v_add_u32_e32 v213, 1, v214
	v_fma_f32 v178, -v216, v214, v211
	v_add_f32_dpp v26, v26, v26 row_mirror row_mask:0xf bank_mask:0xf bound_ctrl:1
	v_fma_f32 v179, -v213, v214, v211
	v_readlane_b32 s8, v26, 16
	v_readlane_b32 s9, v26, 48
	v_readlane_b32 s6, v26, 0
	v_readlane_b32 s7, v26, 32
	v_mov_b32_e32 v26, s8
	v_mov_b32_e32 v27, s9
	v_pk_add_f32 v[26:27], s[6:7], v[26:27]
	s_nop 0
	v_add_f32_e32 v26, v26, v27
	v_fmamk_f32 v26, v26, 0x3b800000, v252
	v_cmp_gt_f32_e64 s[30:31], s55, v26
	v_mul_f32_e32 v27, 0x4f800000, v26
	s_nop 0
	v_cndmask_b32_e64 v202, v26, v27, s[30:31]
	v_add_f32_dpp v26, v38, v38 quad_perm:[1,0,3,2] row_mask:0xf bank_mask:0xf bound_ctrl:1
	v_sqrt_f32_e32 v205, v202
	s_nop 0
	v_add_f32_dpp v26, v26, v26 quad_perm:[2,3,0,1] row_mask:0xf bank_mask:0xf bound_ctrl:1
	v_add_u32_e32 v209, -1, v205
	s_nop 0
	v_add_f32_dpp v26, v26, v26 row_half_mirror row_mask:0xf bank_mask:0xf bound_ctrl:1
	v_add_u32_e32 v207, 1, v205
	s_nop 0
	v_add_f32_dpp v26, v26, v26 row_mirror row_mask:0xf bank_mask:0xf bound_ctrl:1
	s_nop 0
	v_readlane_b32 s8, v26, 16
	v_readlane_b32 s9, v26, 48
	v_readlane_b32 s6, v26, 0
	v_readlane_b32 s7, v26, 32
	v_mov_b32_e32 v26, s8
	v_mov_b32_e32 v27, s9
	v_pk_add_f32 v[26:27], s[6:7], v[26:27]
	s_nop 0
	v_add_f32_e32 v26, v26, v27
	v_fmamk_f32 v26, v26, 0x3b800000, v252
	v_cmp_gt_f32_e64 s[26:27], s55, v26
	v_mul_f32_e32 v27, 0x4f800000, v26
	s_nop 0
	v_cndmask_b32_e64 v194, v26, v27, s[26:27]
	v_add_f32_dpp v26, v39, v39 quad_perm:[1,0,3,2] row_mask:0xf bank_mask:0xf bound_ctrl:1
	v_sqrt_f32_e32 v197, v194
	s_nop 0
	v_add_f32_dpp v26, v26, v26 quad_perm:[2,3,0,1] row_mask:0xf bank_mask:0xf bound_ctrl:1
	v_add_u32_e32 v199, -1, v197
	s_nop 0
	v_add_f32_dpp v26, v26, v26 row_half_mirror row_mask:0xf bank_mask:0xf bound_ctrl:1
	v_add_u32_e32 v196, 1, v197
	s_nop 0
	v_add_f32_dpp v26, v26, v26 row_mirror row_mask:0xf bank_mask:0xf bound_ctrl:1
	s_nop 0
	v_readlane_b32 s8, v26, 16
	v_readlane_b32 s9, v26, 48
	v_readlane_b32 s6, v26, 0
	v_readlane_b32 s7, v26, 32
	v_mov_b32_e32 v26, s8
	v_mov_b32_e32 v27, s9
	v_pk_add_f32 v[26:27], s[6:7], v[26:27]
	s_nop 0
	v_add_f32_e32 v26, v26, v27
	v_fmamk_f32 v26, v26, 0x3b800000, v252
	v_cmp_gt_f32_e64 s[22:23], s55, v26
	v_mul_f32_e32 v27, 0x4f800000, v26
	s_nop 0
	v_cndmask_b32_e64 v186, v26, v27, s[22:23]
	v_add_f32_dpp v26, v56, v56 quad_perm:[1,0,3,2] row_mask:0xf bank_mask:0xf bound_ctrl:1
	v_sqrt_f32_e32 v189, v186
	s_nop 0
	v_add_f32_dpp v26, v26, v26 quad_perm:[2,3,0,1] row_mask:0xf bank_mask:0xf bound_ctrl:1
	v_add_u32_e32 v193, -1, v189
	s_nop 0
	v_add_f32_dpp v26, v26, v26 row_half_mirror row_mask:0xf bank_mask:0xf bound_ctrl:1
	v_add_u32_e32 v191, 1, v189
	s_nop 0
	v_add_f32_dpp v26, v26, v26 row_mirror row_mask:0xf bank_mask:0xf bound_ctrl:1
	s_nop 0
	v_readlane_b32 s8, v26, 16
	v_readlane_b32 s9, v26, 48
	v_readlane_b32 s6, v26, 0
	v_readlane_b32 s7, v26, 32
	v_mov_b32_e32 v26, s8
	v_mov_b32_e32 v27, s9
	v_pk_add_f32 v[26:27], s[6:7], v[26:27]
	s_nop 0
	v_add_f32_e32 v26, v26, v27
	v_fmamk_f32 v26, v26, 0x3b800000, v252
	v_cmp_gt_f32_e64 s[18:19], s55, v26
	v_mul_f32_e32 v27, 0x4f800000, v26
	s_nop 0
	v_cndmask_b32_e64 v172, v26, v27, s[18:19]
	v_add_f32_dpp v26, v57, v57 quad_perm:[1,0,3,2] row_mask:0xf bank_mask:0xf bound_ctrl:1
	v_sqrt_f32_e32 v175, v172
	s_nop 0
	v_add_f32_dpp v26, v26, v26 quad_perm:[2,3,0,1] row_mask:0xf bank_mask:0xf bound_ctrl:1
	v_add_u32_e32 v177, -1, v175
	s_nop 0
	v_add_f32_dpp v26, v26, v26 row_half_mirror row_mask:0xf bank_mask:0xf bound_ctrl:1
	v_add_u32_e32 v174, 1, v175
	s_nop 0
	v_add_f32_dpp v26, v26, v26 row_mirror row_mask:0xf bank_mask:0xf bound_ctrl:1
	s_nop 0
	v_readlane_b32 s8, v26, 16
	v_readlane_b32 s9, v26, 48
	v_readlane_b32 s6, v26, 0
	v_readlane_b32 s7, v26, 32
	v_mov_b32_e32 v26, s8
	v_mov_b32_e32 v27, s9
	v_pk_add_f32 v[26:27], s[6:7], v[26:27]
	s_nop 0
	v_add_f32_e32 v26, v26, v27
	v_fmamk_f32 v26, v26, 0x3b800000, v252
	v_cmp_gt_f32_e64 s[14:15], s55, v26
	v_mul_f32_e32 v27, 0x4f800000, v26
	s_nop 0
	v_cndmask_b32_e64 v164, v26, v27, s[14:15]
	v_add_f32_dpp v26, v74, v74 quad_perm:[1,0,3,2] row_mask:0xf bank_mask:0xf bound_ctrl:1
	v_sqrt_f32_e32 v167, v164
	s_nop 0
	v_add_f32_dpp v26, v26, v26 quad_perm:[2,3,0,1] row_mask:0xf bank_mask:0xf bound_ctrl:1
	v_add_u32_e32 v171, -1, v167
	s_nop 0
	v_add_f32_dpp v26, v26, v26 row_half_mirror row_mask:0xf bank_mask:0xf bound_ctrl:1
	v_add_u32_e32 v169, 1, v167
	s_nop 0
	v_add_f32_dpp v26, v26, v26 row_mirror row_mask:0xf bank_mask:0xf bound_ctrl:1
	s_nop 0
	v_readlane_b32 s8, v26, 16
	v_readlane_b32 s9, v26, 48
	v_readlane_b32 s6, v26, 0
	v_readlane_b32 s7, v26, 32
	v_mov_b32_e32 v26, s8
	v_mov_b32_e32 v27, s9
	v_pk_add_f32 v[26:27], s[6:7], v[26:27]
	s_nop 0
	v_add_f32_e32 v26, v26, v27
	v_fmamk_f32 v26, v26, 0x3b800000, v252
	v_cmp_gt_f32_e64 s[10:11], s55, v26
	v_mul_f32_e32 v27, 0x4f800000, v26
	s_nop 0
	v_cndmask_b32_e64 v156, v26, v27, s[10:11]
	v_add_f32_dpp v26, v30, v30 quad_perm:[1,0,3,2] row_mask:0xf bank_mask:0xf bound_ctrl:1
	v_lshlrev_b32_e32 v30, 16, v138
	v_sqrt_f32_e32 v159, v156
	v_add_f32_dpp v26, v26, v26 quad_perm:[2,3,0,1] row_mask:0xf bank_mask:0xf bound_ctrl:1
	v_add_u32_e32 v161, -1, v159
	s_nop 0
	v_add_f32_dpp v26, v26, v26 row_half_mirror row_mask:0xf bank_mask:0xf bound_ctrl:1
	v_add_u32_e32 v158, 1, v159
	s_nop 0
	v_add_f32_dpp v26, v26, v26 row_mirror row_mask:0xf bank_mask:0xf bound_ctrl:1
	s_nop 0
	v_readlane_b32 s8, v26, 16
	v_readlane_b32 s9, v26, 48
	v_readlane_b32 s6, v26, 0
	v_readlane_b32 s7, v26, 32
	v_mov_b32_e32 v26, s8
	v_mov_b32_e32 v27, s9
	v_pk_add_f32 v[26:27], s[6:7], v[26:27]
	s_nop 0
	v_add_f32_e32 v26, v26, v27
	v_fmamk_f32 v26, v26, 0x3b800000, v252
	v_cmp_gt_f32_e64 s[6:7], s55, v26
	v_mul_f32_e32 v27, 0x4f800000, v26
	s_nop 0
	v_cndmask_b32_e64 v150, v26, v27, s[6:7]
	v_lshlrev_b32_e32 v26, 16, v144
	v_and_b32_e32 v27, 0xffff0000, v144
	v_pk_add_f32 v[126:127], v[26:27], v[30:31]
	v_lshlrev_b32_e32 v26, 16, v145
	v_and_b32_e32 v27, 0xffff0000, v145
	v_lshlrev_b32_e32 v30, 16, v139
	v_and_b32_e32 v31, 0xffff0000, v139
	v_pk_add_f32 v[138:139], v[26:27], v[30:31]
	v_mov_b32_e32 v30, v127
	v_mov_b32_e32 v31, v139
	v_mov_b32_e32 v26, v126
	v_mov_b32_e32 v27, v138
	v_pk_mul_f32 v[30:31], v[30:31], v[30:31]
	v_sqrt_f32_e32 v151, v150
	v_pk_fma_f32 v[26:27], v[26:27], v[26:27], v[30:31]
	s_waitcnt vmcnt(27)
	v_lshlrev_b32_e32 v30, 16, v128
	v_add_f32_e32 v34, v26, v27
	v_lshlrev_b32_e32 v26, 16, v132
	v_and_b32_e32 v27, 0xffff0000, v132
	v_and_b32_e32 v31, 0xffff0000, v128
	v_pk_add_f32 v[114:115], v[26:27], v[30:31]
	v_lshlrev_b32_e32 v26, 16, v133
	v_and_b32_e32 v27, 0xffff0000, v133
	v_lshlrev_b32_e32 v30, 16, v129
	v_and_b32_e32 v31, 0xffff0000, v129
	v_pk_add_f32 v[118:119], v[26:27], v[30:31]
	v_mov_b32_e32 v30, v115
	v_mov_b32_e32 v31, v119
	v_mov_b32_e32 v26, v114
	v_mov_b32_e32 v27, v118
	v_pk_mul_f32 v[30:31], v[30:31], v[30:31]
	v_add_u32_e32 v155, -1, v151
	v_pk_fma_f32 v[26:27], v[26:27], v[26:27], v[30:31]
	s_waitcnt vmcnt(24)
	v_lshlrev_b32_e32 v30, 16, v120
	v_add_f32_e32 v35, v26, v27
	v_lshlrev_b32_e32 v26, 16, v124
	v_and_b32_e32 v27, 0xffff0000, v124
	v_and_b32_e32 v31, 0xffff0000, v120
	v_pk_add_f32 v[102:103], v[26:27], v[30:31]
	v_lshlrev_b32_e32 v26, 16, v125
	v_and_b32_e32 v27, 0xffff0000, v125
	v_lshlrev_b32_e32 v30, 16, v121
	v_and_b32_e32 v31, 0xffff0000, v121
	v_pk_add_f32 v[106:107], v[26:27], v[30:31]
	v_mov_b32_e32 v30, v103
	v_mov_b32_e32 v31, v107
	v_mov_b32_e32 v26, v102
	v_mov_b32_e32 v27, v106
	v_pk_mul_f32 v[30:31], v[30:31], v[30:31]
	v_add_u32_e32 v153, 1, v151
	v_pk_fma_f32 v[26:27], v[26:27], v[26:27], v[30:31]
	s_waitcnt vmcnt(21)
	v_lshlrev_b32_e32 v30, 16, v116
	v_add_f32_e32 v38, v26, v27
	v_lshlrev_b32_e32 v26, 16, v112
	v_and_b32_e32 v27, 0xffff0000, v112
	v_and_b32_e32 v31, 0xffff0000, v116
	v_pk_add_f32 v[90:91], v[26:27], v[30:31]
	v_lshlrev_b32_e32 v26, 16, v113
	v_and_b32_e32 v27, 0xffff0000, v113
	v_lshlrev_b32_e32 v30, 16, v117
	v_and_b32_e32 v31, 0xffff0000, v117
	v_pk_add_f32 v[94:95], v[26:27], v[30:31]
	v_mov_b32_e32 v30, v91
	v_mov_b32_e32 v31, v95
	v_mov_b32_e32 v26, v90
	v_mov_b32_e32 v27, v94
	v_pk_mul_f32 v[30:31], v[30:31], v[30:31]
	s_nop 0
	v_pk_fma_f32 v[26:27], v[26:27], v[26:27], v[30:31]
	s_waitcnt vmcnt(18)
	v_lshlrev_b32_e32 v30, 16, v104
	v_add_f32_e32 v39, v26, v27
	v_lshlrev_b32_e32 v26, 16, v108
	v_and_b32_e32 v27, 0xffff0000, v108
	v_and_b32_e32 v31, 0xffff0000, v104
	v_pk_add_f32 v[82:83], v[26:27], v[30:31]
	v_lshlrev_b32_e32 v26, 16, v109
	v_and_b32_e32 v27, 0xffff0000, v109
	v_lshlrev_b32_e32 v30, 16, v105
	v_and_b32_e32 v31, 0xffff0000, v105
	v_pk_add_f32 v[84:85], v[26:27], v[30:31]
	v_mov_b32_e32 v30, v83
	v_mov_b32_e32 v31, v85
	v_mov_b32_e32 v26, v82
	v_mov_b32_e32 v27, v84
	v_pk_mul_f32 v[30:31], v[30:31], v[30:31]
	s_nop 0
	v_pk_fma_f32 v[26:27], v[26:27], v[26:27], v[30:31]
	s_waitcnt vmcnt(15)
	v_lshlrev_b32_e32 v30, 16, v96
	v_add_f32_e32 v58, v26, v27
	v_lshlrev_b32_e32 v26, 16, v100
	v_and_b32_e32 v27, 0xffff0000, v100
	v_and_b32_e32 v31, 0xffff0000, v96
	v_pk_add_f32 v[74:75], v[26:27], v[30:31]
	v_lshlrev_b32_e32 v26, 16, v101
	v_and_b32_e32 v27, 0xffff0000, v101
	v_lshlrev_b32_e32 v30, 16, v97
	v_and_b32_e32 v31, 0xffff0000, v97
	v_pk_add_f32 v[76:77], v[26:27], v[30:31]
	v_mov_b32_e32 v30, v75
	v_mov_b32_e32 v31, v77
	v_mov_b32_e32 v26, v74
	v_mov_b32_e32 v27, v76
	v_pk_mul_f32 v[30:31], v[30:31], v[30:31]
	s_nop 0
	v_pk_fma_f32 v[26:27], v[26:27], v[26:27], v[30:31]
	s_waitcnt vmcnt(12)
	v_lshlrev_b32_e32 v30, 16, v66
	v_add_f32_e32 v59, v26, v27
	v_lshlrev_b32_e32 v26, 16, v92
	v_and_b32_e32 v27, 0xffff0000, v92
	v_and_b32_e32 v31, 0xffff0000, v66
	v_pk_add_f32 v[64:65], v[26:27], v[30:31]
	v_lshlrev_b32_e32 v26, 16, v93
	v_and_b32_e32 v27, 0xffff0000, v93
	v_lshlrev_b32_e32 v30, 16, v67
	v_and_b32_e32 v31, 0xffff0000, v67
	v_pk_add_f32 v[66:67], v[26:27], v[30:31]
	v_mov_b32_e32 v30, v65
	v_mov_b32_e32 v31, v67
	v_mov_b32_e32 v26, v64
	v_mov_b32_e32 v27, v66
	v_pk_mul_f32 v[30:31], v[30:31], v[30:31]
	s_nop 0
	v_pk_fma_f32 v[26:27], v[26:27], v[26:27], v[30:31]
	s_waitcnt vmcnt(9)
	v_lshlrev_b32_e32 v30, 16, v60
	v_add_f32_e32 v92, v26, v27
	v_lshlrev_b32_e32 v26, 16, v54
	v_and_b32_e32 v27, 0xffff0000, v54
	v_and_b32_e32 v31, 0xffff0000, v60
	v_pk_add_f32 v[56:57], v[26:27], v[30:31]
	v_lshlrev_b32_e32 v26, 16, v55
	v_and_b32_e32 v27, 0xffff0000, v55
	v_lshlrev_b32_e32 v30, 16, v61
	v_and_b32_e32 v31, 0xffff0000, v61
	v_pk_add_f32 v[54:55], v[26:27], v[30:31]
	v_mov_b32_e32 v30, v57
	v_mov_b32_e32 v31, v55
	v_mov_b32_e32 v26, v56
	v_mov_b32_e32 v27, v54
	v_pk_mul_f32 v[30:31], v[30:31], v[30:31]
	v_lshl_add_u64 v[60:61], v[6:7], 0, v[0:1]
	v_pk_fma_f32 v[26:27], v[26:27], v[26:27], v[30:31]
	v_lshl_add_u64 v[6:7], v[8:9], 0, s[48:49]
	v_add_f32_e32 v30, v26, v27
	v_add_f32_dpp v26, v34, v34 quad_perm:[1,0,3,2] row_mask:0xf bank_mask:0xf bound_ctrl:1
	v_lshl_add_u64 v[148:149], v[6:7], 0, v[0:1]
	s_nop 0
	v_add_f32_dpp v26, v26, v26 quad_perm:[2,3,0,1] row_mask:0xf bank_mask:0xf bound_ctrl:1
	s_nop 1
	v_add_f32_dpp v26, v26, v26 row_half_mirror row_mask:0xf bank_mask:0xf bound_ctrl:1
	s_nop 1
	v_add_f32_dpp v26, v26, v26 row_mirror row_mask:0xf bank_mask:0xf bound_ctrl:1
	s_nop 0
	v_readlane_b32 s12, v26, 16
	v_readlane_b32 s13, v26, 48
	v_readlane_b32 s8, v26, 0
	v_readlane_b32 s9, v26, 32
	v_mov_b32_e32 v26, s12
	v_mov_b32_e32 v27, s13
	v_pk_add_f32 v[26:27], s[8:9], v[26:27]
	s_nop 0
	v_add_f32_e32 v26, v26, v27
	v_fmamk_f32 v26, v26, 0x3b800000, v252
	v_cmp_gt_f32_e64 s[36:37], s55, v26
	v_mul_f32_e32 v27, 0x4f800000, v26
	s_nop 0
	v_cndmask_b32_e64 v215, v26, v27, s[36:37]
	v_add_f32_dpp v26, v35, v35 quad_perm:[1,0,3,2] row_mask:0xf bank_mask:0xf bound_ctrl:1
	v_sqrt_f32_e32 v218, v215
	s_nop 0
	v_add_f32_dpp v26, v26, v26 quad_perm:[2,3,0,1] row_mask:0xf bank_mask:0xf bound_ctrl:1
	v_add_u32_e32 v219, -1, v218
	s_nop 0
	v_add_f32_dpp v26, v26, v26 row_half_mirror row_mask:0xf bank_mask:0xf bound_ctrl:1
	v_add_u32_e32 v217, 1, v218
	s_nop 0
	v_add_f32_dpp v26, v26, v26 row_mirror row_mask:0xf bank_mask:0xf bound_ctrl:1
	s_nop 0
	v_readlane_b32 s12, v26, 16
	v_readlane_b32 s13, v26, 48
	v_readlane_b32 s8, v26, 0
	v_readlane_b32 s9, v26, 32
	v_mov_b32_e32 v26, s12
	v_mov_b32_e32 v27, s13
	v_pk_add_f32 v[26:27], s[8:9], v[26:27]
	s_nop 0
	v_add_f32_e32 v26, v26, v27
	v_fmamk_f32 v26, v26, 0x3b800000, v252
	v_cmp_gt_f32_e64 s[34:35], s55, v26
	v_mul_f32_e32 v27, 0x4f800000, v26
	s_nop 0
	v_cndmask_b32_e64 v206, v26, v27, s[34:35]
	v_add_f32_dpp v26, v38, v38 quad_perm:[1,0,3,2] row_mask:0xf bank_mask:0xf bound_ctrl:1
	v_sqrt_f32_e32 v208, v206
	s_nop 0
	v_add_f32_dpp v26, v26, v26 quad_perm:[2,3,0,1] row_mask:0xf bank_mask:0xf bound_ctrl:1
	v_add_u32_e32 v212, -1, v208
	s_nop 0
	v_add_f32_dpp v26, v26, v26 row_half_mirror row_mask:0xf bank_mask:0xf bound_ctrl:1
	v_add_u32_e32 v210, 1, v208
	s_nop 0
	v_add_f32_dpp v26, v26, v26 row_mirror row_mask:0xf bank_mask:0xf bound_ctrl:1
	s_nop 0
	v_readlane_b32 s12, v26, 16
	v_readlane_b32 s13, v26, 48
	v_readlane_b32 s8, v26, 0
	v_readlane_b32 s9, v26, 32
	v_mov_b32_e32 v26, s12
	v_mov_b32_e32 v27, s13
	v_pk_add_f32 v[26:27], s[8:9], v[26:27]
	s_nop 0
	v_add_f32_e32 v26, v26, v27
	v_fmamk_f32 v26, v26, 0x3b800000, v252
	v_cmp_gt_f32_e64 s[28:29], s55, v26
	v_mul_f32_e32 v27, 0x4f800000, v26
	s_nop 0
	v_cndmask_b32_e64 v200, v26, v27, s[28:29]
	v_add_f32_dpp v26, v39, v39 quad_perm:[1,0,3,2] row_mask:0xf bank_mask:0xf bound_ctrl:1
	v_sqrt_f32_e32 v203, v200
	s_nop 0
	v_add_f32_dpp v26, v26, v26 quad_perm:[2,3,0,1] row_mask:0xf bank_mask:0xf bound_ctrl:1
	v_add_u32_e32 v204, -1, v203
	s_nop 0
	v_add_f32_dpp v26, v26, v26 row_half_mirror row_mask:0xf bank_mask:0xf bound_ctrl:1
	v_add_u32_e32 v201, 1, v203
	s_nop 0
	v_add_f32_dpp v26, v26, v26 row_mirror row_mask:0xf bank_mask:0xf bound_ctrl:1
	s_nop 0
	v_readlane_b32 s12, v26, 16
	v_readlane_b32 s13, v26, 48
	v_readlane_b32 s8, v26, 0
	v_readlane_b32 s9, v26, 32
	v_mov_b32_e32 v26, s12
	v_mov_b32_e32 v27, s13
	v_pk_add_f32 v[26:27], s[8:9], v[26:27]
	s_nop 0
	v_add_f32_e32 v26, v26, v27
	v_fmamk_f32 v26, v26, 0x3b800000, v252
	v_cmp_gt_f32_e64 s[24:25], s55, v26
	v_mul_f32_e32 v27, 0x4f800000, v26
	s_nop 0
	v_cndmask_b32_e64 v190, v26, v27, s[24:25]
	v_add_f32_dpp v26, v58, v58 quad_perm:[1,0,3,2] row_mask:0xf bank_mask:0xf bound_ctrl:1
	v_sqrt_f32_e32 v192, v190
	s_nop 0
	v_add_f32_dpp v26, v26, v26 quad_perm:[2,3,0,1] row_mask:0xf bank_mask:0xf bound_ctrl:1
	v_add_u32_e32 v198, -1, v192
	s_nop 0
	v_add_f32_dpp v26, v26, v26 row_half_mirror row_mask:0xf bank_mask:0xf bound_ctrl:1
	v_add_u32_e32 v195, 1, v192
	s_nop 0
	v_add_f32_dpp v26, v26, v26 row_mirror row_mask:0xf bank_mask:0xf bound_ctrl:1
	s_nop 0
	v_readlane_b32 s12, v26, 16
	v_readlane_b32 s13, v26, 48
	v_readlane_b32 s8, v26, 0
	v_readlane_b32 s9, v26, 32
	v_mov_b32_e32 v26, s12
	v_mov_b32_e32 v27, s13
	v_pk_add_f32 v[26:27], s[8:9], v[26:27]
	s_nop 0
	v_add_f32_e32 v26, v26, v27
	v_fmamk_f32 v26, v26, 0x3b800000, v252
	v_cmp_gt_f32_e64 s[20:21], s55, v26
	v_mul_f32_e32 v27, 0x4f800000, v26
	s_nop 0
	v_cndmask_b32_e64 v184, v26, v27, s[20:21]
	v_add_f32_dpp v26, v59, v59 quad_perm:[1,0,3,2] row_mask:0xf bank_mask:0xf bound_ctrl:1
	v_sqrt_f32_e32 v187, v184
	s_nop 0
	v_add_f32_dpp v26, v26, v26 quad_perm:[2,3,0,1] row_mask:0xf bank_mask:0xf bound_ctrl:1
	v_add_u32_e32 v188, -1, v187
	s_nop 0
	v_add_f32_dpp v26, v26, v26 row_half_mirror row_mask:0xf bank_mask:0xf bound_ctrl:1
	v_add_u32_e32 v185, 1, v187
	s_nop 0
	v_add_f32_dpp v26, v26, v26 row_mirror row_mask:0xf bank_mask:0xf bound_ctrl:1
	s_nop 0
	v_readlane_b32 s12, v26, 16
	v_readlane_b32 s13, v26, 48
	v_readlane_b32 s8, v26, 0
	v_readlane_b32 s9, v26, 32
	v_mov_b32_e32 v26, s12
	v_mov_b32_e32 v27, s13
; template <bool HG>
; __device__ __forceinline__ void readout_phase2(const Args& a, Frame& F, const float* gain, int nrows) {
;     ...
;     RO_LOAD(f2, b2, g2, cx ? ML + nw : nw + 7 * 2048);
	v_pk_add_f32 v[26:27], s[8:9], v[26:27]
	s_nop 0
	v_add_f32_e32 v26, v26, v27
	v_fmamk_f32 v26, v26, 0x3b800000, v252
	v_cmp_gt_f32_e64 s[16:17], s55, v26
	v_mul_f32_e32 v27, 0x4f800000, v26
	s_nop 0
	v_cndmask_b32_e64 v168, v26, v27, s[16:17]
	v_add_f32_dpp v26, v92, v92 quad_perm:[1,0,3,2] row_mask:0xf bank_mask:0xf bound_ctrl:1
	v_sqrt_f32_e32 v170, v168
	s_nop 0
	v_add_f32_dpp v26, v26, v26 quad_perm:[2,3,0,1] row_mask:0xf bank_mask:0xf bound_ctrl:1
	v_add_u32_e32 v176, -1, v170
	s_nop 0
	v_add_f32_dpp v26, v26, v26 row_half_mirror row_mask:0xf bank_mask:0xf bound_ctrl:1
	v_add_u32_e32 v173, 1, v170
	s_nop 0
	v_add_f32_dpp v26, v26, v26 row_mirror row_mask:0xf bank_mask:0xf bound_ctrl:1
	s_nop 0
	v_readlane_b32 s12, v26, 16
	v_readlane_b32 s13, v26, 48
	v_readlane_b32 s8, v26, 0
	v_readlane_b32 s9, v26, 32
	v_mov_b32_e32 v26, s12
	v_mov_b32_e32 v27, s13
	v_pk_add_f32 v[26:27], s[8:9], v[26:27]
	s_nop 0
	v_add_f32_e32 v26, v26, v27
	v_fmamk_f32 v26, v26, 0x3b800000, v252
	v_cmp_gt_f32_e64 s[12:13], s55, v26
	v_mul_f32_e32 v27, 0x4f800000, v26
	s_nop 0
	v_cndmask_b32_e64 v162, v26, v27, s[12:13]
	v_add_f32_dpp v26, v30, v30 quad_perm:[1,0,3,2] row_mask:0xf bank_mask:0xf bound_ctrl:1
	v_sqrt_f32_e32 v165, v162
	s_nop 0
	v_add_f32_dpp v26, v26, v26 quad_perm:[2,3,0,1] row_mask:0xf bank_mask:0xf bound_ctrl:1
	v_add_u32_e32 v166, -1, v165
	s_nop 0
	v_add_f32_dpp v26, v26, v26 row_half_mirror row_mask:0xf bank_mask:0xf bound_ctrl:1
	v_add_u32_e32 v163, 1, v165
	s_nop 0
	v_add_f32_dpp v26, v26, v26 row_mirror row_mask:0xf bank_mask:0xf bound_ctrl:1
	s_nop 0
	v_readlane_b32 s33, v26, 16
	v_readlane_b32 s44, v26, 48
	v_readlane_b32 s8, v26, 0
	v_readlane_b32 s9, v26, 32
	v_mov_b32_e32 v26, s33
	v_mov_b32_e32 v27, s44
	v_pk_add_f32 v[26:27], s[8:9], v[26:27]
	s_nop 0
	v_add_f32_e32 v26, v26, v27
	v_fmamk_f32 v26, v26, 0x3b800000, v252
	v_cmp_gt_f32_e64 s[8:9], s55, v26
	v_mul_f32_e32 v27, 0x4f800000, v26
	s_nop 0
	v_cndmask_b32_e64 v152, v26, v27, s[8:9]
	global_load_dwordx2 v[146:147], v[4:5], off nt
	global_load_dwordx2 v[144:145], v[60:61], off nt
	global_load_dwordx2 v[58:59], v[148:149], off nt
	global_load_dwordx2 v[132:133], v[4:5], off offset:512 nt
	global_load_dwordx2 v[128:129], v[60:61], off offset:512 nt
	global_load_dwordx2 v[38:39], v[148:149], off offset:512 nt
	global_load_dwordx2 v[124:125], v[4:5], off offset:1024 nt
	global_load_dwordx2 v[120:121], v[60:61], off offset:1024 nt
	global_load_dwordx2 v[34:35], v[148:149], off offset:1024 nt
	global_load_dwordx2 v[116:117], v[4:5], off offset:1536 nt
	global_load_dwordx2 v[112:113], v[60:61], off offset:1536 nt
	global_load_dwordx2 v[30:31], v[148:149], off offset:1536 nt
	global_load_dwordx2 v[110:111], v[4:5], off offset:2048 nt
	global_load_dwordx2 v[108:109], v[60:61], off offset:2048 nt
	global_load_dwordx2 v[26:27], v[148:149], off offset:2048 nt
	global_load_dwordx2 v[104:105], v[4:5], off offset:2560 nt
	global_load_dwordx2 v[100:101], v[60:61], off offset:2560 nt
	global_load_dwordx2 v[8:9], v[148:149], off offset:2560 nt
	global_load_dwordx2 v[98:99], v[4:5], off offset:3072 nt
	global_load_dwordx2 v[96:97], v[60:61], off offset:3072 nt
	global_load_dwordx2 v[6:7], v[148:149], off offset:3072 nt
	global_load_dwordx2 v[92:93], v[4:5], off offset:3584 nt
	s_nop 0
	global_load_dwordx2 v[60:61], v[60:61], off offset:3584 nt
	s_nop 0
	global_load_dwordx2 v[4:5], v[148:149], off offset:3584 nt
	v_lshl_add_u64 v[148:149], v[2:3], 0, s[40:41]
	v_cmp_ge_f32_e64 s[40:41], 0, v178
	v_lshl_add_u64 v[148:149], v[148:149], 0, v[0:1]
	v_sqrt_f32_e32 v154, v152
	v_cndmask_b32_e64 v178, v214, v216, s[40:41]
	v_cmp_lt_f32_e64 s[40:41], 0, v179
	v_add_u32_e32 v160, -1, v154
	s_nop 0
	v_cndmask_b32_e64 v178, v178, v213, s[40:41]
	v_mul_f32_e32 v179, 0x37800000, v178
	v_cndmask_b32_e32 v178, v178, v179, vcc
	v_cmp_class_f32_e32 vcc, v211, v253
	v_add_u32_e32 v157, 1, v154
	s_nop 0
	v_cndmask_b32_e32 v178, v178, v211, vcc
	v_div_scale_f32 v179, s[40:41], v178, v178, 1.0
	v_rcp_f32_e32 v180, v179
	s_nop 0
	v_fma_f32 v181, -v179, v180, 1.0
	v_fmac_f32_e32 v180, v181, v180
	v_div_scale_f32 v181, vcc, 1.0, v178, 1.0
	v_mul_f32_e32 v211, v181, v180
	v_fma_f32 v213, -v179, v211, v181
	v_fmac_f32_e32 v211, v213, v180
	v_fma_f32 v179, -v179, v211, v181
	v_div_fmas_f32 v179, v179, v180, v211
	v_div_fixup_f32 v178, v179, v178, 1.0
	v_lshlrev_b32_e32 v180, 16, v24
	v_and_b32_e32 v181, 0xffff0000, v24
	v_lshlrev_b32_e32 v24, 16, v25
	v_and_b32_e32 v25, 0xffff0000, v25
	v_pk_mul_f32 v[140:141], v[140:141], v[178:179] op_sel_hi:[1,0]
	v_pk_mul_f32 v[142:143], v[142:143], v[178:179] op_sel_hi:[1,0]
	v_pk_mul_f32 v[140:141], v[140:141], v[180:181]
	v_pk_mul_f32 v[24:25], v[142:143], v[24:25]
	v_cvt_pk_bf16_f32 v140, v140, v141
	v_cvt_pk_bf16_f32 v141, v24, v25
	v_fma_f32 v24, -v209, v205, v202
	v_cmp_ge_f32_e32 vcc, 0, v24
	v_fma_f32 v25, -v207, v205, v202
	global_store_dwordx2 v[148:149], v[140:141], off
	v_cndmask_b32_e32 v24, v205, v209, vcc
	v_cmp_lt_f32_e32 vcc, 0, v25
	s_nop 1
	v_cndmask_b32_e32 v24, v24, v207, vcc
	v_mul_f32_e32 v25, 0x37800000, v24
	v_cndmask_b32_e64 v24, v24, v25, s[30:31]
	v_cmp_class_f32_e32 vcc, v202, v253
	s_nop 1
	v_cndmask_b32_e32 v24, v24, v202, vcc
	v_div_scale_f32 v25, s[30:31], v24, v24, 1.0
	v_rcp_f32_e32 v140, v25
	s_nop 0
	v_fma_f32 v141, -v25, v140, 1.0
	v_fmac_f32_e32 v140, v141, v140
	v_div_scale_f32 v141, vcc, 1.0, v24, 1.0
	v_mul_f32_e32 v142, v141, v140
	v_fma_f32 v143, -v25, v142, v141
	v_fmac_f32_e32 v142, v143, v140
	v_fma_f32 v25, -v25, v142, v141
	v_div_fmas_f32 v25, v25, v140, v142
	v_div_fixup_f32 v24, v25, v24, 1.0
	v_lshlrev_b32_e32 v140, 16, v22
	v_and_b32_e32 v141, 0xffff0000, v22
	v_lshlrev_b32_e32 v22, 16, v23
	v_and_b32_e32 v23, 0xffff0000, v23
	v_pk_mul_f32 v[134:135], v[134:135], v[24:25] op_sel_hi:[1,0]
	v_pk_mul_f32 v[24:25], v[136:137], v[24:25] op_sel_hi:[1,0]
	s_nop 0
	v_pk_mul_f32 v[22:23], v[24:25], v[22:23]
	v_pk_mul_f32 v[24:25], v[134:135], v[140:141]
	s_nop 0
	v_cvt_pk_bf16_f32 v24, v24, v25
	v_cvt_pk_bf16_f32 v25, v22, v23
	v_fma_f32 v22, -v199, v197, v194
	v_cmp_ge_f32_e32 vcc, 0, v22
	v_fma_f32 v23, -v196, v197, v194
	global_store_dwordx2 v[148:149], v[24:25], off offset:512
	v_cndmask_b32_e32 v22, v197, v199, vcc
	v_cmp_lt_f32_e32 vcc, 0, v23
	s_nop 1
	v_cndmask_b32_e32 v22, v22, v196, vcc
	v_mul_f32_e32 v23, 0x37800000, v22
	v_cndmask_b32_e64 v22, v22, v23, s[26:27]
	v_cmp_class_f32_e32 vcc, v194, v253
	s_nop 1
	v_cndmask_b32_e32 v22, v22, v194, vcc
	v_div_scale_f32 v23, s[26:27], v22, v22, 1.0
	v_rcp_f32_e32 v24, v23
	s_nop 0
	v_fma_f32 v25, -v23, v24, 1.0
	v_fmac_f32_e32 v24, v25, v24
	v_div_scale_f32 v25, vcc, 1.0, v22, 1.0
	v_mul_f32_e32 v134, v25, v24
	v_fma_f32 v135, -v23, v134, v25
	v_fmac_f32_e32 v134, v135, v24
	v_fma_f32 v23, -v23, v134, v25
	v_div_fmas_f32 v23, v23, v24, v134
	v_div_fixup_f32 v22, v23, v22, 1.0
	v_lshlrev_b32_e32 v24, 16, v20
	v_and_b32_e32 v25, 0xffff0000, v20
	v_lshlrev_b32_e32 v20, 16, v21
	v_and_b32_e32 v21, 0xffff0000, v21
	v_pk_mul_f32 v[130:131], v[130:131], v[22:23] op_sel_hi:[1,0]
	v_pk_mul_f32 v[22:23], v[122:123], v[22:23] op_sel_hi:[1,0]
	s_nop 0
	v_pk_mul_f32 v[20:21], v[22:23], v[20:21]
	v_pk_mul_f32 v[22:23], v[130:131], v[24:25]
	s_nop 0
	v_cvt_pk_bf16_f32 v22, v22, v23
	v_cvt_pk_bf16_f32 v23, v20, v21
	v_fma_f32 v20, -v193, v189, v186
	v_cmp_ge_f32_e32 vcc, 0, v20
	v_fma_f32 v21, -v191, v189, v186
	global_store_dwordx2 v[148:149], v[22:23], off offset:1024
	v_cndmask_b32_e32 v20, v189, v193, vcc
	v_cmp_lt_f32_e32 vcc, 0, v21
	s_nop 1
	v_cndmask_b32_e32 v20, v20, v191, vcc
	v_mul_f32_e32 v21, 0x37800000, v20
	v_cndmask_b32_e64 v20, v20, v21, s[22:23]
	v_cmp_class_f32_e32 vcc, v186, v253
	s_nop 1
	v_cndmask_b32_e32 v20, v20, v186, vcc
	v_div_scale_f32 v21, s[22:23], v20, v20, 1.0
	v_rcp_f32_e32 v22, v21
	s_nop 0
	v_fma_f32 v23, -v21, v22, 1.0
	v_fmac_f32_e32 v22, v23, v22
	v_div_scale_f32 v23, vcc, 1.0, v20, 1.0
	v_mul_f32_e32 v24, v23, v22
	v_fma_f32 v25, -v21, v24, v23
	v_fmac_f32_e32 v24, v25, v22
	v_fma_f32 v21, -v21, v24, v23
	v_div_fmas_f32 v21, v21, v22, v24
	v_div_fixup_f32 v20, v21, v20, 1.0
	v_lshlrev_b32_e32 v22, 16, v18
	v_and_b32_e32 v23, 0xffff0000, v18
	v_lshlrev_b32_e32 v18, 16, v19
	v_and_b32_e32 v19, 0xffff0000, v19
	v_pk_mul_f32 v[24:25], v[86:87], v[20:21] op_sel_hi:[1,0]
	v_pk_mul_f32 v[20:21], v[88:89], v[20:21] op_sel_hi:[1,0]
	s_nop 0
	v_pk_mul_f32 v[18:19], v[20:21], v[18:19]
	v_pk_mul_f32 v[20:21], v[24:25], v[22:23]
	s_nop 0
	v_cvt_pk_bf16_f32 v20, v20, v21
	v_cvt_pk_bf16_f32 v21, v18, v19
	v_fma_f32 v18, -v177, v175, v172
	v_cmp_ge_f32_e32 vcc, 0, v18
	v_fma_f32 v19, -v174, v175, v172
	global_store_dwordx2 v[148:149], v[20:21], off offset:1536
	v_cndmask_b32_e32 v18, v175, v177, vcc
	v_cmp_lt_f32_e32 vcc, 0, v19
	s_nop 1
	v_cndmask_b32_e32 v18, v18, v174, vcc
	v_mul_f32_e32 v19, 0x37800000, v18
	v_cndmask_b32_e64 v18, v18, v19, s[18:19]
	v_cmp_class_f32_e32 vcc, v172, v253
	s_nop 1
	v_cndmask_b32_e32 v18, v18, v172, vcc
	v_div_scale_f32 v19, s[18:19], v18, v18, 1.0
	v_rcp_f32_e32 v20, v19
	s_nop 0
	v_fma_f32 v21, -v19, v20, 1.0
	v_fmac_f32_e32 v20, v21, v20
	v_div_scale_f32 v21, vcc, 1.0, v18, 1.0
	v_mul_f32_e32 v22, v21, v20
	v_fma_f32 v23, -v19, v22, v21
	v_fmac_f32_e32 v22, v23, v20
	v_fma_f32 v19, -v19, v22, v21
	v_div_fmas_f32 v19, v19, v20, v22
	v_div_fixup_f32 v18, v19, v18, 1.0
	v_lshlrev_b32_e32 v20, 16, v16
	v_and_b32_e32 v21, 0xffff0000, v16
	v_lshlrev_b32_e32 v16, 16, v17
	v_and_b32_e32 v17, 0xffff0000, v17
	v_pk_mul_f32 v[22:23], v[78:79], v[18:19] op_sel_hi:[1,0]
	v_pk_mul_f32 v[18:19], v[80:81], v[18:19] op_sel_hi:[1,0]
	s_nop 0
	v_pk_mul_f32 v[16:17], v[18:19], v[16:17]
	v_pk_mul_f32 v[18:19], v[22:23], v[20:21]
	s_nop 0
	v_cvt_pk_bf16_f32 v18, v18, v19
	v_cvt_pk_bf16_f32 v19, v16, v17
	v_fma_f32 v16, -v171, v167, v164
	v_cmp_ge_f32_e32 vcc, 0, v16
	v_fma_f32 v17, -v169, v167, v164
	global_store_dwordx2 v[148:149], v[18:19], off offset:2048
	v_cndmask_b32_e32 v16, v167, v171, vcc
	v_cmp_lt_f32_e32 vcc, 0, v17
	s_nop 1
	v_cndmask_b32_e32 v16, v16, v169, vcc
	v_mul_f32_e32 v17, 0x37800000, v16
	v_cndmask_b32_e64 v16, v16, v17, s[14:15]
	v_cmp_class_f32_e32 vcc, v164, v253
	s_nop 1
	v_cndmask_b32_e32 v16, v16, v164, vcc
	v_div_scale_f32 v17, s[14:15], v16, v16, 1.0
	v_rcp_f32_e32 v18, v17
	s_nop 0
	v_fma_f32 v19, -v17, v18, 1.0
	v_fmac_f32_e32 v18, v19, v18
	v_div_scale_f32 v19, vcc, 1.0, v16, 1.0
	v_mul_f32_e32 v20, v19, v18
	v_fma_f32 v21, -v17, v20, v19
	v_fmac_f32_e32 v20, v21, v18
	v_fma_f32 v17, -v17, v20, v19
	v_div_fmas_f32 v17, v17, v18, v20
	v_div_fixup_f32 v16, v17, v16, 1.0
	v_lshlrev_b32_e32 v18, 16, v14
	v_and_b32_e32 v19, 0xffff0000, v14
	v_lshlrev_b32_e32 v14, 16, v15
	v_and_b32_e32 v15, 0xffff0000, v15
	v_pk_mul_f32 v[20:21], v[70:71], v[16:17] op_sel_hi:[1,0]
	v_pk_mul_f32 v[16:17], v[72:73], v[16:17] op_sel_hi:[1,0]
	s_nop 0
	v_pk_mul_f32 v[14:15], v[16:17], v[14:15]
	v_pk_mul_f32 v[16:17], v[20:21], v[18:19]
	s_nop 0
	v_cvt_pk_bf16_f32 v16, v16, v17
	v_cvt_pk_bf16_f32 v17, v14, v15
	v_fma_f32 v14, -v161, v159, v156
	v_cmp_ge_f32_e32 vcc, 0, v14
	v_fma_f32 v15, -v158, v159, v156
	global_store_dwordx2 v[148:149], v[16:17], off offset:2560
	v_cndmask_b32_e32 v14, v159, v161, vcc
	v_cmp_lt_f32_e32 vcc, 0, v15
	s_nop 1
	v_cndmask_b32_e32 v14, v14, v158, vcc
	v_mul_f32_e32 v15, 0x37800000, v14
	v_cndmask_b32_e64 v14, v14, v15, s[10:11]
	v_cmp_class_f32_e32 vcc, v156, v253
	s_nop 1
	v_cndmask_b32_e32 v14, v14, v156, vcc
	v_div_scale_f32 v15, s[10:11], v14, v14, 1.0
	v_rcp_f32_e32 v16, v15
	s_nop 0
	v_fma_f32 v17, -v15, v16, 1.0
	v_fmac_f32_e32 v16, v17, v16
	v_div_scale_f32 v17, vcc, 1.0, v14, 1.0
	v_mul_f32_e32 v18, v17, v16
	v_fma_f32 v19, -v15, v18, v17
	v_fmac_f32_e32 v18, v19, v16
	v_fma_f32 v15, -v15, v18, v17
	v_div_fmas_f32 v15, v15, v16, v18
	v_div_fixup_f32 v14, v15, v14, 1.0
	v_lshlrev_b32_e32 v16, 16, v12
	v_and_b32_e32 v17, 0xffff0000, v12
	v_lshlrev_b32_e32 v12, 16, v13
	v_and_b32_e32 v13, 0xffff0000, v13
	v_pk_mul_f32 v[18:19], v[62:63], v[14:15] op_sel_hi:[1,0]
	v_pk_mul_f32 v[14:15], v[68:69], v[14:15] op_sel_hi:[1,0]
	s_nop 0
	v_pk_mul_f32 v[12:13], v[14:15], v[12:13]
	v_pk_mul_f32 v[14:15], v[18:19], v[16:17]
	s_nop 0
	v_cvt_pk_bf16_f32 v14, v14, v15
	v_cvt_pk_bf16_f32 v15, v12, v13
	v_fma_f32 v12, -v155, v151, v150
	v_cmp_ge_f32_e32 vcc, 0, v12
	v_fma_f32 v13, -v153, v151, v150
	global_store_dwordx2 v[148:149], v[14:15], off offset:3072
	v_cndmask_b32_e32 v12, v151, v155, vcc
	v_cmp_lt_f32_e32 vcc, 0, v13
	s_nop 1
	v_cndmask_b32_e32 v12, v12, v153, vcc
	v_mul_f32_e32 v13, 0x37800000, v12
	v_cndmask_b32_e64 v12, v12, v13, s[6:7]
	v_cmp_class_f32_e32 vcc, v150, v253
	s_nop 1
	v_cndmask_b32_e32 v12, v12, v150, vcc
	v_div_scale_f32 v13, s[6:7], v12, v12, 1.0
	v_rcp_f32_e32 v14, v13
	s_nop 0
	v_fma_f32 v15, -v13, v14, 1.0
	v_fmac_f32_e32 v14, v15, v14
	v_div_scale_f32 v15, vcc, 1.0, v12, 1.0
	v_mul_f32_e32 v16, v15, v14
	v_fma_f32 v17, -v13, v16, v15
	v_fmac_f32_e32 v16, v17, v14
	v_fma_f32 v13, -v13, v16, v15
	v_div_fmas_f32 v13, v13, v14, v16
	v_div_fixup_f32 v12, v13, v12, 1.0
	v_lshlrev_b32_e32 v14, 16, v10
	v_and_b32_e32 v15, 0xffff0000, v10
	v_lshlrev_b32_e32 v10, 16, v11
	v_and_b32_e32 v11, 0xffff0000, v11
	v_pk_mul_f32 v[16:17], v[44:45], v[12:13] op_sel_hi:[1,0]
	v_pk_mul_f32 v[12:13], v[50:51], v[12:13] op_sel_hi:[1,0]
	s_nop 0
	v_pk_mul_f32 v[10:11], v[12:13], v[10:11]
	v_pk_mul_f32 v[12:13], v[16:17], v[14:15]
	s_nop 0
	v_cvt_pk_bf16_f32 v12, v12, v13
	v_cvt_pk_bf16_f32 v13, v10, v11
	global_store_dwordx2 v[148:149], v[12:13], off offset:3584
	v_fma_f32 v12, -v219, v218, v215
	v_cmp_ge_f32_e32 vcc, 0, v12
	v_fma_f32 v13, -v217, v218, v215
	v_lshl_add_u64 v[10:11], v[2:3], 0, s[78:79]
	v_cndmask_b32_e32 v12, v218, v219, vcc
	v_cmp_lt_f32_e32 vcc, 0, v13
	v_lshl_add_u64 v[10:11], v[10:11], 0, v[0:1]
	s_nop 0
	v_cndmask_b32_e32 v12, v12, v217, vcc
	v_mul_f32_e32 v13, 0x37800000, v12
	v_cndmask_b32_e64 v12, v12, v13, s[36:37]
	v_cmp_class_f32_e32 vcc, v215, v253
	s_nop 1
	v_cndmask_b32_e32 v12, v12, v215, vcc
	v_div_scale_f32 v13, s[6:7], v12, v12, 1.0
	v_rcp_f32_e32 v14, v13
	s_nop 0
	v_fma_f32 v15, -v13, v14, 1.0
	v_fmac_f32_e32 v14, v15, v14
	v_div_scale_f32 v15, vcc, 1.0, v12, 1.0
	v_mul_f32_e32 v16, v15, v14
	v_fma_f32 v17, -v13, v16, v15
	v_fmac_f32_e32 v16, v17, v14
	v_fma_f32 v13, -v13, v16, v15
	v_div_fmas_f32 v13, v13, v14, v16
	v_div_fixup_f32 v12, v13, v12, 1.0
	v_lshlrev_b32_e32 v14, 16, v52
	v_and_b32_e32 v15, 0xffff0000, v52
	v_lshlrev_b32_e32 v16, 16, v53
	v_and_b32_e32 v17, 0xffff0000, v53
	v_pk_mul_f32 v[18:19], v[126:127], v[12:13] op_sel_hi:[1,0]
	v_pk_mul_f32 v[12:13], v[138:139], v[12:13] op_sel_hi:[1,0]
	v_pk_mul_f32 v[14:15], v[18:19], v[14:15]
	v_pk_mul_f32 v[12:13], v[12:13], v[16:17]
	v_cvt_pk_bf16_f32 v14, v14, v15
	v_cvt_pk_bf16_f32 v15, v12, v13
	v_fma_f32 v12, -v212, v208, v206
	v_cmp_ge_f32_e32 vcc, 0, v12
	v_fma_f32 v13, -v210, v208, v206
	global_store_dwordx2 v[10:11], v[14:15], off
	v_cndmask_b32_e32 v12, v208, v212, vcc
	v_cmp_lt_f32_e32 vcc, 0, v13
	s_nop 1
	v_cndmask_b32_e32 v12, v12, v210, vcc
	v_mul_f32_e32 v13, 0x37800000, v12
	v_cndmask_b32_e64 v12, v12, v13, s[34:35]
	v_cmp_class_f32_e32 vcc, v206, v253
	s_nop 1
	v_cndmask_b32_e32 v12, v12, v206, vcc
	v_div_scale_f32 v13, s[6:7], v12, v12, 1.0
	v_rcp_f32_e32 v14, v13
	s_nop 0
	v_fma_f32 v15, -v13, v14, 1.0
	v_fmac_f32_e32 v14, v15, v14
	v_div_scale_f32 v15, vcc, 1.0, v12, 1.0
	v_mul_f32_e32 v16, v15, v14
	v_fma_f32 v17, -v13, v16, v15
	v_fmac_f32_e32 v16, v17, v14
	v_fma_f32 v13, -v13, v16, v15
	v_div_fmas_f32 v13, v13, v14, v16
	v_div_fixup_f32 v12, v13, v12, 1.0
	v_lshlrev_b32_e32 v14, 16, v48
	v_and_b32_e32 v15, 0xffff0000, v48
	v_lshlrev_b32_e32 v16, 16, v49
	v_and_b32_e32 v17, 0xffff0000, v49
	v_pk_mul_f32 v[18:19], v[114:115], v[12:13] op_sel_hi:[1,0]
	v_pk_mul_f32 v[12:13], v[118:119], v[12:13] op_sel_hi:[1,0]
	v_pk_mul_f32 v[14:15], v[18:19], v[14:15]
	v_pk_mul_f32 v[12:13], v[12:13], v[16:17]
	v_cvt_pk_bf16_f32 v14, v14, v15
	v_cvt_pk_bf16_f32 v15, v12, v13
	v_fma_f32 v12, -v204, v203, v200
	v_cmp_ge_f32_e32 vcc, 0, v12
	v_fma_f32 v13, -v201, v203, v200
	global_store_dwordx2 v[10:11], v[14:15], off offset:512
	v_cndmask_b32_e32 v12, v203, v204, vcc
	v_cmp_lt_f32_e32 vcc, 0, v13
	s_nop 1
	v_cndmask_b32_e32 v12, v12, v201, vcc
	v_mul_f32_e32 v13, 0x37800000, v12
	v_cndmask_b32_e64 v12, v12, v13, s[28:29]
	v_cmp_class_f32_e32 vcc, v200, v253
	s_nop 1
	v_cndmask_b32_e32 v12, v12, v200, vcc
	v_div_scale_f32 v13, s[6:7], v12, v12, 1.0
	v_rcp_f32_e32 v14, v13
	s_nop 0
	v_fma_f32 v15, -v13, v14, 1.0
	v_fmac_f32_e32 v14, v15, v14
	v_div_scale_f32 v15, vcc, 1.0, v12, 1.0
	v_mul_f32_e32 v16, v15, v14
	v_fma_f32 v17, -v13, v16, v15
	v_fmac_f32_e32 v16, v17, v14
	v_fma_f32 v13, -v13, v16, v15
	v_div_fmas_f32 v13, v13, v14, v16
	v_div_fixup_f32 v12, v13, v12, 1.0
	v_lshlrev_b32_e32 v14, 16, v46
	v_and_b32_e32 v15, 0xffff0000, v46
	v_lshlrev_b32_e32 v16, 16, v47
; template <bool HG>
; __device__ __forceinline__ void readout_phase2(const Args& a, Frame& F, const float* gain, int nrows) {
;     ...
;     if (cx) RO_FINISH(f2, b2, g2, ML + nw);
	v_and_b32_e32 v17, 0xffff0000, v47
	v_pk_mul_f32 v[18:19], v[102:103], v[12:13] op_sel_hi:[1,0]
	v_pk_mul_f32 v[12:13], v[106:107], v[12:13] op_sel_hi:[1,0]
	v_pk_mul_f32 v[14:15], v[18:19], v[14:15]
	v_pk_mul_f32 v[12:13], v[12:13], v[16:17]
	v_cvt_pk_bf16_f32 v14, v14, v15
	v_cvt_pk_bf16_f32 v15, v12, v13
	v_fma_f32 v12, -v198, v192, v190
	v_cmp_ge_f32_e32 vcc, 0, v12
	v_fma_f32 v13, -v195, v192, v190
	global_store_dwordx2 v[10:11], v[14:15], off offset:1024
	v_cndmask_b32_e32 v12, v192, v198, vcc
	v_cmp_lt_f32_e32 vcc, 0, v13
	s_nop 1
	v_cndmask_b32_e32 v12, v12, v195, vcc
	v_mul_f32_e32 v13, 0x37800000, v12
	v_cndmask_b32_e64 v12, v12, v13, s[24:25]
	v_cmp_class_f32_e32 vcc, v190, v253
	s_nop 1
	v_cndmask_b32_e32 v12, v12, v190, vcc
	v_div_scale_f32 v13, s[6:7], v12, v12, 1.0
	v_rcp_f32_e32 v14, v13
	s_nop 0
	v_fma_f32 v15, -v13, v14, 1.0
	v_fmac_f32_e32 v14, v15, v14
	v_div_scale_f32 v15, vcc, 1.0, v12, 1.0
	v_mul_f32_e32 v16, v15, v14
	v_fma_f32 v17, -v13, v16, v15
	v_fmac_f32_e32 v16, v17, v14
	v_fma_f32 v13, -v13, v16, v15
	v_div_fmas_f32 v13, v13, v14, v16
	v_div_fixup_f32 v12, v13, v12, 1.0
	v_lshlrev_b32_e32 v14, 16, v42
	v_and_b32_e32 v15, 0xffff0000, v42
	v_lshlrev_b32_e32 v16, 16, v43
	v_and_b32_e32 v17, 0xffff0000, v43
	v_pk_mul_f32 v[18:19], v[90:91], v[12:13] op_sel_hi:[1,0]
	v_pk_mul_f32 v[12:13], v[94:95], v[12:13] op_sel_hi:[1,0]
	v_pk_mul_f32 v[14:15], v[18:19], v[14:15]
	v_pk_mul_f32 v[12:13], v[12:13], v[16:17]
	v_cvt_pk_bf16_f32 v14, v14, v15
	v_cvt_pk_bf16_f32 v15, v12, v13
	v_fma_f32 v12, -v188, v187, v184
	v_cmp_ge_f32_e32 vcc, 0, v12
	v_fma_f32 v13, -v185, v187, v184
	global_store_dwordx2 v[10:11], v[14:15], off offset:1536
	v_cndmask_b32_e32 v12, v187, v188, vcc
	v_cmp_lt_f32_e32 vcc, 0, v13
	s_nop 1
	v_cndmask_b32_e32 v12, v12, v185, vcc
	v_mul_f32_e32 v13, 0x37800000, v12
	v_cndmask_b32_e64 v12, v12, v13, s[20:21]
	v_cmp_class_f32_e32 vcc, v184, v253
	s_nop 1
	v_cndmask_b32_e32 v12, v12, v184, vcc
	v_div_scale_f32 v13, s[6:7], v12, v12, 1.0
	v_rcp_f32_e32 v14, v13
	s_nop 0
	v_fma_f32 v15, -v13, v14, 1.0
	v_fmac_f32_e32 v14, v15, v14
	v_div_scale_f32 v15, vcc, 1.0, v12, 1.0
	v_mul_f32_e32 v16, v15, v14
	v_fma_f32 v17, -v13, v16, v15
	v_fmac_f32_e32 v16, v17, v14
	v_fma_f32 v13, -v13, v16, v15
	v_div_fmas_f32 v13, v13, v14, v16
	v_div_fixup_f32 v12, v13, v12, 1.0
	v_lshlrev_b32_e32 v14, 16, v40
	v_and_b32_e32 v15, 0xffff0000, v40
	v_lshlrev_b32_e32 v16, 16, v41
	v_and_b32_e32 v17, 0xffff0000, v41
	v_pk_mul_f32 v[18:19], v[82:83], v[12:13] op_sel_hi:[1,0]
	v_pk_mul_f32 v[12:13], v[84:85], v[12:13] op_sel_hi:[1,0]
	v_pk_mul_f32 v[14:15], v[18:19], v[14:15]
	v_pk_mul_f32 v[12:13], v[12:13], v[16:17]
	v_cvt_pk_bf16_f32 v14, v14, v15
	v_cvt_pk_bf16_f32 v15, v12, v13
	v_fma_f32 v12, -v176, v170, v168
	v_cmp_ge_f32_e32 vcc, 0, v12
	v_fma_f32 v13, -v173, v170, v168
	global_store_dwordx2 v[10:11], v[14:15], off offset:2048
	v_cndmask_b32_e32 v12, v170, v176, vcc
	v_cmp_lt_f32_e32 vcc, 0, v13
	s_nop 1
	v_cndmask_b32_e32 v12, v12, v173, vcc
	v_mul_f32_e32 v13, 0x37800000, v12
	v_cndmask_b32_e64 v12, v12, v13, s[16:17]
	v_cmp_class_f32_e32 vcc, v168, v253
	s_nop 1
	v_cndmask_b32_e32 v12, v12, v168, vcc
	v_div_scale_f32 v13, s[6:7], v12, v12, 1.0
	v_rcp_f32_e32 v14, v13
	s_nop 0
	v_fma_f32 v15, -v13, v14, 1.0
	v_fmac_f32_e32 v14, v15, v14
	v_div_scale_f32 v15, vcc, 1.0, v12, 1.0
	v_mul_f32_e32 v16, v15, v14
	v_fma_f32 v17, -v13, v16, v15
	v_fmac_f32_e32 v16, v17, v14
	v_fma_f32 v13, -v13, v16, v15
	v_div_fmas_f32 v13, v13, v14, v16
	v_div_fixup_f32 v12, v13, v12, 1.0
	v_lshlrev_b32_e32 v14, 16, v36
	v_and_b32_e32 v15, 0xffff0000, v36
	v_lshlrev_b32_e32 v16, 16, v37
	v_and_b32_e32 v17, 0xffff0000, v37
	v_pk_mul_f32 v[18:19], v[74:75], v[12:13] op_sel_hi:[1,0]
	v_pk_mul_f32 v[12:13], v[76:77], v[12:13] op_sel_hi:[1,0]
	v_pk_mul_f32 v[14:15], v[18:19], v[14:15]
	v_pk_mul_f32 v[12:13], v[12:13], v[16:17]
	v_cvt_pk_bf16_f32 v14, v14, v15
	v_cvt_pk_bf16_f32 v15, v12, v13
	v_fma_f32 v12, -v166, v165, v162
	v_cmp_ge_f32_e32 vcc, 0, v12
	v_fma_f32 v13, -v163, v165, v162
	global_store_dwordx2 v[10:11], v[14:15], off offset:2560
	v_cndmask_b32_e32 v12, v165, v166, vcc
	v_cmp_lt_f32_e32 vcc, 0, v13
	s_nop 1
	v_cndmask_b32_e32 v12, v12, v163, vcc
	v_mul_f32_e32 v13, 0x37800000, v12
	v_cndmask_b32_e64 v12, v12, v13, s[12:13]
	v_cmp_class_f32_e32 vcc, v162, v253
	s_nop 1
	v_cndmask_b32_e32 v12, v12, v162, vcc
	v_div_scale_f32 v13, s[6:7], v12, v12, 1.0
	v_rcp_f32_e32 v14, v13
	s_nop 0
	v_fma_f32 v15, -v13, v14, 1.0
	v_fmac_f32_e32 v14, v15, v14
	v_div_scale_f32 v15, vcc, 1.0, v12, 1.0
	v_mul_f32_e32 v16, v15, v14
	v_fma_f32 v17, -v13, v16, v15
	v_fmac_f32_e32 v16, v17, v14
	v_fma_f32 v13, -v13, v16, v15
	v_div_fmas_f32 v13, v13, v14, v16
	v_div_fixup_f32 v12, v13, v12, 1.0
	v_lshlrev_b32_e32 v14, 16, v32
	v_and_b32_e32 v15, 0xffff0000, v32
	v_lshlrev_b32_e32 v16, 16, v33
	v_and_b32_e32 v17, 0xffff0000, v33
	v_pk_mul_f32 v[18:19], v[64:65], v[12:13] op_sel_hi:[1,0]
	v_pk_mul_f32 v[12:13], v[66:67], v[12:13] op_sel_hi:[1,0]
	v_pk_mul_f32 v[14:15], v[18:19], v[14:15]
	v_pk_mul_f32 v[12:13], v[12:13], v[16:17]
	v_cvt_pk_bf16_f32 v14, v14, v15
	v_cvt_pk_bf16_f32 v15, v12, v13
	v_fma_f32 v12, -v160, v154, v152
	v_cmp_ge_f32_e32 vcc, 0, v12
	v_fma_f32 v13, -v157, v154, v152
	global_store_dwordx2 v[10:11], v[14:15], off offset:3072
	v_cndmask_b32_e32 v12, v154, v160, vcc
	v_cmp_lt_f32_e32 vcc, 0, v13
	s_nop 1
	v_cndmask_b32_e32 v12, v12, v157, vcc
	v_mul_f32_e32 v13, 0x37800000, v12
	v_cndmask_b32_e64 v12, v12, v13, s[8:9]
	v_cmp_class_f32_e32 vcc, v152, v253
	s_nop 1
	v_cndmask_b32_e32 v12, v12, v152, vcc
	v_div_scale_f32 v13, s[6:7], v12, v12, 1.0
	v_rcp_f32_e32 v14, v13
	s_nop 0
	v_fma_f32 v15, -v13, v14, 1.0
	v_fmac_f32_e32 v14, v15, v14
	v_div_scale_f32 v15, vcc, 1.0, v12, 1.0
	v_mul_f32_e32 v16, v15, v14
	v_fma_f32 v17, -v13, v16, v15
	v_fmac_f32_e32 v16, v17, v14
	v_fma_f32 v13, -v13, v16, v15
	v_div_fmas_f32 v13, v13, v14, v16
	v_div_fixup_f32 v12, v13, v12, 1.0
	s_waitcnt vmcnt(47)
	v_lshlrev_b32_e32 v14, 16, v28
	v_and_b32_e32 v15, 0xffff0000, v28
	v_lshlrev_b32_e32 v16, 16, v29
	v_and_b32_e32 v17, 0xffff0000, v29
	v_pk_mul_f32 v[18:19], v[56:57], v[12:13] op_sel_hi:[1,0]
	v_pk_mul_f32 v[12:13], v[54:55], v[12:13] op_sel_hi:[1,0]
	v_pk_mul_f32 v[14:15], v[18:19], v[14:15]
	v_pk_mul_f32 v[12:13], v[12:13], v[16:17]
	v_cvt_pk_bf16_f32 v14, v14, v15
	v_cvt_pk_bf16_f32 v15, v12, v13
	global_store_dwordx2 v[10:11], v[14:15], off offset:3584
	s_cbranch_scc1 .LBB0_864
; template <bool HG>
; __device__ __forceinline__ void readout_phase2(const Args& a, Frame& F, const float* gain, int nrows) {
;     ...
;     if (cx) RO_FINISH(f2, b2, g2, ML + nw);
	s_waitcnt vmcnt(39)
	v_lshlrev_b32_e32 v10, 16, v146
	v_and_b32_e32 v11, 0xffff0000, v146
	s_waitcnt vmcnt(38)
	v_lshlrev_b32_e32 v12, 16, v144
	v_and_b32_e32 v13, 0xffff0000, v144
	v_pk_add_f32 v[46:47], v[10:11], v[12:13]
	v_lshlrev_b32_e32 v10, 16, v147
	v_and_b32_e32 v11, 0xffff0000, v147
	v_lshlrev_b32_e32 v12, 16, v145
	v_and_b32_e32 v13, 0xffff0000, v145
	v_pk_add_f32 v[48:49], v[10:11], v[12:13]
	v_mov_b32_e32 v12, v47
	v_mov_b32_e32 v13, v49
	v_mov_b32_e32 v10, v46
	v_mov_b32_e32 v11, v48
	v_pk_mul_f32 v[12:13], v[12:13], v[12:13]
	s_ashr_i32 s83, s82, 31
	v_pk_fma_f32 v[10:11], v[10:11], v[10:11], v[12:13]
	s_waitcnt vmcnt(35)
	v_lshlrev_b32_e32 v12, 16, v128
	v_add_f32_e32 v62, v10, v11
	v_lshlrev_b32_e32 v10, 16, v132
	v_and_b32_e32 v11, 0xffff0000, v132
	v_and_b32_e32 v13, 0xffff0000, v128
	v_pk_add_f32 v[42:43], v[10:11], v[12:13]
	v_lshlrev_b32_e32 v10, 16, v133
	v_and_b32_e32 v11, 0xffff0000, v133
	v_lshlrev_b32_e32 v12, 16, v129
	v_and_b32_e32 v13, 0xffff0000, v129
	v_pk_add_f32 v[44:45], v[10:11], v[12:13]
	v_mov_b32_e32 v12, v43
	v_mov_b32_e32 v13, v45
	v_mov_b32_e32 v10, v42
	v_mov_b32_e32 v11, v44
	v_pk_mul_f32 v[12:13], v[12:13], v[12:13]
	s_lshl_b64 s[6:7], s[82:83], 12
	v_pk_fma_f32 v[10:11], v[10:11], v[10:11], v[12:13]
	s_waitcnt vmcnt(32)
	v_lshlrev_b32_e32 v12, 16, v120
	v_add_f32_e32 v63, v10, v11
	v_lshlrev_b32_e32 v10, 16, v124
	v_and_b32_e32 v11, 0xffff0000, v124
	v_and_b32_e32 v13, 0xffff0000, v120
	v_pk_add_f32 v[36:37], v[10:11], v[12:13]
	v_lshlrev_b32_e32 v10, 16, v125
	v_and_b32_e32 v11, 0xffff0000, v125
	v_lshlrev_b32_e32 v12, 16, v121
	v_and_b32_e32 v13, 0xffff0000, v121
	v_pk_add_f32 v[40:41], v[10:11], v[12:13]
	v_mov_b32_e32 v12, v37
	v_mov_b32_e32 v13, v41
	v_mov_b32_e32 v10, v36
	v_mov_b32_e32 v11, v40
	v_pk_mul_f32 v[12:13], v[12:13], v[12:13]
	v_lshl_add_u64 v[2:3], v[2:3], 0, s[6:7]
	v_pk_fma_f32 v[10:11], v[10:11], v[10:11], v[12:13]
	s_waitcnt vmcnt(29)
	v_lshlrev_b32_e32 v12, 16, v112
	v_add_f32_e32 v64, v10, v11
	v_lshlrev_b32_e32 v10, 16, v116
	v_and_b32_e32 v11, 0xffff0000, v116
	v_and_b32_e32 v13, 0xffff0000, v112
	v_pk_add_f32 v[28:29], v[10:11], v[12:13]
	v_lshlrev_b32_e32 v10, 16, v117
	v_and_b32_e32 v11, 0xffff0000, v117
	v_lshlrev_b32_e32 v12, 16, v113
	v_and_b32_e32 v13, 0xffff0000, v113
	v_pk_add_f32 v[32:33], v[10:11], v[12:13]
	v_mov_b32_e32 v12, v29
	v_mov_b32_e32 v13, v33
	v_mov_b32_e32 v10, v28
	v_mov_b32_e32 v11, v32
	v_pk_mul_f32 v[12:13], v[12:13], v[12:13]
	s_waitcnt vmcnt(17)
	v_lshlrev_b32_e32 v54, 16, v61
	v_pk_fma_f32 v[10:11], v[10:11], v[10:11], v[12:13]
	v_lshlrev_b32_e32 v12, 16, v108
	v_add_f32_e32 v65, v10, v11
	v_lshlrev_b32_e32 v10, 16, v110
	v_and_b32_e32 v11, 0xffff0000, v110
	v_and_b32_e32 v13, 0xffff0000, v108
	v_pk_add_f32 v[22:23], v[10:11], v[12:13]
	v_lshlrev_b32_e32 v10, 16, v111
	v_and_b32_e32 v11, 0xffff0000, v111
	v_lshlrev_b32_e32 v12, 16, v109
	v_and_b32_e32 v13, 0xffff0000, v109
	v_pk_add_f32 v[24:25], v[10:11], v[12:13]
	v_mov_b32_e32 v12, v23
	v_mov_b32_e32 v13, v25
	v_mov_b32_e32 v10, v22
	v_mov_b32_e32 v11, v24
	v_pk_mul_f32 v[12:13], v[12:13], v[12:13]
	v_and_b32_e32 v55, 0xffff0000, v61
	v_pk_fma_f32 v[10:11], v[10:11], v[10:11], v[12:13]
	v_lshlrev_b32_e32 v12, 16, v100
	v_add_f32_e32 v53, v10, v11
	v_lshlrev_b32_e32 v10, 16, v104
	v_and_b32_e32 v11, 0xffff0000, v104
	v_and_b32_e32 v13, 0xffff0000, v100
	v_pk_add_f32 v[18:19], v[10:11], v[12:13]
	v_lshlrev_b32_e32 v10, 16, v105
	v_and_b32_e32 v11, 0xffff0000, v105
	v_lshlrev_b32_e32 v12, 16, v101
	v_and_b32_e32 v13, 0xffff0000, v101
	v_pk_add_f32 v[20:21], v[10:11], v[12:13]
	v_mov_b32_e32 v12, v19
	v_mov_b32_e32 v13, v21
	v_mov_b32_e32 v10, v18
	v_mov_b32_e32 v11, v20
	v_pk_mul_f32 v[12:13], v[12:13], v[12:13]
	v_lshl_add_u64 v[2:3], v[2:3], 0, v[0:1]
	v_pk_fma_f32 v[10:11], v[10:11], v[10:11], v[12:13]
	v_lshlrev_b32_e32 v12, 16, v96
	v_add_f32_e32 v52, v10, v11
	v_lshlrev_b32_e32 v10, 16, v98
	v_and_b32_e32 v11, 0xffff0000, v98
	v_and_b32_e32 v13, 0xffff0000, v96
	v_pk_add_f32 v[14:15], v[10:11], v[12:13]
	v_lshlrev_b32_e32 v10, 16, v99
	v_and_b32_e32 v11, 0xffff0000, v99
	v_lshlrev_b32_e32 v12, 16, v97
	v_and_b32_e32 v13, 0xffff0000, v97
	v_pk_add_f32 v[16:17], v[10:11], v[12:13]
	v_mov_b32_e32 v12, v15
	v_mov_b32_e32 v13, v17
	v_mov_b32_e32 v10, v14
	v_mov_b32_e32 v11, v16
	v_pk_mul_f32 v[12:13], v[12:13], v[12:13]
	v_add_f32_dpp v0, v62, v62 quad_perm:[1,0,3,2] row_mask:0xf bank_mask:0xf bound_ctrl:1
	v_pk_fma_f32 v[10:11], v[10:11], v[10:11], v[12:13]
	v_lshlrev_b32_e32 v12, 16, v60
	v_add_f32_e32 v51, v10, v11
	v_lshlrev_b32_e32 v10, 16, v92
	v_and_b32_e32 v11, 0xffff0000, v92
	v_and_b32_e32 v13, 0xffff0000, v60
	v_pk_add_f32 v[10:11], v[10:11], v[12:13]
	v_lshlrev_b32_e32 v12, 16, v93
	v_and_b32_e32 v13, 0xffff0000, v93
	v_pk_add_f32 v[12:13], v[12:13], v[54:55]
	v_add_f32_dpp v0, v0, v0 quad_perm:[2,3,0,1] row_mask:0xf bank_mask:0xf bound_ctrl:1
	v_mov_b32_e32 v56, v11
	v_mov_b32_e32 v57, v13
	v_add_f32_dpp v0, v0, v0 row_half_mirror row_mask:0xf bank_mask:0xf bound_ctrl:1
	v_mov_b32_e32 v54, v10
	v_mov_b32_e32 v55, v12
	v_pk_mul_f32 v[56:57], v[56:57], v[56:57]
	v_add_f32_dpp v0, v0, v0 row_mirror row_mask:0xf bank_mask:0xf bound_ctrl:1
	v_pk_fma_f32 v[54:55], v[54:55], v[54:55], v[56:57]
	v_readlane_b32 s8, v0, 16
	v_readlane_b32 s9, v0, 48
	v_add_f32_e32 v50, v54, v55
	v_readlane_b32 s6, v0, 0
	v_readlane_b32 s7, v0, 32
	v_mov_b32_e32 v54, s8
	v_mov_b32_e32 v55, s9
	v_pk_add_f32 v[54:55], s[6:7], v[54:55]
	s_mov_b32 s83, 0x80000
	v_add_f32_e32 v0, v54, v55
	v_fmamk_f32 v0, v0, 0x3b800000, v252
	v_cmp_gt_f32_e32 vcc, s55, v0
	v_mul_f32_e32 v54, 0x4f800000, v0
	s_nop 0
	v_cndmask_b32_e32 v0, v0, v54, vcc
	v_sqrt_f32_e32 v54, v0
	s_nop 0
	v_add_u32_e32 v55, -1, v54
	v_fma_f32 v56, -v55, v54, v0
	v_cmp_ge_f32_e64 s[6:7], 0, v56
	v_add_u32_e32 v56, 1, v54
	s_nop 0
	v_cndmask_b32_e64 v55, v54, v55, s[6:7]
	v_fma_f32 v54, -v56, v54, v0
	v_cmp_lt_f32_e64 s[6:7], 0, v54
	s_nop 1
	v_cndmask_b32_e64 v54, v55, v56, s[6:7]
	v_mul_f32_e32 v55, 0x37800000, v54
	v_cndmask_b32_e32 v54, v54, v55, vcc
	v_cmp_class_f32_e32 vcc, v0, v253
	s_nop 1
	v_cndmask_b32_e32 v0, v54, v0, vcc
	v_div_scale_f32 v54, s[6:7], v0, v0, 1.0
	v_rcp_f32_e32 v55, v54
	s_nop 0
	v_fma_f32 v56, -v54, v55, 1.0
	v_fmac_f32_e32 v55, v56, v55
	v_div_scale_f32 v56, vcc, 1.0, v0, 1.0
	v_mul_f32_e32 v57, v56, v55
	v_fma_f32 v60, -v54, v57, v56
	v_fmac_f32_e32 v57, v60, v55
	v_fma_f32 v54, -v54, v57, v56
	v_div_fmas_f32 v54, v54, v55, v57
	v_div_fixup_f32 v0, v54, v0, 1.0
	v_pk_mul_f32 v[46:47], v[46:47], v[0:1] op_sel_hi:[1,0]
	v_pk_mul_f32 v[48:49], v[48:49], v[0:1] op_sel_hi:[1,0]
	v_add_f32_dpp v0, v63, v63 quad_perm:[1,0,3,2] row_mask:0xf bank_mask:0xf bound_ctrl:1
	v_lshlrev_b32_e32 v54, 16, v58
	v_and_b32_e32 v55, 0xffff0000, v58
	v_add_f32_dpp v0, v0, v0 quad_perm:[2,3,0,1] row_mask:0xf bank_mask:0xf bound_ctrl:1
	v_lshlrev_b32_e32 v56, 16, v59
	v_and_b32_e32 v57, 0xffff0000, v59
	v_add_f32_dpp v0, v0, v0 row_half_mirror row_mask:0xf bank_mask:0xf bound_ctrl:1
	v_pk_mul_f32 v[48:49], v[48:49], v[56:57]
	v_pk_mul_f32 v[46:47], v[46:47], v[54:55]
	v_add_f32_dpp v0, v0, v0 row_mirror row_mask:0xf bank_mask:0xf bound_ctrl:1
	v_cvt_pk_bf16_f32 v46, v46, v47
	v_cvt_pk_bf16_f32 v47, v48, v49
	v_readlane_b32 s8, v0, 16
	v_readlane_b32 s9, v0, 48
	global_store_dwordx2 v[2:3], v[46:47], off
	v_readlane_b32 s6, v0, 0
	v_readlane_b32 s7, v0, 32
	v_mov_b32_e32 v46, s8
	v_mov_b32_e32 v47, s9
	v_pk_add_f32 v[46:47], s[6:7], v[46:47]
	s_nop 0
	v_add_f32_e32 v0, v46, v47
	v_fmamk_f32 v0, v0, 0x3b800000, v252
	v_cmp_gt_f32_e32 vcc, s55, v0
	v_mul_f32_e32 v46, 0x4f800000, v0
	s_nop 0
	v_cndmask_b32_e32 v0, v0, v46, vcc
	v_sqrt_f32_e32 v46, v0
	s_nop 0
	v_add_u32_e32 v47, -1, v46
	v_fma_f32 v48, -v47, v46, v0
	v_cmp_ge_f32_e64 s[6:7], 0, v48
	v_add_u32_e32 v48, 1, v46
	s_nop 0
	v_cndmask_b32_e64 v47, v46, v47, s[6:7]
	v_fma_f32 v46, -v48, v46, v0
	v_cmp_lt_f32_e64 s[6:7], 0, v46
	s_nop 1
	v_cndmask_b32_e64 v46, v47, v48, s[6:7]
	v_mul_f32_e32 v47, 0x37800000, v46
	v_cndmask_b32_e32 v46, v46, v47, vcc
	v_cmp_class_f32_e32 vcc, v0, v253
	s_nop 1
	v_cndmask_b32_e32 v0, v46, v0, vcc
	v_div_scale_f32 v46, s[6:7], v0, v0, 1.0
	v_rcp_f32_e32 v47, v46
	s_nop 0
	v_fma_f32 v48, -v46, v47, 1.0
	v_fmac_f32_e32 v47, v48, v47
	v_div_scale_f32 v48, vcc, 1.0, v0, 1.0
	v_mul_f32_e32 v49, v48, v47
	v_fma_f32 v54, -v46, v49, v48
	v_fmac_f32_e32 v49, v54, v47
	v_fma_f32 v46, -v46, v49, v48
	v_div_fmas_f32 v46, v46, v47, v49
	v_div_fixup_f32 v0, v46, v0, 1.0
	v_pk_mul_f32 v[42:43], v[42:43], v[0:1] op_sel_hi:[1,0]
	v_pk_mul_f32 v[44:45], v[44:45], v[0:1] op_sel_hi:[1,0]
	v_add_f32_dpp v0, v64, v64 quad_perm:[1,0,3,2] row_mask:0xf bank_mask:0xf bound_ctrl:1
	v_lshlrev_b32_e32 v46, 16, v38
	v_and_b32_e32 v47, 0xffff0000, v38
	v_add_f32_dpp v0, v0, v0 quad_perm:[2,3,0,1] row_mask:0xf bank_mask:0xf bound_ctrl:1
	v_lshlrev_b32_e32 v38, 16, v39
	v_and_b32_e32 v39, 0xffff0000, v39
	v_add_f32_dpp v0, v0, v0 row_half_mirror row_mask:0xf bank_mask:0xf bound_ctrl:1
	v_pk_mul_f32 v[38:39], v[44:45], v[38:39]
	v_pk_mul_f32 v[42:43], v[42:43], v[46:47]
	v_add_f32_dpp v0, v0, v0 row_mirror row_mask:0xf bank_mask:0xf bound_ctrl:1
	v_cvt_pk_bf16_f32 v42, v42, v43
	v_readlane_b32 s8, v0, 16
	v_readlane_b32 s9, v0, 48
	v_cvt_pk_bf16_f32 v43, v38, v39
	v_readlane_b32 s6, v0, 0
	v_readlane_b32 s7, v0, 32
	v_mov_b32_e32 v38, s8
	v_mov_b32_e32 v39, s9
	v_pk_add_f32 v[38:39], s[6:7], v[38:39]
	global_store_dwordx2 v[2:3], v[42:43], off offset:512
	v_add_f32_e32 v0, v38, v39
	v_fmamk_f32 v0, v0, 0x3b800000, v252
	v_cmp_gt_f32_e32 vcc, s55, v0
	v_mul_f32_e32 v38, 0x4f800000, v0
	s_nop 0
	v_cndmask_b32_e32 v0, v0, v38, vcc
	v_sqrt_f32_e32 v38, v0
	s_nop 0
	v_add_u32_e32 v39, -1, v38
	v_fma_f32 v42, -v39, v38, v0
	v_cmp_ge_f32_e64 s[6:7], 0, v42
	v_add_u32_e32 v42, 1, v38
	s_nop 0
	v_cndmask_b32_e64 v39, v38, v39, s[6:7]
	v_fma_f32 v38, -v42, v38, v0
	v_cmp_lt_f32_e64 s[6:7], 0, v38
	s_nop 1
	v_cndmask_b32_e64 v38, v39, v42, s[6:7]
	v_mul_f32_e32 v39, 0x37800000, v38
	v_cndmask_b32_e32 v38, v38, v39, vcc
	v_cmp_class_f32_e32 vcc, v0, v253
	s_nop 1
	v_cndmask_b32_e32 v0, v38, v0, vcc
	v_div_scale_f32 v38, s[6:7], v0, v0, 1.0
	v_rcp_f32_e32 v39, v38
	s_nop 0
	v_fma_f32 v42, -v38, v39, 1.0
	v_fmac_f32_e32 v39, v42, v39
	v_div_scale_f32 v42, vcc, 1.0, v0, 1.0
	v_mul_f32_e32 v43, v42, v39
	v_fma_f32 v44, -v38, v43, v42
	v_fmac_f32_e32 v43, v44, v39
	v_fma_f32 v38, -v38, v43, v42
	v_div_fmas_f32 v38, v38, v39, v43
	v_div_fixup_f32 v0, v38, v0, 1.0
	v_pk_mul_f32 v[36:37], v[36:37], v[0:1] op_sel_hi:[1,0]
	v_pk_mul_f32 v[40:41], v[40:41], v[0:1] op_sel_hi:[1,0]
	v_add_f32_dpp v0, v65, v65 quad_perm:[1,0,3,2] row_mask:0xf bank_mask:0xf bound_ctrl:1
	v_lshlrev_b32_e32 v38, 16, v34
	v_and_b32_e32 v39, 0xffff0000, v34
	v_add_f32_dpp v0, v0, v0 quad_perm:[2,3,0,1] row_mask:0xf bank_mask:0xf bound_ctrl:1
	v_lshlrev_b32_e32 v34, 16, v35
	v_and_b32_e32 v35, 0xffff0000, v35
	v_add_f32_dpp v0, v0, v0 row_half_mirror row_mask:0xf bank_mask:0xf bound_ctrl:1
	v_pk_mul_f32 v[34:35], v[40:41], v[34:35]
	v_pk_mul_f32 v[36:37], v[36:37], v[38:39]
	v_add_f32_dpp v0, v0, v0 row_mirror row_mask:0xf bank_mask:0xf bound_ctrl:1
	v_cvt_pk_bf16_f32 v36, v36, v37
	v_readlane_b32 s8, v0, 16
	v_readlane_b32 s9, v0, 48
	v_cvt_pk_bf16_f32 v37, v34, v35
	v_readlane_b32 s6, v0, 0
	v_readlane_b32 s7, v0, 32
	v_mov_b32_e32 v34, s8
	v_mov_b32_e32 v35, s9
	v_pk_add_f32 v[34:35], s[6:7], v[34:35]
	global_store_dwordx2 v[2:3], v[36:37], off offset:1024
	v_add_f32_e32 v0, v34, v35
	v_fmamk_f32 v0, v0, 0x3b800000, v252
	v_cmp_gt_f32_e32 vcc, s55, v0
	v_mul_f32_e32 v34, 0x4f800000, v0
	s_nop 0
	v_cndmask_b32_e32 v0, v0, v34, vcc
	v_sqrt_f32_e32 v34, v0
	s_nop 0
	v_add_u32_e32 v35, -1, v34
	v_fma_f32 v36, -v35, v34, v0
	v_cmp_ge_f32_e64 s[6:7], 0, v36
	v_add_u32_e32 v36, 1, v34
	s_nop 0
	v_cndmask_b32_e64 v35, v34, v35, s[6:7]
	v_fma_f32 v34, -v36, v34, v0
	v_cmp_lt_f32_e64 s[6:7], 0, v34
	s_nop 1
	v_cndmask_b32_e64 v34, v35, v36, s[6:7]
	v_mul_f32_e32 v35, 0x37800000, v34
	v_cndmask_b32_e32 v34, v34, v35, vcc
	v_cmp_class_f32_e32 vcc, v0, v253
	s_nop 1
	v_cndmask_b32_e32 v0, v34, v0, vcc
	v_div_scale_f32 v34, s[6:7], v0, v0, 1.0
	v_rcp_f32_e32 v35, v34
	s_nop 0
	v_fma_f32 v36, -v34, v35, 1.0
	v_fmac_f32_e32 v35, v36, v35
	v_div_scale_f32 v36, vcc, 1.0, v0, 1.0
	v_mul_f32_e32 v37, v36, v35
	v_fma_f32 v38, -v34, v37, v36
	v_fmac_f32_e32 v37, v38, v35
	v_fma_f32 v34, -v34, v37, v36
	v_div_fmas_f32 v34, v34, v35, v37
	v_div_fixup_f32 v0, v34, v0, 1.0
	v_pk_mul_f32 v[28:29], v[28:29], v[0:1] op_sel_hi:[1,0]
	v_pk_mul_f32 v[32:33], v[32:33], v[0:1] op_sel_hi:[1,0]
	v_add_f32_dpp v0, v53, v53 quad_perm:[1,0,3,2] row_mask:0xf bank_mask:0xf bound_ctrl:1
	v_lshlrev_b32_e32 v34, 16, v30
	v_and_b32_e32 v35, 0xffff0000, v30
	v_add_f32_dpp v0, v0, v0 quad_perm:[2,3,0,1] row_mask:0xf bank_mask:0xf bound_ctrl:1
	v_lshlrev_b32_e32 v30, 16, v31
	v_and_b32_e32 v31, 0xffff0000, v31
	v_add_f32_dpp v0, v0, v0 row_half_mirror row_mask:0xf bank_mask:0xf bound_ctrl:1
	v_pk_mul_f32 v[30:31], v[32:33], v[30:31]
	v_pk_mul_f32 v[28:29], v[28:29], v[34:35]
	v_add_f32_dpp v0, v0, v0 row_mirror row_mask:0xf bank_mask:0xf bound_ctrl:1
	v_cvt_pk_bf16_f32 v28, v28, v29
	v_cvt_pk_bf16_f32 v29, v30, v31
	v_readlane_b32 s8, v0, 16
	v_readlane_b32 s9, v0, 48
	global_store_dwordx2 v[2:3], v[28:29], off offset:1536
	v_readlane_b32 s6, v0, 0
	v_readlane_b32 s7, v0, 32
	v_mov_b32_e32 v28, s8
	v_mov_b32_e32 v29, s9
	v_pk_add_f32 v[28:29], s[6:7], v[28:29]
	s_nop 0
	v_add_f32_e32 v0, v28, v29
	v_fmamk_f32 v0, v0, 0x3b800000, v252
	v_cmp_gt_f32_e32 vcc, s55, v0
	v_mul_f32_e32 v28, 0x4f800000, v0
	s_nop 0
	v_cndmask_b32_e32 v0, v0, v28, vcc
	v_sqrt_f32_e32 v28, v0
	s_nop 0
	v_add_u32_e32 v29, -1, v28
	v_fma_f32 v30, -v29, v28, v0
	v_cmp_ge_f32_e64 s[6:7], 0, v30
	v_add_u32_e32 v30, 1, v28
	s_nop 0
	v_cndmask_b32_e64 v29, v28, v29, s[6:7]
	v_fma_f32 v28, -v30, v28, v0
	v_cmp_lt_f32_e64 s[6:7], 0, v28
	s_nop 1
	v_cndmask_b32_e64 v28, v29, v30, s[6:7]
	v_mul_f32_e32 v29, 0x37800000, v28
	v_cndmask_b32_e32 v28, v28, v29, vcc
	v_cmp_class_f32_e32 vcc, v0, v253
	s_nop 1
	v_cndmask_b32_e32 v0, v28, v0, vcc
	v_div_scale_f32 v28, s[6:7], v0, v0, 1.0
	v_rcp_f32_e32 v29, v28
	s_nop 0
	v_fma_f32 v30, -v28, v29, 1.0
	v_fmac_f32_e32 v29, v30, v29
	v_div_scale_f32 v30, vcc, 1.0, v0, 1.0
	v_mul_f32_e32 v31, v30, v29
	v_fma_f32 v32, -v28, v31, v30
	v_fmac_f32_e32 v31, v32, v29
	v_fma_f32 v28, -v28, v31, v30
	v_div_fmas_f32 v28, v28, v29, v31
	v_div_fixup_f32 v0, v28, v0, 1.0
	v_pk_mul_f32 v[22:23], v[22:23], v[0:1] op_sel_hi:[1,0]
	v_pk_mul_f32 v[24:25], v[24:25], v[0:1] op_sel_hi:[1,0]
	v_add_f32_dpp v0, v52, v52 quad_perm:[1,0,3,2] row_mask:0xf bank_mask:0xf bound_ctrl:1
	v_lshlrev_b32_e32 v28, 16, v26
	v_and_b32_e32 v29, 0xffff0000, v26
	v_add_f32_dpp v0, v0, v0 quad_perm:[2,3,0,1] row_mask:0xf bank_mask:0xf bound_ctrl:1
	v_lshlrev_b32_e32 v26, 16, v27
	v_and_b32_e32 v27, 0xffff0000, v27
	v_add_f32_dpp v0, v0, v0 row_half_mirror row_mask:0xf bank_mask:0xf bound_ctrl:1
	v_pk_mul_f32 v[24:25], v[24:25], v[26:27]
	v_pk_mul_f32 v[22:23], v[22:23], v[28:29]
	v_add_f32_dpp v0, v0, v0 row_mirror row_mask:0xf bank_mask:0xf bound_ctrl:1
	v_cvt_pk_bf16_f32 v22, v22, v23
	v_cvt_pk_bf16_f32 v23, v24, v25
	v_readlane_b32 s8, v0, 16
	v_readlane_b32 s9, v0, 48
	global_store_dwordx2 v[2:3], v[22:23], off offset:2048
	v_readlane_b32 s6, v0, 0
	v_readlane_b32 s7, v0, 32
	v_mov_b32_e32 v22, s8
	v_mov_b32_e32 v23, s9
	v_pk_add_f32 v[22:23], s[6:7], v[22:23]
	s_nop 0
	v_add_f32_e32 v0, v22, v23
	v_fmamk_f32 v0, v0, 0x3b800000, v252
	v_cmp_gt_f32_e32 vcc, s55, v0
	v_mul_f32_e32 v22, 0x4f800000, v0
	s_nop 0
	v_cndmask_b32_e32 v0, v0, v22, vcc
	v_sqrt_f32_e32 v22, v0
	s_nop 0
	v_add_u32_e32 v23, -1, v22
	v_fma_f32 v24, -v23, v22, v0
	v_cmp_ge_f32_e64 s[6:7], 0, v24
	v_add_u32_e32 v24, 1, v22
	s_nop 0
	v_cndmask_b32_e64 v23, v22, v23, s[6:7]
	v_fma_f32 v22, -v24, v22, v0
	v_cmp_lt_f32_e64 s[6:7], 0, v22
	s_nop 1
	v_cndmask_b32_e64 v22, v23, v24, s[6:7]
	v_mul_f32_e32 v23, 0x37800000, v22
	v_cndmask_b32_e32 v22, v22, v23, vcc
	v_cmp_class_f32_e32 vcc, v0, v253
	s_nop 1
	v_cndmask_b32_e32 v0, v22, v0, vcc
	v_div_scale_f32 v22, s[6:7], v0, v0, 1.0
	v_rcp_f32_e32 v23, v22
	s_nop 0
	v_fma_f32 v24, -v22, v23, 1.0
	v_fmac_f32_e32 v23, v24, v23
	v_div_scale_f32 v24, vcc, 1.0, v0, 1.0
	v_mul_f32_e32 v25, v24, v23
	v_fma_f32 v26, -v22, v25, v24
	v_fmac_f32_e32 v25, v26, v23
	v_fma_f32 v22, -v22, v25, v24
	v_div_fmas_f32 v22, v22, v23, v25
	v_div_fixup_f32 v0, v22, v0, 1.0
	v_pk_mul_f32 v[18:19], v[18:19], v[0:1] op_sel_hi:[1,0]
	v_pk_mul_f32 v[20:21], v[20:21], v[0:1] op_sel_hi:[1,0]
	v_add_f32_dpp v0, v51, v51 quad_perm:[1,0,3,2] row_mask:0xf bank_mask:0xf bound_ctrl:1
	v_lshlrev_b32_e32 v22, 16, v8
	v_and_b32_e32 v23, 0xffff0000, v8
	v_add_f32_dpp v0, v0, v0 quad_perm:[2,3,0,1] row_mask:0xf bank_mask:0xf bound_ctrl:1
	v_lshlrev_b32_e32 v8, 16, v9
	v_and_b32_e32 v9, 0xffff0000, v9
	v_add_f32_dpp v0, v0, v0 row_half_mirror row_mask:0xf bank_mask:0xf bound_ctrl:1
	v_pk_mul_f32 v[8:9], v[20:21], v[8:9]
	v_pk_mul_f32 v[18:19], v[18:19], v[22:23]
	v_add_f32_dpp v0, v0, v0 row_mirror row_mask:0xf bank_mask:0xf bound_ctrl:1
	v_cvt_pk_bf16_f32 v18, v18, v19
	v_readlane_b32 s8, v0, 16
	v_readlane_b32 s9, v0, 48
	v_cvt_pk_bf16_f32 v19, v8, v9
	v_readlane_b32 s6, v0, 0
	v_readlane_b32 s7, v0, 32
	v_mov_b32_e32 v8, s8
	v_mov_b32_e32 v9, s9
	v_pk_add_f32 v[8:9], s[6:7], v[8:9]
	global_store_dwordx2 v[2:3], v[18:19], off offset:2560
	v_add_f32_e32 v0, v8, v9
	v_fmamk_f32 v0, v0, 0x3b800000, v252
	v_cmp_gt_f32_e32 vcc, s55, v0
	v_mul_f32_e32 v8, 0x4f800000, v0
	s_nop 0
	v_cndmask_b32_e32 v0, v0, v8, vcc
	v_sqrt_f32_e32 v8, v0
	s_nop 0
	v_add_u32_e32 v9, -1, v8
	v_fma_f32 v18, -v9, v8, v0
	v_cmp_ge_f32_e64 s[6:7], 0, v18
	v_add_u32_e32 v18, 1, v8
	s_nop 0
	v_cndmask_b32_e64 v9, v8, v9, s[6:7]
	v_fma_f32 v8, -v18, v8, v0
	v_cmp_lt_f32_e64 s[6:7], 0, v8
	s_nop 1
	v_cndmask_b32_e64 v8, v9, v18, s[6:7]
	v_mul_f32_e32 v9, 0x37800000, v8
	v_cndmask_b32_e32 v8, v8, v9, vcc
	v_cmp_class_f32_e32 vcc, v0, v253
	s_nop 1
	v_cndmask_b32_e32 v0, v8, v0, vcc
	v_div_scale_f32 v8, s[6:7], v0, v0, 1.0
	v_rcp_f32_e32 v9, v8
	s_nop 0
	v_fma_f32 v18, -v8, v9, 1.0
	v_fmac_f32_e32 v9, v18, v9
	v_div_scale_f32 v18, vcc, 1.0, v0, 1.0
	v_mul_f32_e32 v19, v18, v9
	v_fma_f32 v20, -v8, v19, v18
	v_fmac_f32_e32 v19, v20, v9
	v_fma_f32 v8, -v8, v19, v18
	v_div_fmas_f32 v8, v8, v9, v19
	v_div_fixup_f32 v0, v8, v0, 1.0
	v_pk_mul_f32 v[14:15], v[14:15], v[0:1] op_sel_hi:[1,0]
	v_pk_mul_f32 v[16:17], v[16:17], v[0:1] op_sel_hi:[1,0]
	v_add_f32_dpp v0, v50, v50 quad_perm:[1,0,3,2] row_mask:0xf bank_mask:0xf bound_ctrl:1
	v_lshlrev_b32_e32 v8, 16, v6
	v_and_b32_e32 v9, 0xffff0000, v6
	v_add_f32_dpp v0, v0, v0 quad_perm:[2,3,0,1] row_mask:0xf bank_mask:0xf bound_ctrl:1
	v_lshlrev_b32_e32 v6, 16, v7
	v_and_b32_e32 v7, 0xffff0000, v7
	v_add_f32_dpp v0, v0, v0 row_half_mirror row_mask:0xf bank_mask:0xf bound_ctrl:1
	v_pk_mul_f32 v[6:7], v[16:17], v[6:7]
	v_pk_mul_f32 v[8:9], v[14:15], v[8:9]
	v_add_f32_dpp v0, v0, v0 row_mirror row_mask:0xf bank_mask:0xf bound_ctrl:1
	v_cvt_pk_bf16_f32 v8, v8, v9
	v_readlane_b32 s8, v0, 16
	v_readlane_b32 s9, v0, 48
	v_cvt_pk_bf16_f32 v9, v6, v7
	v_readlane_b32 s6, v0, 0
	v_readlane_b32 s7, v0, 32
	v_mov_b32_e32 v6, s8
	v_mov_b32_e32 v7, s9
	v_pk_add_f32 v[6:7], s[6:7], v[6:7]
	global_store_dwordx2 v[2:3], v[8:9], off offset:3072
	v_add_f32_e32 v0, v6, v7
	v_fmamk_f32 v0, v0, 0x3b800000, v252
	v_cmp_gt_f32_e32 vcc, s55, v0
	v_mul_f32_e32 v6, 0x4f800000, v0
	s_nop 0
	v_cndmask_b32_e32 v0, v0, v6, vcc
	v_sqrt_f32_e32 v6, v0
	s_nop 0
	v_add_u32_e32 v7, -1, v6
	v_fma_f32 v8, -v7, v6, v0
	v_cmp_ge_f32_e64 s[6:7], 0, v8
	v_add_u32_e32 v8, 1, v6
	s_nop 0
	v_cndmask_b32_e64 v7, v6, v7, s[6:7]
	v_fma_f32 v6, -v8, v6, v0
	v_cmp_lt_f32_e64 s[6:7], 0, v6
	s_nop 1
	v_cndmask_b32_e64 v6, v7, v8, s[6:7]
	v_mul_f32_e32 v7, 0x37800000, v6
	v_cndmask_b32_e32 v6, v6, v7, vcc
	v_cmp_class_f32_e32 vcc, v0, v253
	s_nop 1
	v_cndmask_b32_e32 v0, v6, v0, vcc
	v_div_scale_f32 v6, s[6:7], v0, v0, 1.0
	v_rcp_f32_e32 v7, v6
	s_nop 0
	v_fma_f32 v8, -v6, v7, 1.0
	v_fmac_f32_e32 v7, v8, v7
	v_div_scale_f32 v8, vcc, 1.0, v0, 1.0
	v_mul_f32_e32 v9, v8, v7
	v_fma_f32 v14, -v6, v9, v8
	v_fmac_f32_e32 v9, v14, v7
	v_fma_f32 v6, -v6, v9, v8
	v_div_fmas_f32 v6, v6, v7, v9
	v_div_fixup_f32 v0, v6, v0, 1.0
	s_waitcnt vmcnt(23)
	v_lshlrev_b32_e32 v6, 16, v4
	v_and_b32_e32 v7, 0xffff0000, v4
	v_lshlrev_b32_e32 v4, 16, v5
	v_and_b32_e32 v5, 0xffff0000, v5
	v_pk_mul_f32 v[8:9], v[10:11], v[0:1] op_sel_hi:[1,0]
	v_pk_mul_f32 v[10:11], v[12:13], v[0:1] op_sel_hi:[1,0]
	v_pk_mul_f32 v[6:7], v[8:9], v[6:7]
	v_pk_mul_f32 v[4:5], v[10:11], v[4:5]
	v_cvt_pk_bf16_f32 v6, v6, v7
	v_cvt_pk_bf16_f32 v7, v4, v5
	global_store_dwordx2 v[2:3], v[6:7], off offset:3584

; #define GAS __attribute__((address_space(1)))
; __device__ __forceinline__ void relaunder(Frame& F) { int t = mk_tid(); asm volatile("" : "+v"(t)); F.tid = t; F.lane = t & 63; F.wave = __builtin_amdgcn_readfirstlane(t >> 6); }
; #define NORM_FN(...) do { if (NORM_PIPE && F.G == 256) norm_mod_phase2(__VA_ARGS__); else norm_mod_phase(__VA_ARGS__); } while (0)
; __device__ __forceinline__ void norm_mod_phase(const Args& a, Frame& F, const float* gain, const float* modl, int sh_off, int sc_off, int nrows, const float* slab_gate) {
;     relaunder(F);
;     const int gw = F.vcu * NWAVES + F.wave, NGW = F.G * NWAVES;
;     bf16* X = (bf16*)(a.ws + WS_X); bf16* HN = (bf16*)(a.ws + WS_HN);
;     for (int r = gw; r < nrows; r += NGW) {
;         const int b = (r < ML) ? (r >> 12) : 4;
;         const GAS v2u* xr = (const GAS v2u*)(X + (size_t)r * D) + F.lane;
;         f32x4 v[8]; float ss = 0.f;
; #pragma unroll
; __global__ void __launch_bounds__(NWAVES * 64, 2) fwd_kernel(Args args_in) {
;     ...
;         if (IN(pb + 5)) NORM_FN(args, F, args.in[7] + (size_t)layer * D, modl, 3 * D, 4 * D, Mr, last ? nullptr : modl + 4 * MOD_LD + 2 * D);
.LBB0_1034:
	s_andn2_b64 vcc, exec, s[8:9]
	s_cbranch_vccnz .LBB0_1097
	v_mov_b64_e32 v[2:3], s[0:1]
	s_waitcnt vmcnt(0) lgkmcnt(0)
	v_readlane_b32 s100, v255, 34
	v_readlane_b32 s101, v255, 35
	v_mov_b32_e32 v74, s100
	v_mov_b32_e32 v75, s101
	v_readlane_b32 s6, v254, 22
	v_readlane_b32 s7, v254, 23
	s_mov_b64 s[8:9], -1
	s_and_b64 vcc, exec, s[6:7]
	s_cbranch_vccz .LBB0_1042
	s_getreg_b32 s6, hwreg(HW_REG_HW_ID, 0, 6)
	s_lshl_b32 s6, s6, 2
	s_add_i32 s6, s6, 0
	s_add_i32 s6, s6, 0x20540
	v_mov_b32_e32 v0, s6
	ds_read_b32 v0, v0
	s_waitcnt lgkmcnt(0)
	v_readfirstlane_b32 s6, v0
	v_mbcnt_lo_u32_b32 v0, -1, 0
	v_mbcnt_hi_u32_b32 v0, -1, v0
	s_nop 1
	v_lshl_add_u32 v0, s6, 6, v0
	s_nop 0
	v_readfirstlane_b32 s6, v0
	s_ashr_i32 s6, s6, 6
	s_add_i32 s12, s6, s91
	s_cmp_ge_i32 s12, s47
	s_cbranch_scc1 .LBB0_1041
	v_mov_b64_e32 v[2:3], s[0:1]
	flat_load_dwordx2 v[2:3], v[2:3] offset:152
	s_add_u32 s8, s86, 0x34000
	v_and_b32_e32 v14, 63, v0
	s_addc_u32 s9, s87, 0
	s_lshl_b64 s[10:11], s[76:77], 13
	v_lshlrev_b32_e32 v4, 2, v14
	v_lshlrev_b32_e32 v0, 4, v14
	s_waitcnt vmcnt(0)
	v_lshl_add_u64 v[12:13], v[74:75], 0, s[10:11]
	s_and_b64 s[10:11], s[4:5], exec
	v_or_b32_e32 v28, 0x500, v4
	v_lshl_add_u64 v[16:17], s[8:9], 0, v[0:1]
	s_cselect_b32 s9, s9, 0
	s_cselect_b32 s8, s8, 0
	v_or_b32_e32 v30, 0x600, v4
	v_lshlrev_b32_e32 v6, 2, v28
	v_lshlrev_b32_e32 v86, 2, v28
	v_lshl_add_u64 v[28:29], s[8:9], 0, v[0:1]
	s_mov_b64 s[8:9], 0x1000
	v_lshlrev_b32_e32 v8, 2, v30
	v_lshlrev_b32_e32 v87, 2, v30
	v_lshl_add_u64 v[30:31], v[28:29], 0, s[8:9]
	s_mov_b64 s[8:9], 0x1400
	v_lshl_add_u64 v[32:33], v[28:29], 0, s[8:9]
	s_mov_b64 s[8:9], 0x1800
	s_ashr_i32 s7, s6, 31
	v_lshl_add_u64 v[34:35], v[28:29], 0, s[8:9]
	s_mov_b64 s[8:9], 0x1c00
	s_add_u32 s6, s91, s6
	v_lshl_add_u64 v[36:37], v[28:29], 0, s[8:9]
	v_readlane_b32 s8, v254, 59
	s_addc_u32 s7, s8, s7
	v_or_b32_e32 v26, 0x400, v4
	v_or_b32_e32 v40, 0x700, v4
	s_lshl_b64 s[6:7], s[6:7], 12
	v_mov_b32_e32 v5, v1
	v_mov_b32_e32 v7, v1
	v_mov_b32_e32 v9, v1
	v_mov_b32_e32 v11, v1
	v_or_b32_e32 v20, 0x100, v4
	v_or_b32_e32 v22, 0x200, v4
	v_or_b32_e32 v24, 0x300, v4
	v_lshlrev_b32_e32 v15, 2, v4
	v_lshlrev_b32_e32 v4, 2, v26
	v_lshlrev_b32_e32 v10, 2, v40
	v_lshl_add_u64 v[18:19], v[12:13], 0, v[0:1]
	v_lshlrev_b32_e32 v82, 2, v20
	v_lshlrev_b32_e32 v83, 2, v22
	v_lshlrev_b32_e32 v84, 2, v24
	v_lshlrev_b32_e32 v85, 2, v26
	v_lshl_add_u64 v[20:21], v[12:13], 0, v[4:5]
	v_lshl_add_u64 v[22:23], v[12:13], 0, v[6:7]
	v_lshl_add_u64 v[24:25], v[12:13], 0, v[8:9]
	v_lshl_add_u64 v[26:27], v[12:13], 0, v[10:11]
	v_lshlrev_b32_e32 v88, 2, v40
	s_waitcnt lgkmcnt(0)
	v_lshl_add_u64 v[2:3], v[2:3], 0, s[6:7]
	s_mov_b64 s[6:7], 0x8c00000
	v_lshl_add_u64 v[38:39], v[2:3], 0, s[6:7]
	s_branch .LBB0_1039

; #define GAS __attribute__((address_space(1)))
; #define LAS __attribute__((address_space(3)))
; #define NR_LOAD(dst, k_) do { const GAS v2u* xr_ = (const GAS v2u*)(X + (size_t)(nw + 2048 * (k_)) * D) + F.lane; \
;         _Pragma("unroll") for (int j = 0; j < 8; ++j) dst[j] = __builtin_nontemporal_load(xr_ + 64 * j); } while (0)
; __device__ __forceinline__ void norm_mod_phase2(const Args& a, Frame& F, const float* gain, const float* modl, int sh_off, int sc_off, int nrows, const float* slab_gate) {
;     ...
;     const int nw = F.vcu * NWAVES + F.wave;
;     bf16* X = (bf16*)(a.ws + WS_X); bf16* HN = (bf16*)(a.ws + WS_HN);
;     LAS float* CA = (LAS float*)F.lds; LAS float* CB = CA + 5 * D;
;     v2u r0[8], r1[8], r2[8], r3[8], r4[8], r5[8], r6[8], r7[8];
;     ...
;     NR_LOAD(r0, 0); NR_LOAD(r1, 1); NR_LOAD(r2, 2); NR_LOAD(r3, 3); NR_LOAD(r4, 4); NR_LOAD(r5, 5); NR_LOAD(r6, 6); NR_LOAD(r7, 7);
;     { const GAS f32x4* g4 = (const GAS f32x4*)gain;
;       for (int q = F.tid; q < 5 * D / 4; q += NWAVES * 64) { const int bq = q >> 9, cq = q & 511; const GAS f32x4* mb4 = (const GAS f32x4*)(modl + (size_t)bq * MOD_LD);
;           ((LAS f32x4*)CA)[q] = g4[cq] * (mb4[sc_off / 4 + cq] + 1.0f); ((LAS f32x4*)CB)[q] = mb4[sh_off / 4 + cq]; } }
.LBB0_1042:
	s_andn2_b64 vcc, exec, s[8:9]
	s_cbranch_vccnz .LBB0_1051
	s_getreg_b32 s6, hwreg(HW_REG_HW_ID, 0, 6)
	s_lshl_b32 s6, s6, 2
	s_add_i32 s6, s6, 0
	s_add_i32 s6, s6, 0x20540
	v_mov_b32_e32 v0, s6
	ds_read_b32 v0, v0
	v_mov_b64_e32 v[2:3], s[0:1]
	v_mov_b32_e32 v7, v1
	s_waitcnt lgkmcnt(0)
	v_readfirstlane_b32 s6, v0
	v_mbcnt_lo_u32_b32 v0, -1, 0
	v_mbcnt_hi_u32_b32 v0, -1, v0
	s_nop 1
	v_lshl_add_u32 v142, s6, 6, v0
	v_mov_b32_e32 v136, s72
	v_mov_b32_e32 v137, s73
	v_readfirstlane_b32 s6, v142
	s_ashr_i32 s6, s6, 6
	s_add_i32 s10, s6, s91
	s_mov_b64 s[6:7], 0x400000
	s_ashr_i32 s11, s10, 31
	v_and_b32_e32 v147, 63, v142
	s_add_i32 s78, s10, 0x800
	v_lshlrev_b32_e32 v6, 3, v147
	s_ashr_i32 s79, s78, 31
	s_add_i32 s36, s10, 0x1000
	s_ashr_i32 s37, s36, 31
	s_add_i32 s30, s10, 0x1800
	s_ashr_i32 s31, s30, 31
	s_add_i32 s26, s10, 0x2000
	s_ashr_i32 s27, s26, 31
	s_add_i32 s22, s10, 0x2800
	s_ashr_i32 s23, s22, 31
	s_add_i32 s18, s10, 0x3000
	s_ashr_i32 s19, s18, 31
	s_add_i32 s14, s10, 0x3800
	s_ashr_i32 s15, s14, 31
	s_waitcnt vmcnt(0) lgkmcnt(0)
	v_lshl_add_u64 v[8:9], v[136:137], 0, s[6:7]
	s_lshl_b64 s[6:7], s[10:11], 12
	v_lshl_add_u64 v[2:3], v[8:9], 0, s[6:7]
	v_lshl_add_u64 v[2:3], v[2:3], 0, v[6:7]
	s_lshl_b64 s[6:7], s[78:79], 12
	global_load_dwordx2 v[140:141], v[2:3], off nt
	global_load_dwordx2 v[138:139], v[2:3], off offset:512 nt
	global_load_dwordx2 v[134:135], v[2:3], off offset:1024 nt
	global_load_dwordx2 v[132:133], v[2:3], off offset:1536 nt
	global_load_dwordx2 v[130:131], v[2:3], off offset:2048 nt
	global_load_dwordx2 v[128:129], v[2:3], off offset:2560 nt
	global_load_dwordx2 v[126:127], v[2:3], off offset:3072 nt
	global_load_dwordx2 v[124:125], v[2:3], off offset:3584 nt
	v_lshl_add_u64 v[2:3], v[8:9], 0, s[6:7]
	v_lshl_add_u64 v[2:3], v[2:3], 0, v[6:7]
	s_lshl_b64 s[6:7], s[36:37], 12
	global_load_dwordx2 v[122:123], v[2:3], off nt
	global_load_dwordx2 v[120:121], v[2:3], off offset:512 nt
	global_load_dwordx2 v[118:119], v[2:3], off offset:1024 nt
	global_load_dwordx2 v[116:117], v[2:3], off offset:1536 nt
	global_load_dwordx2 v[114:115], v[2:3], off offset:2048 nt
	global_load_dwordx2 v[112:113], v[2:3], off offset:2560 nt
	global_load_dwordx2 v[110:111], v[2:3], off offset:3072 nt
	global_load_dwordx2 v[108:109], v[2:3], off offset:3584 nt
	v_lshl_add_u64 v[2:3], v[8:9], 0, s[6:7]
	v_lshl_add_u64 v[2:3], v[2:3], 0, v[6:7]
	s_lshl_b64 s[6:7], s[30:31], 12
	global_load_dwordx2 v[106:107], v[2:3], off nt
	global_load_dwordx2 v[104:105], v[2:3], off offset:512 nt
	global_load_dwordx2 v[102:103], v[2:3], off offset:1024 nt
	global_load_dwordx2 v[100:101], v[2:3], off offset:1536 nt
	global_load_dwordx2 v[98:99], v[2:3], off offset:2048 nt
	global_load_dwordx2 v[96:97], v[2:3], off offset:2560 nt
	global_load_dwordx2 v[94:95], v[2:3], off offset:3072 nt
	global_load_dwordx2 v[92:93], v[2:3], off offset:3584 nt
	v_lshl_add_u64 v[2:3], v[8:9], 0, s[6:7]
	v_lshl_add_u64 v[2:3], v[2:3], 0, v[6:7]
	s_lshl_b64 s[6:7], s[26:27], 12
	global_load_dwordx2 v[90:91], v[2:3], off nt
	global_load_dwordx2 v[88:89], v[2:3], off offset:512 nt
	global_load_dwordx2 v[86:87], v[2:3], off offset:1024 nt
	global_load_dwordx2 v[84:85], v[2:3], off offset:1536 nt
	global_load_dwordx2 v[82:83], v[2:3], off offset:2048 nt
	global_load_dwordx2 v[80:81], v[2:3], off offset:2560 nt
	global_load_dwordx2 v[78:79], v[2:3], off offset:3072 nt
	global_load_dwordx2 v[76:77], v[2:3], off offset:3584 nt
	v_lshl_add_u64 v[2:3], v[8:9], 0, s[6:7]
	v_lshl_add_u64 v[2:3], v[2:3], 0, v[6:7]
	s_lshl_b64 s[6:7], s[22:23], 12
	global_load_dwordx2 v[72:73], v[2:3], off nt
	global_load_dwordx2 v[70:71], v[2:3], off offset:512 nt
	global_load_dwordx2 v[68:69], v[2:3], off offset:1024 nt
	global_load_dwordx2 v[66:67], v[2:3], off offset:1536 nt
	global_load_dwordx2 v[64:65], v[2:3], off offset:2048 nt
	global_load_dwordx2 v[62:63], v[2:3], off offset:2560 nt
	global_load_dwordx2 v[60:61], v[2:3], off offset:3072 nt
	global_load_dwordx2 v[58:59], v[2:3], off offset:3584 nt
	v_lshl_add_u64 v[2:3], v[8:9], 0, s[6:7]
	v_lshl_add_u64 v[2:3], v[2:3], 0, v[6:7]
	s_lshl_b64 s[6:7], s[18:19], 12
	global_load_dwordx2 v[56:57], v[2:3], off nt
	global_load_dwordx2 v[54:55], v[2:3], off offset:512 nt
	global_load_dwordx2 v[52:53], v[2:3], off offset:1024 nt
	global_load_dwordx2 v[50:51], v[2:3], off offset:1536 nt
	global_load_dwordx2 v[48:49], v[2:3], off offset:2048 nt
	global_load_dwordx2 v[46:47], v[2:3], off offset:2560 nt
	global_load_dwordx2 v[44:45], v[2:3], off offset:3072 nt
	global_load_dwordx2 v[42:43], v[2:3], off offset:3584 nt
	v_lshl_add_u64 v[2:3], v[8:9], 0, s[6:7]
	v_lshl_add_u64 v[2:3], v[2:3], 0, v[6:7]
	s_lshl_b64 s[6:7], s[14:15], 12
	global_load_dwordx2 v[40:41], v[2:3], off nt
	global_load_dwordx2 v[38:39], v[2:3], off offset:512 nt
	global_load_dwordx2 v[36:37], v[2:3], off offset:1024 nt
	global_load_dwordx2 v[34:35], v[2:3], off offset:1536 nt
	global_load_dwordx2 v[32:33], v[2:3], off offset:2048 nt
	global_load_dwordx2 v[30:31], v[2:3], off offset:2560 nt
	global_load_dwordx2 v[28:29], v[2:3], off offset:3072 nt
	global_load_dwordx2 v[26:27], v[2:3], off offset:3584 nt
	v_lshl_add_u64 v[2:3], v[8:9], 0, s[6:7]
	v_lshl_add_u64 v[2:3], v[2:3], 0, v[6:7]
	global_load_dwordx2 v[24:25], v[2:3], off nt
	global_load_dwordx2 v[22:23], v[2:3], off offset:512 nt
	global_load_dwordx2 v[20:21], v[2:3], off offset:1024 nt
	global_load_dwordx2 v[18:19], v[2:3], off offset:1536 nt
	global_load_dwordx2 v[16:17], v[2:3], off offset:2048 nt
	global_load_dwordx2 v[14:15], v[2:3], off offset:2560 nt
	global_load_dwordx2 v[12:13], v[2:3], off offset:3072 nt
	global_load_dwordx2 v[10:11], v[2:3], off offset:3584 nt
	s_movk_i32 s6, 0xa00
	v_cmp_gt_i32_e32 vcc, s6, v142
	s_and_saveexec_b64 s[8:9], vcc
	s_cbranch_execz .LBB0_1046
	s_lshl_b64 s[6:7], s[76:77], 13
	v_lshl_add_u64 v[2:3], v[74:75], 0, s[6:7]
	v_and_b32_e32 v74, 0x1ff, v142
	v_lshlrev_b32_e32 v0, 4, v74
	v_lshl_add_u64 v[2:3], v[2:3], 0, v[0:1]
	global_load_dwordx4 v[2:5], v[2:3], off
	v_lshl_add_u32 v7, v142, 4, 0
	s_mov_b64 s[12:13], 0
	v_lshlrev_b32_e32 v0, 4, v74

; __global__ void __launch_bounds__(NWAVES * 64, 2) fwd_kernel(Args args_in) {
	.amdhsa_kernel _Z10fwd_kernel4Args
		.amdhsa_group_segment_fixed_size 0
		.amdhsa_private_segment_fixed_size 0
		.amdhsa_kernarg_size 424
		.amdhsa_user_sgpr_count 2
		.amdhsa_user_sgpr_dispatch_ptr 0
		.amdhsa_user_sgpr_queue_ptr 0
		.amdhsa_user_sgpr_kernarg_segment_ptr 1
		.amdhsa_user_sgpr_dispatch_id 0
		.amdhsa_user_sgpr_kernarg_preload_length 0
		.amdhsa_user_sgpr_kernarg_preload_offset 0
		.amdhsa_user_sgpr_private_segment_size 0
		.amdhsa_uses_dynamic_stack 0
		.amdhsa_enable_private_segment 0
		.amdhsa_system_sgpr_workgroup_id_x 1
		.amdhsa_system_sgpr_workgroup_id_y 0
		.amdhsa_system_sgpr_workgroup_id_z 0
		.amdhsa_system_sgpr_workgroup_info 0
		.amdhsa_system_vgpr_workitem_id 0
		.amdhsa_next_free_vgpr 256
		.amdhsa_next_free_sgpr 102
		.amdhsa_accum_offset 256
		.amdhsa_reserve_vcc 1
		.amdhsa_float_round_mode_32 0
		.amdhsa_float_round_mode_16_64 0
		.amdhsa_float_denorm_mode_32 3
		.amdhsa_float_denorm_mode_16_64 3
		.amdhsa_dx10_clamp 1
		.amdhsa_ieee_mode 1
		.amdhsa_fp16_overflow 0
		.amdhsa_tg_split 0
		.amdhsa_exception_fp_ieee_invalid_op 0
		.amdhsa_exception_fp_denorm_src 0
		.amdhsa_exception_fp_ieee_div_zero 0
		.amdhsa_exception_fp_ieee_overflow 0
		.amdhsa_exception_fp_ieee_underflow 0
		.amdhsa_exception_fp_ieee_inexact 0
		.amdhsa_exception_int_div_zero 0
	.end_amdhsa_kernel

; __global__ void __launch_bounds__(NWAVES * 64, 2) fwd_kernel(Args args_in) {
amdhsa.kernels:
  - .agpr_count:     0
    .args:
      - .offset:         0
        .size:           168
        .value_kind:     by_value
      - .offset:         168
        .size:           4
        .value_kind:     hidden_block_count_x
      - .offset:         172
        .size:           4
        .value_kind:     hidden_block_count_y
      - .offset:         176
        .size:           4
        .value_kind:     hidden_block_count_z
      - .offset:         180
        .size:           2
        .value_kind:     hidden_group_size_x
      - .offset:         182
        .size:           2
        .value_kind:     hidden_group_size_y
      - .offset:         184
        .size:           2
        .value_kind:     hidden_group_size_z
      - .offset:         186
        .size:           2
        .value_kind:     hidden_remainder_x
      - .offset:         188
        .size:           2
        .value_kind:     hidden_remainder_y
      - .offset:         190
        .size:           2
        .value_kind:     hidden_remainder_z
      - .offset:         208
        .size:           8
        .value_kind:     hidden_global_offset_x
      - .offset:         216
        .size:           8
        .value_kind:     hidden_global_offset_y
      - .offset:         224
        .size:           8
        .value_kind:     hidden_global_offset_z
      - .offset:         232
        .size:           2
        .value_kind:     hidden_grid_dims
      - .offset:         288
        .size:           4
        .value_kind:     hidden_dynamic_lds_size
    .group_segment_fixed_size: 0
    .kernarg_segment_align: 8
    .kernarg_segment_size: 424
    .language:       OpenCL C
    .language_version:
      - 2
      - 0
    .max_flat_workgroup_size: 512
    .name:           _Z10fwd_kernel4Args
    .private_segment_fixed_size: 0
    .sgpr_count:     108
    .sgpr_spill_count: 94
    .symbol:         _Z10fwd_kernel4Args.kd
    .uniform_work_group_size: 1
    .uses_dynamic_stack: false
    .vgpr_count:     256
    .vgpr_spill_count: 0
    .wavefront_size: 64
